# all per-phase s_setprio flips removed (on v7)
# speedup vs baseline: 1.0070x; 1.0070x over previous
;     ...
;         G_PAIR(0, 1);
.LBB0_231:
	s_ashr_i32 s19, s18, 31
	ds_read_b128 v[0:3], v152
	ds_read_b128 v[4:7], v152 offset:1024
	ds_read_b128 v[8:11], v152 offset:2048
	ds_read_b128 v[12:15], v152 offset:3072
	s_lshl_b64 s[20:21], s[18:19], 19
	s_add_u32 s20, s10, s20
	s_addc_u32 s21, s11, s21
	s_ashr_i32 s17, s16, 31
	s_lshl_b64 s[22:23], s[16:17], 19
	s_add_u32 s22, s39, s22
	s_addc_u32 s23, s40, s23
	s_add_u32 s34, s26, 0x40080
	s_addc_u32 s35, s27, 0
	s_mov_b32 m0, s47
	v_lshl_add_u64 v[48:49], s[34:35], 0, v[136:137]
	ds_read_b128 v[16:19], v153
	ds_read_b128 v[20:23], v153 offset:1024
	ds_read_b128 v[24:27], v153 offset:2048
	ds_read_b128 v[28:31], v153 offset:3072
	ds_read_b128 v[32:35], v153 offset:4096
	ds_read_b128 v[36:39], v153 offset:5120
	ds_read_b128 v[40:43], v153 offset:6144
	ds_read_b128 v[44:47], v153 offset:7168
	global_load_lds_dwordx4 v[48:49], off
	s_mov_b32 m0, s48
	v_lshl_add_u64 v[48:49], s[34:35], 0, v[132:133]
	global_load_lds_dwordx4 v[48:49], off
	s_waitcnt lgkmcnt(8)
	s_barrier
	s_waitcnt lgkmcnt(0)
	v_mfma_f32_16x16x32_bf16 v[48:51], v[0:3], v[16:19], 0
	v_mfma_f32_16x16x32_bf16 v[52:55], v[8:11], v[16:19], 0
	v_mfma_f32_16x16x32_bf16 v[56:59], v[0:3], v[24:27], 0
	v_mfma_f32_16x16x32_bf16 v[60:63], v[8:11], v[24:27], 0
	v_mfma_f32_16x16x32_bf16 v[64:67], v[0:3], v[32:35], 0
	v_mfma_f32_16x16x32_bf16 v[68:71], v[8:11], v[32:35], 0
	v_mfma_f32_16x16x32_bf16 v[72:75], v[0:3], v[40:43], 0
	v_mfma_f32_16x16x32_bf16 v[76:79], v[8:11], v[40:43], 0
	v_mfma_f32_16x16x32_bf16 v[48:51], v[4:7], v[20:23], v[48:51]
	v_mfma_f32_16x16x32_bf16 v[52:55], v[12:15], v[20:23], v[52:55]
	v_mfma_f32_16x16x32_bf16 v[56:59], v[4:7], v[28:31], v[56:59]
	v_mfma_f32_16x16x32_bf16 v[60:63], v[12:15], v[28:31], v[60:63]
	v_mfma_f32_16x16x32_bf16 v[64:67], v[4:7], v[36:39], v[64:67]
	v_mfma_f32_16x16x32_bf16 v[68:71], v[12:15], v[36:39], v[68:71]
	v_mfma_f32_16x16x32_bf16 v[72:75], v[4:7], v[44:47], v[72:75]
	v_mfma_f32_16x16x32_bf16 v[76:79], v[12:15], v[44:47], v[76:79]
	s_barrier
	v_lshl_add_u64 v[218:219], s[28:29], 0, v[134:135]
	s_mov_b32 m0, s49
	v_lshl_add_u64 v[96:97], v[218:219], 0, s[8:9]
	v_lshl_add_u64 v[238:239], s[28:29], 0, v[130:131]
	ds_read_b128 v[80:83], v154
	ds_read_b128 v[84:87], v154 offset:1024
	ds_read_b128 v[88:91], v154 offset:2048
	ds_read_b128 v[92:95], v154 offset:3072
	global_load_lds_dwordx4 v[96:97], off
	s_mov_b32 m0, s50
	v_lshl_add_u64 v[96:97], v[238:239], 0, s[8:9]
	global_load_lds_dwordx4 v[96:97], off
	s_barrier
	s_waitcnt lgkmcnt(0)
	v_mfma_f32_16x16x32_bf16 v[96:99], v[80:83], v[16:19], 0
	v_mfma_f32_16x16x32_bf16 v[16:19], v[88:91], v[16:19], 0
	v_mfma_f32_16x16x32_bf16 v[100:103], v[80:83], v[24:27], 0
	v_mfma_f32_16x16x32_bf16 v[24:27], v[88:91], v[24:27], 0
	v_mfma_f32_16x16x32_bf16 v[104:107], v[80:83], v[32:35], 0
	v_mfma_f32_16x16x32_bf16 v[32:35], v[88:91], v[32:35], 0
	v_mfma_f32_16x16x32_bf16 v[108:111], v[80:83], v[40:43], 0
	v_mfma_f32_16x16x32_bf16 v[40:43], v[88:91], v[40:43], 0
	v_mfma_f32_16x16x32_bf16 v[116:119], v[84:87], v[20:23], v[96:99]
	v_mfma_f32_16x16x32_bf16 v[16:19], v[92:95], v[20:23], v[16:19]
	v_mfma_f32_16x16x32_bf16 v[20:23], v[84:87], v[28:31], v[100:103]
	v_mfma_f32_16x16x32_bf16 v[24:27], v[92:95], v[28:31], v[24:27]
	v_mfma_f32_16x16x32_bf16 v[28:31], v[84:87], v[36:39], v[104:107]
	v_mfma_f32_16x16x32_bf16 v[32:35], v[92:95], v[36:39], v[32:35]
	v_mfma_f32_16x16x32_bf16 v[36:39], v[84:87], v[44:47], v[108:111]
	v_mfma_f32_16x16x32_bf16 v[40:43], v[92:95], v[44:47], v[40:43]
	v_lshl_add_u64 v[246:247], s[26:27], 0, v[136:137]
	s_mov_b32 m0, s25
	v_lshl_add_u64 v[142:143], v[246:247], 0, s[8:9]
	v_lshl_add_u64 v[248:249], s[26:27], 0, v[132:133]
	s_barrier
	ds_read_b128 v[44:47], v153 offset:16384
	ds_read_b128 v[96:99], v153 offset:17408
	ds_read_b128 v[100:103], v153 offset:18432
	ds_read_b128 v[104:107], v153 offset:19456
	ds_read_b128 v[108:111], v153 offset:20480
	ds_read_b128 v[112:115], v153 offset:21504
	ds_read_b128 v[120:123], v153 offset:22528
	ds_read_b128 v[124:127], v153 offset:23552
	global_load_lds_dwordx4 v[142:143], off
	s_mov_b32 m0, s41
	v_lshl_add_u64 v[142:143], v[248:249], 0, s[8:9]
	global_load_lds_dwordx4 v[142:143], off
	s_barrier
	s_waitcnt lgkmcnt(0)
	v_mfma_f32_16x16x32_bf16 v[142:145], v[0:3], v[44:47], 0
	v_mfma_f32_16x16x32_bf16 v[158:161], v[8:11], v[44:47], 0
	v_mfma_f32_16x16x32_bf16 v[162:165], v[0:3], v[100:103], 0
	v_mfma_f32_16x16x32_bf16 v[166:169], v[8:11], v[100:103], 0
	v_mfma_f32_16x16x32_bf16 v[170:173], v[0:3], v[108:111], 0
	v_mfma_f32_16x16x32_bf16 v[174:177], v[8:11], v[108:111], 0
	v_mfma_f32_16x16x32_bf16 v[0:3], v[0:3], v[120:123], 0
	v_mfma_f32_16x16x32_bf16 v[8:11], v[8:11], v[120:123], 0
	v_mfma_f32_16x16x32_bf16 v[142:145], v[4:7], v[96:99], v[142:145]
	v_mfma_f32_16x16x32_bf16 v[162:165], v[4:7], v[104:107], v[162:165]
	v_mfma_f32_16x16x32_bf16 v[170:173], v[4:7], v[112:115], v[170:173]
	v_mfma_f32_16x16x32_bf16 v[0:3], v[4:7], v[124:127], v[0:3]
	v_mfma_f32_16x16x32_bf16 v[4:7], v[12:15], v[124:127], v[8:11]
	v_mfma_f32_16x16x32_bf16 v[158:161], v[12:15], v[96:99], v[158:161]
	v_mfma_f32_16x16x32_bf16 v[166:169], v[12:15], v[104:107], v[166:169]
	v_mfma_f32_16x16x32_bf16 v[174:177], v[12:15], v[112:115], v[174:177]
	s_barrier
	s_add_u32 s34, s28, 0x40100
	s_addc_u32 s35, s29, 0
	s_mov_b32 m0, s55
	v_lshl_add_u64 v[8:9], s[34:35], 0, v[134:135]
	global_load_lds_dwordx4 v[8:9], off
	s_mov_b32 m0, s56
	v_lshl_add_u64 v[8:9], s[34:35], 0, v[130:131]
	global_load_lds_dwordx4 v[8:9], off
	s_waitcnt vmcnt(6)
	s_barrier
	v_mfma_f32_16x16x32_bf16 v[8:11], v[80:83], v[44:47], 0
	v_mfma_f32_16x16x32_bf16 v[12:15], v[88:91], v[44:47], 0
	v_mfma_f32_16x16x32_bf16 v[44:47], v[80:83], v[100:103], 0
	v_mfma_f32_16x16x32_bf16 v[100:103], v[88:91], v[100:103], 0
	v_mfma_f32_16x16x32_bf16 v[178:181], v[80:83], v[108:111], 0
	v_mfma_f32_16x16x32_bf16 v[108:111], v[88:91], v[108:111], 0
	v_mfma_f32_16x16x32_bf16 v[80:83], v[80:83], v[120:123], 0
	v_mfma_f32_16x16x32_bf16 v[88:91], v[88:91], v[120:123], 0
	v_mfma_f32_16x16x32_bf16 v[12:15], v[92:95], v[96:99], v[12:15]
	v_mfma_f32_16x16x32_bf16 v[44:47], v[84:87], v[104:107], v[44:47]
	v_mfma_f32_16x16x32_bf16 v[182:185], v[84:87], v[96:99], v[8:11]
	v_mfma_f32_16x16x32_bf16 v[186:189], v[92:95], v[104:107], v[100:103]
	v_mfma_f32_16x16x32_bf16 v[178:181], v[84:87], v[112:115], v[178:181]
	v_mfma_f32_16x16x32_bf16 v[190:193], v[92:95], v[112:115], v[108:111]
	v_mfma_f32_16x16x32_bf16 v[194:197], v[84:87], v[124:127], v[80:83]
	v_mfma_f32_16x16x32_bf16 v[198:201], v[92:95], v[124:127], v[88:91]
	s_barrier
	ds_read_b128 v[8:11], v155
	ds_read_b128 v[202:205], v155 offset:1024
	ds_read_b128 v[206:209], v155 offset:2048
	ds_read_b128 v[210:213], v155 offset:3072
	s_add_u32 s34, s26, 0x40100
	s_addc_u32 s35, s27, 0
	s_mov_b32 m0, s42
	v_lshl_add_u64 v[80:81], s[34:35], 0, v[136:137]
	ds_read_b128 v[84:87], v153 offset:32768
	ds_read_b128 v[92:95], v153 offset:33792
	ds_read_b128 v[100:103], v153 offset:34816
	ds_read_b128 v[214:217], v153 offset:35840
	ds_read_b128 v[108:111], v153 offset:36864
	ds_read_b128 v[222:225], v153 offset:37888
	ds_read_b128 v[124:127], v153 offset:38912
	ds_read_b128 v[226:229], v153 offset:39936
	global_load_lds_dwordx4 v[80:81], off
	s_mov_b32 m0, s43
	v_lshl_add_u64 v[80:81], s[34:35], 0, v[132:133]
	global_load_lds_dwordx4 v[80:81], off
	s_waitcnt lgkmcnt(8)
	s_barrier
	s_waitcnt lgkmcnt(0)
	v_mfma_f32_16x16x32_bf16 v[48:51], v[8:11], v[84:87], v[48:51]
	v_mfma_f32_16x16x32_bf16 v[52:55], v[206:209], v[84:87], v[52:55]
	v_mfma_f32_16x16x32_bf16 v[56:59], v[8:11], v[100:103], v[56:59]
	v_mfma_f32_16x16x32_bf16 v[60:63], v[206:209], v[100:103], v[60:63]
	v_mfma_f32_16x16x32_bf16 v[64:67], v[8:11], v[108:111], v[64:67]
	v_mfma_f32_16x16x32_bf16 v[68:71], v[206:209], v[108:111], v[68:71]
	v_mfma_f32_16x16x32_bf16 v[72:75], v[8:11], v[124:127], v[72:75]
	v_mfma_f32_16x16x32_bf16 v[76:79], v[206:209], v[124:127], v[76:79]
	v_mfma_f32_16x16x32_bf16 v[120:123], v[202:205], v[92:95], v[48:51]
	v_mfma_f32_16x16x32_bf16 v[112:115], v[210:213], v[92:95], v[52:55]
	v_mfma_f32_16x16x32_bf16 v[104:107], v[202:205], v[214:217], v[56:59]
	v_mfma_f32_16x16x32_bf16 v[96:99], v[210:213], v[214:217], v[60:63]
	v_mfma_f32_16x16x32_bf16 v[88:91], v[202:205], v[222:225], v[64:67]
	v_mfma_f32_16x16x32_bf16 v[80:83], v[210:213], v[222:225], v[68:71]
	v_mfma_f32_16x16x32_bf16 v[72:75], v[202:205], v[226:229], v[72:75]
	v_mfma_f32_16x16x32_bf16 v[60:63], v[210:213], v[226:229], v[76:79]
	s_barrier
	s_mov_b32 m0, s57
	v_lshl_add_u64 v[48:49], v[218:219], 0, s[12:13]
	ds_read_b128 v[52:55], v156
	ds_read_b128 v[230:233], v156 offset:1024
	ds_read_b128 v[68:71], v156 offset:2048
	ds_read_b128 v[234:237], v156 offset:3072
	global_load_lds_dwordx4 v[48:49], off
	s_mov_b32 m0, s58
	v_lshl_add_u64 v[48:49], v[238:239], 0, s[12:13]
	global_load_lds_dwordx4 v[48:49], off
	s_barrier
	s_waitcnt lgkmcnt(0)
	v_mfma_f32_16x16x32_bf16 v[48:51], v[52:55], v[84:87], v[116:119]
	v_mfma_f32_16x16x32_bf16 v[16:19], v[68:71], v[84:87], v[16:19]
	v_mfma_f32_16x16x32_bf16 v[20:23], v[52:55], v[100:103], v[20:23]
	v_mfma_f32_16x16x32_bf16 v[24:27], v[68:71], v[100:103], v[24:27]
	v_mfma_f32_16x16x32_bf16 v[28:31], v[52:55], v[108:111], v[28:31]
	v_mfma_f32_16x16x32_bf16 v[32:35], v[68:71], v[108:111], v[32:35]
	v_mfma_f32_16x16x32_bf16 v[36:39], v[52:55], v[124:127], v[36:39]
	v_mfma_f32_16x16x32_bf16 v[40:43], v[68:71], v[124:127], v[40:43]
	v_mfma_f32_16x16x32_bf16 v[124:127], v[230:233], v[92:95], v[48:51]
	v_mfma_f32_16x16x32_bf16 v[116:119], v[234:237], v[92:95], v[16:19]
	v_mfma_f32_16x16x32_bf16 v[108:111], v[230:233], v[214:217], v[20:23]
	v_mfma_f32_16x16x32_bf16 v[100:103], v[234:237], v[214:217], v[24:27]
	v_mfma_f32_16x16x32_bf16 v[92:95], v[230:233], v[222:225], v[28:31]
	v_mfma_f32_16x16x32_bf16 v[84:87], v[234:237], v[222:225], v[32:35]
	v_mfma_f32_16x16x32_bf16 v[76:79], v[230:233], v[226:229], v[36:39]
	v_mfma_f32_16x16x32_bf16 v[64:67], v[234:237], v[226:229], v[40:43]
	s_mov_b32 m0, s44
	v_lshl_add_u64 v[16:17], v[246:247], 0, s[12:13]
	s_barrier
	ds_read_b128 v[20:23], v153 offset:49152
	ds_read_b128 v[28:31], v153 offset:50176
	ds_read_b128 v[36:39], v153 offset:51200
	ds_read_b128 v[214:217], v153 offset:52224
	ds_read_b128 v[222:225], v153 offset:53248
	ds_read_b128 v[226:229], v153 offset:54272
	ds_read_b128 v[238:241], v153 offset:55296
	ds_read_b128 v[242:245], v153 offset:56320
	global_load_lds_dwordx4 v[16:17], off
	s_mov_b32 m0, s45
	v_lshl_add_u64 v[16:17], v[248:249], 0, s[12:13]
	global_load_lds_dwordx4 v[16:17], off
	s_barrier
	s_waitcnt lgkmcnt(0)
	v_mfma_f32_16x16x32_bf16 v[16:19], v[8:11], v[20:23], v[142:145]
	v_mfma_f32_16x16x32_bf16 v[24:27], v[206:209], v[20:23], v[158:161]
	v_mfma_f32_16x16x32_bf16 v[32:35], v[8:11], v[36:39], v[162:165]
	v_mfma_f32_16x16x32_bf16 v[142:145], v[206:209], v[36:39], v[166:169]
	v_mfma_f32_16x16x32_bf16 v[158:161], v[8:11], v[222:225], v[170:173]
	v_mfma_f32_16x16x32_bf16 v[162:165], v[206:209], v[222:225], v[174:177]
	v_mfma_f32_16x16x32_bf16 v[0:3], v[8:11], v[238:241], v[0:3]
	v_mfma_f32_16x16x32_bf16 v[4:7], v[206:209], v[238:241], v[4:7]
	v_mfma_f32_16x16x32_bf16 v[56:59], v[202:205], v[28:31], v[16:19]
	v_mfma_f32_16x16x32_bf16 v[48:51], v[210:213], v[28:31], v[24:27]
	v_mfma_f32_16x16x32_bf16 v[40:43], v[202:205], v[214:217], v[32:35]
	v_mfma_f32_16x16x32_bf16 v[32:35], v[210:213], v[214:217], v[142:145]
	v_mfma_f32_16x16x32_bf16 v[24:27], v[202:205], v[226:229], v[158:161]
	v_mfma_f32_16x16x32_bf16 v[16:19], v[210:213], v[226:229], v[162:165]
	v_mfma_f32_16x16x32_bf16 v[8:11], v[202:205], v[242:245], v[0:3]
	v_mfma_f32_16x16x32_bf16 v[0:3], v[210:213], v[242:245], v[4:7]
	s_barrier
;     ...
;         G_PAIR(0, 1);
; #pragma unroll 1
;         for (int t = 2; t < nt; t += 2) G_PAIR(t, 0);
	s_add_u32 s34, s28, 0x40180
	s_addc_u32 s35, s29, 0
	s_mov_b32 m0, s59
	v_lshl_add_u64 v[4:5], s[34:35], 0, v[134:135]
	s_add_i32 s17, s59, 0x2000
	global_load_lds_dwordx4 v[4:5], off
	v_lshl_add_u64 v[4:5], s[34:35], 0, v[130:131]
	s_mov_b32 m0, s17
	s_mov_b64 s[34:35], 0x40180
	global_load_lds_dwordx4 v[4:5], off
	s_waitcnt vmcnt(6)
	s_barrier
	v_mfma_f32_16x16x32_bf16 v[4:7], v[52:55], v[20:23], v[182:185]
	v_mfma_f32_16x16x32_bf16 v[12:15], v[68:71], v[20:23], v[12:15]
	v_mfma_f32_16x16x32_bf16 v[20:23], v[52:55], v[36:39], v[44:47]
	v_mfma_f32_16x16x32_bf16 v[36:39], v[68:71], v[36:39], v[186:189]
	v_mfma_f32_16x16x32_bf16 v[142:145], v[52:55], v[222:225], v[178:181]
	v_mfma_f32_16x16x32_bf16 v[158:161], v[68:71], v[222:225], v[190:193]
	v_mfma_f32_16x16x32_bf16 v[162:165], v[52:55], v[238:241], v[194:197]
	v_mfma_f32_16x16x32_bf16 v[166:169], v[68:71], v[238:241], v[198:201]
	v_mfma_f32_16x16x32_bf16 v[68:71], v[230:233], v[28:31], v[4:7]
	v_mfma_f32_16x16x32_bf16 v[52:55], v[234:237], v[28:31], v[12:15]
	v_mfma_f32_16x16x32_bf16 v[44:47], v[230:233], v[214:217], v[20:23]
	v_mfma_f32_16x16x32_bf16 v[36:39], v[234:237], v[214:217], v[36:39]
	v_mfma_f32_16x16x32_bf16 v[28:31], v[230:233], v[226:229], v[142:145]
	v_mfma_f32_16x16x32_bf16 v[20:23], v[234:237], v[226:229], v[158:161]
	v_mfma_f32_16x16x32_bf16 v[12:15], v[230:233], v[242:245], v[162:165]
	v_mfma_f32_16x16x32_bf16 v[4:7], v[234:237], v[242:245], v[166:169]
	v_lshl_add_u64 v[142:143], s[26:27], 0, v[138:139]
	v_lshl_add_u64 v[144:145], s[26:27], 0, v[140:141]
	s_mov_b32 s19, 0
	s_barrier
.LBB0_232:
	ds_read_b128 v[158:161], v152
	ds_read_b128 v[162:165], v152 offset:1024
	ds_read_b128 v[166:169], v152 offset:2048
	ds_read_b128 v[170:173], v152 offset:3072
	s_mov_b32 m0, s47
	v_lshl_add_u64 v[206:207], v[142:143], 0, s[34:35]
	ds_read_b128 v[174:177], v153
	ds_read_b128 v[178:181], v153 offset:1024
	ds_read_b128 v[182:185], v153 offset:2048
	ds_read_b128 v[186:189], v153 offset:3072
	ds_read_b128 v[190:193], v153 offset:4096
	ds_read_b128 v[194:197], v153 offset:5120
	ds_read_b128 v[198:201], v153 offset:6144
	ds_read_b128 v[202:205], v153 offset:7168
	global_load_lds_dwordx4 v[206:207], off
	s_mov_b32 m0, s48
	v_lshl_add_u64 v[206:207], v[144:145], 0, s[34:35]
	global_load_lds_dwordx4 v[206:207], off
	s_waitcnt lgkmcnt(8)
	s_barrier
	s_waitcnt lgkmcnt(0)
	v_mfma_f32_16x16x32_bf16 v[120:123], v[158:161], v[174:177], v[120:123]
	s_add_i32 s61, s34, 0xfffc0080
	v_mfma_f32_16x16x32_bf16 v[112:115], v[166:169], v[174:177], v[112:115]
	s_cmp_eq_u32 s19, 12
	v_mfma_f32_16x16x32_bf16 v[104:107], v[158:161], v[182:185], v[104:107]
	s_cselect_b64 s[36:37], -1, 0
	v_mfma_f32_16x16x32_bf16 v[96:99], v[166:169], v[182:185], v[96:99]
	s_and_b64 s[62:63], s[36:37], exec
	v_mfma_f32_16x16x32_bf16 v[88:91], v[158:161], v[190:193], v[88:91]
	s_cselect_b32 s61, 0, s61
	v_mfma_f32_16x16x32_bf16 v[80:83], v[166:169], v[190:193], v[80:83]
	s_and_b64 s[36:37], s[30:31], s[36:37]
	v_mfma_f32_16x16x32_bf16 v[72:75], v[158:161], v[198:201], v[72:75]
	s_and_b64 s[36:37], s[36:37], exec
	v_mfma_f32_16x16x32_bf16 v[60:63], v[166:169], v[198:201], v[60:63]
	s_cselect_b32 s63, s21, s27
	v_mfma_f32_16x16x32_bf16 v[120:123], v[162:165], v[178:181], v[120:123]
	s_cselect_b32 s62, s20, s26
	v_mfma_f32_16x16x32_bf16 v[112:115], v[170:173], v[178:181], v[112:115]
	s_cselect_b32 s37, s23, s29
	v_mfma_f32_16x16x32_bf16 v[104:107], v[162:165], v[186:189], v[104:107]
	s_cselect_b32 s36, s22, s28
	v_mfma_f32_16x16x32_bf16 v[96:99], v[170:173], v[186:189], v[96:99]
	v_mfma_f32_16x16x32_bf16 v[88:91], v[162:165], v[194:197], v[88:91]
	v_mfma_f32_16x16x32_bf16 v[80:83], v[170:173], v[194:197], v[80:83]
	v_mfma_f32_16x16x32_bf16 v[72:75], v[162:165], v[202:205], v[72:75]
	v_mfma_f32_16x16x32_bf16 v[60:63], v[170:173], v[202:205], v[60:63]
	s_barrier
	s_add_u32 s36, s36, s61
	s_addc_u32 s37, s37, 0
	s_mov_b32 m0, s49
	v_lshl_add_u64 v[218:219], s[36:37], 0, v[134:135]
	ds_read_b128 v[206:209], v154
	ds_read_b128 v[210:213], v154 offset:1024
	ds_read_b128 v[214:217], v154 offset:2048
	ds_read_b128 v[222:225], v154 offset:3072
	global_load_lds_dwordx4 v[218:219], off
	s_mov_b32 m0, s50
	v_lshl_add_u64 v[226:227], s[36:37], 0, v[130:131]
	global_load_lds_dwordx4 v[226:227], off
	s_barrier
	s_waitcnt lgkmcnt(0)
	v_mfma_f32_16x16x32_bf16 v[124:127], v[206:209], v[174:177], v[124:127]
	v_mfma_f32_16x16x32_bf16 v[116:119], v[214:217], v[174:177], v[116:119]
	v_mfma_f32_16x16x32_bf16 v[108:111], v[206:209], v[182:185], v[108:111]
	v_mfma_f32_16x16x32_bf16 v[100:103], v[214:217], v[182:185], v[100:103]
	v_mfma_f32_16x16x32_bf16 v[92:95], v[206:209], v[190:193], v[92:95]
	v_mfma_f32_16x16x32_bf16 v[84:87], v[214:217], v[190:193], v[84:87]
	v_mfma_f32_16x16x32_bf16 v[76:79], v[206:209], v[198:201], v[76:79]
	v_mfma_f32_16x16x32_bf16 v[64:67], v[214:217], v[198:201], v[64:67]
	v_mfma_f32_16x16x32_bf16 v[124:127], v[210:213], v[178:181], v[124:127]
	v_mfma_f32_16x16x32_bf16 v[116:119], v[222:225], v[178:181], v[116:119]
	v_mfma_f32_16x16x32_bf16 v[108:111], v[210:213], v[186:189], v[108:111]
	v_mfma_f32_16x16x32_bf16 v[100:103], v[222:225], v[186:189], v[100:103]
	v_mfma_f32_16x16x32_bf16 v[92:95], v[210:213], v[194:197], v[92:95]
	v_mfma_f32_16x16x32_bf16 v[84:87], v[222:225], v[194:197], v[84:87]
	v_mfma_f32_16x16x32_bf16 v[76:79], v[210:213], v[202:205], v[76:79]
	v_mfma_f32_16x16x32_bf16 v[64:67], v[222:225], v[202:205], v[64:67]
	s_add_u32 s62, s62, s61
	s_addc_u32 s63, s63, 0
	s_mov_b32 m0, s25
	v_lshl_add_u64 v[228:229], s[62:63], 0, v[136:137]
	s_barrier
	ds_read_b128 v[174:177], v153 offset:16384
	ds_read_b128 v[178:181], v153 offset:17408
	ds_read_b128 v[182:185], v153 offset:18432
	ds_read_b128 v[186:189], v153 offset:19456
	ds_read_b128 v[190:193], v153 offset:20480
	ds_read_b128 v[194:197], v153 offset:21504
	ds_read_b128 v[198:201], v153 offset:22528
	ds_read_b128 v[202:205], v153 offset:23552
	global_load_lds_dwordx4 v[228:229], off
	s_mov_b32 m0, s41
	v_lshl_add_u64 v[230:231], s[62:63], 0, v[132:133]
	global_load_lds_dwordx4 v[230:231], off
	s_barrier
	s_waitcnt lgkmcnt(0)
	v_mfma_f32_16x16x32_bf16 v[56:59], v[158:161], v[174:177], v[56:59]
	v_mfma_f32_16x16x32_bf16 v[48:51], v[166:169], v[174:177], v[48:51]
	v_mfma_f32_16x16x32_bf16 v[40:43], v[158:161], v[182:185], v[40:43]
	v_mfma_f32_16x16x32_bf16 v[32:35], v[166:169], v[182:185], v[32:35]
	v_mfma_f32_16x16x32_bf16 v[24:27], v[158:161], v[190:193], v[24:27]
	v_mfma_f32_16x16x32_bf16 v[16:19], v[166:169], v[190:193], v[16:19]
	v_mfma_f32_16x16x32_bf16 v[8:11], v[158:161], v[198:201], v[8:11]
	v_mfma_f32_16x16x32_bf16 v[0:3], v[166:169], v[198:201], v[0:3]
	v_mfma_f32_16x16x32_bf16 v[56:59], v[162:165], v[178:181], v[56:59]
	v_mfma_f32_16x16x32_bf16 v[48:51], v[170:173], v[178:181], v[48:51]
	v_mfma_f32_16x16x32_bf16 v[40:43], v[162:165], v[186:189], v[40:43]
	v_mfma_f32_16x16x32_bf16 v[32:35], v[170:173], v[186:189], v[32:35]
	v_mfma_f32_16x16x32_bf16 v[24:27], v[162:165], v[194:197], v[24:27]
	v_mfma_f32_16x16x32_bf16 v[16:19], v[170:173], v[194:197], v[16:19]
	v_mfma_f32_16x16x32_bf16 v[8:11], v[162:165], v[202:205], v[8:11]
	v_mfma_f32_16x16x32_bf16 v[0:3], v[170:173], v[202:205], v[0:3]
	s_barrier
	s_add_u32 s64, s36, 0x40000
	s_addc_u32 s65, s37, 0
	s_mov_b32 m0, s55
	v_lshl_add_u64 v[158:159], s[64:65], 0, v[134:135]
	global_load_lds_dwordx4 v[158:159], off
	s_mov_b32 m0, s56
	v_lshl_add_u64 v[158:159], s[64:65], 0, v[130:131]
	global_load_lds_dwordx4 v[158:159], off
	s_waitcnt vmcnt(6)
	s_barrier
	v_mfma_f32_16x16x32_bf16 v[68:71], v[206:209], v[174:177], v[68:71]
	v_mfma_f32_16x16x32_bf16 v[52:55], v[214:217], v[174:177], v[52:55]
	v_mfma_f32_16x16x32_bf16 v[44:47], v[206:209], v[182:185], v[44:47]
	v_mfma_f32_16x16x32_bf16 v[36:39], v[214:217], v[182:185], v[36:39]
	v_mfma_f32_16x16x32_bf16 v[28:31], v[206:209], v[190:193], v[28:31]
	v_mfma_f32_16x16x32_bf16 v[20:23], v[214:217], v[190:193], v[20:23]
	v_mfma_f32_16x16x32_bf16 v[12:15], v[206:209], v[198:201], v[12:15]
	v_mfma_f32_16x16x32_bf16 v[4:7], v[214:217], v[198:201], v[4:7]
	v_mfma_f32_16x16x32_bf16 v[68:71], v[210:213], v[178:181], v[68:71]
	v_mfma_f32_16x16x32_bf16 v[52:55], v[222:225], v[178:181], v[52:55]
	v_mfma_f32_16x16x32_bf16 v[44:47], v[210:213], v[186:189], v[44:47]
	v_mfma_f32_16x16x32_bf16 v[36:39], v[222:225], v[186:189], v[36:39]
	v_mfma_f32_16x16x32_bf16 v[28:31], v[210:213], v[194:197], v[28:31]
	v_mfma_f32_16x16x32_bf16 v[20:23], v[222:225], v[194:197], v[20:23]
	v_mfma_f32_16x16x32_bf16 v[12:15], v[210:213], v[202:205], v[12:15]
	v_mfma_f32_16x16x32_bf16 v[4:7], v[222:225], v[202:205], v[4:7]
	s_barrier
	ds_read_b128 v[158:161], v155
	ds_read_b128 v[162:165], v155 offset:1024
	ds_read_b128 v[166:169], v155 offset:2048
	ds_read_b128 v[170:173], v155 offset:3072
	s_add_u32 s62, s62, 0x40000
	s_addc_u32 s63, s63, 0
	s_mov_b32 m0, s42
	v_lshl_add_u64 v[206:207], s[62:63], 0, v[136:137]
	ds_read_b128 v[174:177], v153 offset:32768
	ds_read_b128 v[178:181], v153 offset:33792
	ds_read_b128 v[182:185], v153 offset:34816
	ds_read_b128 v[186:189], v153 offset:35840
	ds_read_b128 v[190:193], v153 offset:36864
	ds_read_b128 v[194:197], v153 offset:37888
	ds_read_b128 v[198:201], v153 offset:38912
	ds_read_b128 v[202:205], v153 offset:39936
	global_load_lds_dwordx4 v[206:207], off
	s_mov_b32 m0, s43
	v_lshl_add_u64 v[206:207], s[62:63], 0, v[132:133]
	global_load_lds_dwordx4 v[206:207], off
	s_waitcnt lgkmcnt(8)
	s_barrier
	s_waitcnt lgkmcnt(0)
	v_mfma_f32_16x16x32_bf16 v[120:123], v[158:161], v[174:177], v[120:123]
	v_mfma_f32_16x16x32_bf16 v[112:115], v[166:169], v[174:177], v[112:115]
	v_mfma_f32_16x16x32_bf16 v[104:107], v[158:161], v[182:185], v[104:107]
	v_mfma_f32_16x16x32_bf16 v[96:99], v[166:169], v[182:185], v[96:99]
	v_mfma_f32_16x16x32_bf16 v[88:91], v[158:161], v[190:193], v[88:91]
	v_mfma_f32_16x16x32_bf16 v[80:83], v[166:169], v[190:193], v[80:83]
	v_mfma_f32_16x16x32_bf16 v[72:75], v[158:161], v[198:201], v[72:75]
	v_mfma_f32_16x16x32_bf16 v[60:63], v[166:169], v[198:201], v[60:63]
	v_mfma_f32_16x16x32_bf16 v[120:123], v[162:165], v[178:181], v[120:123]
	v_mfma_f32_16x16x32_bf16 v[112:115], v[170:173], v[178:181], v[112:115]
	v_mfma_f32_16x16x32_bf16 v[104:107], v[162:165], v[186:189], v[104:107]
	v_mfma_f32_16x16x32_bf16 v[96:99], v[170:173], v[186:189], v[96:99]
	v_mfma_f32_16x16x32_bf16 v[88:91], v[162:165], v[194:197], v[88:91]
	v_mfma_f32_16x16x32_bf16 v[80:83], v[170:173], v[194:197], v[80:83]
	v_mfma_f32_16x16x32_bf16 v[72:75], v[162:165], v[202:205], v[72:75]
	v_mfma_f32_16x16x32_bf16 v[60:63], v[170:173], v[202:205], v[60:63]
	s_barrier
	s_mov_b32 m0, s57
	v_lshl_add_u64 v[218:219], v[218:219], 0, s[6:7]
	ds_read_b128 v[206:209], v156
	ds_read_b128 v[210:213], v156 offset:1024
	ds_read_b128 v[214:217], v156 offset:2048
	ds_read_b128 v[222:225], v156 offset:3072
	global_load_lds_dwordx4 v[218:219], off
	s_mov_b32 m0, s58
	v_lshl_add_u64 v[218:219], v[226:227], 0, s[6:7]
	global_load_lds_dwordx4 v[218:219], off
	s_barrier
;     ...
;         G_PAIR(0, 1);
; #pragma unroll 1
;         for (int t = 2; t < nt; t += 2) G_PAIR(t, 0);
	s_waitcnt lgkmcnt(0)
	v_mfma_f32_16x16x32_bf16 v[124:127], v[206:209], v[174:177], v[124:127]
	v_mfma_f32_16x16x32_bf16 v[116:119], v[214:217], v[174:177], v[116:119]
	v_mfma_f32_16x16x32_bf16 v[108:111], v[206:209], v[182:185], v[108:111]
	v_mfma_f32_16x16x32_bf16 v[100:103], v[214:217], v[182:185], v[100:103]
	v_mfma_f32_16x16x32_bf16 v[92:95], v[206:209], v[190:193], v[92:95]
	v_mfma_f32_16x16x32_bf16 v[84:87], v[214:217], v[190:193], v[84:87]
	v_mfma_f32_16x16x32_bf16 v[76:79], v[206:209], v[198:201], v[76:79]
	v_mfma_f32_16x16x32_bf16 v[64:67], v[214:217], v[198:201], v[64:67]
	v_mfma_f32_16x16x32_bf16 v[124:127], v[210:213], v[178:181], v[124:127]
	v_mfma_f32_16x16x32_bf16 v[116:119], v[222:225], v[178:181], v[116:119]
	v_mfma_f32_16x16x32_bf16 v[108:111], v[210:213], v[186:189], v[108:111]
	v_mfma_f32_16x16x32_bf16 v[100:103], v[222:225], v[186:189], v[100:103]
	v_mfma_f32_16x16x32_bf16 v[92:95], v[210:213], v[194:197], v[92:95]
	v_mfma_f32_16x16x32_bf16 v[84:87], v[222:225], v[194:197], v[84:87]
	v_mfma_f32_16x16x32_bf16 v[76:79], v[210:213], v[202:205], v[76:79]
	v_mfma_f32_16x16x32_bf16 v[64:67], v[222:225], v[202:205], v[64:67]
	s_mov_b32 m0, s44
	v_lshl_add_u64 v[218:219], v[228:229], 0, s[6:7]
	s_barrier
	ds_read_b128 v[174:177], v153 offset:49152
	ds_read_b128 v[178:181], v153 offset:50176
	ds_read_b128 v[182:185], v153 offset:51200
	ds_read_b128 v[186:189], v153 offset:52224
	ds_read_b128 v[190:193], v153 offset:53248
	ds_read_b128 v[194:197], v153 offset:54272
	ds_read_b128 v[198:201], v153 offset:55296
	ds_read_b128 v[202:205], v153 offset:56320
	global_load_lds_dwordx4 v[218:219], off
	s_mov_b32 m0, s45
	v_lshl_add_u64 v[218:219], v[230:231], 0, s[6:7]
	global_load_lds_dwordx4 v[218:219], off
	s_barrier
	s_waitcnt lgkmcnt(0)
	v_mfma_f32_16x16x32_bf16 v[56:59], v[158:161], v[174:177], v[56:59]
	v_mfma_f32_16x16x32_bf16 v[48:51], v[166:169], v[174:177], v[48:51]
	v_mfma_f32_16x16x32_bf16 v[40:43], v[158:161], v[182:185], v[40:43]
	v_mfma_f32_16x16x32_bf16 v[32:35], v[166:169], v[182:185], v[32:35]
	v_mfma_f32_16x16x32_bf16 v[24:27], v[158:161], v[190:193], v[24:27]
	v_mfma_f32_16x16x32_bf16 v[16:19], v[166:169], v[190:193], v[16:19]
	v_mfma_f32_16x16x32_bf16 v[8:11], v[158:161], v[198:201], v[8:11]
	v_mfma_f32_16x16x32_bf16 v[0:3], v[166:169], v[198:201], v[0:3]
	v_mfma_f32_16x16x32_bf16 v[56:59], v[162:165], v[178:181], v[56:59]
	v_mfma_f32_16x16x32_bf16 v[48:51], v[170:173], v[178:181], v[48:51]
	v_mfma_f32_16x16x32_bf16 v[40:43], v[162:165], v[186:189], v[40:43]
	v_mfma_f32_16x16x32_bf16 v[32:35], v[170:173], v[186:189], v[32:35]
	v_mfma_f32_16x16x32_bf16 v[24:27], v[162:165], v[194:197], v[24:27]
	v_mfma_f32_16x16x32_bf16 v[16:19], v[170:173], v[194:197], v[16:19]
	v_mfma_f32_16x16x32_bf16 v[8:11], v[162:165], v[202:205], v[8:11]
	v_mfma_f32_16x16x32_bf16 v[0:3], v[170:173], v[202:205], v[0:3]
	s_barrier
	s_add_u32 s36, s36, 0x40080
	s_addc_u32 s37, s37, 0
	s_mov_b32 m0, s59
	v_lshl_add_u64 v[158:159], s[36:37], 0, v[134:135]
	global_load_lds_dwordx4 v[158:159], off
	s_mov_b32 m0, s17
	v_lshl_add_u64 v[158:159], s[36:37], 0, v[130:131]
	global_load_lds_dwordx4 v[158:159], off
	s_waitcnt vmcnt(6)
	s_barrier
	v_mfma_f32_16x16x32_bf16 v[68:71], v[206:209], v[174:177], v[68:71]
	v_mfma_f32_16x16x32_bf16 v[52:55], v[214:217], v[174:177], v[52:55]
	v_mfma_f32_16x16x32_bf16 v[44:47], v[206:209], v[182:185], v[44:47]
	v_mfma_f32_16x16x32_bf16 v[36:39], v[214:217], v[182:185], v[36:39]
	v_mfma_f32_16x16x32_bf16 v[28:31], v[206:209], v[190:193], v[28:31]
	v_mfma_f32_16x16x32_bf16 v[20:23], v[214:217], v[190:193], v[20:23]
	v_mfma_f32_16x16x32_bf16 v[12:15], v[206:209], v[198:201], v[12:15]
	v_mfma_f32_16x16x32_bf16 v[4:7], v[214:217], v[198:201], v[4:7]
	v_mfma_f32_16x16x32_bf16 v[68:71], v[210:213], v[178:181], v[68:71]
	v_mfma_f32_16x16x32_bf16 v[52:55], v[222:225], v[178:181], v[52:55]
	v_mfma_f32_16x16x32_bf16 v[44:47], v[210:213], v[186:189], v[44:47]
	v_mfma_f32_16x16x32_bf16 v[36:39], v[222:225], v[186:189], v[36:39]
	v_mfma_f32_16x16x32_bf16 v[28:31], v[210:213], v[194:197], v[28:31]
	v_mfma_f32_16x16x32_bf16 v[20:23], v[222:225], v[194:197], v[20:23]
	v_mfma_f32_16x16x32_bf16 v[12:15], v[210:213], v[202:205], v[12:15]
	v_mfma_f32_16x16x32_bf16 v[4:7], v[222:225], v[202:205], v[4:7]
	s_add_i32 s19, s19, 2
	s_add_u32 s34, s34, 0x100
	s_addc_u32 s35, s35, 0
	s_cmp_gt_u32 s19, 13
	s_barrier
	s_cbranch_scc0 .LBB0_232
; __device__ __forceinline__ unsigned pk2(float lo, float hi) { unsigned r; asm volatile("v_cvt_pk_bf16_f32 %0, %1, %2" : "=v"(r) : "v"(lo), "v"(hi)); return r; }
; __device__ __forceinline__ unsigned pk2(float lo, float hi) { return f2bf(lo) | (f2bf(hi) << 16); }
;     __device__ __forceinline__ void epi(const f32x4 (&acc)[2][2][4][2], const Unit& u, int wr, int wc, int fr, int fq) const {
;     ...
;         const int row0 = u.pm * 256 + wr * 64 + fr, col0 = u.pn * 128 + wc * 32 + 8 * fq;
; #pragma unroll
;         for (int ai = 0; ai < 2; ++ai)
; #pragma unroll
;             for (int m = 0; m < 4; ++m) {
;                 const int row = row0 + ai * 128 + m * 16; const float rs = rs_lds[((u.pm >> 3) & 1) * 256 + (row & 255)];
;                 const float rs2 = rs * -1.4426950408889634f, rsq = rs * rs;
;                 f32x2 v[4];
; #pragma unroll
;                 for (int n = 0; n < 2; ++n)
; #pragma unroll
;                     for (int jp = 0; jp < 2; ++jp) {
;                         const f32x2 gg = (f32x2){acc[ai][0][m][n][2 * jp], acc[ai][0][m][n][2 * jp + 1]}, uu = (f32x2){acc[ai][1][m][n][2 * jp], acc[ai][1][m][n][2 * jp + 1]};
;                         const f32x2 t = gg * rs2; f32x2 e; e.x = __builtin_amdgcn_exp2f(t.x); e.y = __builtin_amdgcn_exp2f(t.y);
;                         const f32x2 d = e + 1.0f; f32x2 r; r.x = __builtin_amdgcn_rcpf(d.x); r.y = __builtin_amdgcn_rcpf(d.y);
;                         v[n * 2 + jp] = (gg * uu) * (r * rsq);
;                     }
;                 u32x4 w; w.x = pk2(v[0].x, v[0].y); w.y = pk2(v[1].x, v[1].y); w.z = pk2(v[2].x, v[2].y); w.w = pk2(v[3].x, v[3].y);
;                 *(u32x4*)(H + (size_t)row * FF + col0) = w;
	s_lshl_b32 s17, s24, 7
	s_and_b32 s17, s17, 0x400
	s_add_i32 s17, s17, 0
	s_add_i32 s17, s17, 0x20000
	v_lshl_add_u32 v142, v151, 2, s17
	ds_read_b32 v143, v142
	v_lshl_add_u32 v142, s24, 8, v129
	v_lshl_or_b32 v144, s60, 7, v150
	v_ashrrev_i32_e32 v145, 31, v144
	s_and_b64 vcc, exec, s[14:15]
	s_waitcnt lgkmcnt(0)
	v_mul_f32_e32 v158, 0xbfb8aa3b, v143
	v_pk_mul_f32 v[160:161], v[120:121], v[158:159] op_sel_hi:[1,0]
	v_pk_mul_f32 v[164:165], v[122:123], v[158:159] op_sel_hi:[1,0]
	v_exp_f32_e32 v160, v160
	v_exp_f32_e32 v161, v161
	v_exp_f32_e32 v164, v164
	v_exp_f32_e32 v165, v165
	v_pk_mul_f32 v[122:123], v[122:123], v[126:127]
	v_pk_add_f32 v[160:161], v[160:161], 1.0 op_sel_hi:[1,0]
	v_mul_f32_e32 v162, v143, v143
	v_rcp_f32_e32 v160, v160
	v_rcp_f32_e32 v161, v161
	v_pk_add_f32 v[126:127], v[164:165], 1.0 op_sel_hi:[1,0]
	v_pk_mul_f32 v[120:121], v[120:121], v[124:125]
	v_rcp_f32_e32 v126, v126
	v_rcp_f32_e32 v127, v127
	v_pk_mul_f32 v[124:125], v[162:163], v[160:161] op_sel_hi:[0,1]
	v_pk_mul_f32 v[160:161], v[112:113], v[158:159] op_sel_hi:[1,0]
	v_pk_mul_f32 v[120:121], v[120:121], v[124:125]
	v_exp_f32_e32 v160, v160
	v_exp_f32_e32 v161, v161
	v_pk_mul_f32 v[124:125], v[162:163], v[126:127] op_sel_hi:[0,1]
	v_pk_mul_f32 v[126:127], v[114:115], v[158:159] op_sel_hi:[1,0]
	v_pk_mul_f32 v[122:123], v[122:123], v[124:125]
	v_exp_f32_e32 v126, v126
	v_exp_f32_e32 v127, v127
	v_pk_add_f32 v[124:125], v[160:161], 1.0 op_sel_hi:[1,0]
	v_pk_mul_f32 v[114:115], v[114:115], v[118:119]
	v_rcp_f32_e32 v124, v124
	v_rcp_f32_e32 v125, v125
	v_pk_add_f32 v[118:119], v[126:127], 1.0 op_sel_hi:[1,0]
	v_pk_mul_f32 v[112:113], v[112:113], v[116:117]
	v_rcp_f32_e32 v118, v118
	v_rcp_f32_e32 v119, v119
	v_pk_mul_f32 v[116:117], v[162:163], v[124:125] op_sel_hi:[0,1]
	v_pk_mul_f32 v[112:113], v[112:113], v[116:117]
	s_mov_b32 s60, s16
	v_pk_mul_f32 v[116:117], v[162:163], v[118:119] op_sel_hi:[0,1]
	v_pk_mul_f32 v[114:115], v[114:115], v[116:117]
	v_cvt_pk_bf16_f32 v116, v120, v121
	v_cvt_pk_bf16_f32 v117, v122, v123
	v_cvt_pk_bf16_f32 v118, v112, v113
	v_bitop3_b32 v112, v142, s52, 16 bitop3:0xc8
	v_lshl_add_u32 v112, v112, 2, s17
	v_cvt_pk_bf16_f32 v119, v114, v115
	ds_read_b32 v123, v112
	v_mov_b64_e32 v[112:113], s[2:3]
	v_mad_i64_i32 v[120:121], s[26:27], v142, s51, v[112:113]
	v_lshlrev_b64 v[114:115], 1, v[144:145]
	s_waitcnt lgkmcnt(0)
	v_mul_f32_e32 v122, 0xbfb8aa3b, v123
	v_pk_mul_f32 v[124:125], v[104:105], v[122:123] op_sel_hi:[1,0]
	v_lshl_add_u64 v[120:121], v[120:121], 0, v[114:115]
	v_exp_f32_e32 v124, v124
	v_exp_f32_e32 v125, v125
	global_store_dwordx4 v[120:121], v[116:119], off
	v_pk_mul_f32 v[120:121], v[106:107], v[122:123] op_sel_hi:[1,0]
	v_pk_mul_f32 v[106:107], v[106:107], v[110:111]
	v_exp_f32_e32 v120, v120
	v_exp_f32_e32 v121, v121
	v_pk_add_f32 v[118:119], v[124:125], 1.0 op_sel_hi:[1,0]
	v_mul_f32_e32 v116, v123, v123
	v_rcp_f32_e32 v118, v118
	v_rcp_f32_e32 v119, v119
	v_pk_add_f32 v[110:111], v[120:121], 1.0 op_sel_hi:[1,0]
	v_pk_mul_f32 v[104:105], v[104:105], v[108:109]
	v_rcp_f32_e32 v110, v110
	v_rcp_f32_e32 v111, v111
	v_pk_mul_f32 v[108:109], v[116:117], v[118:119] op_sel_hi:[0,1]
	v_pk_mul_f32 v[118:119], v[96:97], v[122:123] op_sel_hi:[1,0]
	v_pk_mul_f32 v[104:105], v[104:105], v[108:109]
	v_exp_f32_e32 v118, v118
	v_exp_f32_e32 v119, v119
	v_pk_mul_f32 v[108:109], v[116:117], v[110:111] op_sel_hi:[0,1]
	v_pk_mul_f32 v[110:111], v[98:99], v[122:123] op_sel_hi:[1,0]
	v_pk_mul_f32 v[106:107], v[106:107], v[108:109]
	v_exp_f32_e32 v110, v110
	v_exp_f32_e32 v111, v111
	v_pk_add_f32 v[108:109], v[118:119], 1.0 op_sel_hi:[1,0]
	v_pk_mul_f32 v[98:99], v[98:99], v[102:103]
	v_rcp_f32_e32 v108, v108
	v_rcp_f32_e32 v109, v109
	v_pk_add_f32 v[102:103], v[110:111], 1.0 op_sel_hi:[1,0]
	v_pk_mul_f32 v[96:97], v[96:97], v[100:101]
	v_rcp_f32_e32 v102, v102
	v_rcp_f32_e32 v103, v103
	v_pk_mul_f32 v[100:101], v[116:117], v[108:109] op_sel_hi:[0,1]
	v_pk_mul_f32 v[100:101], v[96:97], v[100:101]
	s_mov_b32 s24, s18
	v_pk_mul_f32 v[96:97], v[116:117], v[102:103] op_sel_hi:[0,1]
	v_pk_mul_f32 v[102:103], v[98:99], v[96:97]
	v_cvt_pk_bf16_f32 v96, v104, v105
	v_cvt_pk_bf16_f32 v97, v106, v107
	v_cvt_pk_bf16_f32 v98, v100, v101
	v_bitop3_b32 v100, v142, s53, 32 bitop3:0xc8
	v_lshl_add_u32 v100, v100, 2, s17
	v_cvt_pk_bf16_f32 v99, v102, v103
	ds_read_b32 v103, v100
	v_or_b32_e32 v100, 16, v142
	v_mad_i64_i32 v[100:101], s[26:27], v100, s51, v[112:113]
	v_lshl_add_u64 v[100:101], v[100:101], 0, v[114:115]
	s_waitcnt lgkmcnt(0)
	v_mul_f32_e32 v102, 0xbfb8aa3b, v103
	v_pk_mul_f32 v[104:105], v[88:89], v[102:103] op_sel_hi:[1,0]
	global_store_dwordx4 v[100:101], v[96:99], off
	v_exp_f32_e32 v104, v104
	v_exp_f32_e32 v105, v105
	v_pk_mul_f32 v[100:101], v[90:91], v[102:103] op_sel_hi:[1,0]
	v_pk_mul_f32 v[90:91], v[90:91], v[94:95]
	v_exp_f32_e32 v100, v100
	v_exp_f32_e32 v101, v101
	v_pk_add_f32 v[98:99], v[104:105], 1.0 op_sel_hi:[1,0]
	v_mul_f32_e32 v96, v103, v103
	v_rcp_f32_e32 v98, v98
	v_rcp_f32_e32 v99, v99
	v_pk_add_f32 v[94:95], v[100:101], 1.0 op_sel_hi:[1,0]
	v_pk_mul_f32 v[88:89], v[88:89], v[92:93]
	v_rcp_f32_e32 v94, v94
	v_rcp_f32_e32 v95, v95
	v_pk_mul_f32 v[92:93], v[96:97], v[98:99] op_sel_hi:[0,1]
	v_pk_mul_f32 v[98:99], v[80:81], v[102:103] op_sel_hi:[1,0]
	v_pk_mul_f32 v[88:89], v[88:89], v[92:93]
	v_exp_f32_e32 v98, v98
	v_exp_f32_e32 v99, v99
	v_pk_mul_f32 v[92:93], v[96:97], v[94:95] op_sel_hi:[0,1]
	v_pk_mul_f32 v[94:95], v[82:83], v[102:103] op_sel_hi:[1,0]
	v_pk_mul_f32 v[90:91], v[90:91], v[92:93]
	v_exp_f32_e32 v94, v94
	v_exp_f32_e32 v95, v95
	v_pk_add_f32 v[92:93], v[98:99], 1.0 op_sel_hi:[1,0]
	v_pk_mul_f32 v[82:83], v[82:83], v[86:87]
	v_rcp_f32_e32 v92, v92
	v_rcp_f32_e32 v93, v93
	v_pk_add_f32 v[86:87], v[94:95], 1.0 op_sel_hi:[1,0]
	v_pk_mul_f32 v[80:81], v[80:81], v[84:85]
	v_rcp_f32_e32 v86, v86
	v_rcp_f32_e32 v87, v87
	v_pk_mul_f32 v[84:85], v[96:97], v[92:93] op_sel_hi:[0,1]
	v_pk_mul_f32 v[84:85], v[80:81], v[84:85]
	s_mov_b64 s[28:29], s[22:23]
	v_pk_mul_f32 v[80:81], v[96:97], v[86:87] op_sel_hi:[0,1]
	v_pk_mul_f32 v[86:87], v[82:83], v[80:81]
	v_cvt_pk_bf16_f32 v80, v88, v89
	v_cvt_pk_bf16_f32 v81, v90, v91
	v_cvt_pk_bf16_f32 v82, v84, v85
	v_bitop3_b32 v84, v142, s54, 48 bitop3:0xc8
	v_lshl_add_u32 v84, v84, 2, s17
	v_cvt_pk_bf16_f32 v83, v86, v87
	ds_read_b32 v87, v84
	v_or_b32_e32 v84, 32, v142
	v_mad_i64_i32 v[84:85], s[26:27], v84, s51, v[112:113]
	v_lshl_add_u64 v[84:85], v[84:85], 0, v[114:115]
	s_waitcnt lgkmcnt(0)
; __device__ __forceinline__ unsigned pk2(float lo, float hi) { unsigned r; asm volatile("v_cvt_pk_bf16_f32 %0, %1, %2" : "=v"(r) : "v"(lo), "v"(hi)); return r; }
; __device__ __forceinline__ unsigned pk2(float lo, float hi) { return f2bf(lo) | (f2bf(hi) << 16); }
;     __device__ __forceinline__ void epi(const f32x4 (&acc)[2][2][4][2], const Unit& u, int wr, int wc, int fr, int fq) const {
;     ...
;             for (int m = 0; m < 4; ++m) {
;                 const int row = row0 + ai * 128 + m * 16; const float rs = rs_lds[((u.pm >> 3) & 1) * 256 + (row & 255)];
;                 const float rs2 = rs * -1.4426950408889634f, rsq = rs * rs;
;                 f32x2 v[4];
; #pragma unroll
;                 for (int n = 0; n < 2; ++n)
; #pragma unroll
;                     for (int jp = 0; jp < 2; ++jp) {
;                         const f32x2 gg = (f32x2){acc[ai][0][m][n][2 * jp], acc[ai][0][m][n][2 * jp + 1]}, uu = (f32x2){acc[ai][1][m][n][2 * jp], acc[ai][1][m][n][2 * jp + 1]};
;                         const f32x2 t = gg * rs2; f32x2 e; e.x = __builtin_amdgcn_exp2f(t.x); e.y = __builtin_amdgcn_exp2f(t.y);
;                         const f32x2 d = e + 1.0f; f32x2 r; r.x = __builtin_amdgcn_rcpf(d.x); r.y = __builtin_amdgcn_rcpf(d.y);
;                         v[n * 2 + jp] = (gg * uu) * (r * rsq);
;                     }
;                 u32x4 w; w.x = pk2(v[0].x, v[0].y); w.y = pk2(v[1].x, v[1].y); w.z = pk2(v[2].x, v[2].y); w.w = pk2(v[3].x, v[3].y);
;                 *(u32x4*)(H + (size_t)row * FF + col0) = w;
	v_mul_f32_e32 v86, 0xbfb8aa3b, v87
	v_pk_mul_f32 v[88:89], v[72:73], v[86:87] op_sel_hi:[1,0]
	global_store_dwordx4 v[84:85], v[80:83], off
	v_exp_f32_e32 v88, v88
	v_exp_f32_e32 v89, v89
	v_pk_mul_f32 v[84:85], v[74:75], v[86:87] op_sel_hi:[1,0]
	v_pk_mul_f32 v[74:75], v[74:75], v[78:79]
	v_exp_f32_e32 v84, v84
	v_exp_f32_e32 v85, v85
	v_pk_add_f32 v[82:83], v[88:89], 1.0 op_sel_hi:[1,0]
	v_mul_f32_e32 v80, v87, v87
	v_rcp_f32_e32 v82, v82
	v_rcp_f32_e32 v83, v83
	v_pk_add_f32 v[78:79], v[84:85], 1.0 op_sel_hi:[1,0]
	v_pk_mul_f32 v[72:73], v[72:73], v[76:77]
	v_rcp_f32_e32 v78, v78
	v_rcp_f32_e32 v79, v79
	v_pk_mul_f32 v[76:77], v[80:81], v[82:83] op_sel_hi:[0,1]
	v_pk_mul_f32 v[82:83], v[60:61], v[86:87] op_sel_hi:[1,0]
	v_pk_mul_f32 v[72:73], v[72:73], v[76:77]
	v_exp_f32_e32 v82, v82
	v_exp_f32_e32 v83, v83
	v_pk_mul_f32 v[76:77], v[80:81], v[78:79] op_sel_hi:[0,1]
	v_pk_mul_f32 v[78:79], v[62:63], v[86:87] op_sel_hi:[1,0]
	v_pk_mul_f32 v[74:75], v[74:75], v[76:77]
	v_exp_f32_e32 v78, v78
	v_exp_f32_e32 v79, v79
	v_pk_add_f32 v[76:77], v[82:83], 1.0 op_sel_hi:[1,0]
	v_pk_mul_f32 v[62:63], v[62:63], v[66:67]
	v_rcp_f32_e32 v76, v76
	v_rcp_f32_e32 v77, v77
	v_pk_add_f32 v[66:67], v[78:79], 1.0 op_sel_hi:[1,0]
	v_pk_mul_f32 v[60:61], v[60:61], v[64:65]
	v_rcp_f32_e32 v66, v66
	v_rcp_f32_e32 v67, v67
	v_pk_mul_f32 v[64:65], v[80:81], v[76:77] op_sel_hi:[0,1]
	v_pk_mul_f32 v[64:65], v[60:61], v[64:65]
	v_pk_mul_f32 v[60:61], v[80:81], v[66:67] op_sel_hi:[0,1]
	v_pk_mul_f32 v[66:67], v[62:63], v[60:61]
	v_cvt_pk_bf16_f32 v60, v72, v73
	v_cvt_pk_bf16_f32 v61, v74, v75
	v_cvt_pk_bf16_f32 v62, v64, v65
	s_nop 0
	v_cvt_pk_bf16_f32 v63, v66, v67
	v_add_u32_e32 v67, 0x80, v142
	v_and_b32_e32 v64, 0xcf, v67
	v_lshl_add_u32 v64, v64, 2, s17
	ds_read_b32 v74, v64
	v_or_b32_e32 v64, 48, v142
	v_mad_i64_i32 v[64:65], s[26:27], v64, s51, v[112:113]
	v_lshl_add_u64 v[64:65], v[64:65], 0, v[114:115]
	s_waitcnt lgkmcnt(0)
	v_mul_f32_e32 v66, 0xbfb8aa3b, v74
	v_pk_mul_f32 v[72:73], v[56:57], v[66:67] op_sel_hi:[1,0]
	global_store_dwordx4 v[64:65], v[60:63], off
	v_exp_f32_e32 v72, v72
	v_exp_f32_e32 v73, v73
	v_pk_mul_f32 v[64:65], v[58:59], v[66:67] op_sel_hi:[1,0]
	v_mul_f32_e32 v60, v74, v74
	v_exp_f32_e32 v64, v64
	v_exp_f32_e32 v65, v65
	v_pk_add_f32 v[62:63], v[72:73], 1.0 op_sel_hi:[1,0]
	v_pk_mul_f32 v[56:57], v[56:57], v[68:69]
	v_rcp_f32_e32 v62, v62
	v_rcp_f32_e32 v63, v63
	v_pk_add_f32 v[64:65], v[64:65], 1.0 op_sel_hi:[1,0]
	v_pk_mul_f32 v[68:69], v[48:49], v[66:67] op_sel_hi:[1,0]
	v_rcp_f32_e32 v64, v64
	v_rcp_f32_e32 v65, v65
	v_pk_mul_f32 v[62:63], v[60:61], v[62:63] op_sel_hi:[0,1]
	v_exp_f32_e32 v68, v68
	v_exp_f32_e32 v69, v69
	v_pk_mul_f32 v[56:57], v[56:57], v[62:63]
	v_pk_mul_f32 v[62:63], v[60:61], v[64:65] op_sel_hi:[0,1]
	v_pk_mul_f32 v[64:65], v[50:51], v[66:67] op_sel_hi:[1,0]
	v_pk_mul_f32 v[58:59], v[58:59], v[70:71]
	v_exp_f32_e32 v64, v64
	v_exp_f32_e32 v65, v65
	v_pk_mul_f32 v[58:59], v[58:59], v[62:63]
	v_pk_add_f32 v[62:63], v[68:69], 1.0 op_sel_hi:[1,0]
	v_pk_mul_f32 v[50:51], v[50:51], v[54:55]
	v_rcp_f32_e32 v62, v62
	v_rcp_f32_e32 v63, v63
	v_pk_add_f32 v[54:55], v[64:65], 1.0 op_sel_hi:[1,0]
	v_pk_mul_f32 v[48:49], v[48:49], v[52:53]
	v_rcp_f32_e32 v54, v54
	v_rcp_f32_e32 v55, v55
	v_pk_mul_f32 v[52:53], v[60:61], v[62:63] op_sel_hi:[0,1]
	v_pk_mul_f32 v[52:53], v[48:49], v[52:53]
	v_pk_mul_f32 v[48:49], v[60:61], v[54:55] op_sel_hi:[0,1]
	v_pk_mul_f32 v[54:55], v[50:51], v[48:49]
	v_cvt_pk_bf16_f32 v48, v56, v57
	v_cvt_pk_bf16_f32 v49, v58, v59
	v_cvt_pk_bf16_f32 v50, v52, v53
	s_nop 0
	v_cvt_pk_bf16_f32 v51, v54, v55
	v_add_u32_e32 v55, 0x90, v142
	v_and_b32_e32 v52, 0xdf, v55
	v_lshl_add_u32 v52, v52, 2, s17
	ds_read_b32 v58, v52
	v_mad_i64_i32 v[52:53], s[26:27], v67, s51, v[112:113]
	v_lshl_add_u64 v[52:53], v[52:53], 0, v[114:115]
	global_store_dwordx4 v[52:53], v[48:51], off
	s_waitcnt lgkmcnt(0)
; __device__ __forceinline__ unsigned pk2(float lo, float hi) { unsigned r; asm volatile("v_cvt_pk_bf16_f32 %0, %1, %2" : "=v"(r) : "v"(lo), "v"(hi)); return r; }
; __device__ __forceinline__ unsigned pk2(float lo, float hi) { return f2bf(lo) | (f2bf(hi) << 16); }
; #define G_WAIT_V(n) asm volatile("s_waitcnt vmcnt(" #n ")" ::: "memory")
; #define G_BAR __builtin_amdgcn_s_barrier()
;     ...
;         p.epi(acc, cur, wr, wc, fr, fq);
;         if (!has_next) break;
;         cur = nxt; cA = nA; cB = nB; cA2 = nA2; cB2 = nB2; ++ui;
;     }
;     G_WAIT_V(0);
;     if (wr == 0) G_BAR;
;     G_BAR;
;     __device__ __forceinline__ void epi(const f32x4 (&acc)[2][2][4][2], const Unit& u, int wr, int wc, int fr, int fq) const {
;     ...
;             for (int m = 0; m < 4; ++m) {
;                 const int row = row0 + ai * 128 + m * 16; const float rs = rs_lds[((u.pm >> 3) & 1) * 256 + (row & 255)];
;                 const float rs2 = rs * -1.4426950408889634f, rsq = rs * rs;
;                 f32x2 v[4];
; #pragma unroll
;                 for (int n = 0; n < 2; ++n)
; #pragma unroll
;                     for (int jp = 0; jp < 2; ++jp) {
;                         const f32x2 gg = (f32x2){acc[ai][0][m][n][2 * jp], acc[ai][0][m][n][2 * jp + 1]}, uu = (f32x2){acc[ai][1][m][n][2 * jp], acc[ai][1][m][n][2 * jp + 1]};
;                         const f32x2 t = gg * rs2; f32x2 e; e.x = __builtin_amdgcn_exp2f(t.x); e.y = __builtin_amdgcn_exp2f(t.y);
;                         const f32x2 d = e + 1.0f; f32x2 r; r.x = __builtin_amdgcn_rcpf(d.x); r.y = __builtin_amdgcn_rcpf(d.y);
;                         v[n * 2 + jp] = (gg * uu) * (r * rsq);
;                     }
;                 u32x4 w; w.x = pk2(v[0].x, v[0].y); w.y = pk2(v[1].x, v[1].y); w.z = pk2(v[2].x, v[2].y); w.w = pk2(v[3].x, v[3].y);
;                 *(u32x4*)(H + (size_t)row * FF + col0) = w;
	v_mul_f32_e32 v54, 0xbfb8aa3b, v58
	v_pk_mul_f32 v[56:57], v[40:41], v[54:55] op_sel_hi:[1,0]
	v_pk_mul_f32 v[52:53], v[42:43], v[54:55] op_sel_hi:[1,0]
	v_exp_f32_e32 v56, v56
	v_exp_f32_e32 v57, v57
	v_exp_f32_e32 v52, v52
	v_exp_f32_e32 v53, v53
	v_pk_mul_f32 v[42:43], v[42:43], v[46:47]
	v_pk_add_f32 v[50:51], v[56:57], 1.0 op_sel_hi:[1,0]
	v_mul_f32_e32 v48, v58, v58
	v_rcp_f32_e32 v50, v50
	v_rcp_f32_e32 v51, v51
	v_pk_add_f32 v[46:47], v[52:53], 1.0 op_sel_hi:[1,0]
	v_pk_mul_f32 v[40:41], v[40:41], v[44:45]
	v_rcp_f32_e32 v46, v46
	v_rcp_f32_e32 v47, v47
	v_pk_mul_f32 v[44:45], v[48:49], v[50:51] op_sel_hi:[0,1]
	v_pk_mul_f32 v[50:51], v[32:33], v[54:55] op_sel_hi:[1,0]
	v_pk_mul_f32 v[40:41], v[40:41], v[44:45]
	v_exp_f32_e32 v50, v50
	v_exp_f32_e32 v51, v51
	v_pk_mul_f32 v[44:45], v[48:49], v[46:47] op_sel_hi:[0,1]
	v_pk_mul_f32 v[46:47], v[34:35], v[54:55] op_sel_hi:[1,0]
	v_pk_mul_f32 v[42:43], v[42:43], v[44:45]
	v_exp_f32_e32 v46, v46
	v_exp_f32_e32 v47, v47
	v_pk_add_f32 v[44:45], v[50:51], 1.0 op_sel_hi:[1,0]
	v_pk_mul_f32 v[34:35], v[34:35], v[38:39]
	v_rcp_f32_e32 v44, v44
	v_rcp_f32_e32 v45, v45
	v_pk_add_f32 v[38:39], v[46:47], 1.0 op_sel_hi:[1,0]
	v_pk_mul_f32 v[32:33], v[32:33], v[36:37]
	v_rcp_f32_e32 v38, v38
	v_rcp_f32_e32 v39, v39
	v_pk_mul_f32 v[36:37], v[48:49], v[44:45] op_sel_hi:[0,1]
	v_pk_mul_f32 v[36:37], v[32:33], v[36:37]
	v_pk_mul_f32 v[32:33], v[48:49], v[38:39] op_sel_hi:[0,1]
	v_pk_mul_f32 v[38:39], v[34:35], v[32:33]
	v_cvt_pk_bf16_f32 v32, v40, v41
	v_cvt_pk_bf16_f32 v33, v42, v43
	v_cvt_pk_bf16_f32 v34, v36, v37
	s_nop 0
	v_cvt_pk_bf16_f32 v35, v38, v39
	v_add_u32_e32 v39, 0xa0, v142
	v_and_b32_e32 v36, 0xef, v39
	v_lshl_add_u32 v36, v36, 2, s17
	ds_read_b32 v42, v36
	v_mad_i64_i32 v[36:37], s[26:27], v55, s51, v[112:113]
	v_lshl_add_u64 v[36:37], v[36:37], 0, v[114:115]
	global_store_dwordx4 v[36:37], v[32:35], off
	s_waitcnt lgkmcnt(0)
	v_mul_f32_e32 v38, 0xbfb8aa3b, v42
	v_pk_mul_f32 v[40:41], v[24:25], v[38:39] op_sel_hi:[1,0]
	v_pk_mul_f32 v[36:37], v[26:27], v[38:39] op_sel_hi:[1,0]
	v_exp_f32_e32 v40, v40
	v_exp_f32_e32 v41, v41
	v_exp_f32_e32 v36, v36
	v_exp_f32_e32 v37, v37
	v_pk_mul_f32 v[26:27], v[26:27], v[30:31]
	v_pk_add_f32 v[34:35], v[40:41], 1.0 op_sel_hi:[1,0]
	v_mul_f32_e32 v32, v42, v42
	v_rcp_f32_e32 v34, v34
	v_rcp_f32_e32 v35, v35
	v_pk_add_f32 v[30:31], v[36:37], 1.0 op_sel_hi:[1,0]
	v_pk_mul_f32 v[24:25], v[24:25], v[28:29]
	v_rcp_f32_e32 v30, v30
	v_rcp_f32_e32 v31, v31
	v_pk_mul_f32 v[28:29], v[32:33], v[34:35] op_sel_hi:[0,1]
	v_pk_mul_f32 v[34:35], v[16:17], v[38:39] op_sel_hi:[1,0]
	v_pk_mul_f32 v[24:25], v[24:25], v[28:29]
	v_exp_f32_e32 v34, v34
	v_exp_f32_e32 v35, v35
	v_pk_mul_f32 v[28:29], v[32:33], v[30:31] op_sel_hi:[0,1]
	v_pk_mul_f32 v[30:31], v[18:19], v[38:39] op_sel_hi:[1,0]
	v_pk_mul_f32 v[26:27], v[26:27], v[28:29]
	v_exp_f32_e32 v30, v30
	v_exp_f32_e32 v31, v31
	v_pk_add_f32 v[28:29], v[34:35], 1.0 op_sel_hi:[1,0]
	v_pk_mul_f32 v[18:19], v[18:19], v[22:23]
	v_rcp_f32_e32 v28, v28
	v_rcp_f32_e32 v29, v29
	v_pk_add_f32 v[22:23], v[30:31], 1.0 op_sel_hi:[1,0]
	v_pk_mul_f32 v[16:17], v[16:17], v[20:21]
	v_rcp_f32_e32 v22, v22
	v_rcp_f32_e32 v23, v23
	v_pk_mul_f32 v[20:21], v[32:33], v[28:29] op_sel_hi:[0,1]
	v_pk_mul_f32 v[20:21], v[16:17], v[20:21]
	v_pk_mul_f32 v[16:17], v[32:33], v[22:23] op_sel_hi:[0,1]
	v_pk_mul_f32 v[22:23], v[18:19], v[16:17]
	v_cvt_pk_bf16_f32 v16, v24, v25
	v_cvt_pk_bf16_f32 v17, v26, v27
	v_cvt_pk_bf16_f32 v18, v20, v21
	s_nop 0
	v_cvt_pk_bf16_f32 v19, v22, v23
	v_add_u32_e32 v23, 0xb0, v142
	v_and_b32_e32 v20, 0xff, v23
	v_lshl_add_u32 v20, v20, 2, s17
	ds_read_b32 v26, v20
	v_mad_i64_i32 v[20:21], s[26:27], v39, s51, v[112:113]
	v_lshl_add_u64 v[20:21], v[20:21], 0, v[114:115]
	global_store_dwordx4 v[20:21], v[16:19], off
	s_waitcnt lgkmcnt(0)
	v_mul_f32_e32 v22, 0xbfb8aa3b, v26
	v_pk_mul_f32 v[24:25], v[8:9], v[22:23] op_sel_hi:[1,0]
	v_pk_mul_f32 v[20:21], v[10:11], v[22:23] op_sel_hi:[1,0]
	v_exp_f32_e32 v24, v24
	v_exp_f32_e32 v25, v25
	v_exp_f32_e32 v20, v20
	v_exp_f32_e32 v21, v21
	v_pk_mul_f32 v[10:11], v[10:11], v[14:15]
	v_pk_add_f32 v[18:19], v[24:25], 1.0 op_sel_hi:[1,0]
	v_mul_f32_e32 v16, v26, v26
	v_rcp_f32_e32 v18, v18
	v_rcp_f32_e32 v19, v19
	v_pk_add_f32 v[14:15], v[20:21], 1.0 op_sel_hi:[1,0]
	v_pk_mul_f32 v[8:9], v[8:9], v[12:13]
	v_rcp_f32_e32 v14, v14
	v_rcp_f32_e32 v15, v15
	v_pk_mul_f32 v[12:13], v[16:17], v[18:19] op_sel_hi:[0,1]
	v_pk_mul_f32 v[18:19], v[0:1], v[22:23] op_sel_hi:[1,0]
	v_pk_mul_f32 v[8:9], v[8:9], v[12:13]
	v_exp_f32_e32 v18, v18
	v_exp_f32_e32 v19, v19
	v_pk_mul_f32 v[12:13], v[16:17], v[14:15] op_sel_hi:[0,1]
	v_pk_mul_f32 v[14:15], v[2:3], v[22:23] op_sel_hi:[1,0]
	v_pk_mul_f32 v[10:11], v[10:11], v[12:13]
	v_exp_f32_e32 v14, v14
	v_exp_f32_e32 v15, v15
	v_pk_add_f32 v[12:13], v[18:19], 1.0 op_sel_hi:[1,0]
	v_pk_mul_f32 v[2:3], v[2:3], v[6:7]
	v_rcp_f32_e32 v12, v12
	v_rcp_f32_e32 v13, v13
	v_pk_add_f32 v[6:7], v[14:15], 1.0 op_sel_hi:[1,0]
	v_pk_mul_f32 v[0:1], v[0:1], v[4:5]
	v_rcp_f32_e32 v6, v6
	v_rcp_f32_e32 v7, v7
	v_pk_mul_f32 v[4:5], v[16:17], v[12:13] op_sel_hi:[0,1]
	v_pk_mul_f32 v[4:5], v[0:1], v[4:5]
	v_pk_mul_f32 v[0:1], v[16:17], v[6:7] op_sel_hi:[0,1]
	v_pk_mul_f32 v[6:7], v[2:3], v[0:1]
	v_cvt_pk_bf16_f32 v0, v8, v9
	v_cvt_pk_bf16_f32 v1, v10, v11
	v_cvt_pk_bf16_f32 v2, v4, v5
	v_mad_i64_i32 v[4:5], s[26:27], v23, s51, v[112:113]
	v_lshl_add_u64 v[4:5], v[4:5], 0, v[114:115]
	s_mov_b64 s[26:27], s[20:21]
	v_cvt_pk_bf16_f32 v3, v6, v7
	global_store_dwordx4 v[4:5], v[0:3], off
	s_cbranch_vccz .LBB0_229
	s_waitcnt vmcnt(0)
	s_cmpk_gt_u32 s38, 0xff
	s_cbranch_scc1 .LBB0_236
	s_barrier

;     ...
;         G_PAIR(0, 1);
.LBB0_356:
	s_waitcnt lgkmcnt(0)
	ds_read_b128 v[0:3], v190
	ds_read_b128 v[4:7], v190 offset:1024
	ds_read_b128 v[8:11], v190 offset:2048
	ds_read_b128 v[12:15], v190 offset:3072
	s_add_u32 s34, s28, 0xb0080
	s_addc_u32 s35, s29, 0
	s_mov_b32 m0, s54
	v_lshl_add_u64 v[48:49], s[34:35], 0, v[154:155]
	ds_read_b128 v[16:19], v191
	ds_read_b128 v[20:23], v191 offset:1024
	ds_read_b128 v[24:27], v191 offset:2048
	ds_read_b128 v[28:31], v191 offset:3072
	ds_read_b128 v[32:35], v191 offset:4096
	ds_read_b128 v[36:39], v191 offset:5120
	ds_read_b128 v[40:43], v191 offset:6144
	ds_read_b128 v[44:47], v191 offset:7168
	global_load_lds_dwordx4 v[48:49], off
	s_mov_b32 m0, s55
	v_lshl_add_u64 v[48:49], s[34:35], 0, v[158:159]
	global_load_lds_dwordx4 v[48:49], off
	s_waitcnt lgkmcnt(8)
	s_barrier
	s_waitcnt lgkmcnt(0)
	v_mfma_f32_16x16x32_bf16 v[48:51], v[0:3], v[16:19], 0
	v_mfma_f32_16x16x32_bf16 v[52:55], v[8:11], v[16:19], 0
	v_mfma_f32_16x16x32_bf16 v[56:59], v[0:3], v[24:27], 0
	v_mfma_f32_16x16x32_bf16 v[60:63], v[8:11], v[24:27], 0
	v_mfma_f32_16x16x32_bf16 v[64:67], v[0:3], v[32:35], 0
	v_mfma_f32_16x16x32_bf16 v[68:71], v[8:11], v[32:35], 0
	v_mfma_f32_16x16x32_bf16 v[72:75], v[0:3], v[40:43], 0
	v_mfma_f32_16x16x32_bf16 v[76:79], v[8:11], v[40:43], 0
	v_mfma_f32_16x16x32_bf16 v[48:51], v[4:7], v[20:23], v[48:51]
	v_mfma_f32_16x16x32_bf16 v[52:55], v[12:15], v[20:23], v[52:55]
	v_mfma_f32_16x16x32_bf16 v[56:59], v[4:7], v[28:31], v[56:59]
	v_mfma_f32_16x16x32_bf16 v[60:63], v[12:15], v[28:31], v[60:63]
	v_mfma_f32_16x16x32_bf16 v[64:67], v[4:7], v[36:39], v[64:67]
	v_mfma_f32_16x16x32_bf16 v[68:71], v[12:15], v[36:39], v[68:71]
	v_mfma_f32_16x16x32_bf16 v[72:75], v[4:7], v[44:47], v[72:75]
	v_mfma_f32_16x16x32_bf16 v[76:79], v[12:15], v[44:47], v[76:79]
	s_barrier
	v_lshl_add_u64 v[182:183], s[30:31], 0, v[156:157]
	s_mov_b32 m0, s56
	v_lshl_add_u64 v[96:97], v[182:183], 0, s[12:13]
	v_lshl_add_u64 v[218:219], s[30:31], 0, v[160:161]
	ds_read_b128 v[80:83], v192
	ds_read_b128 v[84:87], v192 offset:1024
	ds_read_b128 v[88:91], v192 offset:2048
	ds_read_b128 v[92:95], v192 offset:3072
	global_load_lds_dwordx4 v[96:97], off
	s_mov_b32 m0, s57
	v_lshl_add_u64 v[96:97], v[218:219], 0, s[12:13]
	global_load_lds_dwordx4 v[96:97], off
	s_barrier
	s_waitcnt lgkmcnt(0)
	v_mfma_f32_16x16x32_bf16 v[96:99], v[80:83], v[16:19], 0
	v_mfma_f32_16x16x32_bf16 v[16:19], v[88:91], v[16:19], 0
	v_mfma_f32_16x16x32_bf16 v[100:103], v[80:83], v[24:27], 0
	v_mfma_f32_16x16x32_bf16 v[24:27], v[88:91], v[24:27], 0
	v_mfma_f32_16x16x32_bf16 v[104:107], v[80:83], v[32:35], 0
	v_mfma_f32_16x16x32_bf16 v[32:35], v[88:91], v[32:35], 0
	v_mfma_f32_16x16x32_bf16 v[108:111], v[80:83], v[40:43], 0
	v_mfma_f32_16x16x32_bf16 v[40:43], v[88:91], v[40:43], 0
	v_mfma_f32_16x16x32_bf16 v[96:99], v[84:87], v[20:23], v[96:99]
	v_mfma_f32_16x16x32_bf16 v[16:19], v[92:95], v[20:23], v[16:19]
	v_mfma_f32_16x16x32_bf16 v[20:23], v[84:87], v[28:31], v[100:103]
	v_mfma_f32_16x16x32_bf16 v[24:27], v[92:95], v[28:31], v[24:27]
	v_mfma_f32_16x16x32_bf16 v[28:31], v[84:87], v[36:39], v[104:107]
	v_mfma_f32_16x16x32_bf16 v[32:35], v[92:95], v[36:39], v[32:35]
	v_mfma_f32_16x16x32_bf16 v[36:39], v[84:87], v[44:47], v[108:111]
	v_mfma_f32_16x16x32_bf16 v[40:43], v[92:95], v[44:47], v[40:43]
	v_lshl_add_u64 v[246:247], s[28:29], 0, v[154:155]
	s_mov_b32 m0, s46
	v_lshl_add_u64 v[128:129], v[246:247], 0, s[12:13]
	v_lshl_add_u64 v[248:249], s[28:29], 0, v[158:159]
	s_barrier
	ds_read_b128 v[44:47], v191 offset:16384
	ds_read_b128 v[100:103], v191 offset:17408
	ds_read_b128 v[104:107], v191 offset:18432
	ds_read_b128 v[108:111], v191 offset:19456
	ds_read_b128 v[112:115], v191 offset:20480
	ds_read_b128 v[116:119], v191 offset:21504
	ds_read_b128 v[120:123], v191 offset:22528
	ds_read_b128 v[124:127], v191 offset:23552
	global_load_lds_dwordx4 v[128:129], off
	s_mov_b32 m0, s47
	v_lshl_add_u64 v[128:129], v[248:249], 0, s[12:13]
	global_load_lds_dwordx4 v[128:129], off
	s_barrier
	s_waitcnt lgkmcnt(0)
	v_mfma_f32_16x16x32_bf16 v[128:131], v[0:3], v[44:47], 0
	v_mfma_f32_16x16x32_bf16 v[132:135], v[8:11], v[44:47], 0
	v_mfma_f32_16x16x32_bf16 v[136:139], v[0:3], v[104:107], 0
	v_mfma_f32_16x16x32_bf16 v[140:143], v[8:11], v[104:107], 0
	v_mfma_f32_16x16x32_bf16 v[144:147], v[0:3], v[112:115], 0
	v_mfma_f32_16x16x32_bf16 v[148:151], v[8:11], v[112:115], 0
	v_mfma_f32_16x16x32_bf16 v[0:3], v[0:3], v[120:123], 0
	v_mfma_f32_16x16x32_bf16 v[8:11], v[8:11], v[120:123], 0
	v_mfma_f32_16x16x32_bf16 v[128:131], v[4:7], v[100:103], v[128:131]
	v_mfma_f32_16x16x32_bf16 v[166:169], v[12:15], v[100:103], v[132:135]
	v_mfma_f32_16x16x32_bf16 v[134:137], v[4:7], v[108:111], v[136:139]
	v_mfma_f32_16x16x32_bf16 v[138:141], v[12:15], v[108:111], v[140:143]
	v_mfma_f32_16x16x32_bf16 v[142:145], v[4:7], v[116:119], v[144:147]
	v_mfma_f32_16x16x32_bf16 v[0:3], v[4:7], v[124:127], v[0:3]
	v_mfma_f32_16x16x32_bf16 v[4:7], v[12:15], v[124:127], v[8:11]
	v_mfma_f32_16x16x32_bf16 v[146:149], v[12:15], v[116:119], v[148:151]
	s_barrier
	s_add_u32 s34, s30, 0xb0100
	s_addc_u32 s35, s31, 0
	s_add_i32 s0, s53, s43
	v_lshl_add_u64 v[8:9], s[34:35], 0, v[156:157]
	s_mov_b32 m0, s0
	s_add_i32 s62, s0, 0x2000
	global_load_lds_dwordx4 v[8:9], off
	s_mov_b32 m0, s62
	v_lshl_add_u64 v[8:9], s[34:35], 0, v[160:161]
	global_load_lds_dwordx4 v[8:9], off
	s_waitcnt vmcnt(6)
	s_barrier
	v_mfma_f32_16x16x32_bf16 v[8:11], v[80:83], v[44:47], 0
	v_mfma_f32_16x16x32_bf16 v[12:15], v[88:91], v[44:47], 0
	v_mfma_f32_16x16x32_bf16 v[44:47], v[80:83], v[104:107], 0
	v_mfma_f32_16x16x32_bf16 v[104:107], v[88:91], v[104:107], 0
	v_mfma_f32_16x16x32_bf16 v[170:173], v[80:83], v[112:115], 0
	v_mfma_f32_16x16x32_bf16 v[112:115], v[88:91], v[112:115], 0
	v_mfma_f32_16x16x32_bf16 v[80:83], v[80:83], v[120:123], 0
	v_mfma_f32_16x16x32_bf16 v[88:91], v[88:91], v[120:123], 0
	v_mfma_f32_16x16x32_bf16 v[8:11], v[84:87], v[100:103], v[8:11]
	v_mfma_f32_16x16x32_bf16 v[174:177], v[92:95], v[100:103], v[12:15]
	v_mfma_f32_16x16x32_bf16 v[178:181], v[84:87], v[108:111], v[44:47]
	v_mfma_f32_16x16x32_bf16 v[194:197], v[92:95], v[108:111], v[104:107]
	v_mfma_f32_16x16x32_bf16 v[170:173], v[84:87], v[116:119], v[170:173]
	v_mfma_f32_16x16x32_bf16 v[198:201], v[92:95], v[116:119], v[112:115]
	v_mfma_f32_16x16x32_bf16 v[202:205], v[84:87], v[124:127], v[80:83]
	v_mfma_f32_16x16x32_bf16 v[206:209], v[92:95], v[124:127], v[88:91]
	s_add_i32 s63, 0, 0x18000
	v_add_u32_e32 v132, s63, v188
	s_barrier
	ds_read_b128 v[12:15], v132
	ds_read_b128 v[210:213], v132 offset:1024
	ds_read_b128 v[44:47], v132 offset:2048
	ds_read_b128 v[214:217], v132 offset:3072
	s_add_u32 s34, s28, 0xb0100
	s_addc_u32 s35, s29, 0
	s_mov_b32 m0, s48
	v_lshl_add_u64 v[88:89], s[34:35], 0, v[154:155]
	ds_read_b128 v[80:83], v191 offset:32768
	ds_read_b128 v[84:87], v191 offset:33792
	ds_read_b128 v[100:103], v191 offset:34816
	ds_read_b128 v[222:225], v191 offset:35840
	ds_read_b128 v[120:123], v191 offset:36864
	ds_read_b128 v[226:229], v191 offset:37888
	ds_read_b128 v[124:127], v191 offset:38912
	ds_read_b128 v[230:233], v191 offset:39936
	global_load_lds_dwordx4 v[88:89], off
	s_mov_b32 m0, s49
	v_lshl_add_u64 v[88:89], s[34:35], 0, v[158:159]
	global_load_lds_dwordx4 v[88:89], off
	s_waitcnt lgkmcnt(8)
	s_barrier
	s_waitcnt lgkmcnt(0)
	v_mfma_f32_16x16x32_bf16 v[48:51], v[12:15], v[80:83], v[48:51]
	v_mfma_f32_16x16x32_bf16 v[52:55], v[44:47], v[80:83], v[52:55]
	v_mfma_f32_16x16x32_bf16 v[56:59], v[12:15], v[100:103], v[56:59]
	v_mfma_f32_16x16x32_bf16 v[60:63], v[44:47], v[100:103], v[60:63]
	v_mfma_f32_16x16x32_bf16 v[64:67], v[12:15], v[120:123], v[64:67]
	v_mfma_f32_16x16x32_bf16 v[68:71], v[44:47], v[120:123], v[68:71]
	v_mfma_f32_16x16x32_bf16 v[72:75], v[12:15], v[124:127], v[72:75]
	v_mfma_f32_16x16x32_bf16 v[234:237], v[44:47], v[124:127], v[76:79]
	v_mfma_f32_16x16x32_bf16 v[116:119], v[210:213], v[84:87], v[48:51]
	v_mfma_f32_16x16x32_bf16 v[112:115], v[214:217], v[84:87], v[52:55]
	v_mfma_f32_16x16x32_bf16 v[108:111], v[210:213], v[222:225], v[56:59]
	v_mfma_f32_16x16x32_bf16 v[104:107], v[214:217], v[222:225], v[60:63]
	v_mfma_f32_16x16x32_bf16 v[92:95], v[210:213], v[226:229], v[64:67]
	v_mfma_f32_16x16x32_bf16 v[88:91], v[214:217], v[226:229], v[68:71]
	v_mfma_f32_16x16x32_bf16 v[76:79], v[210:213], v[230:233], v[72:75]
	v_mfma_f32_16x16x32_bf16 v[72:75], v[214:217], v[230:233], v[234:237]
	s_barrier
	s_add_i32 s65, 0, 0x1c000
	s_add_i32 s63, s63, s43
	v_add_u32_e32 v133, s65, v188
	v_lshl_add_u64 v[48:49], v[182:183], 0, s[14:15]
	s_mov_b32 m0, s63
	s_add_i32 s64, s63, 0x2000
	ds_read_b128 v[56:59], v133
	ds_read_b128 v[234:237], v133 offset:1024
	ds_read_b128 v[60:63], v133 offset:2048
	ds_read_b128 v[238:241], v133 offset:3072
	global_load_lds_dwordx4 v[48:49], off
	s_mov_b32 m0, s64
	v_lshl_add_u64 v[48:49], v[218:219], 0, s[14:15]
	global_load_lds_dwordx4 v[48:49], off
	s_barrier
	s_waitcnt lgkmcnt(0)
	v_mfma_f32_16x16x32_bf16 v[48:51], v[56:59], v[80:83], v[96:99]
	v_mfma_f32_16x16x32_bf16 v[16:19], v[60:63], v[80:83], v[16:19]
	v_mfma_f32_16x16x32_bf16 v[20:23], v[56:59], v[100:103], v[20:23]
	v_mfma_f32_16x16x32_bf16 v[24:27], v[60:63], v[100:103], v[24:27]
	v_mfma_f32_16x16x32_bf16 v[28:31], v[56:59], v[120:123], v[28:31]
	v_mfma_f32_16x16x32_bf16 v[32:35], v[60:63], v[120:123], v[32:35]
	v_mfma_f32_16x16x32_bf16 v[36:39], v[56:59], v[124:127], v[36:39]
	v_mfma_f32_16x16x32_bf16 v[40:43], v[60:63], v[124:127], v[40:43]
	v_mfma_f32_16x16x32_bf16 v[124:127], v[234:237], v[84:87], v[48:51]
	v_mfma_f32_16x16x32_bf16 v[120:123], v[238:241], v[84:87], v[16:19]
	v_mfma_f32_16x16x32_bf16 v[100:103], v[234:237], v[222:225], v[20:23]
	v_mfma_f32_16x16x32_bf16 v[96:99], v[238:241], v[222:225], v[24:27]
	v_mfma_f32_16x16x32_bf16 v[84:87], v[234:237], v[226:229], v[28:31]
	v_mfma_f32_16x16x32_bf16 v[80:83], v[238:241], v[226:229], v[32:35]
	v_mfma_f32_16x16x32_bf16 v[68:71], v[234:237], v[230:233], v[36:39]
	v_mfma_f32_16x16x32_bf16 v[64:67], v[238:241], v[230:233], v[40:43]
	s_mov_b32 m0, s51
	v_lshl_add_u64 v[20:21], v[246:247], 0, s[14:15]
	s_barrier
	ds_read_b128 v[16:19], v191 offset:49152
	ds_read_b128 v[24:27], v191 offset:50176
	ds_read_b128 v[32:35], v191 offset:51200
	ds_read_b128 v[222:225], v191 offset:52224
	ds_read_b128 v[40:43], v191 offset:53248
	ds_read_b128 v[226:229], v191 offset:54272
	ds_read_b128 v[230:233], v191 offset:55296
	ds_read_b128 v[242:245], v191 offset:56320
	global_load_lds_dwordx4 v[20:21], off
	s_mov_b32 m0, s52
	v_lshl_add_u64 v[20:21], v[248:249], 0, s[14:15]
	global_load_lds_dwordx4 v[20:21], off
	s_barrier
;     ...
;         G_PAIR(0, 1);
; #pragma unroll 1
;         for (int t = 2; t < nt; t += 2) G_PAIR(t, 0);
	s_waitcnt lgkmcnt(0)
	v_mfma_f32_16x16x32_bf16 v[20:23], v[12:15], v[16:19], v[128:131]
	v_mfma_f32_16x16x32_bf16 v[28:31], v[44:47], v[16:19], v[166:169]
	v_mfma_f32_16x16x32_bf16 v[36:39], v[12:15], v[32:35], v[134:137]
	v_mfma_f32_16x16x32_bf16 v[128:131], v[44:47], v[32:35], v[138:141]
	v_mfma_f32_16x16x32_bf16 v[134:137], v[12:15], v[40:43], v[142:145]
	v_mfma_f32_16x16x32_bf16 v[138:141], v[44:47], v[40:43], v[146:149]
	v_mfma_f32_16x16x32_bf16 v[0:3], v[12:15], v[230:233], v[0:3]
	v_mfma_f32_16x16x32_bf16 v[4:7], v[44:47], v[230:233], v[4:7]
	v_mfma_f32_16x16x32_bf16 v[52:55], v[210:213], v[24:27], v[20:23]
	v_mfma_f32_16x16x32_bf16 v[48:51], v[214:217], v[24:27], v[28:31]
	v_mfma_f32_16x16x32_bf16 v[44:47], v[210:213], v[222:225], v[36:39]
	v_mfma_f32_16x16x32_bf16 v[36:39], v[214:217], v[222:225], v[128:131]
	v_mfma_f32_16x16x32_bf16 v[28:31], v[210:213], v[226:229], v[134:137]
	v_mfma_f32_16x16x32_bf16 v[20:23], v[214:217], v[226:229], v[138:141]
	v_mfma_f32_16x16x32_bf16 v[12:15], v[210:213], v[242:245], v[0:3]
	v_mfma_f32_16x16x32_bf16 v[4:7], v[214:217], v[242:245], v[4:7]
	s_barrier
	s_add_u32 s34, s30, 0xb0180
	s_addc_u32 s35, s31, 0
	s_add_i32 s65, s65, s43
	v_lshl_add_u64 v[0:1], s[34:35], 0, v[156:157]
	s_mov_b32 m0, s65
	s_add_i32 s66, s65, 0x2000
	global_load_lds_dwordx4 v[0:1], off
	v_lshl_add_u64 v[0:1], s[34:35], 0, v[160:161]
	s_mov_b32 m0, s66
	s_mov_b64 s[34:35], 0xb0180
	global_load_lds_dwordx4 v[0:1], off
	s_waitcnt vmcnt(6)
	s_barrier
	v_mfma_f32_16x16x32_bf16 v[0:3], v[56:59], v[16:19], v[8:11]
	v_mfma_f32_16x16x32_bf16 v[8:11], v[60:63], v[16:19], v[174:177]
	v_mfma_f32_16x16x32_bf16 v[16:19], v[56:59], v[32:35], v[178:181]
	v_mfma_f32_16x16x32_bf16 v[32:35], v[60:63], v[32:35], v[194:197]
	v_mfma_f32_16x16x32_bf16 v[128:131], v[56:59], v[40:43], v[170:173]
	v_mfma_f32_16x16x32_bf16 v[134:137], v[60:63], v[40:43], v[198:201]
	v_mfma_f32_16x16x32_bf16 v[138:141], v[56:59], v[230:233], v[202:205]
	v_mfma_f32_16x16x32_bf16 v[142:145], v[60:63], v[230:233], v[206:209]
	v_mfma_f32_16x16x32_bf16 v[60:63], v[234:237], v[24:27], v[0:3]
	v_mfma_f32_16x16x32_bf16 v[56:59], v[238:241], v[24:27], v[8:11]
	v_mfma_f32_16x16x32_bf16 v[40:43], v[234:237], v[222:225], v[16:19]
	v_mfma_f32_16x16x32_bf16 v[32:35], v[238:241], v[222:225], v[32:35]
	v_mfma_f32_16x16x32_bf16 v[24:27], v[234:237], v[226:229], v[128:131]
	v_mfma_f32_16x16x32_bf16 v[16:19], v[238:241], v[226:229], v[134:137]
	v_mfma_f32_16x16x32_bf16 v[8:11], v[234:237], v[242:245], v[138:141]
	v_mfma_f32_16x16x32_bf16 v[0:3], v[238:241], v[242:245], v[142:145]
	v_lshl_add_u64 v[128:129], s[28:29], 0, v[162:163]
	v_lshl_add_u64 v[130:131], s[28:29], 0, v[164:165]
	s_mov_b32 s67, 0
	s_barrier
.LBB0_357:
	ds_read_b128 v[134:137], v190
	ds_read_b128 v[138:141], v190 offset:1024
	ds_read_b128 v[142:145], v190 offset:2048
	ds_read_b128 v[146:149], v190 offset:3072
	s_mov_b32 m0, s54
	v_lshl_add_u64 v[150:151], v[128:129], 0, s[34:35]
	ds_read_b128 v[166:169], v191
	ds_read_b128 v[170:173], v191 offset:1024
	ds_read_b128 v[174:177], v191 offset:2048
	ds_read_b128 v[178:181], v191 offset:3072
	ds_read_b128 v[194:197], v191 offset:4096
	ds_read_b128 v[198:201], v191 offset:5120
	ds_read_b128 v[202:205], v191 offset:6144
	ds_read_b128 v[206:209], v191 offset:7168
	global_load_lds_dwordx4 v[150:151], off
	s_mov_b32 m0, s55
	v_lshl_add_u64 v[150:151], v[130:131], 0, s[34:35]
	global_load_lds_dwordx4 v[150:151], off
	s_waitcnt lgkmcnt(8)
	s_barrier
	s_waitcnt lgkmcnt(0)
	v_mfma_f32_16x16x32_bf16 v[116:119], v[134:137], v[166:169], v[116:119]
	s_add_i32 s36, s34, 0xfff50080
	v_mfma_f32_16x16x32_bf16 v[112:115], v[142:145], v[166:169], v[112:115]
	s_cmp_eq_u32 s67, 40
	v_mfma_f32_16x16x32_bf16 v[108:111], v[134:137], v[174:177], v[108:111]
	s_cselect_b32 s69, s27, s29
	v_mfma_f32_16x16x32_bf16 v[104:107], v[142:145], v[174:177], v[104:107]
	s_cselect_b32 s68, s26, s28
	v_mfma_f32_16x16x32_bf16 v[92:95], v[134:137], v[194:197], v[92:95]
	s_cselect_b32 s37, s9, s31
	v_mfma_f32_16x16x32_bf16 v[88:91], v[142:145], v[194:197], v[88:91]
	s_cselect_b32 s70, s8, s30
	v_mfma_f32_16x16x32_bf16 v[76:79], v[134:137], v[202:205], v[76:79]
	v_mfma_f32_16x16x32_bf16 v[72:75], v[142:145], v[202:205], v[72:75]
	v_mfma_f32_16x16x32_bf16 v[116:119], v[138:141], v[170:173], v[116:119]
	v_mfma_f32_16x16x32_bf16 v[112:115], v[146:149], v[170:173], v[112:115]
	v_mfma_f32_16x16x32_bf16 v[108:111], v[138:141], v[178:181], v[108:111]
	v_mfma_f32_16x16x32_bf16 v[104:107], v[146:149], v[178:181], v[104:107]
	v_mfma_f32_16x16x32_bf16 v[92:95], v[138:141], v[198:201], v[92:95]
	v_mfma_f32_16x16x32_bf16 v[88:91], v[146:149], v[198:201], v[88:91]
	v_mfma_f32_16x16x32_bf16 v[76:79], v[138:141], v[206:209], v[76:79]
	v_mfma_f32_16x16x32_bf16 v[72:75], v[146:149], v[206:209], v[72:75]
	s_barrier
	s_cselect_b32 s71, 0, s36
	s_add_u32 s36, s70, s71
	s_addc_u32 s37, s37, 0
	s_mov_b32 m0, s56
	v_lshl_add_u64 v[150:151], s[36:37], 0, v[156:157]
	ds_read_b128 v[210:213], v192
	ds_read_b128 v[214:217], v192 offset:1024
	ds_read_b128 v[222:225], v192 offset:2048
	ds_read_b128 v[226:229], v192 offset:3072
	global_load_lds_dwordx4 v[150:151], off
	s_mov_b32 m0, s57
	v_lshl_add_u64 v[182:183], s[36:37], 0, v[160:161]
	global_load_lds_dwordx4 v[182:183], off
	s_barrier
	s_waitcnt lgkmcnt(0)
	v_mfma_f32_16x16x32_bf16 v[124:127], v[210:213], v[166:169], v[124:127]
	v_mfma_f32_16x16x32_bf16 v[120:123], v[222:225], v[166:169], v[120:123]
	v_mfma_f32_16x16x32_bf16 v[100:103], v[210:213], v[174:177], v[100:103]
	v_mfma_f32_16x16x32_bf16 v[96:99], v[222:225], v[174:177], v[96:99]
	v_mfma_f32_16x16x32_bf16 v[84:87], v[210:213], v[194:197], v[84:87]
	v_mfma_f32_16x16x32_bf16 v[80:83], v[222:225], v[194:197], v[80:83]
	v_mfma_f32_16x16x32_bf16 v[68:71], v[210:213], v[202:205], v[68:71]
	v_mfma_f32_16x16x32_bf16 v[64:67], v[222:225], v[202:205], v[64:67]
	v_mfma_f32_16x16x32_bf16 v[124:127], v[214:217], v[170:173], v[124:127]
	v_mfma_f32_16x16x32_bf16 v[120:123], v[226:229], v[170:173], v[120:123]
	v_mfma_f32_16x16x32_bf16 v[100:103], v[214:217], v[178:181], v[100:103]
	v_mfma_f32_16x16x32_bf16 v[96:99], v[226:229], v[178:181], v[96:99]
	v_mfma_f32_16x16x32_bf16 v[84:87], v[214:217], v[198:201], v[84:87]
	v_mfma_f32_16x16x32_bf16 v[80:83], v[226:229], v[198:201], v[80:83]
	v_mfma_f32_16x16x32_bf16 v[68:71], v[214:217], v[206:209], v[68:71]
	v_mfma_f32_16x16x32_bf16 v[64:67], v[226:229], v[206:209], v[64:67]
	s_add_u32 s68, s68, s71
	s_addc_u32 s69, s69, 0
	s_mov_b32 m0, s46
	v_lshl_add_u64 v[218:219], s[68:69], 0, v[154:155]
	s_barrier
	ds_read_b128 v[166:169], v191 offset:16384
	ds_read_b128 v[170:173], v191 offset:17408
	ds_read_b128 v[174:177], v191 offset:18432
	ds_read_b128 v[178:181], v191 offset:19456
	ds_read_b128 v[194:197], v191 offset:20480
	ds_read_b128 v[198:201], v191 offset:21504
	ds_read_b128 v[202:205], v191 offset:22528
	ds_read_b128 v[206:209], v191 offset:23552
	global_load_lds_dwordx4 v[218:219], off
	s_mov_b32 m0, s47
	v_lshl_add_u64 v[230:231], s[68:69], 0, v[158:159]
	global_load_lds_dwordx4 v[230:231], off
	s_barrier
	s_waitcnt lgkmcnt(0)
	v_mfma_f32_16x16x32_bf16 v[52:55], v[134:137], v[166:169], v[52:55]
	v_mfma_f32_16x16x32_bf16 v[48:51], v[142:145], v[166:169], v[48:51]
	v_mfma_f32_16x16x32_bf16 v[44:47], v[134:137], v[174:177], v[44:47]
	v_mfma_f32_16x16x32_bf16 v[36:39], v[142:145], v[174:177], v[36:39]
	v_mfma_f32_16x16x32_bf16 v[28:31], v[134:137], v[194:197], v[28:31]
	v_mfma_f32_16x16x32_bf16 v[20:23], v[142:145], v[194:197], v[20:23]
	v_mfma_f32_16x16x32_bf16 v[12:15], v[134:137], v[202:205], v[12:15]
	v_mfma_f32_16x16x32_bf16 v[4:7], v[142:145], v[202:205], v[4:7]
	v_mfma_f32_16x16x32_bf16 v[52:55], v[138:141], v[170:173], v[52:55]
	v_mfma_f32_16x16x32_bf16 v[48:51], v[146:149], v[170:173], v[48:51]
	v_mfma_f32_16x16x32_bf16 v[44:47], v[138:141], v[178:181], v[44:47]
	v_mfma_f32_16x16x32_bf16 v[36:39], v[146:149], v[178:181], v[36:39]
	v_mfma_f32_16x16x32_bf16 v[28:31], v[138:141], v[198:201], v[28:31]
	v_mfma_f32_16x16x32_bf16 v[20:23], v[146:149], v[198:201], v[20:23]
	v_mfma_f32_16x16x32_bf16 v[12:15], v[138:141], v[206:209], v[12:15]
	v_mfma_f32_16x16x32_bf16 v[4:7], v[146:149], v[206:209], v[4:7]
	s_barrier
	s_add_u32 s70, s36, 0xb0000
	s_addc_u32 s71, s37, 0
	s_mov_b32 m0, s0
	v_lshl_add_u64 v[134:135], s[70:71], 0, v[156:157]
	global_load_lds_dwordx4 v[134:135], off
	s_mov_b32 m0, s62
	v_lshl_add_u64 v[134:135], s[70:71], 0, v[160:161]
	global_load_lds_dwordx4 v[134:135], off
	s_waitcnt vmcnt(6)
	s_barrier
	v_mfma_f32_16x16x32_bf16 v[60:63], v[210:213], v[166:169], v[60:63]
	v_mfma_f32_16x16x32_bf16 v[56:59], v[222:225], v[166:169], v[56:59]
	v_mfma_f32_16x16x32_bf16 v[40:43], v[210:213], v[174:177], v[40:43]
	v_mfma_f32_16x16x32_bf16 v[32:35], v[222:225], v[174:177], v[32:35]
	v_mfma_f32_16x16x32_bf16 v[24:27], v[210:213], v[194:197], v[24:27]
	v_mfma_f32_16x16x32_bf16 v[16:19], v[222:225], v[194:197], v[16:19]
	v_mfma_f32_16x16x32_bf16 v[8:11], v[210:213], v[202:205], v[8:11]
	v_mfma_f32_16x16x32_bf16 v[0:3], v[222:225], v[202:205], v[0:3]
	v_mfma_f32_16x16x32_bf16 v[60:63], v[214:217], v[170:173], v[60:63]
	v_mfma_f32_16x16x32_bf16 v[56:59], v[226:229], v[170:173], v[56:59]
	v_mfma_f32_16x16x32_bf16 v[40:43], v[214:217], v[178:181], v[40:43]
	v_mfma_f32_16x16x32_bf16 v[32:35], v[226:229], v[178:181], v[32:35]
	v_mfma_f32_16x16x32_bf16 v[24:27], v[214:217], v[198:201], v[24:27]
	v_mfma_f32_16x16x32_bf16 v[16:19], v[226:229], v[198:201], v[16:19]
	v_mfma_f32_16x16x32_bf16 v[8:11], v[214:217], v[206:209], v[8:11]
	v_mfma_f32_16x16x32_bf16 v[0:3], v[226:229], v[206:209], v[0:3]
	s_barrier
	ds_read_b128 v[134:137], v132
	ds_read_b128 v[138:141], v132 offset:1024
	ds_read_b128 v[142:145], v132 offset:2048
	ds_read_b128 v[146:149], v132 offset:3072
	s_add_u32 s68, s68, 0xb0000
	s_addc_u32 s69, s69, 0
	s_mov_b32 m0, s48
	v_lshl_add_u64 v[210:211], s[68:69], 0, v[154:155]
	ds_read_b128 v[166:169], v191 offset:32768
	ds_read_b128 v[170:173], v191 offset:33792
	ds_read_b128 v[174:177], v191 offset:34816
	ds_read_b128 v[178:181], v191 offset:35840
	ds_read_b128 v[194:197], v191 offset:36864
	ds_read_b128 v[198:201], v191 offset:37888
	ds_read_b128 v[202:205], v191 offset:38912
	ds_read_b128 v[206:209], v191 offset:39936
	global_load_lds_dwordx4 v[210:211], off
	s_mov_b32 m0, s49
	v_lshl_add_u64 v[210:211], s[68:69], 0, v[158:159]
	global_load_lds_dwordx4 v[210:211], off
	s_waitcnt lgkmcnt(8)
	s_barrier
;     ...
;         G_PAIR(0, 1);
; #pragma unroll 1
;         for (int t = 2; t < nt; t += 2) G_PAIR(t, 0);
	s_waitcnt lgkmcnt(0)
	v_mfma_f32_16x16x32_bf16 v[116:119], v[134:137], v[166:169], v[116:119]
	v_mfma_f32_16x16x32_bf16 v[112:115], v[142:145], v[166:169], v[112:115]
	v_mfma_f32_16x16x32_bf16 v[108:111], v[134:137], v[174:177], v[108:111]
	v_mfma_f32_16x16x32_bf16 v[104:107], v[142:145], v[174:177], v[104:107]
	v_mfma_f32_16x16x32_bf16 v[92:95], v[134:137], v[194:197], v[92:95]
	v_mfma_f32_16x16x32_bf16 v[88:91], v[142:145], v[194:197], v[88:91]
	v_mfma_f32_16x16x32_bf16 v[76:79], v[134:137], v[202:205], v[76:79]
	v_mfma_f32_16x16x32_bf16 v[72:75], v[142:145], v[202:205], v[72:75]
	v_mfma_f32_16x16x32_bf16 v[116:119], v[138:141], v[170:173], v[116:119]
	v_mfma_f32_16x16x32_bf16 v[112:115], v[146:149], v[170:173], v[112:115]
	v_mfma_f32_16x16x32_bf16 v[108:111], v[138:141], v[178:181], v[108:111]
	v_mfma_f32_16x16x32_bf16 v[104:107], v[146:149], v[178:181], v[104:107]
	v_mfma_f32_16x16x32_bf16 v[92:95], v[138:141], v[198:201], v[92:95]
	v_mfma_f32_16x16x32_bf16 v[88:91], v[146:149], v[198:201], v[88:91]
	v_mfma_f32_16x16x32_bf16 v[76:79], v[138:141], v[206:209], v[76:79]
	v_mfma_f32_16x16x32_bf16 v[72:75], v[146:149], v[206:209], v[72:75]
	s_barrier
	s_mov_b32 m0, s63
	v_lshl_add_u64 v[150:151], v[150:151], 0, s[10:11]
	ds_read_b128 v[210:213], v133
	ds_read_b128 v[214:217], v133 offset:1024
	ds_read_b128 v[222:225], v133 offset:2048
	ds_read_b128 v[226:229], v133 offset:3072
	global_load_lds_dwordx4 v[150:151], off
	s_mov_b32 m0, s64
	v_lshl_add_u64 v[150:151], v[182:183], 0, s[10:11]
	global_load_lds_dwordx4 v[150:151], off
	s_barrier
	s_waitcnt lgkmcnt(0)
	v_mfma_f32_16x16x32_bf16 v[124:127], v[210:213], v[166:169], v[124:127]
	v_mfma_f32_16x16x32_bf16 v[120:123], v[222:225], v[166:169], v[120:123]
	v_mfma_f32_16x16x32_bf16 v[100:103], v[210:213], v[174:177], v[100:103]
	v_mfma_f32_16x16x32_bf16 v[96:99], v[222:225], v[174:177], v[96:99]
	v_mfma_f32_16x16x32_bf16 v[84:87], v[210:213], v[194:197], v[84:87]
	v_mfma_f32_16x16x32_bf16 v[80:83], v[222:225], v[194:197], v[80:83]
	v_mfma_f32_16x16x32_bf16 v[68:71], v[210:213], v[202:205], v[68:71]
	v_mfma_f32_16x16x32_bf16 v[64:67], v[222:225], v[202:205], v[64:67]
	v_mfma_f32_16x16x32_bf16 v[124:127], v[214:217], v[170:173], v[124:127]
	v_mfma_f32_16x16x32_bf16 v[120:123], v[226:229], v[170:173], v[120:123]
	v_mfma_f32_16x16x32_bf16 v[100:103], v[214:217], v[178:181], v[100:103]
	v_mfma_f32_16x16x32_bf16 v[96:99], v[226:229], v[178:181], v[96:99]
	v_mfma_f32_16x16x32_bf16 v[84:87], v[214:217], v[198:201], v[84:87]
	v_mfma_f32_16x16x32_bf16 v[80:83], v[226:229], v[198:201], v[80:83]
	v_mfma_f32_16x16x32_bf16 v[68:71], v[214:217], v[206:209], v[68:71]
	v_mfma_f32_16x16x32_bf16 v[64:67], v[226:229], v[206:209], v[64:67]
	s_mov_b32 m0, s51
	v_lshl_add_u64 v[150:151], v[218:219], 0, s[10:11]
	s_barrier
	ds_read_b128 v[166:169], v191 offset:49152
	ds_read_b128 v[170:173], v191 offset:50176
	ds_read_b128 v[174:177], v191 offset:51200
	ds_read_b128 v[178:181], v191 offset:52224
	ds_read_b128 v[194:197], v191 offset:53248
	ds_read_b128 v[198:201], v191 offset:54272
	ds_read_b128 v[202:205], v191 offset:55296
	ds_read_b128 v[206:209], v191 offset:56320
	global_load_lds_dwordx4 v[150:151], off
	s_mov_b32 m0, s52
	v_lshl_add_u64 v[150:151], v[230:231], 0, s[10:11]
	global_load_lds_dwordx4 v[150:151], off
	s_barrier
	s_waitcnt lgkmcnt(0)
	v_mfma_f32_16x16x32_bf16 v[52:55], v[134:137], v[166:169], v[52:55]
	v_mfma_f32_16x16x32_bf16 v[48:51], v[142:145], v[166:169], v[48:51]
	v_mfma_f32_16x16x32_bf16 v[44:47], v[134:137], v[174:177], v[44:47]
	v_mfma_f32_16x16x32_bf16 v[36:39], v[142:145], v[174:177], v[36:39]
	v_mfma_f32_16x16x32_bf16 v[28:31], v[134:137], v[194:197], v[28:31]
	v_mfma_f32_16x16x32_bf16 v[20:23], v[142:145], v[194:197], v[20:23]
	v_mfma_f32_16x16x32_bf16 v[12:15], v[134:137], v[202:205], v[12:15]
	v_mfma_f32_16x16x32_bf16 v[4:7], v[142:145], v[202:205], v[4:7]
	v_mfma_f32_16x16x32_bf16 v[52:55], v[138:141], v[170:173], v[52:55]
	v_mfma_f32_16x16x32_bf16 v[48:51], v[146:149], v[170:173], v[48:51]
	v_mfma_f32_16x16x32_bf16 v[44:47], v[138:141], v[178:181], v[44:47]
	v_mfma_f32_16x16x32_bf16 v[36:39], v[146:149], v[178:181], v[36:39]
	v_mfma_f32_16x16x32_bf16 v[28:31], v[138:141], v[198:201], v[28:31]
	v_mfma_f32_16x16x32_bf16 v[20:23], v[146:149], v[198:201], v[20:23]
	v_mfma_f32_16x16x32_bf16 v[12:15], v[138:141], v[206:209], v[12:15]
	v_mfma_f32_16x16x32_bf16 v[4:7], v[146:149], v[206:209], v[4:7]
	s_barrier
	s_add_u32 s36, s36, 0xb0080
	s_addc_u32 s37, s37, 0
	s_mov_b32 m0, s65
	v_lshl_add_u64 v[134:135], s[36:37], 0, v[156:157]
	global_load_lds_dwordx4 v[134:135], off
	s_mov_b32 m0, s66
	v_lshl_add_u64 v[134:135], s[36:37], 0, v[160:161]
	global_load_lds_dwordx4 v[134:135], off
	s_waitcnt vmcnt(6)
	s_barrier
	v_mfma_f32_16x16x32_bf16 v[60:63], v[210:213], v[166:169], v[60:63]
	v_mfma_f32_16x16x32_bf16 v[56:59], v[222:225], v[166:169], v[56:59]
	v_mfma_f32_16x16x32_bf16 v[40:43], v[210:213], v[174:177], v[40:43]
	v_mfma_f32_16x16x32_bf16 v[32:35], v[222:225], v[174:177], v[32:35]
	v_mfma_f32_16x16x32_bf16 v[24:27], v[210:213], v[194:197], v[24:27]
	v_mfma_f32_16x16x32_bf16 v[16:19], v[222:225], v[194:197], v[16:19]
	v_mfma_f32_16x16x32_bf16 v[8:11], v[210:213], v[202:205], v[8:11]
	v_mfma_f32_16x16x32_bf16 v[0:3], v[222:225], v[202:205], v[0:3]
	v_mfma_f32_16x16x32_bf16 v[60:63], v[214:217], v[170:173], v[60:63]
	v_mfma_f32_16x16x32_bf16 v[56:59], v[226:229], v[170:173], v[56:59]
	v_mfma_f32_16x16x32_bf16 v[40:43], v[214:217], v[178:181], v[40:43]
	v_mfma_f32_16x16x32_bf16 v[32:35], v[226:229], v[178:181], v[32:35]
	v_mfma_f32_16x16x32_bf16 v[24:27], v[214:217], v[198:201], v[24:27]
	v_mfma_f32_16x16x32_bf16 v[16:19], v[226:229], v[198:201], v[16:19]
	v_mfma_f32_16x16x32_bf16 v[8:11], v[214:217], v[206:209], v[8:11]
	v_mfma_f32_16x16x32_bf16 v[0:3], v[226:229], v[206:209], v[0:3]
	s_add_i32 s67, s67, 2
	s_add_u32 s34, s34, 0x100
	s_addc_u32 s35, s35, 0
	s_cmp_gt_u32 s67, 39
	s_barrier
	s_cbranch_scc0 .LBB0_357
	ds_read_b128 v[134:137], v190
	ds_read_b128 v[138:141], v190 offset:1024
	ds_read_b128 v[142:145], v190 offset:2048
	ds_read_b128 v[146:149], v190 offset:3072
	s_mov_b32 m0, s54
	v_lshl_add_u64 v[150:151], v[128:129], 0, s[34:35]
	ds_read_b128 v[166:169], v191
	ds_read_b128 v[170:173], v191 offset:1024
	ds_read_b128 v[174:177], v191 offset:2048
	ds_read_b128 v[178:181], v191 offset:3072
	ds_read_b128 v[194:197], v191 offset:4096
	ds_read_b128 v[198:201], v191 offset:5120
	ds_read_b128 v[202:205], v191 offset:6144
	ds_read_b128 v[206:209], v191 offset:7168
	global_load_lds_dwordx4 v[150:151], off
	s_mov_b32 m0, s55
	v_lshl_add_u64 v[150:151], v[130:131], 0, s[34:35]
	global_load_lds_dwordx4 v[150:151], off
	s_waitcnt lgkmcnt(8)
	s_barrier
	s_waitcnt lgkmcnt(0)
	v_mfma_f32_16x16x32_bf16 v[116:119], v[134:137], v[166:169], v[116:119]
	s_add_i32 s36, s34, 0xfff50080
	v_mfma_f32_16x16x32_bf16 v[112:115], v[142:145], v[166:169], v[112:115]
	s_cmp_eq_u32 s67, 40
	v_mfma_f32_16x16x32_bf16 v[108:111], v[134:137], v[174:177], v[108:111]
	s_cselect_b32 s69, s27, s29
	v_mfma_f32_16x16x32_bf16 v[104:107], v[142:145], v[174:177], v[104:107]
	s_cselect_b32 s68, s26, s28
	v_mfma_f32_16x16x32_bf16 v[92:95], v[134:137], v[194:197], v[92:95]
	s_cselect_b32 s37, s9, s31
	v_mfma_f32_16x16x32_bf16 v[88:91], v[142:145], v[194:197], v[88:91]
	s_cselect_b32 s70, s8, s30
	v_mfma_f32_16x16x32_bf16 v[76:79], v[134:137], v[202:205], v[76:79]
	v_mfma_f32_16x16x32_bf16 v[72:75], v[142:145], v[202:205], v[72:75]
	v_mfma_f32_16x16x32_bf16 v[116:119], v[138:141], v[170:173], v[116:119]
	v_mfma_f32_16x16x32_bf16 v[112:115], v[146:149], v[170:173], v[112:115]
	v_mfma_f32_16x16x32_bf16 v[108:111], v[138:141], v[178:181], v[108:111]
	v_mfma_f32_16x16x32_bf16 v[104:107], v[146:149], v[178:181], v[104:107]
	v_mfma_f32_16x16x32_bf16 v[92:95], v[138:141], v[198:201], v[92:95]
	v_mfma_f32_16x16x32_bf16 v[88:91], v[146:149], v[198:201], v[88:91]
	v_mfma_f32_16x16x32_bf16 v[76:79], v[138:141], v[206:209], v[76:79]
	v_mfma_f32_16x16x32_bf16 v[72:75], v[146:149], v[206:209], v[72:75]
	s_barrier
	s_cselect_b32 s71, 0, s36
	s_add_u32 s36, s70, s71
	s_addc_u32 s37, s37, 0
	s_mov_b32 m0, s56
	v_lshl_add_u64 v[150:151], s[36:37], 0, v[156:157]
	ds_read_b128 v[210:213], v192
	ds_read_b128 v[214:217], v192 offset:1024
	ds_read_b128 v[222:225], v192 offset:2048
	ds_read_b128 v[226:229], v192 offset:3072
	global_load_lds_dwordx4 v[150:151], off
	s_mov_b32 m0, s57
	v_lshl_add_u64 v[182:183], s[36:37], 0, v[160:161]
	global_load_lds_dwordx4 v[182:183], off
	s_barrier
	s_waitcnt lgkmcnt(0)
	v_mfma_f32_16x16x32_bf16 v[124:127], v[210:213], v[166:169], v[124:127]
	v_mfma_f32_16x16x32_bf16 v[120:123], v[222:225], v[166:169], v[120:123]
	v_mfma_f32_16x16x32_bf16 v[100:103], v[210:213], v[174:177], v[100:103]
	v_mfma_f32_16x16x32_bf16 v[96:99], v[222:225], v[174:177], v[96:99]
	v_mfma_f32_16x16x32_bf16 v[84:87], v[210:213], v[194:197], v[84:87]
	v_mfma_f32_16x16x32_bf16 v[80:83], v[222:225], v[194:197], v[80:83]
	v_mfma_f32_16x16x32_bf16 v[68:71], v[210:213], v[202:205], v[68:71]
	v_mfma_f32_16x16x32_bf16 v[64:67], v[222:225], v[202:205], v[64:67]
	v_mfma_f32_16x16x32_bf16 v[124:127], v[214:217], v[170:173], v[124:127]
	v_mfma_f32_16x16x32_bf16 v[120:123], v[226:229], v[170:173], v[120:123]
	v_mfma_f32_16x16x32_bf16 v[100:103], v[214:217], v[178:181], v[100:103]
	v_mfma_f32_16x16x32_bf16 v[96:99], v[226:229], v[178:181], v[96:99]
	v_mfma_f32_16x16x32_bf16 v[84:87], v[214:217], v[198:201], v[84:87]
	v_mfma_f32_16x16x32_bf16 v[80:83], v[226:229], v[198:201], v[80:83]
	v_mfma_f32_16x16x32_bf16 v[68:71], v[214:217], v[206:209], v[68:71]
	v_mfma_f32_16x16x32_bf16 v[64:67], v[226:229], v[206:209], v[64:67]
	s_add_u32 s68, s68, s71
	s_addc_u32 s69, s69, 0
	s_mov_b32 m0, s46
	v_lshl_add_u64 v[218:219], s[68:69], 0, v[154:155]
	s_barrier
	ds_read_b128 v[166:169], v191 offset:16384
	ds_read_b128 v[170:173], v191 offset:17408
	ds_read_b128 v[174:177], v191 offset:18432
	ds_read_b128 v[178:181], v191 offset:19456
	ds_read_b128 v[194:197], v191 offset:20480
	ds_read_b128 v[198:201], v191 offset:21504
	ds_read_b128 v[202:205], v191 offset:22528
	ds_read_b128 v[206:209], v191 offset:23552
	global_load_lds_dwordx4 v[218:219], off
	s_mov_b32 m0, s47
	v_lshl_add_u64 v[230:231], s[68:69], 0, v[158:159]
	global_load_lds_dwordx4 v[230:231], off
	s_barrier
	s_waitcnt lgkmcnt(0)
	v_mfma_f32_16x16x32_bf16 v[52:55], v[134:137], v[166:169], v[52:55]
	v_mfma_f32_16x16x32_bf16 v[48:51], v[142:145], v[166:169], v[48:51]
	v_mfma_f32_16x16x32_bf16 v[44:47], v[134:137], v[174:177], v[44:47]
	v_mfma_f32_16x16x32_bf16 v[36:39], v[142:145], v[174:177], v[36:39]
	v_mfma_f32_16x16x32_bf16 v[28:31], v[134:137], v[194:197], v[28:31]
	v_mfma_f32_16x16x32_bf16 v[20:23], v[142:145], v[194:197], v[20:23]
	v_mfma_f32_16x16x32_bf16 v[12:15], v[134:137], v[202:205], v[12:15]
	v_mfma_f32_16x16x32_bf16 v[4:7], v[142:145], v[202:205], v[4:7]
	v_mfma_f32_16x16x32_bf16 v[52:55], v[138:141], v[170:173], v[52:55]
	v_mfma_f32_16x16x32_bf16 v[48:51], v[146:149], v[170:173], v[48:51]
	v_mfma_f32_16x16x32_bf16 v[44:47], v[138:141], v[178:181], v[44:47]
	v_mfma_f32_16x16x32_bf16 v[36:39], v[146:149], v[178:181], v[36:39]
	v_mfma_f32_16x16x32_bf16 v[28:31], v[138:141], v[198:201], v[28:31]
	v_mfma_f32_16x16x32_bf16 v[20:23], v[146:149], v[198:201], v[20:23]
	v_mfma_f32_16x16x32_bf16 v[12:15], v[138:141], v[206:209], v[12:15]
	v_mfma_f32_16x16x32_bf16 v[4:7], v[146:149], v[206:209], v[4:7]
	s_barrier
;     __device__ __forceinline__ void epi(const f32x4 (&acc)[2][2][4][2], const Unit& u, int wr, int wc, int fr, int fq) const {
;     ...
;                 for (int bj = 0; bj < 2; ++bj) xo[m][bj] = *(const u32x4*)(xb + (size_t)(row0 + ai * 128 + m * 16) * D + col0 + bj * 128);
	s_add_u32 s70, s36, 0xb0000
	s_addc_u32 s71, s37, 0
	s_mov_b32 m0, s0
	v_lshl_add_u64 v[134:135], s[70:71], 0, v[156:157]
	global_load_lds_dwordx4 v[134:135], off
	s_mov_b32 m0, s62
	v_lshl_add_u64 v[134:135], s[70:71], 0, v[160:161]
	global_load_lds_dwordx4 v[134:135], off
	s_waitcnt vmcnt(6)
	s_barrier
	v_mfma_f32_16x16x32_bf16 v[60:63], v[210:213], v[166:169], v[60:63]
	v_lshl_or_b32 v248, s40, 8, v189
	v_mfma_f32_16x16x32_bf16 v[56:59], v[222:225], v[166:169], v[56:59]
	v_lshl_add_u32 v250, s61, 8, v153
	v_mfma_f32_16x16x32_bf16 v[40:43], v[210:213], v[174:177], v[40:43]
	v_ashrrev_i32_e32 v249, 31, v248
	v_mfma_f32_16x16x32_bf16 v[32:35], v[222:225], v[174:177], v[32:35]
	v_lshlrev_b64 v[248:249], 1, v[248:249]
	v_mfma_f32_16x16x32_bf16 v[24:27], v[210:213], v[194:197], v[24:27]
	v_ashrrev_i32_e32 v251, 31, v250
	v_mfma_f32_16x16x32_bf16 v[16:19], v[222:225], v[194:197], v[16:19]
	v_lshl_add_u64 v[248:249], s[20:21], 0, v[248:249]
	v_mfma_f32_16x16x32_bf16 v[8:11], v[210:213], v[202:205], v[8:11]
	v_lshlrev_b64 v[250:251], 11, v[250:251]
	v_mfma_f32_16x16x32_bf16 v[0:3], v[222:225], v[202:205], v[0:3]
	v_lshl_add_u64 v[252:253], v[248:249], 0, v[250:251]
	v_mfma_f32_16x16x32_bf16 v[60:63], v[214:217], v[170:173], v[60:63]
	global_load_dwordx4 v[232:235], v[252:253], off
	v_mfma_f32_16x16x32_bf16 v[56:59], v[226:229], v[170:173], v[56:59]
	global_load_dwordx4 v[236:239], v[252:253], off offset:256
	v_mfma_f32_16x16x32_bf16 v[40:43], v[214:217], v[178:181], v[40:43]
	v_mov_b32_e32 v250, 0x8000
	v_mfma_f32_16x16x32_bf16 v[32:35], v[226:229], v[178:181], v[32:35]
	v_mov_b32_e32 v251, 0
	v_mfma_f32_16x16x32_bf16 v[24:27], v[214:217], v[198:201], v[24:27]
	v_lshl_add_u64 v[250:251], v[252:253], 0, v[250:251]
	v_mfma_f32_16x16x32_bf16 v[16:19], v[226:229], v[198:201], v[16:19]
	global_load_dwordx4 v[240:243], v[250:251], off
	v_mfma_f32_16x16x32_bf16 v[8:11], v[214:217], v[206:209], v[8:11]
	global_load_dwordx4 v[244:247], v[250:251], off offset:256
	v_mfma_f32_16x16x32_bf16 v[0:3], v[226:229], v[206:209], v[0:3]
	s_barrier
	ds_read_b128 v[134:137], v132
	ds_read_b128 v[138:141], v132 offset:1024
	ds_read_b128 v[142:145], v132 offset:2048
	ds_read_b128 v[146:149], v132 offset:3072
	s_add_u32 s68, s68, 0xb0000
	s_addc_u32 s69, s69, 0
	s_mov_b32 m0, s48
	v_lshl_add_u64 v[210:211], s[68:69], 0, v[154:155]
	ds_read_b128 v[166:169], v191 offset:32768
	ds_read_b128 v[170:173], v191 offset:33792
	ds_read_b128 v[174:177], v191 offset:34816
	ds_read_b128 v[178:181], v191 offset:35840
	ds_read_b128 v[194:197], v191 offset:36864
	ds_read_b128 v[198:201], v191 offset:37888
	ds_read_b128 v[202:205], v191 offset:38912
	ds_read_b128 v[206:209], v191 offset:39936
	global_load_lds_dwordx4 v[210:211], off
	s_mov_b32 m0, s49
	v_lshl_add_u64 v[210:211], s[68:69], 0, v[158:159]
	global_load_lds_dwordx4 v[210:211], off
	s_waitcnt lgkmcnt(8)
	s_barrier
	s_waitcnt lgkmcnt(0)
	v_mfma_f32_16x16x32_bf16 v[116:119], v[134:137], v[166:169], v[116:119]
	v_mfma_f32_16x16x32_bf16 v[112:115], v[142:145], v[166:169], v[112:115]
	v_mfma_f32_16x16x32_bf16 v[108:111], v[134:137], v[174:177], v[108:111]
	v_mfma_f32_16x16x32_bf16 v[104:107], v[142:145], v[174:177], v[104:107]
	v_mfma_f32_16x16x32_bf16 v[92:95], v[134:137], v[194:197], v[92:95]
	v_mfma_f32_16x16x32_bf16 v[88:91], v[142:145], v[194:197], v[88:91]
	v_mfma_f32_16x16x32_bf16 v[76:79], v[134:137], v[202:205], v[76:79]
	v_mfma_f32_16x16x32_bf16 v[72:75], v[142:145], v[202:205], v[72:75]
	v_mfma_f32_16x16x32_bf16 v[116:119], v[138:141], v[170:173], v[116:119]
	v_mfma_f32_16x16x32_bf16 v[112:115], v[146:149], v[170:173], v[112:115]
	v_mfma_f32_16x16x32_bf16 v[108:111], v[138:141], v[178:181], v[108:111]
	v_mfma_f32_16x16x32_bf16 v[104:107], v[146:149], v[178:181], v[104:107]
	v_mfma_f32_16x16x32_bf16 v[92:95], v[138:141], v[198:201], v[92:95]
	v_mfma_f32_16x16x32_bf16 v[88:91], v[146:149], v[198:201], v[88:91]
	v_mfma_f32_16x16x32_bf16 v[76:79], v[138:141], v[206:209], v[76:79]
	v_mfma_f32_16x16x32_bf16 v[72:75], v[146:149], v[206:209], v[72:75]
	s_barrier
	s_mov_b32 m0, s63
	v_lshl_add_u64 v[150:151], v[150:151], 0, s[10:11]
	ds_read_b128 v[210:213], v133
	ds_read_b128 v[214:217], v133 offset:1024
	ds_read_b128 v[222:225], v133 offset:2048
	ds_read_b128 v[226:229], v133 offset:3072
	global_load_lds_dwordx4 v[150:151], off
	s_mov_b32 m0, s64
	v_lshl_add_u64 v[150:151], v[182:183], 0, s[10:11]
	global_load_lds_dwordx4 v[150:151], off
	s_barrier
	s_waitcnt lgkmcnt(0)
	v_mfma_f32_16x16x32_bf16 v[124:127], v[210:213], v[166:169], v[124:127]
	v_mfma_f32_16x16x32_bf16 v[120:123], v[222:225], v[166:169], v[120:123]
	v_mfma_f32_16x16x32_bf16 v[100:103], v[210:213], v[174:177], v[100:103]
	v_mfma_f32_16x16x32_bf16 v[96:99], v[222:225], v[174:177], v[96:99]
	v_mfma_f32_16x16x32_bf16 v[84:87], v[210:213], v[194:197], v[84:87]
	v_mfma_f32_16x16x32_bf16 v[80:83], v[222:225], v[194:197], v[80:83]
	v_mfma_f32_16x16x32_bf16 v[68:71], v[210:213], v[202:205], v[68:71]
	v_mfma_f32_16x16x32_bf16 v[64:67], v[222:225], v[202:205], v[64:67]
	v_mfma_f32_16x16x32_bf16 v[124:127], v[214:217], v[170:173], v[124:127]
	v_mfma_f32_16x16x32_bf16 v[120:123], v[226:229], v[170:173], v[120:123]
	v_mfma_f32_16x16x32_bf16 v[100:103], v[214:217], v[178:181], v[100:103]
	v_mfma_f32_16x16x32_bf16 v[96:99], v[226:229], v[178:181], v[96:99]
	v_mfma_f32_16x16x32_bf16 v[84:87], v[214:217], v[198:201], v[84:87]
	v_mfma_f32_16x16x32_bf16 v[80:83], v[226:229], v[198:201], v[80:83]
	v_mfma_f32_16x16x32_bf16 v[68:71], v[214:217], v[206:209], v[68:71]
	v_mfma_f32_16x16x32_bf16 v[64:67], v[226:229], v[206:209], v[64:67]
	s_mov_b32 m0, s51
	v_lshl_add_u64 v[150:151], v[218:219], 0, s[10:11]
	s_barrier
	ds_read_b128 v[166:169], v191 offset:49152
	ds_read_b128 v[170:173], v191 offset:50176
	ds_read_b128 v[174:177], v191 offset:51200
	ds_read_b128 v[178:181], v191 offset:52224
	ds_read_b128 v[194:197], v191 offset:53248
	ds_read_b128 v[198:201], v191 offset:54272
	ds_read_b128 v[202:205], v191 offset:55296
	ds_read_b128 v[206:209], v191 offset:56320
	global_load_lds_dwordx4 v[150:151], off
	s_mov_b32 m0, s52
	v_lshl_add_u64 v[150:151], v[230:231], 0, s[10:11]
	global_load_lds_dwordx4 v[150:151], off
	s_barrier
	s_waitcnt lgkmcnt(0)
	v_mfma_f32_16x16x32_bf16 v[52:55], v[134:137], v[166:169], v[52:55]
	v_mfma_f32_16x16x32_bf16 v[48:51], v[142:145], v[166:169], v[48:51]
	v_mfma_f32_16x16x32_bf16 v[44:47], v[134:137], v[174:177], v[44:47]
	v_mfma_f32_16x16x32_bf16 v[36:39], v[142:145], v[174:177], v[36:39]
	v_mfma_f32_16x16x32_bf16 v[28:31], v[134:137], v[194:197], v[28:31]
	v_mfma_f32_16x16x32_bf16 v[20:23], v[142:145], v[194:197], v[20:23]
	v_mfma_f32_16x16x32_bf16 v[12:15], v[134:137], v[202:205], v[12:15]
	v_mfma_f32_16x16x32_bf16 v[4:7], v[142:145], v[202:205], v[4:7]
	v_mfma_f32_16x16x32_bf16 v[52:55], v[138:141], v[170:173], v[52:55]
	v_mfma_f32_16x16x32_bf16 v[48:51], v[146:149], v[170:173], v[48:51]
	v_mfma_f32_16x16x32_bf16 v[44:47], v[138:141], v[178:181], v[44:47]
	v_mfma_f32_16x16x32_bf16 v[36:39], v[146:149], v[178:181], v[36:39]
	v_mfma_f32_16x16x32_bf16 v[28:31], v[138:141], v[198:201], v[28:31]
	v_mfma_f32_16x16x32_bf16 v[20:23], v[146:149], v[198:201], v[20:23]
	v_mfma_f32_16x16x32_bf16 v[12:15], v[138:141], v[206:209], v[12:15]
	v_mfma_f32_16x16x32_bf16 v[4:7], v[146:149], v[206:209], v[4:7]
	s_barrier
	s_add_u32 s36, s36, 0xb0080
	s_addc_u32 s37, s37, 0
	s_mov_b32 m0, s65
	v_lshl_add_u64 v[134:135], s[36:37], 0, v[156:157]
	global_load_lds_dwordx4 v[134:135], off
	s_mov_b32 m0, s66
	v_lshl_add_u64 v[134:135], s[36:37], 0, v[160:161]
	global_load_lds_dwordx4 v[134:135], off
	s_waitcnt vmcnt(6)
	s_barrier
	v_mfma_f32_16x16x32_bf16 v[60:63], v[210:213], v[166:169], v[60:63]
	v_mfma_f32_16x16x32_bf16 v[56:59], v[222:225], v[166:169], v[56:59]
	v_mfma_f32_16x16x32_bf16 v[40:43], v[210:213], v[174:177], v[40:43]
	v_mfma_f32_16x16x32_bf16 v[32:35], v[222:225], v[174:177], v[32:35]
	v_mfma_f32_16x16x32_bf16 v[24:27], v[210:213], v[194:197], v[24:27]
	v_mfma_f32_16x16x32_bf16 v[16:19], v[222:225], v[194:197], v[16:19]
	v_mfma_f32_16x16x32_bf16 v[8:11], v[210:213], v[202:205], v[8:11]
	v_mfma_f32_16x16x32_bf16 v[0:3], v[222:225], v[202:205], v[0:3]
	v_mfma_f32_16x16x32_bf16 v[60:63], v[214:217], v[170:173], v[60:63]
	v_mfma_f32_16x16x32_bf16 v[56:59], v[226:229], v[170:173], v[56:59]
	v_mfma_f32_16x16x32_bf16 v[40:43], v[214:217], v[178:181], v[40:43]
	v_mfma_f32_16x16x32_bf16 v[32:35], v[226:229], v[178:181], v[32:35]
	v_mfma_f32_16x16x32_bf16 v[24:27], v[214:217], v[198:201], v[24:27]
	v_mfma_f32_16x16x32_bf16 v[16:19], v[226:229], v[198:201], v[16:19]
	v_mfma_f32_16x16x32_bf16 v[8:11], v[214:217], v[206:209], v[8:11]
	v_mfma_f32_16x16x32_bf16 v[0:3], v[226:229], v[206:209], v[0:3]
	s_add_i32 s67, s67, 2
	s_add_u32 s34, s34, 0x100
	s_addc_u32 s35, s35, 0
	s_cmp_gt_u32 s67, 41
	s_barrier
; __device__ __forceinline__ unsigned pk2(float lo, float hi) { unsigned r; asm volatile("v_cvt_pk_bf16_f32 %0, %1, %2" : "=v"(r) : "v"(lo), "v"(hi)); return r; }
; __device__ __forceinline__ unsigned pk2(float lo, float hi) { return f2bf(lo) | (f2bf(hi) << 16); }
;     __device__ __forceinline__ void epi(const f32x4 (&acc)[2][2][4][2], const Unit& u, int wr, int wc, int fr, int fq) const {
;     ...
;         for (int ai = 0; ai < 2; ++ai) {
;             u32x4 xo[4][2];
; #pragma unroll
;             for (int m = 0; m < 4; ++m)
; #pragma unroll
;                 for (int bj = 0; bj < 2; ++bj) xo[m][bj] = *(const u32x4*)(xb + (size_t)(row0 + ai * 128 + m * 16) * D + col0 + bj * 128);
; #pragma unroll
;             for (int m = 0; m < 4; ++m) {
;                 const int row = row0 + ai * 128 + m * 16; const size_t off = (size_t)row * D + col0; float ss = 0.f;
; #pragma unroll
;                 for (int bj = 0; bj < 2; ++bj) {
;                     const u32x4 o = xo[m][bj]; const f32x4 a0v = acc[ai][bj][m][0], a1v = acc[ai][bj][m][1];
;                     const float v0 = bf_lo(o.x) + coef * a0v[0], v1 = bf_hi(o.x) + coef * a0v[1], v2 = bf_lo(o.y) + coef * a0v[2], v3 = bf_hi(o.y) + coef * a0v[3];
;                     const float v4 = bf_lo(o.z) + coef * a1v[0], v5 = bf_hi(o.z) + coef * a1v[1], v6 = bf_lo(o.w) + coef * a1v[2], v7 = bf_hi(o.w) + coef * a1v[3];
;                     u32x4 w; w.x = pk2(v0, v1); w.y = pk2(v2, v3); w.z = pk2(v4, v5); w.w = pk2(v6, v7);
;                     *(u32x4*)(xb + off + bj * 128) = w;
;                     ss += ((v0 * v0 + v1 * v1) + (v2 * v2 + v3 * v3)) + ((v4 * v4 + v5 * v5) + (v6 * v6 + v7 * v7));
;                 }
;                 ss += __shfl_xor(ss, 16); ss += __shfl_xor(ss, 32);
;                 if (fq == 0) rowss[(size_t)row * 32 + u.pn * 4 + wc] = ss;
	v_lshl_or_b32 v166, s40, 8, v189
	v_lshl_add_u32 v170, s61, 8, v153
	v_ashrrev_i32_e32 v167, 31, v166
	v_lshlrev_b64 v[202:203], 1, v[166:167]
	v_ashrrev_i32_e32 v171, 31, v170
	v_lshl_add_u64 v[168:169], s[20:21], 0, v[202:203]
	v_lshlrev_b64 v[204:205], 11, v[170:171]
	v_lshl_add_u64 v[128:129], v[168:169], 0, v[204:205]
	v_mov_b32_e32 v218, 0x40000
	v_mov_b32_e32 v219, 0
	v_lshl_add_u64 v[216:217], v[128:129], 0, v[218:219]
	v_mov_b32_e32 v218, 0x8000
	s_waitcnt vmcnt(8)
	v_mov_b64_e32 v[194:195], v[232:233]
	v_mov_b64_e32 v[196:197], v[234:235]
	v_mov_b64_e32 v[198:199], v[236:237]
	v_mov_b64_e32 v[200:201], v[238:239]
	v_or_b32_e32 v180, 16, v170
	v_or_b32_e32 v176, 32, v170
	v_or_b32_e32 v172, 48, v170
	v_ashrrev_i32_e32 v181, 31, v180
	v_ashrrev_i32_e32 v177, 31, v176
	v_ashrrev_i32_e32 v173, 31, v172
	v_lshlrev_b64 v[182:183], 11, v[180:181]
	v_lshlrev_b64 v[178:179], 11, v[176:177]
	v_lshlrev_b64 v[174:175], 11, v[172:173]
	v_lshl_add_u64 v[128:129], v[168:169], 0, v[182:183]
	v_lshl_add_u64 v[130:131], v[168:169], 0, v[178:179]
	v_lshl_add_u64 v[206:207], v[168:169], 0, v[174:175]
	v_mov_b64_e32 v[148:149], v[240:241]
	v_mov_b64_e32 v[150:151], v[242:243]
	v_mov_b64_e32 v[144:145], v[244:245]
	v_mov_b64_e32 v[146:147], v[246:247]
	global_load_dwordx4 v[140:143], v[130:131], off
	global_load_dwordx4 v[136:139], v[130:131], off offset:256
	global_load_dwordx4 v[132:135], v[206:207], off
	s_nop 0
	global_load_dwordx4 v[128:131], v[206:207], off offset:256
	global_load_dwordx4 v[222:225], v[216:217], off
	global_load_dwordx4 v[226:229], v[216:217], off offset:256
	v_lshl_add_u64 v[216:217], v[216:217], 0, v[218:219]
	global_load_dwordx4 v[230:233], v[216:217], off
	global_load_dwordx4 v[234:237], v[216:217], off offset:256
	v_lshl_add_u64 v[216:217], v[216:217], 0, v[218:219]
	global_load_dwordx4 v[238:241], v[216:217], off
	global_load_dwordx4 v[242:245], v[216:217], off offset:256
	v_lshl_add_u64 v[216:217], v[216:217], 0, v[218:219]
	global_load_dwordx4 v[246:249], v[216:217], off
	global_load_dwordx4 v[250:253], v[216:217], off offset:256
	v_and_b32_e32 v206, 64, v193
	v_xor_b32_e32 v208, 16, v193
	v_add_u32_e32 v206, 64, v206
	v_cmp_lt_i32_e32 vcc, v208, v206
	v_lshlrev_b32_e32 v209, 16, v195
	v_cndmask_b32_e32 v207, v193, v208, vcc
	v_lshlrev_b32_e32 v208, 16, v194
	v_and_b32_e32 v194, 0xffff0000, v194
	v_and_b32_e32 v195, 0xffff0000, v195
	v_lshlrev_b32_e32 v210, 16, v196
	v_and_b32_e32 v196, 0xffff0000, v196
	v_lshlrev_b32_e32 v211, 16, v197
	v_and_b32_e32 v197, 0xffff0000, v197
	v_lshlrev_b32_e32 v212, 16, v198
	v_and_b32_e32 v198, 0xffff0000, v198
	v_lshlrev_b32_e32 v213, 16, v199
	v_and_b32_e32 v199, 0xffff0000, v199
	v_lshlrev_b32_e32 v214, 16, v200
	v_and_b32_e32 v200, 0xffff0000, v200
	v_lshlrev_b32_e32 v215, 16, v201
	v_and_b32_e32 v201, 0xffff0000, v201
	v_fmac_f32_e32 v194, 0.5, v117
	v_fmac_f32_e32 v195, 0.5, v119
	v_fmac_f32_e32 v196, 0.5, v113
	v_fmac_f32_e32 v197, 0.5, v115
	v_fmac_f32_e32 v198, 0.5, v125
	v_fmac_f32_e32 v199, 0.5, v127
	v_fmac_f32_e32 v200, 0.5, v121
	v_fmac_f32_e32 v201, 0.5, v123
	v_fmac_f32_e32 v208, 0.5, v116
	v_fmac_f32_e32 v209, 0.5, v118
	v_fmac_f32_e32 v210, 0.5, v112
	v_fmac_f32_e32 v211, 0.5, v114
	v_fmac_f32_e32 v212, 0.5, v124
	v_fmac_f32_e32 v213, 0.5, v126
	v_fmac_f32_e32 v214, 0.5, v120
	v_fmac_f32_e32 v215, 0.5, v122
	v_mul_f32_e32 v112, v194, v194
	v_mul_f32_e32 v113, v195, v195
	v_mul_f32_e32 v118, v196, v196
	v_mul_f32_e32 v119, v197, v197
	v_mul_f32_e32 v120, v198, v198
	v_mul_f32_e32 v121, v199, v199
	v_mul_f32_e32 v122, v200, v200
	v_mul_f32_e32 v123, v201, v201
	v_fmac_f32_e32 v112, v208, v208
	v_fmac_f32_e32 v113, v209, v209
	v_fmac_f32_e32 v118, v210, v210
	v_fmac_f32_e32 v119, v211, v211
	v_fmac_f32_e32 v120, v212, v212
	v_fmac_f32_e32 v121, v213, v213
	v_fmac_f32_e32 v122, v214, v214
	v_fmac_f32_e32 v123, v215, v215
	v_add_f32_e32 v112, v112, v113
	v_add_f32_e32 v113, v118, v119
	v_add_f32_e32 v118, v120, v121
	v_add_f32_e32 v119, v122, v123
	v_add_f32_e32 v112, v112, v113
	v_add_f32_e32 v113, v118, v119
	v_add_f32_e32 v113, v112, v113
	v_lshlrev_b32_e32 v112, 2, v207
	ds_bpermute_b32 v122, v112, v113
	v_lshl_add_u64 v[118:119], s[20:21], 0, v[204:205]
	v_cvt_pk_bf16_f32 v114, v208, v194
	v_lshl_add_u64 v[120:121], v[118:119], 0, v[202:203]
	v_cvt_pk_bf16_f32 v115, v209, v195
	v_cvt_pk_bf16_f32 v116, v210, v196
	v_cvt_pk_bf16_f32 v117, v211, v197
	global_store_dwordx4 v[120:121], v[114:117], off
	s_waitcnt lgkmcnt(0)
	s_nop 0
	v_add_f32_e32 v114, v113, v122
	v_xor_b32_e32 v113, 32, v193
	v_cmp_lt_i32_e32 vcc, v113, v206
	v_cvt_pk_bf16_f32 v116, v212, v198
	v_cvt_pk_bf16_f32 v117, v213, v199
	v_cvt_pk_bf16_f32 v118, v214, v200
	v_cvt_pk_bf16_f32 v119, v215, v201
	global_store_dwordx4 v[120:121], v[116:119], off offset:256
	s_nop 0
	v_cndmask_b32_e32 v113, v193, v113, vcc
	v_lshlrev_b32_e32 v113, 2, v113
	ds_bpermute_b32 v115, v113, v114
	s_and_saveexec_b64 s[28:29], s[6:7]
	s_cbranch_execz .LBB0_360
	s_waitcnt lgkmcnt(0)
	v_add_f32_e32 v116, v114, v115
	s_lshl_b32 s30, s40, 2
	v_lshlrev_b64 v[114:115], 7, v[170:171]
	s_ashr_i32 s31, s30, 31
	v_lshl_add_u64 v[114:115], s[2:3], 0, v[114:115]
	v_lshl_add_u64 v[114:115], s[30:31], 2, v[114:115]
	s_lshl_b32 s0, s50, 2
	v_lshl_add_u64 v[114:115], v[114:115], 0, s[0:1]
	global_store_dword v[114:115], v116, off

;     ...
;         G_PAIR(0, 1);
.LBB0_579:
	ds_read_b128 v[0:3], v144
	ds_read_b128 v[4:7], v144 offset:1024
	ds_read_b128 v[8:11], v144 offset:2048
	ds_read_b128 v[12:15], v144 offset:3072
	s_lshl_b64 s[44:45], s[44:45], 19
	s_add_u32 s1, s49, s44
	s_addc_u32 s12, s50, s45
	s_add_u32 s40, s1, s40
	s_addc_u32 s41, s12, s41
	s_add_u32 s44, s4, 0x40080
	s_addc_u32 s45, s5, 0
	s_add_i32 s1, s52, 0xc000
	v_lshl_add_u64 v[48:49], s[44:45], 0, v[130:131]
	s_mov_b32 m0, s1
	s_add_i32 s12, s52, 0xe000
	ds_read_b128 v[16:19], v145
	ds_read_b128 v[20:23], v145 offset:1024
	ds_read_b128 v[24:27], v145 offset:2048
	ds_read_b128 v[28:31], v145 offset:3072
	ds_read_b128 v[32:35], v145 offset:4096
	ds_read_b128 v[36:39], v145 offset:5120
	ds_read_b128 v[40:43], v145 offset:6144
	ds_read_b128 v[44:47], v145 offset:7168
	global_load_lds_dwordx4 v[48:49], off
	s_mov_b32 m0, s12
	v_lshl_add_u64 v[48:49], s[44:45], 0, v[128:129]
	global_load_lds_dwordx4 v[48:49], off
	s_waitcnt lgkmcnt(8)
	s_barrier
	s_waitcnt lgkmcnt(0)
	v_mfma_f32_16x16x32_bf16 v[48:51], v[0:3], v[16:19], 0
	v_mfma_f32_16x16x32_bf16 v[52:55], v[8:11], v[16:19], 0
	v_mfma_f32_16x16x32_bf16 v[56:59], v[0:3], v[24:27], 0
	v_mfma_f32_16x16x32_bf16 v[60:63], v[8:11], v[24:27], 0
	v_mfma_f32_16x16x32_bf16 v[64:67], v[0:3], v[32:35], 0
	v_mfma_f32_16x16x32_bf16 v[68:71], v[8:11], v[32:35], 0
	v_mfma_f32_16x16x32_bf16 v[72:75], v[0:3], v[40:43], 0
	v_mfma_f32_16x16x32_bf16 v[76:79], v[8:11], v[40:43], 0
	v_mfma_f32_16x16x32_bf16 v[48:51], v[4:7], v[20:23], v[48:51]
	v_mfma_f32_16x16x32_bf16 v[52:55], v[12:15], v[20:23], v[52:55]
	v_mfma_f32_16x16x32_bf16 v[56:59], v[4:7], v[28:31], v[56:59]
	v_mfma_f32_16x16x32_bf16 v[60:63], v[12:15], v[28:31], v[60:63]
	v_mfma_f32_16x16x32_bf16 v[64:67], v[4:7], v[36:39], v[64:67]
	v_mfma_f32_16x16x32_bf16 v[68:71], v[12:15], v[36:39], v[68:71]
	v_mfma_f32_16x16x32_bf16 v[72:75], v[4:7], v[44:47], v[72:75]
	v_mfma_f32_16x16x32_bf16 v[76:79], v[12:15], v[44:47], v[76:79]
	s_barrier
	v_lshl_add_u64 v[246:247], s[6:7], 0, v[130:131]
	s_add_i32 s35, s64, s51
	v_lshl_add_u64 v[96:97], v[246:247], 0, s[14:15]
	s_mov_b32 m0, s35
	v_lshl_add_u64 v[248:249], s[6:7], 0, v[128:129]
	s_add_i32 s73, s35, 0x2000
	ds_read_b128 v[80:83], v146
	ds_read_b128 v[84:87], v146 offset:1024
	ds_read_b128 v[88:91], v146 offset:2048
	ds_read_b128 v[92:95], v146 offset:3072
	global_load_lds_dwordx4 v[96:97], off
	s_mov_b32 m0, s73
	v_lshl_add_u64 v[96:97], v[248:249], 0, s[14:15]
	global_load_lds_dwordx4 v[96:97], off
	s_barrier
	s_waitcnt lgkmcnt(0)
	v_mfma_f32_16x16x32_bf16 v[96:99], v[80:83], v[16:19], 0
	v_mfma_f32_16x16x32_bf16 v[16:19], v[88:91], v[16:19], 0
	v_mfma_f32_16x16x32_bf16 v[100:103], v[80:83], v[24:27], 0
	v_mfma_f32_16x16x32_bf16 v[24:27], v[88:91], v[24:27], 0
	v_mfma_f32_16x16x32_bf16 v[104:107], v[80:83], v[32:35], 0
	v_mfma_f32_16x16x32_bf16 v[32:35], v[88:91], v[32:35], 0
	v_mfma_f32_16x16x32_bf16 v[108:111], v[80:83], v[40:43], 0
	v_mfma_f32_16x16x32_bf16 v[40:43], v[88:91], v[40:43], 0
	v_mfma_f32_16x16x32_bf16 v[96:99], v[84:87], v[20:23], v[96:99]
	v_mfma_f32_16x16x32_bf16 v[112:115], v[92:95], v[20:23], v[16:19]
	v_mfma_f32_16x16x32_bf16 v[100:103], v[84:87], v[28:31], v[100:103]
	v_mfma_f32_16x16x32_bf16 v[116:119], v[92:95], v[28:31], v[24:27]
	v_mfma_f32_16x16x32_bf16 v[104:107], v[84:87], v[36:39], v[104:107]
	v_mfma_f32_16x16x32_bf16 v[32:35], v[92:95], v[36:39], v[32:35]
	v_mfma_f32_16x16x32_bf16 v[36:39], v[84:87], v[44:47], v[108:111]
	v_mfma_f32_16x16x32_bf16 v[40:43], v[92:95], v[44:47], v[40:43]
	v_lshl_add_u64 v[250:251], s[4:5], 0, v[130:131]
	s_mov_b32 m0, s52
	v_lshl_add_u64 v[138:139], v[250:251], 0, s[14:15]
	v_lshl_add_u64 v[252:253], s[4:5], 0, v[128:129]
	s_barrier
	ds_read_b128 v[16:19], v145 offset:16384
	ds_read_b128 v[20:23], v145 offset:17408
	ds_read_b128 v[24:27], v145 offset:18432
	ds_read_b128 v[28:31], v145 offset:19456
	ds_read_b128 v[44:47], v145 offset:20480
	ds_read_b128 v[108:111], v145 offset:21504
	ds_read_b128 v[120:123], v145 offset:22528
	ds_read_b128 v[124:127], v145 offset:23552
	global_load_lds_dwordx4 v[138:139], off
	s_mov_b32 m0, s55
	v_lshl_add_u64 v[138:139], v[252:253], 0, s[14:15]
	global_load_lds_dwordx4 v[138:139], off
	s_barrier
	s_waitcnt lgkmcnt(0)
	v_mfma_f32_16x16x32_bf16 v[138:141], v[0:3], v[16:19], 0
	v_mfma_f32_16x16x32_bf16 v[148:151], v[8:11], v[16:19], 0
	v_mfma_f32_16x16x32_bf16 v[152:155], v[0:3], v[24:27], 0
	v_mfma_f32_16x16x32_bf16 v[156:159], v[8:11], v[24:27], 0
	v_mfma_f32_16x16x32_bf16 v[160:163], v[0:3], v[44:47], 0
	v_mfma_f32_16x16x32_bf16 v[164:167], v[8:11], v[44:47], 0
	v_mfma_f32_16x16x32_bf16 v[0:3], v[0:3], v[120:123], 0
	v_mfma_f32_16x16x32_bf16 v[8:11], v[8:11], v[120:123], 0
	v_mfma_f32_16x16x32_bf16 v[138:141], v[4:7], v[20:23], v[138:141]
	v_mfma_f32_16x16x32_bf16 v[168:171], v[12:15], v[20:23], v[148:151]
	v_mfma_f32_16x16x32_bf16 v[150:153], v[4:7], v[28:31], v[152:155]
	v_mfma_f32_16x16x32_bf16 v[154:157], v[12:15], v[28:31], v[156:159]
	v_mfma_f32_16x16x32_bf16 v[158:161], v[4:7], v[108:111], v[160:163]
	v_mfma_f32_16x16x32_bf16 v[162:165], v[12:15], v[108:111], v[164:167]
	v_mfma_f32_16x16x32_bf16 v[172:175], v[4:7], v[124:127], v[0:3]
	v_mfma_f32_16x16x32_bf16 v[176:179], v[12:15], v[124:127], v[8:11]
	s_barrier
	s_add_u32 s44, s6, 0x40100
	s_addc_u32 s45, s7, 0
	s_add_i32 s74, s66, s51
	v_lshl_add_u64 v[0:1], s[44:45], 0, v[130:131]
	s_mov_b32 m0, s74
	s_add_i32 s75, s74, 0x2000
	global_load_lds_dwordx4 v[0:1], off
	s_mov_b32 m0, s75
	v_lshl_add_u64 v[0:1], s[44:45], 0, v[128:129]
	global_load_lds_dwordx4 v[0:1], off
	s_waitcnt vmcnt(6)
	s_barrier
	v_mfma_f32_16x16x32_bf16 v[0:3], v[80:83], v[16:19], 0
	v_mfma_f32_16x16x32_bf16 v[4:7], v[88:91], v[16:19], 0
	v_mfma_f32_16x16x32_bf16 v[8:11], v[80:83], v[24:27], 0
	v_mfma_f32_16x16x32_bf16 v[12:15], v[88:91], v[24:27], 0
	v_mfma_f32_16x16x32_bf16 v[16:19], v[80:83], v[44:47], 0
	v_mfma_f32_16x16x32_bf16 v[24:27], v[88:91], v[44:47], 0
	v_mfma_f32_16x16x32_bf16 v[44:47], v[80:83], v[120:123], 0
	v_mfma_f32_16x16x32_bf16 v[80:83], v[88:91], v[120:123], 0
	v_mfma_f32_16x16x32_bf16 v[120:123], v[84:87], v[20:23], v[0:3]
	v_mfma_f32_16x16x32_bf16 v[192:195], v[84:87], v[108:111], v[16:19]
	v_mfma_f32_16x16x32_bf16 v[108:111], v[92:95], v[108:111], v[24:27]
	v_mfma_f32_16x16x32_bf16 v[196:199], v[84:87], v[124:127], v[44:47]
	v_mfma_f32_16x16x32_bf16 v[124:127], v[92:95], v[124:127], v[80:83]
	v_mfma_f32_16x16x32_bf16 v[180:183], v[92:95], v[20:23], v[4:7]
	v_mfma_f32_16x16x32_bf16 v[184:187], v[84:87], v[28:31], v[8:11]
	v_mfma_f32_16x16x32_bf16 v[188:191], v[92:95], v[28:31], v[12:15]
	s_add_i32 s76, 0, 0x18000
	v_add_u32_e32 v147, s76, v143
	s_barrier
	ds_read_b128 v[80:83], v147
	ds_read_b128 v[200:203], v147 offset:1024
	ds_read_b128 v[84:87], v147 offset:2048
	ds_read_b128 v[204:207], v147 offset:3072
	s_add_u32 s44, s4, 0x40100
	s_addc_u32 s45, s5, 0
	s_mov_b32 m0, s56
	v_lshl_add_u64 v[0:1], s[44:45], 0, v[130:131]
	ds_read_b128 v[44:47], v145 offset:32768
	ds_read_b128 v[88:91], v145 offset:33792
	ds_read_b128 v[92:95], v145 offset:34816
	ds_read_b128 v[208:211], v145 offset:35840
	ds_read_b128 v[212:215], v145 offset:36864
	ds_read_b128 v[216:219], v145 offset:37888
	ds_read_b128 v[222:225], v145 offset:38912
	ds_read_b128 v[226:229], v145 offset:39936
	global_load_lds_dwordx4 v[0:1], off
	s_mov_b32 m0, s57
	v_lshl_add_u64 v[0:1], s[44:45], 0, v[128:129]
	global_load_lds_dwordx4 v[0:1], off
	s_waitcnt lgkmcnt(8)
	s_barrier
	s_waitcnt lgkmcnt(0)
	v_mfma_f32_16x16x32_bf16 v[0:3], v[80:83], v[44:47], v[48:51]
	v_mfma_f32_16x16x32_bf16 v[4:7], v[84:87], v[44:47], v[52:55]
	v_mfma_f32_16x16x32_bf16 v[8:11], v[80:83], v[92:95], v[56:59]
	v_mfma_f32_16x16x32_bf16 v[12:15], v[84:87], v[92:95], v[60:63]
	v_mfma_f32_16x16x32_bf16 v[48:51], v[80:83], v[212:215], v[64:67]
	v_mfma_f32_16x16x32_bf16 v[52:55], v[84:87], v[212:215], v[68:71]
	v_mfma_f32_16x16x32_bf16 v[56:59], v[80:83], v[222:225], v[72:75]
	v_mfma_f32_16x16x32_bf16 v[60:63], v[84:87], v[222:225], v[76:79]
	v_mfma_f32_16x16x32_bf16 v[28:31], v[200:203], v[88:91], v[0:3]
	v_mfma_f32_16x16x32_bf16 v[24:27], v[204:207], v[88:91], v[4:7]
	v_mfma_f32_16x16x32_bf16 v[20:23], v[200:203], v[208:211], v[8:11]
	v_mfma_f32_16x16x32_bf16 v[16:19], v[204:207], v[208:211], v[12:15]
	v_mfma_f32_16x16x32_bf16 v[12:15], v[200:203], v[216:219], v[48:51]
	v_mfma_f32_16x16x32_bf16 v[8:11], v[204:207], v[216:219], v[52:55]
	v_mfma_f32_16x16x32_bf16 v[4:7], v[200:203], v[226:229], v[56:59]
	v_mfma_f32_16x16x32_bf16 v[0:3], v[204:207], v[226:229], v[60:63]
	s_barrier
	s_add_i32 s78, 0, 0x1c000
	s_add_i32 s76, s76, s51
	v_add_u32_e32 v148, s78, v143
	v_lshl_add_u64 v[48:49], v[246:247], 0, s[16:17]
	s_mov_b32 m0, s76
	s_add_i32 s77, s76, 0x2000
	ds_read_b128 v[230:233], v148
	ds_read_b128 v[234:237], v148 offset:1024
	ds_read_b128 v[238:241], v148 offset:2048
	ds_read_b128 v[242:245], v148 offset:3072
	global_load_lds_dwordx4 v[48:49], off
	s_mov_b32 m0, s77
	v_lshl_add_u64 v[48:49], v[248:249], 0, s[16:17]
	global_load_lds_dwordx4 v[48:49], off
	s_barrier
	s_waitcnt lgkmcnt(0)
	v_mfma_f32_16x16x32_bf16 v[48:51], v[230:233], v[44:47], v[96:99]
	v_mfma_f32_16x16x32_bf16 v[44:47], v[238:241], v[44:47], v[112:115]
	v_mfma_f32_16x16x32_bf16 v[52:55], v[230:233], v[92:95], v[100:103]
	v_mfma_f32_16x16x32_bf16 v[56:59], v[238:241], v[92:95], v[116:119]
	v_mfma_f32_16x16x32_bf16 v[60:63], v[230:233], v[212:215], v[104:107]
	v_mfma_f32_16x16x32_bf16 v[32:35], v[238:241], v[212:215], v[32:35]
	v_mfma_f32_16x16x32_bf16 v[36:39], v[230:233], v[222:225], v[36:39]
	v_mfma_f32_16x16x32_bf16 v[40:43], v[238:241], v[222:225], v[40:43]
	v_mfma_f32_16x16x32_bf16 v[92:95], v[234:237], v[88:91], v[48:51]
	v_mfma_f32_16x16x32_bf16 v[88:91], v[242:245], v[88:91], v[44:47]
	v_mfma_f32_16x16x32_bf16 v[76:79], v[234:237], v[208:211], v[52:55]
	v_mfma_f32_16x16x32_bf16 v[72:75], v[242:245], v[208:211], v[56:59]
	v_mfma_f32_16x16x32_bf16 v[60:63], v[234:237], v[216:219], v[60:63]
	v_mfma_f32_16x16x32_bf16 v[56:59], v[242:245], v[216:219], v[32:35]
	v_mfma_f32_16x16x32_bf16 v[44:47], v[234:237], v[226:229], v[36:39]
	v_mfma_f32_16x16x32_bf16 v[40:43], v[242:245], v[226:229], v[40:43]
	s_mov_b32 m0, s61
	v_lshl_add_u64 v[32:33], v[250:251], 0, s[16:17]
	s_barrier
	ds_read_b128 v[96:99], v145 offset:49152
	ds_read_b128 v[100:103], v145 offset:50176
	ds_read_b128 v[104:107], v145 offset:51200
	ds_read_b128 v[112:115], v145 offset:52224
	ds_read_b128 v[116:119], v145 offset:53248
	ds_read_b128 v[208:211], v145 offset:54272
	ds_read_b128 v[212:215], v145 offset:55296
	ds_read_b128 v[216:219], v145 offset:56320
	global_load_lds_dwordx4 v[32:33], off
	s_mov_b32 m0, s62
	v_lshl_add_u64 v[32:33], v[252:253], 0, s[16:17]
	global_load_lds_dwordx4 v[32:33], off
	s_barrier
;     ...
;         G_PAIR(0, 1);
; #pragma unroll 1
;         for (int t = 2; t < nt; t += 2) G_PAIR(t, 0);
	s_waitcnt lgkmcnt(0)
	v_mfma_f32_16x16x32_bf16 v[32:35], v[80:83], v[96:99], v[138:141]
	v_mfma_f32_16x16x32_bf16 v[36:39], v[84:87], v[96:99], v[168:171]
	v_mfma_f32_16x16x32_bf16 v[48:51], v[80:83], v[104:107], v[150:153]
	v_mfma_f32_16x16x32_bf16 v[52:55], v[84:87], v[104:107], v[154:157]
	v_mfma_f32_16x16x32_bf16 v[138:141], v[80:83], v[116:119], v[158:161]
	v_mfma_f32_16x16x32_bf16 v[150:153], v[84:87], v[116:119], v[162:165]
	v_mfma_f32_16x16x32_bf16 v[154:157], v[80:83], v[212:215], v[172:175]
	v_mfma_f32_16x16x32_bf16 v[158:161], v[84:87], v[212:215], v[176:179]
	v_mfma_f32_16x16x32_bf16 v[84:87], v[200:203], v[100:103], v[32:35]
	v_mfma_f32_16x16x32_bf16 v[80:83], v[204:207], v[100:103], v[36:39]
	v_mfma_f32_16x16x32_bf16 v[68:71], v[200:203], v[112:115], v[48:51]
	v_mfma_f32_16x16x32_bf16 v[64:67], v[204:207], v[112:115], v[52:55]
	v_mfma_f32_16x16x32_bf16 v[52:55], v[200:203], v[208:211], v[138:141]
	v_mfma_f32_16x16x32_bf16 v[48:51], v[204:207], v[208:211], v[150:153]
	v_mfma_f32_16x16x32_bf16 v[36:39], v[200:203], v[216:219], v[154:157]
	v_mfma_f32_16x16x32_bf16 v[32:35], v[204:207], v[216:219], v[158:161]
	s_barrier
	s_add_u32 s44, s6, 0x40180
	s_addc_u32 s45, s7, 0
	s_add_i32 s78, s78, s51
	v_lshl_add_u64 v[138:139], s[44:45], 0, v[130:131]
	s_mov_b32 m0, s78
	s_add_i32 s79, s78, 0x2000
	global_load_lds_dwordx4 v[138:139], off
	v_lshl_add_u64 v[138:139], s[44:45], 0, v[128:129]
	s_mov_b32 m0, s79
	s_mov_b64 s[44:45], 0x40180
	global_load_lds_dwordx4 v[138:139], off
	s_waitcnt vmcnt(6)
	s_barrier
	v_mfma_f32_16x16x32_bf16 v[120:123], v[230:233], v[96:99], v[120:123]
	v_mfma_f32_16x16x32_bf16 v[96:99], v[238:241], v[96:99], v[180:183]
	v_mfma_f32_16x16x32_bf16 v[138:141], v[230:233], v[104:107], v[184:187]
	v_mfma_f32_16x16x32_bf16 v[104:107], v[238:241], v[104:107], v[188:191]
	v_mfma_f32_16x16x32_bf16 v[150:153], v[230:233], v[116:119], v[192:195]
	v_mfma_f32_16x16x32_bf16 v[154:157], v[238:241], v[116:119], v[108:111]
	v_mfma_f32_16x16x32_bf16 v[158:161], v[230:233], v[212:215], v[196:199]
	v_mfma_f32_16x16x32_bf16 v[162:165], v[238:241], v[212:215], v[124:127]
	v_mfma_f32_16x16x32_bf16 v[124:127], v[234:237], v[100:103], v[120:123]
	v_mfma_f32_16x16x32_bf16 v[120:123], v[242:245], v[100:103], v[96:99]
	v_mfma_f32_16x16x32_bf16 v[116:119], v[234:237], v[112:115], v[138:141]
	v_mfma_f32_16x16x32_bf16 v[112:115], v[242:245], v[112:115], v[104:107]
	v_mfma_f32_16x16x32_bf16 v[108:111], v[234:237], v[208:211], v[150:153]
	v_mfma_f32_16x16x32_bf16 v[104:107], v[242:245], v[208:211], v[154:157]
	v_mfma_f32_16x16x32_bf16 v[100:103], v[234:237], v[216:219], v[158:161]
	v_mfma_f32_16x16x32_bf16 v[96:99], v[242:245], v[216:219], v[162:165]
	v_lshl_add_u64 v[138:139], s[4:5], 0, v[134:135]
	v_lshl_add_u64 v[140:141], s[4:5], 0, v[136:137]
	s_mov_b32 s80, 0
	s_barrier
.LBB0_580:
	ds_read_b128 v[150:153], v144
	ds_read_b128 v[154:157], v144 offset:1024
	ds_read_b128 v[158:161], v144 offset:2048
	ds_read_b128 v[162:165], v144 offset:3072
	s_mov_b32 m0, s1
	v_lshl_add_u64 v[198:199], v[138:139], 0, s[44:45]
	ds_read_b128 v[166:169], v145
	ds_read_b128 v[170:173], v145 offset:1024
	ds_read_b128 v[174:177], v145 offset:2048
	ds_read_b128 v[178:181], v145 offset:3072
	ds_read_b128 v[182:185], v145 offset:4096
	ds_read_b128 v[186:189], v145 offset:5120
	ds_read_b128 v[190:193], v145 offset:6144
	ds_read_b128 v[194:197], v145 offset:7168
	global_load_lds_dwordx4 v[198:199], off
	s_mov_b32 m0, s12
	v_lshl_add_u64 v[198:199], v[140:141], 0, s[44:45]
	global_load_lds_dwordx4 v[198:199], off
	s_waitcnt lgkmcnt(8)
	s_barrier
	s_waitcnt lgkmcnt(0)
	v_mfma_f32_16x16x32_bf16 v[28:31], v[150:153], v[166:169], v[28:31]
	s_add_i32 s81, s44, 0xfffc0080
	v_mfma_f32_16x16x32_bf16 v[24:27], v[158:161], v[166:169], v[24:27]
	s_cmp_eq_u32 s80, 4
	v_mfma_f32_16x16x32_bf16 v[20:23], v[150:153], v[174:177], v[20:23]
	s_cselect_b64 s[46:47], -1, 0
	v_mfma_f32_16x16x32_bf16 v[16:19], v[158:161], v[174:177], v[16:19]
	s_and_b64 s[82:83], s[46:47], exec
	v_mfma_f32_16x16x32_bf16 v[12:15], v[150:153], v[182:185], v[12:15]
	s_cselect_b32 s83, s39, s5
	v_mfma_f32_16x16x32_bf16 v[8:11], v[158:161], v[182:185], v[8:11]
	s_cselect_b32 s82, s38, s4
	v_mfma_f32_16x16x32_bf16 v[4:7], v[150:153], v[190:193], v[4:7]
	s_cselect_b32 s81, 0, s81
	v_mfma_f32_16x16x32_bf16 v[0:3], v[158:161], v[190:193], v[0:3]
	s_and_b64 s[46:47], s[42:43], s[46:47]
	v_mfma_f32_16x16x32_bf16 v[28:31], v[154:157], v[170:173], v[28:31]
	s_and_b64 s[46:47], s[46:47], exec
	v_mfma_f32_16x16x32_bf16 v[24:27], v[162:165], v[170:173], v[24:27]
	s_cselect_b32 s47, s41, s7
	v_mfma_f32_16x16x32_bf16 v[20:23], v[154:157], v[178:181], v[20:23]
	s_cselect_b32 s46, s40, s6
	v_mfma_f32_16x16x32_bf16 v[16:19], v[162:165], v[178:181], v[16:19]
	v_mfma_f32_16x16x32_bf16 v[12:15], v[154:157], v[186:189], v[12:15]
	v_mfma_f32_16x16x32_bf16 v[8:11], v[162:165], v[186:189], v[8:11]
	v_mfma_f32_16x16x32_bf16 v[4:7], v[154:157], v[194:197], v[4:7]
	v_mfma_f32_16x16x32_bf16 v[0:3], v[162:165], v[194:197], v[0:3]
	s_barrier
	s_add_u32 s46, s46, s81
	s_addc_u32 s47, s47, 0
	s_mov_b32 m0, s35
	v_lshl_add_u64 v[214:215], s[46:47], 0, v[130:131]
	ds_read_b128 v[198:201], v146
	ds_read_b128 v[202:205], v146 offset:1024
	ds_read_b128 v[206:209], v146 offset:2048
	ds_read_b128 v[210:213], v146 offset:3072
	global_load_lds_dwordx4 v[214:215], off
	s_mov_b32 m0, s73
	v_lshl_add_u64 v[216:217], s[46:47], 0, v[128:129]
	global_load_lds_dwordx4 v[216:217], off
	s_barrier
	s_waitcnt lgkmcnt(0)
	v_mfma_f32_16x16x32_bf16 v[92:95], v[198:201], v[166:169], v[92:95]
	v_mfma_f32_16x16x32_bf16 v[88:91], v[206:209], v[166:169], v[88:91]
	v_mfma_f32_16x16x32_bf16 v[76:79], v[198:201], v[174:177], v[76:79]
	v_mfma_f32_16x16x32_bf16 v[72:75], v[206:209], v[174:177], v[72:75]
	v_mfma_f32_16x16x32_bf16 v[60:63], v[198:201], v[182:185], v[60:63]
	v_mfma_f32_16x16x32_bf16 v[56:59], v[206:209], v[182:185], v[56:59]
	v_mfma_f32_16x16x32_bf16 v[44:47], v[198:201], v[190:193], v[44:47]
	v_mfma_f32_16x16x32_bf16 v[40:43], v[206:209], v[190:193], v[40:43]
	v_mfma_f32_16x16x32_bf16 v[92:95], v[202:205], v[170:173], v[92:95]
	v_mfma_f32_16x16x32_bf16 v[88:91], v[210:213], v[170:173], v[88:91]
	v_mfma_f32_16x16x32_bf16 v[76:79], v[202:205], v[178:181], v[76:79]
	v_mfma_f32_16x16x32_bf16 v[72:75], v[210:213], v[178:181], v[72:75]
	v_mfma_f32_16x16x32_bf16 v[60:63], v[202:205], v[186:189], v[60:63]
	v_mfma_f32_16x16x32_bf16 v[56:59], v[210:213], v[186:189], v[56:59]
	v_mfma_f32_16x16x32_bf16 v[44:47], v[202:205], v[194:197], v[44:47]
	v_mfma_f32_16x16x32_bf16 v[40:43], v[210:213], v[194:197], v[40:43]
	s_add_u32 s82, s82, s81
	s_addc_u32 s83, s83, 0
	s_mov_b32 m0, s52
	v_lshl_add_u64 v[218:219], s[82:83], 0, v[130:131]
	s_barrier
	ds_read_b128 v[166:169], v145 offset:16384
	ds_read_b128 v[170:173], v145 offset:17408
	ds_read_b128 v[174:177], v145 offset:18432
	ds_read_b128 v[178:181], v145 offset:19456
	ds_read_b128 v[182:185], v145 offset:20480
	ds_read_b128 v[186:189], v145 offset:21504
	ds_read_b128 v[190:193], v145 offset:22528
	ds_read_b128 v[194:197], v145 offset:23552
	global_load_lds_dwordx4 v[218:219], off
	s_mov_b32 m0, s55
	v_lshl_add_u64 v[222:223], s[82:83], 0, v[128:129]
	global_load_lds_dwordx4 v[222:223], off
	s_barrier
	s_waitcnt lgkmcnt(0)
	v_mfma_f32_16x16x32_bf16 v[84:87], v[150:153], v[166:169], v[84:87]
	v_mfma_f32_16x16x32_bf16 v[80:83], v[158:161], v[166:169], v[80:83]
	v_mfma_f32_16x16x32_bf16 v[68:71], v[150:153], v[174:177], v[68:71]
	v_mfma_f32_16x16x32_bf16 v[64:67], v[158:161], v[174:177], v[64:67]
	v_mfma_f32_16x16x32_bf16 v[52:55], v[150:153], v[182:185], v[52:55]
	v_mfma_f32_16x16x32_bf16 v[48:51], v[158:161], v[182:185], v[48:51]
	v_mfma_f32_16x16x32_bf16 v[36:39], v[150:153], v[190:193], v[36:39]
	v_mfma_f32_16x16x32_bf16 v[32:35], v[158:161], v[190:193], v[32:35]
	v_mfma_f32_16x16x32_bf16 v[84:87], v[154:157], v[170:173], v[84:87]
	v_mfma_f32_16x16x32_bf16 v[80:83], v[162:165], v[170:173], v[80:83]
	v_mfma_f32_16x16x32_bf16 v[68:71], v[154:157], v[178:181], v[68:71]
	v_mfma_f32_16x16x32_bf16 v[64:67], v[162:165], v[178:181], v[64:67]
	v_mfma_f32_16x16x32_bf16 v[52:55], v[154:157], v[186:189], v[52:55]
	v_mfma_f32_16x16x32_bf16 v[48:51], v[162:165], v[186:189], v[48:51]
	v_mfma_f32_16x16x32_bf16 v[36:39], v[154:157], v[194:197], v[36:39]
	v_mfma_f32_16x16x32_bf16 v[32:35], v[162:165], v[194:197], v[32:35]
	s_barrier
	s_add_u32 s84, s46, 0x40000
	s_addc_u32 s85, s47, 0
	s_mov_b32 m0, s74
	v_lshl_add_u64 v[150:151], s[84:85], 0, v[130:131]
	global_load_lds_dwordx4 v[150:151], off
	s_mov_b32 m0, s75
	v_lshl_add_u64 v[150:151], s[84:85], 0, v[128:129]
	global_load_lds_dwordx4 v[150:151], off
	s_waitcnt vmcnt(6)
	s_barrier
	v_mfma_f32_16x16x32_bf16 v[124:127], v[198:201], v[166:169], v[124:127]
	v_mfma_f32_16x16x32_bf16 v[120:123], v[206:209], v[166:169], v[120:123]
	v_mfma_f32_16x16x32_bf16 v[116:119], v[198:201], v[174:177], v[116:119]
	v_mfma_f32_16x16x32_bf16 v[112:115], v[206:209], v[174:177], v[112:115]
	v_mfma_f32_16x16x32_bf16 v[108:111], v[198:201], v[182:185], v[108:111]
	v_mfma_f32_16x16x32_bf16 v[104:107], v[206:209], v[182:185], v[104:107]
	v_mfma_f32_16x16x32_bf16 v[100:103], v[198:201], v[190:193], v[100:103]
	v_mfma_f32_16x16x32_bf16 v[96:99], v[206:209], v[190:193], v[96:99]
	v_mfma_f32_16x16x32_bf16 v[124:127], v[202:205], v[170:173], v[124:127]
	v_mfma_f32_16x16x32_bf16 v[120:123], v[210:213], v[170:173], v[120:123]
	v_mfma_f32_16x16x32_bf16 v[116:119], v[202:205], v[178:181], v[116:119]
	v_mfma_f32_16x16x32_bf16 v[112:115], v[210:213], v[178:181], v[112:115]
	v_mfma_f32_16x16x32_bf16 v[108:111], v[202:205], v[186:189], v[108:111]
	v_mfma_f32_16x16x32_bf16 v[104:107], v[210:213], v[186:189], v[104:107]
	v_mfma_f32_16x16x32_bf16 v[100:103], v[202:205], v[194:197], v[100:103]
	v_mfma_f32_16x16x32_bf16 v[96:99], v[210:213], v[194:197], v[96:99]
	s_barrier
	ds_read_b128 v[150:153], v147
	ds_read_b128 v[154:157], v147 offset:1024
	ds_read_b128 v[158:161], v147 offset:2048
	ds_read_b128 v[162:165], v147 offset:3072
	s_add_u32 s82, s82, 0x40000
	s_addc_u32 s83, s83, 0
	s_mov_b32 m0, s56
	v_lshl_add_u64 v[198:199], s[82:83], 0, v[130:131]
	ds_read_b128 v[166:169], v145 offset:32768
	ds_read_b128 v[170:173], v145 offset:33792
	ds_read_b128 v[174:177], v145 offset:34816
	ds_read_b128 v[178:181], v145 offset:35840
	ds_read_b128 v[182:185], v145 offset:36864
	ds_read_b128 v[186:189], v145 offset:37888
	ds_read_b128 v[190:193], v145 offset:38912
	ds_read_b128 v[194:197], v145 offset:39936
	global_load_lds_dwordx4 v[198:199], off
	s_mov_b32 m0, s57
	v_lshl_add_u64 v[198:199], s[82:83], 0, v[128:129]
	global_load_lds_dwordx4 v[198:199], off
	s_waitcnt lgkmcnt(8)
	s_barrier
	s_waitcnt lgkmcnt(0)
	v_mfma_f32_16x16x32_bf16 v[28:31], v[150:153], v[166:169], v[28:31]
	v_mfma_f32_16x16x32_bf16 v[24:27], v[158:161], v[166:169], v[24:27]
	v_mfma_f32_16x16x32_bf16 v[20:23], v[150:153], v[174:177], v[20:23]
	v_mfma_f32_16x16x32_bf16 v[16:19], v[158:161], v[174:177], v[16:19]
	v_mfma_f32_16x16x32_bf16 v[12:15], v[150:153], v[182:185], v[12:15]
	v_mfma_f32_16x16x32_bf16 v[8:11], v[158:161], v[182:185], v[8:11]
	v_mfma_f32_16x16x32_bf16 v[4:7], v[150:153], v[190:193], v[4:7]
	v_mfma_f32_16x16x32_bf16 v[0:3], v[158:161], v[190:193], v[0:3]
	v_mfma_f32_16x16x32_bf16 v[28:31], v[154:157], v[170:173], v[28:31]
	v_mfma_f32_16x16x32_bf16 v[24:27], v[162:165], v[170:173], v[24:27]
	v_mfma_f32_16x16x32_bf16 v[20:23], v[154:157], v[178:181], v[20:23]
	v_mfma_f32_16x16x32_bf16 v[16:19], v[162:165], v[178:181], v[16:19]
	v_mfma_f32_16x16x32_bf16 v[12:15], v[154:157], v[186:189], v[12:15]
	v_mfma_f32_16x16x32_bf16 v[8:11], v[162:165], v[186:189], v[8:11]
	v_mfma_f32_16x16x32_bf16 v[4:7], v[154:157], v[194:197], v[4:7]
	v_mfma_f32_16x16x32_bf16 v[0:3], v[162:165], v[194:197], v[0:3]
	s_barrier
	s_mov_b32 m0, s76
	v_lshl_add_u64 v[214:215], v[214:215], 0, s[2:3]
	ds_read_b128 v[198:201], v148
	ds_read_b128 v[202:205], v148 offset:1024
	ds_read_b128 v[206:209], v148 offset:2048
	ds_read_b128 v[210:213], v148 offset:3072
	global_load_lds_dwordx4 v[214:215], off
	s_mov_b32 m0, s77
	v_lshl_add_u64 v[214:215], v[216:217], 0, s[2:3]
	global_load_lds_dwordx4 v[214:215], off
	s_barrier
	s_waitcnt lgkmcnt(0)
	v_mfma_f32_16x16x32_bf16 v[92:95], v[198:201], v[166:169], v[92:95]
	v_mfma_f32_16x16x32_bf16 v[88:91], v[206:209], v[166:169], v[88:91]
	v_mfma_f32_16x16x32_bf16 v[76:79], v[198:201], v[174:177], v[76:79]
	v_mfma_f32_16x16x32_bf16 v[72:75], v[206:209], v[174:177], v[72:75]
	v_mfma_f32_16x16x32_bf16 v[60:63], v[198:201], v[182:185], v[60:63]
	v_mfma_f32_16x16x32_bf16 v[56:59], v[206:209], v[182:185], v[56:59]
	v_mfma_f32_16x16x32_bf16 v[44:47], v[198:201], v[190:193], v[44:47]
	v_mfma_f32_16x16x32_bf16 v[40:43], v[206:209], v[190:193], v[40:43]
	v_mfma_f32_16x16x32_bf16 v[92:95], v[202:205], v[170:173], v[92:95]
	v_mfma_f32_16x16x32_bf16 v[88:91], v[210:213], v[170:173], v[88:91]
	v_mfma_f32_16x16x32_bf16 v[76:79], v[202:205], v[178:181], v[76:79]
	v_mfma_f32_16x16x32_bf16 v[72:75], v[210:213], v[178:181], v[72:75]
	v_mfma_f32_16x16x32_bf16 v[60:63], v[202:205], v[186:189], v[60:63]
	v_mfma_f32_16x16x32_bf16 v[56:59], v[210:213], v[186:189], v[56:59]
	v_mfma_f32_16x16x32_bf16 v[44:47], v[202:205], v[194:197], v[44:47]
	v_mfma_f32_16x16x32_bf16 v[40:43], v[210:213], v[194:197], v[40:43]
	s_mov_b32 m0, s61
	v_lshl_add_u64 v[214:215], v[218:219], 0, s[2:3]
	s_barrier
	ds_read_b128 v[166:169], v145 offset:49152
	ds_read_b128 v[170:173], v145 offset:50176
	ds_read_b128 v[174:177], v145 offset:51200
	ds_read_b128 v[178:181], v145 offset:52224
	ds_read_b128 v[182:185], v145 offset:53248
	ds_read_b128 v[186:189], v145 offset:54272
	ds_read_b128 v[190:193], v145 offset:55296
	ds_read_b128 v[194:197], v145 offset:56320
	global_load_lds_dwordx4 v[214:215], off
	s_mov_b32 m0, s62
	v_lshl_add_u64 v[214:215], v[222:223], 0, s[2:3]
	global_load_lds_dwordx4 v[214:215], off
	s_barrier
	s_waitcnt lgkmcnt(0)
	v_mfma_f32_16x16x32_bf16 v[84:87], v[150:153], v[166:169], v[84:87]
	v_mfma_f32_16x16x32_bf16 v[80:83], v[158:161], v[166:169], v[80:83]
	v_mfma_f32_16x16x32_bf16 v[68:71], v[150:153], v[174:177], v[68:71]
	v_mfma_f32_16x16x32_bf16 v[64:67], v[158:161], v[174:177], v[64:67]
	v_mfma_f32_16x16x32_bf16 v[52:55], v[150:153], v[182:185], v[52:55]
	v_mfma_f32_16x16x32_bf16 v[48:51], v[158:161], v[182:185], v[48:51]
	v_mfma_f32_16x16x32_bf16 v[36:39], v[150:153], v[190:193], v[36:39]
	v_mfma_f32_16x16x32_bf16 v[32:35], v[158:161], v[190:193], v[32:35]
	v_mfma_f32_16x16x32_bf16 v[84:87], v[154:157], v[170:173], v[84:87]
	v_mfma_f32_16x16x32_bf16 v[80:83], v[162:165], v[170:173], v[80:83]
	v_mfma_f32_16x16x32_bf16 v[68:71], v[154:157], v[178:181], v[68:71]
	v_mfma_f32_16x16x32_bf16 v[64:67], v[162:165], v[178:181], v[64:67]
	v_mfma_f32_16x16x32_bf16 v[52:55], v[154:157], v[186:189], v[52:55]
	v_mfma_f32_16x16x32_bf16 v[48:51], v[162:165], v[186:189], v[48:51]
	v_mfma_f32_16x16x32_bf16 v[36:39], v[154:157], v[194:197], v[36:39]
	v_mfma_f32_16x16x32_bf16 v[32:35], v[162:165], v[194:197], v[32:35]
	s_barrier
	s_add_u32 s46, s46, 0x40080
	s_addc_u32 s47, s47, 0
	s_mov_b32 m0, s78
	v_lshl_add_u64 v[150:151], s[46:47], 0, v[130:131]
	global_load_lds_dwordx4 v[150:151], off
	s_mov_b32 m0, s79
	v_lshl_add_u64 v[150:151], s[46:47], 0, v[128:129]
	global_load_lds_dwordx4 v[150:151], off
	s_waitcnt vmcnt(6)
	s_barrier
;     ...
;         G_PAIR(0, 1);
; #pragma unroll 1
;         for (int t = 2; t < nt; t += 2) G_PAIR(t, 0);
;         p.epi(acc, cur, wr, wc, fr, fq);
;         if (!has_next) break;
;         cur = nxt; cA = nA; cB = nB; cA2 = nA2; cB2 = nB2; ++ui;
;     __device__ __forceinline__ void epi(const f32x4 (&acc)[2][2][4][2], const Unit& u, int wr, int wc, int fr, int fq) const {
;         const int row0 = u.pm * 256 + wr * 64 + fr, col0 = wc * 32 + 4 * fq;
; #pragma unroll
;         for (int ai = 0; ai < 2; ++ai)
; #pragma unroll
;             for (int m = 0; m < 4; ++m) {
;                 float* rowp = Send + (size_t)u.pn * NG * NCH * 256 + ((size_t)u.g * NCH + row0 + ai * 128 + m * 16) * 256 + col0;
; #pragma unroll
;                 for (int bj = 0; bj < 2; ++bj)
; #pragma unroll
;                     for (int n = 0; n < 2; ++n) *(f32x4*)(rowp + bj * 128 + n * 16) = acc[ai][bj][m][n];
;             }
;     }
	v_mfma_f32_16x16x32_bf16 v[124:127], v[198:201], v[166:169], v[124:127]
	v_mfma_f32_16x16x32_bf16 v[120:123], v[206:209], v[166:169], v[120:123]
	v_mfma_f32_16x16x32_bf16 v[116:119], v[198:201], v[174:177], v[116:119]
	v_mfma_f32_16x16x32_bf16 v[112:115], v[206:209], v[174:177], v[112:115]
	v_mfma_f32_16x16x32_bf16 v[108:111], v[198:201], v[182:185], v[108:111]
	v_mfma_f32_16x16x32_bf16 v[104:107], v[206:209], v[182:185], v[104:107]
	v_mfma_f32_16x16x32_bf16 v[100:103], v[198:201], v[190:193], v[100:103]
	v_mfma_f32_16x16x32_bf16 v[96:99], v[206:209], v[190:193], v[96:99]
	v_mfma_f32_16x16x32_bf16 v[124:127], v[202:205], v[170:173], v[124:127]
	v_mfma_f32_16x16x32_bf16 v[120:123], v[210:213], v[170:173], v[120:123]
	v_mfma_f32_16x16x32_bf16 v[116:119], v[202:205], v[178:181], v[116:119]
	v_mfma_f32_16x16x32_bf16 v[112:115], v[210:213], v[178:181], v[112:115]
	v_mfma_f32_16x16x32_bf16 v[108:111], v[202:205], v[186:189], v[108:111]
	v_mfma_f32_16x16x32_bf16 v[104:107], v[210:213], v[186:189], v[104:107]
	v_mfma_f32_16x16x32_bf16 v[100:103], v[202:205], v[194:197], v[100:103]
	v_mfma_f32_16x16x32_bf16 v[96:99], v[210:213], v[194:197], v[96:99]
	s_add_i32 s80, s80, 2
	s_add_u32 s44, s44, 0x100
	s_addc_u32 s45, s45, 0
	s_cmp_gt_u32 s80, 5
	s_barrier
	s_cbranch_scc0 .LBB0_580
	s_lshl_b32 s1, s53, 25
	s_add_u32 s4, s59, s1
	s_addc_u32 s5, s60, 0
	s_ashr_i32 s1, s0, 31
	v_lshl_add_u32 v138, s54, 8, v142
	s_lshl_b64 s[0:1], s[0:1], 19
	v_ashrrev_i32_e32 v139, 31, v138
	s_add_u32 s0, s4, s0
	v_lshlrev_b64 v[138:139], 10, v[138:139]
	s_addc_u32 s1, s5, s1
	v_lshl_add_u64 v[138:139], s[0:1], 0, v[138:139]
	v_lshl_add_u64 v[138:139], v[138:139], 0, v[132:133]
	global_store_dwordx4 v[138:139], v[28:31], off
	global_store_dwordx4 v[138:139], v[24:27], off offset:64
	global_store_dwordx4 v[138:139], v[92:95], off offset:512
	global_store_dwordx4 v[138:139], v[88:91], off offset:576
	v_add_co_u32_e32 v26, vcc, s58, v138
	v_lshl_add_u64 v[24:25], v[138:139], 0, s[18:19]
	s_nop 0
	v_addc_co_u32_e32 v27, vcc, 0, v139, vcc
	global_store_dwordx4 v[26:27], v[20:23], off
	global_store_dwordx4 v[24:25], v[16:19], off offset:64
	global_store_dwordx4 v[24:25], v[76:79], off offset:512
	global_store_dwordx4 v[24:25], v[72:75], off offset:576
	v_add_co_u32_e32 v18, vcc, s63, v138
	v_lshl_add_u64 v[16:17], v[138:139], 0, s[20:21]
	s_nop 0
	v_addc_co_u32_e32 v19, vcc, 0, v139, vcc
	global_store_dwordx4 v[18:19], v[12:15], off
	global_store_dwordx4 v[16:17], v[8:11], off offset:64
	global_store_dwordx4 v[16:17], v[60:63], off offset:512
	global_store_dwordx4 v[16:17], v[56:59], off offset:576
	v_add_co_u32_e32 v10, vcc, s65, v138
	v_lshl_add_u64 v[8:9], v[138:139], 0, s[22:23]
	s_nop 0
	v_addc_co_u32_e32 v11, vcc, 0, v139, vcc
	global_store_dwordx4 v[10:11], v[4:7], off
	global_store_dwordx4 v[8:9], v[0:3], off offset:64
	global_store_dwordx4 v[8:9], v[44:47], off offset:512
	global_store_dwordx4 v[8:9], v[40:43], off offset:576
	v_add_co_u32_e32 v2, vcc, s67, v138
	v_lshl_add_u64 v[0:1], v[138:139], 0, s[24:25]
	s_nop 0
	v_addc_co_u32_e32 v3, vcc, 0, v139, vcc
	global_store_dwordx4 v[2:3], v[84:87], off
	global_store_dwordx4 v[0:1], v[80:83], off offset:64
	global_store_dwordx4 v[0:1], v[124:127], off offset:512
	global_store_dwordx4 v[0:1], v[120:123], off offset:576
	v_add_co_u32_e32 v2, vcc, s68, v138
	v_lshl_add_u64 v[0:1], v[138:139], 0, s[26:27]
	s_nop 0
	v_addc_co_u32_e32 v3, vcc, 0, v139, vcc
	global_store_dwordx4 v[2:3], v[68:71], off
	global_store_dwordx4 v[0:1], v[64:67], off offset:64
	global_store_dwordx4 v[0:1], v[116:119], off offset:512
	global_store_dwordx4 v[0:1], v[112:115], off offset:576
	v_add_co_u32_e32 v2, vcc, s69, v138
	v_lshl_add_u64 v[0:1], v[138:139], 0, s[28:29]
	s_nop 0
	v_addc_co_u32_e32 v3, vcc, 0, v139, vcc
	global_store_dwordx4 v[2:3], v[52:55], off
	global_store_dwordx4 v[0:1], v[48:51], off offset:64
	global_store_dwordx4 v[0:1], v[108:111], off offset:512
	global_store_dwordx4 v[0:1], v[104:107], off offset:576
	v_add_co_u32_e32 v2, vcc, 0x2c000, v138
	s_mov_b32 s54, s72
	s_nop 0
	v_addc_co_u32_e32 v3, vcc, 0, v139, vcc
	v_readlane_b32 s72, v254, 3
	v_readlane_b32 s74, v254, 5
	s_and_b64 vcc, exec, s[36:37]
	s_mov_b32 s0, s34
	s_mov_b32 s53, s71
	s_mov_b64 s[6:7], s[40:41]
	s_mov_b64 s[4:5], s[38:39]
	v_readlane_b32 s73, v254, 4
	v_readlane_b32 s75, v254, 6
	v_lshl_add_u64 v[0:1], v[138:139], 0, s[30:31]
	global_store_dwordx4 v[2:3], v[36:39], off
	global_store_dwordx4 v[0:1], v[32:35], off offset:64
	global_store_dwordx4 v[0:1], v[100:103], off offset:512
	global_store_dwordx4 v[0:1], v[96:99], off offset:576
	s_cbranch_vccz .LBB0_575
	s_waitcnt vmcnt(0)
	s_cmpk_gt_u32 s48, 0xff
	s_cbranch_scc1 .LBB0_584
	s_barrier

;     __device__ __forceinline__ bool unit(int L, Unit& u) const { u.g = L; return order_mn(L, T / 256, NGU / 256, u.pm, u.pn); }
;     __device__ __forceinline__ bool unit(int L, Unit& u) const { u.g = L; return order_mn(L, T / 256, D / 256, u.pm, u.pn); }
;     __device__ __forceinline__ bool unit(int L, Unit& u) const { u.g = 0; return order_mn(L, T / 256, 8, u.pm, u.pn); }
;     __device__ __forceinline__ bool unit(int L, Unit& u) const { if (L >= NG * 4) return false; u.g = L >> 2; u.pm = (L >> 1) & 1; u.pn = L & 1; return true; }
;     __device__ __forceinline__ bool unit(int L, Unit& u) const { if (L >= NG * 8) return false; u.g = L >> 3; u.pm = (L >> 2) & 1; u.pn = L & 3; return true; }
;     ...
;         const bool has_next = p.unit((ui + 1) * G + c, nxt);
;         const char* nA = has_next ? p.a0(nxt) : cA; const char* nB = has_next ? p.b0(nxt) : cB;
;         const char* nA2 = P::SEG ? (has_next ? p.a1(nxt) : cA2) : nA; const char* nB2 = P::SEG ? (has_next ? p.b1(nxt) : cB2) : nB;
.LBB0_789:
	s_bfe_u32 s81, s22, 0x10002
	s_and_b64 s[22:23], s[40:41], exec
	s_cselect_b32 s22, s81, s29
	s_cselect_b32 s2, s80, s2
	s_lshl_b32 s24, s22, 8
	s_ashr_i32 s25, s24, 31
	s_lshl_b64 s[22:23], s[24:25], 11
	s_lshl_b64 s[42:43], s[26:27], 20
	s_add_u32 s29, s8, s42
	s_addc_u32 s42, s9, s43
	s_add_u32 s22, s29, s22
	s_addc_u32 s23, s42, s23
	s_lshl_b64 s[24:25], s[24:25], 9
	s_lshl_b64 s[42:43], s[26:27], 18
	s_add_u32 s29, s66, s42
	s_addc_u32 s42, s67, s43
	s_add_u32 s24, s29, s24
	s_addc_u32 s25, s42, s25
	s_lshl_b32 s42, s2, 8
	ds_read_b128 v[0:3], v224
	ds_read_b128 v[4:7], v224 offset:1024
	ds_read_b128 v[8:11], v224 offset:2048
	ds_read_b128 v[12:15], v224 offset:3072
	s_ashr_i32 s43, s42, 31
	s_lshl_b64 s[42:43], s[42:43], 9
	s_lshl_b64 s[26:27], s[26:27], 19
	s_add_u32 s2, s68, s26
	s_addc_u32 s27, s69, s27
	s_add_u32 s26, s2, s42
	s_addc_u32 s27, s27, s43
	s_add_u32 s42, s30, 0x40080
	s_addc_u32 s43, s31, 0
	s_add_i32 s29, s58, 0xc000
	v_lshl_add_u64 v[48:49], s[42:43], 0, v[202:203]
	s_mov_b32 m0, s29
	s_add_i32 s84, s58, 0xe000
	ds_read_b128 v[16:19], v225
	ds_read_b128 v[20:23], v225 offset:1024
	ds_read_b128 v[24:27], v225 offset:2048
	ds_read_b128 v[28:31], v225 offset:3072
	ds_read_b128 v[32:35], v225 offset:4096
	ds_read_b128 v[36:39], v225 offset:5120
	ds_read_b128 v[40:43], v225 offset:6144
	ds_read_b128 v[44:47], v225 offset:7168
	global_load_lds_dwordx4 v[48:49], off
	s_mov_b32 m0, s84
	v_lshl_add_u64 v[48:49], s[42:43], 0, v[198:199]
	global_load_lds_dwordx4 v[48:49], off
	s_waitcnt lgkmcnt(8)
	s_barrier
	s_waitcnt lgkmcnt(0)
	v_mfma_f32_16x16x32_bf16 v[48:51], v[0:3], v[16:19], 0
	v_mfma_f32_16x16x32_bf16 v[52:55], v[8:11], v[16:19], 0
	v_mfma_f32_16x16x32_bf16 v[56:59], v[0:3], v[24:27], 0
	v_mfma_f32_16x16x32_bf16 v[60:63], v[8:11], v[24:27], 0
	v_mfma_f32_16x16x32_bf16 v[64:67], v[0:3], v[32:35], 0
	v_mfma_f32_16x16x32_bf16 v[68:71], v[8:11], v[32:35], 0
	v_mfma_f32_16x16x32_bf16 v[72:75], v[0:3], v[40:43], 0
	v_mfma_f32_16x16x32_bf16 v[76:79], v[8:11], v[40:43], 0
	v_mfma_f32_16x16x32_bf16 v[48:51], v[4:7], v[20:23], v[48:51]
	v_mfma_f32_16x16x32_bf16 v[52:55], v[12:15], v[20:23], v[52:55]
	v_mfma_f32_16x16x32_bf16 v[56:59], v[4:7], v[28:31], v[56:59]
	v_mfma_f32_16x16x32_bf16 v[60:63], v[12:15], v[28:31], v[60:63]
	v_mfma_f32_16x16x32_bf16 v[64:67], v[4:7], v[36:39], v[64:67]
	v_mfma_f32_16x16x32_bf16 v[68:71], v[12:15], v[36:39], v[68:71]
	v_mfma_f32_16x16x32_bf16 v[72:75], v[4:7], v[44:47], v[72:75]
	v_mfma_f32_16x16x32_bf16 v[76:79], v[12:15], v[44:47], v[76:79]
	s_barrier
	v_lshl_add_u64 v[240:241], s[34:35], 0, v[200:201]
	s_add_i32 s2, s76, s57
	v_lshl_add_u64 v[96:97], v[240:241], 0, s[4:5]
	s_mov_b32 m0, s2
	v_lshl_add_u64 v[242:243], s[34:35], 0, v[196:197]
	ds_read_b128 v[80:83], v226
	ds_read_b128 v[84:87], v226 offset:1024
	ds_read_b128 v[88:91], v226 offset:2048
	ds_read_b128 v[92:95], v226 offset:3072
	global_load_lds_dwordx4 v[96:97], off
	v_lshl_add_u64 v[96:97], v[242:243], 0, s[4:5]
	s_add_i32 m0, s2, 0x2000
	s_nop 0
	global_load_lds_dwordx4 v[96:97], off
	s_barrier
	s_waitcnt lgkmcnt(0)
	v_mfma_f32_16x16x32_bf16 v[96:99], v[80:83], v[16:19], 0
	v_mfma_f32_16x16x32_bf16 v[16:19], v[88:91], v[16:19], 0
	v_mfma_f32_16x16x32_bf16 v[100:103], v[80:83], v[24:27], 0
	v_mfma_f32_16x16x32_bf16 v[24:27], v[88:91], v[24:27], 0
	v_mfma_f32_16x16x32_bf16 v[104:107], v[80:83], v[32:35], 0
	v_mfma_f32_16x16x32_bf16 v[32:35], v[88:91], v[32:35], 0
	v_mfma_f32_16x16x32_bf16 v[108:111], v[80:83], v[40:43], 0
	v_mfma_f32_16x16x32_bf16 v[40:43], v[88:91], v[40:43], 0
	v_mfma_f32_16x16x32_bf16 v[96:99], v[84:87], v[20:23], v[96:99]
	v_mfma_f32_16x16x32_bf16 v[16:19], v[92:95], v[20:23], v[16:19]
	v_mfma_f32_16x16x32_bf16 v[20:23], v[84:87], v[28:31], v[100:103]
	v_mfma_f32_16x16x32_bf16 v[24:27], v[92:95], v[28:31], v[24:27]
	v_mfma_f32_16x16x32_bf16 v[28:31], v[84:87], v[36:39], v[104:107]
	v_mfma_f32_16x16x32_bf16 v[32:35], v[92:95], v[36:39], v[32:35]
	v_mfma_f32_16x16x32_bf16 v[36:39], v[84:87], v[44:47], v[108:111]
	v_mfma_f32_16x16x32_bf16 v[40:43], v[92:95], v[44:47], v[40:43]
	v_lshl_add_u64 v[244:245], s[30:31], 0, v[202:203]
	s_mov_b32 m0, s58
	v_lshl_add_u64 v[128:129], v[244:245], 0, s[6:7]
	v_lshl_add_u64 v[246:247], s[30:31], 0, v[198:199]
	s_barrier
	ds_read_b128 v[44:47], v225 offset:16384
	ds_read_b128 v[100:103], v225 offset:17408
	ds_read_b128 v[104:107], v225 offset:18432
	ds_read_b128 v[108:111], v225 offset:19456
	ds_read_b128 v[112:115], v225 offset:20480
	ds_read_b128 v[116:119], v225 offset:21504
	ds_read_b128 v[120:123], v225 offset:22528
	ds_read_b128 v[124:127], v225 offset:23552
	global_load_lds_dwordx4 v[128:129], off
	s_mov_b32 m0, s61
	v_lshl_add_u64 v[128:129], v[246:247], 0, s[6:7]
	global_load_lds_dwordx4 v[128:129], off
	s_barrier
	s_waitcnt lgkmcnt(0)
	v_mfma_f32_16x16x32_bf16 v[128:131], v[0:3], v[44:47], 0
	v_mfma_f32_16x16x32_bf16 v[132:135], v[8:11], v[44:47], 0
	v_mfma_f32_16x16x32_bf16 v[136:139], v[0:3], v[104:107], 0
	v_mfma_f32_16x16x32_bf16 v[140:143], v[8:11], v[104:107], 0
	v_mfma_f32_16x16x32_bf16 v[144:147], v[0:3], v[112:115], 0
	v_mfma_f32_16x16x32_bf16 v[148:151], v[8:11], v[112:115], 0
	v_mfma_f32_16x16x32_bf16 v[0:3], v[0:3], v[120:123], 0
	v_mfma_f32_16x16x32_bf16 v[8:11], v[8:11], v[120:123], 0
	v_mfma_f32_16x16x32_bf16 v[128:131], v[4:7], v[100:103], v[128:131]
	v_mfma_f32_16x16x32_bf16 v[136:139], v[4:7], v[108:111], v[136:139]
	v_mfma_f32_16x16x32_bf16 v[144:147], v[4:7], v[116:119], v[144:147]
	v_mfma_f32_16x16x32_bf16 v[0:3], v[4:7], v[124:127], v[0:3]
	v_mfma_f32_16x16x32_bf16 v[4:7], v[12:15], v[124:127], v[8:11]
	v_mfma_f32_16x16x32_bf16 v[132:135], v[12:15], v[100:103], v[132:135]
	v_mfma_f32_16x16x32_bf16 v[140:143], v[12:15], v[108:111], v[140:143]
	v_mfma_f32_16x16x32_bf16 v[148:151], v[12:15], v[116:119], v[148:151]
	s_barrier
	s_add_i32 s2, s77, s57
	s_mov_b32 m0, s2
	s_nop 0
	global_load_lds_dwordx4 v[240:241], off
	s_add_i32 m0, s2, 0x2000
	s_nop 0
	global_load_lds_dwordx4 v[242:243], off
	s_waitcnt vmcnt(6)
	s_barrier
	v_mfma_f32_16x16x32_bf16 v[8:11], v[80:83], v[44:47], 0
	v_mfma_f32_16x16x32_bf16 v[12:15], v[88:91], v[44:47], 0
	v_mfma_f32_16x16x32_bf16 v[44:47], v[80:83], v[104:107], 0
	v_mfma_f32_16x16x32_bf16 v[104:107], v[88:91], v[104:107], 0
	v_mfma_f32_16x16x32_bf16 v[152:155], v[80:83], v[112:115], 0
	v_mfma_f32_16x16x32_bf16 v[112:115], v[88:91], v[112:115], 0
	v_mfma_f32_16x16x32_bf16 v[80:83], v[80:83], v[120:123], 0
	v_mfma_f32_16x16x32_bf16 v[88:91], v[88:91], v[120:123], 0
	v_mfma_f32_16x16x32_bf16 v[156:159], v[84:87], v[100:103], v[8:11]
	v_mfma_f32_16x16x32_bf16 v[160:163], v[92:95], v[100:103], v[12:15]
	v_mfma_f32_16x16x32_bf16 v[164:167], v[84:87], v[108:111], v[44:47]
	v_mfma_f32_16x16x32_bf16 v[168:171], v[92:95], v[108:111], v[104:107]
	v_mfma_f32_16x16x32_bf16 v[152:155], v[84:87], v[116:119], v[152:155]
	v_mfma_f32_16x16x32_bf16 v[172:175], v[92:95], v[116:119], v[112:115]
	v_mfma_f32_16x16x32_bf16 v[176:179], v[84:87], v[124:127], v[80:83]
	v_mfma_f32_16x16x32_bf16 v[180:183], v[92:95], v[124:127], v[88:91]
	s_add_i32 s2, 0, 0x18000
	v_add_u32_e32 v80, s2, v222
	s_barrier
	ds_read_b128 v[8:11], v80
	ds_read_b128 v[12:15], v80 offset:1024
	ds_read_b128 v[44:47], v80 offset:2048
	ds_read_b128 v[184:187], v80 offset:3072
	s_add_u32 s42, s30, 0x40100
	s_addc_u32 s43, s31, 0
	s_mov_b32 m0, s64
	v_lshl_add_u64 v[88:89], s[42:43], 0, v[202:203]
	ds_read_b128 v[80:83], v225 offset:32768
	ds_read_b128 v[84:87], v225 offset:33792
	ds_read_b128 v[100:103], v225 offset:34816
	ds_read_b128 v[188:191], v225 offset:35840
	ds_read_b128 v[112:115], v225 offset:36864
	ds_read_b128 v[212:215], v225 offset:37888
	ds_read_b128 v[116:119], v225 offset:38912
	ds_read_b128 v[216:219], v225 offset:39936
	global_load_lds_dwordx4 v[88:89], off
	s_mov_b32 m0, s65
	v_lshl_add_u64 v[88:89], s[42:43], 0, v[198:199]
	global_load_lds_dwordx4 v[88:89], off
	s_waitcnt lgkmcnt(8)
	s_barrier
	s_waitcnt lgkmcnt(0)
	v_mfma_f32_16x16x32_bf16 v[48:51], v[8:11], v[80:83], v[48:51]
	v_mfma_f32_16x16x32_bf16 v[52:55], v[44:47], v[80:83], v[52:55]
	v_mfma_f32_16x16x32_bf16 v[56:59], v[8:11], v[100:103], v[56:59]
	v_mfma_f32_16x16x32_bf16 v[60:63], v[44:47], v[100:103], v[60:63]
	v_mfma_f32_16x16x32_bf16 v[64:67], v[8:11], v[112:115], v[64:67]
	v_mfma_f32_16x16x32_bf16 v[68:71], v[44:47], v[112:115], v[68:71]
	v_mfma_f32_16x16x32_bf16 v[72:75], v[8:11], v[116:119], v[72:75]
	v_mfma_f32_16x16x32_bf16 v[228:231], v[44:47], v[116:119], v[76:79]
	v_mfma_f32_16x16x32_bf16 v[124:127], v[12:15], v[84:87], v[48:51]
	v_mfma_f32_16x16x32_bf16 v[120:123], v[184:187], v[84:87], v[52:55]
	v_mfma_f32_16x16x32_bf16 v[108:111], v[12:15], v[188:191], v[56:59]
	v_mfma_f32_16x16x32_bf16 v[104:107], v[184:187], v[188:191], v[60:63]
	v_mfma_f32_16x16x32_bf16 v[92:95], v[12:15], v[212:215], v[64:67]
	v_mfma_f32_16x16x32_bf16 v[88:91], v[184:187], v[212:215], v[68:71]
	v_mfma_f32_16x16x32_bf16 v[76:79], v[12:15], v[216:219], v[72:75]
	v_mfma_f32_16x16x32_bf16 v[72:75], v[184:187], v[216:219], v[228:231]
	s_barrier
	s_add_i32 s44, 0, 0x1c000
	s_add_u32 s42, s34, 0xffffe800
	v_add_u32_e32 v56, s44, v222
	s_addc_u32 s43, s35, -1
	s_add_i32 s2, s2, s57
	ds_read_b128 v[48:51], v56
	ds_read_b128 v[228:231], v56 offset:1024
	ds_read_b128 v[52:55], v56 offset:2048
	ds_read_b128 v[232:235], v56 offset:3072
	v_lshl_add_u64 v[56:57], s[42:43], 0, v[200:201]
	s_mov_b32 m0, s2
	s_nop 0
	global_load_lds_dwordx4 v[56:57], off
	v_lshl_add_u64 v[56:57], s[42:43], 0, v[196:197]
	s_add_i32 m0, s2, 0x2000
	s_nop 0
	global_load_lds_dwordx4 v[56:57], off
	s_barrier
	s_waitcnt lgkmcnt(0)
	v_mfma_f32_16x16x32_bf16 v[56:59], v[48:51], v[80:83], v[96:99]
	v_mfma_f32_16x16x32_bf16 v[16:19], v[52:55], v[80:83], v[16:19]
	v_mfma_f32_16x16x32_bf16 v[20:23], v[48:51], v[100:103], v[20:23]
	v_mfma_f32_16x16x32_bf16 v[24:27], v[52:55], v[100:103], v[24:27]
	v_mfma_f32_16x16x32_bf16 v[28:31], v[48:51], v[112:115], v[28:31]
	v_mfma_f32_16x16x32_bf16 v[32:35], v[52:55], v[112:115], v[32:35]
	v_mfma_f32_16x16x32_bf16 v[36:39], v[48:51], v[116:119], v[36:39]
	v_mfma_f32_16x16x32_bf16 v[40:43], v[52:55], v[116:119], v[40:43]
	v_mfma_f32_16x16x32_bf16 v[116:119], v[228:231], v[84:87], v[56:59]
	v_mfma_f32_16x16x32_bf16 v[112:115], v[232:235], v[84:87], v[16:19]
	v_mfma_f32_16x16x32_bf16 v[100:103], v[228:231], v[188:191], v[20:23]
	v_mfma_f32_16x16x32_bf16 v[96:99], v[232:235], v[188:191], v[24:27]
	v_mfma_f32_16x16x32_bf16 v[84:87], v[228:231], v[212:215], v[28:31]
	v_mfma_f32_16x16x32_bf16 v[80:83], v[232:235], v[212:215], v[32:35]
	v_mfma_f32_16x16x32_bf16 v[68:71], v[228:231], v[216:219], v[36:39]
	v_mfma_f32_16x16x32_bf16 v[64:67], v[232:235], v[216:219], v[40:43]
	s_mov_b32 m0, s72
	v_lshl_add_u64 v[24:25], v[244:245], 0, s[12:13]
	s_barrier
	ds_read_b128 v[16:19], v225 offset:49152
	ds_read_b128 v[20:23], v225 offset:50176
	ds_read_b128 v[32:35], v225 offset:51200
	ds_read_b128 v[188:191], v225 offset:52224
	ds_read_b128 v[36:39], v225 offset:53248
	ds_read_b128 v[212:215], v225 offset:54272
	ds_read_b128 v[216:219], v225 offset:55296
	ds_read_b128 v[236:239], v225 offset:56320
	global_load_lds_dwordx4 v[24:25], off
	s_mov_b32 m0, s73
	v_lshl_add_u64 v[24:25], v[246:247], 0, s[12:13]
	global_load_lds_dwordx4 v[24:25], off
	s_barrier
	s_waitcnt lgkmcnt(0)
	v_mfma_f32_16x16x32_bf16 v[24:27], v[8:11], v[16:19], v[128:131]
	v_mfma_f32_16x16x32_bf16 v[28:31], v[44:47], v[16:19], v[132:135]
	v_mfma_f32_16x16x32_bf16 v[40:43], v[8:11], v[32:35], v[136:139]
	v_mfma_f32_16x16x32_bf16 v[128:131], v[44:47], v[32:35], v[140:143]
	v_mfma_f32_16x16x32_bf16 v[132:135], v[8:11], v[36:39], v[144:147]
	v_mfma_f32_16x16x32_bf16 v[136:139], v[44:47], v[36:39], v[148:151]
	v_mfma_f32_16x16x32_bf16 v[0:3], v[8:11], v[216:219], v[0:3]
	v_mfma_f32_16x16x32_bf16 v[4:7], v[44:47], v[216:219], v[4:7]
	v_mfma_f32_16x16x32_bf16 v[60:63], v[12:15], v[20:23], v[24:27]
	v_mfma_f32_16x16x32_bf16 v[56:59], v[184:187], v[20:23], v[28:31]
	v_mfma_f32_16x16x32_bf16 v[44:47], v[12:15], v[188:191], v[40:43]
	v_mfma_f32_16x16x32_bf16 v[40:43], v[184:187], v[188:191], v[128:131]
	v_mfma_f32_16x16x32_bf16 v[28:31], v[12:15], v[212:215], v[132:135]
	v_mfma_f32_16x16x32_bf16 v[24:27], v[184:187], v[212:215], v[136:139]
	v_mfma_f32_16x16x32_bf16 v[12:15], v[12:15], v[236:239], v[0:3]
	v_mfma_f32_16x16x32_bf16 v[8:11], v[184:187], v[236:239], v[4:7]
	s_barrier
	s_add_i32 s2, s44, s57
	v_lshl_add_u64 v[0:1], v[240:241], 0, s[14:15]
	s_mov_b32 m0, s2
	s_nop 0
	global_load_lds_dwordx4 v[0:1], off
	v_lshl_add_u64 v[0:1], v[242:243], 0, s[14:15]
	s_add_i32 m0, s2, 0x2000
	s_nop 0
	global_load_lds_dwordx4 v[0:1], off
	s_waitcnt vmcnt(6)
	s_barrier
	v_mfma_f32_16x16x32_bf16 v[0:3], v[48:51], v[16:19], v[156:159]
	v_mfma_f32_16x16x32_bf16 v[4:7], v[52:55], v[16:19], v[160:163]
	v_mfma_f32_16x16x32_bf16 v[16:19], v[48:51], v[32:35], v[164:167]
	v_mfma_f32_16x16x32_bf16 v[32:35], v[52:55], v[32:35], v[168:171]
	v_mfma_f32_16x16x32_bf16 v[128:131], v[48:51], v[36:39], v[152:155]
	v_mfma_f32_16x16x32_bf16 v[132:135], v[52:55], v[36:39], v[172:175]
	v_mfma_f32_16x16x32_bf16 v[136:139], v[48:51], v[216:219], v[176:179]
	v_mfma_f32_16x16x32_bf16 v[140:143], v[52:55], v[216:219], v[180:183]
	v_mfma_f32_16x16x32_bf16 v[52:55], v[228:231], v[20:23], v[0:3]
	v_mfma_f32_16x16x32_bf16 v[48:51], v[232:235], v[20:23], v[4:7]
	v_mfma_f32_16x16x32_bf16 v[36:39], v[228:231], v[188:191], v[16:19]
	v_mfma_f32_16x16x32_bf16 v[32:35], v[232:235], v[188:191], v[32:35]
	v_mfma_f32_16x16x32_bf16 v[20:23], v[228:231], v[212:215], v[128:131]
	v_mfma_f32_16x16x32_bf16 v[16:19], v[232:235], v[212:215], v[132:135]
	v_mfma_f32_16x16x32_bf16 v[4:7], v[228:231], v[236:239], v[136:139]
	v_mfma_f32_16x16x32_bf16 v[0:3], v[232:235], v[236:239], v[140:143]
	s_add_u32 s42, s30, 0x40180
	s_addc_u32 s43, s31, 0
	s_mov_b32 s86, 2
	s_mov_b32 s85, -16
	s_barrier

.LBB0_792:
	s_mov_b32 m0, s29
	v_lshl_add_u64 v[142:143], s[44:45], 0, v[142:143]
	global_load_lds_dwordx4 v[142:143], off
	v_lshl_add_u64 v[140:141], s[44:45], 0, v[140:141]
	s_mov_b32 m0, s84
	s_add_i32 s87, s86, 2
	global_load_lds_dwordx4 v[140:141], off
	s_cmp_eq_u32 s85, 0
	s_cselect_b64 s[46:47], -1, 0
	s_and_b64 s[44:45], s[46:47], exec
	s_cselect_b32 s90, s19, s35
	s_cselect_b32 s91, s18, s34
	s_cselect_b32 s44, 0, s87
	s_and_b64 s[48:49], s[40:41], s[46:47]
	s_waitcnt lgkmcnt(8)
	s_barrier
	s_waitcnt lgkmcnt(0)
	s_and_b64 s[46:47], s[48:49], exec
	s_cselect_b32 s88, s27, s39
	s_cselect_b32 s89, s26, s38
	s_waitcnt lgkmcnt(0)
	v_mfma_f32_16x16x32_bf16 v[124:127], v[136:139], v[176:179], v[124:127]
	v_mfma_f32_16x16x32_bf16 v[120:123], v[144:147], v[176:179], v[120:123]
	v_mfma_f32_16x16x32_bf16 v[108:111], v[136:139], v[180:183], v[108:111]
	v_mfma_f32_16x16x32_bf16 v[104:107], v[144:147], v[180:183], v[104:107]
	v_mfma_f32_16x16x32_bf16 v[140:143], v[136:139], v[184:187], v[92:95]
	v_mfma_f32_16x16x32_bf16 v[148:151], v[144:147], v[184:187], v[88:91]
	v_mfma_f32_16x16x32_bf16 v[152:155], v[136:139], v[188:191], v[76:79]
	v_mfma_f32_16x16x32_bf16 v[156:159], v[144:147], v[188:191], v[72:75]
	v_mfma_f32_16x16x32_bf16 v[72:75], v[128:131], v[160:163], v[124:127]
	v_mfma_f32_16x16x32_bf16 v[76:79], v[132:135], v[160:163], v[120:123]
	v_mfma_f32_16x16x32_bf16 v[88:91], v[128:131], v[164:167], v[108:111]
	v_mfma_f32_16x16x32_bf16 v[92:95], v[132:135], v[164:167], v[104:107]
	v_mfma_f32_16x16x32_bf16 v[104:107], v[128:131], v[168:171], v[140:143]
	v_mfma_f32_16x16x32_bf16 v[108:111], v[132:135], v[168:171], v[148:151]
	v_mfma_f32_16x16x32_bf16 v[120:123], v[128:131], v[172:175], v[152:155]
	v_mfma_f32_16x16x32_bf16 v[124:127], v[132:135], v[172:175], v[156:159]
	s_barrier
	v_add_u32_e32 v148, 0x14000, v208
	ds_read_b128 v[152:155], v148
	ds_read_b128 v[140:143], v148 offset:1024
	ds_read_b128 v[156:159], v148 offset:2048
	ds_read_b128 v[148:151], v148 offset:3072
	s_cmp_lt_u32 s44, 16
	s_cselect_b64 s[46:47], -1, 0
	s_mov_b64 s[52:53], -1
	s_and_b64 vcc, exec, s[46:47]
	s_cbranch_vccz .LBB0_794
	s_mov_b32 s45, s3
	s_lshl_b64 s[50:51], s[44:45], 11
	s_sub_u32 s2, 0, s50
	s_subb_u32 s45, 0, s51
	s_add_u32 s50, s91, s2
	s_addc_u32 s51, s90, s45
	s_mov_b64 s[52:53], 0

.LBB0_796:
	s_mov_b32 m0, s59
	v_lshl_add_u64 v[216:217], s[50:51], 0, v[214:215]
	global_load_lds_dwordx4 v[216:217], off
	v_lshl_add_u64 v[216:217], s[50:51], 0, v[212:213]
	s_mov_b32 m0, s60
	s_and_b64 s[48:49], s[48:49], exec
	global_load_lds_dwordx4 v[216:217], off
	s_barrier
	s_waitcnt lgkmcnt(0)
	s_cselect_b32 s94, s23, s31
	s_cselect_b32 s95, s22, s30
	s_cselect_b32 s92, s25, s37
	s_cselect_b32 s93, s24, s36
	s_waitcnt lgkmcnt(0)
	v_mfma_f32_16x16x32_bf16 v[116:119], v[152:155], v[176:179], v[116:119]
	v_mfma_f32_16x16x32_bf16 v[112:115], v[156:159], v[176:179], v[112:115]
	v_mfma_f32_16x16x32_bf16 v[100:103], v[152:155], v[180:183], v[100:103]
	v_mfma_f32_16x16x32_bf16 v[96:99], v[156:159], v[180:183], v[96:99]
	v_mfma_f32_16x16x32_bf16 v[176:179], v[152:155], v[184:187], v[84:87]
	v_mfma_f32_16x16x32_bf16 v[180:183], v[156:159], v[184:187], v[80:83]
	v_mfma_f32_16x16x32_bf16 v[184:187], v[152:155], v[188:191], v[68:71]
	v_mfma_f32_16x16x32_bf16 v[188:191], v[156:159], v[188:191], v[64:67]
	v_mfma_f32_16x16x32_bf16 v[64:67], v[140:143], v[160:163], v[116:119]
	v_mfma_f32_16x16x32_bf16 v[68:71], v[148:151], v[160:163], v[112:115]
	v_mfma_f32_16x16x32_bf16 v[80:83], v[140:143], v[164:167], v[100:103]
	v_mfma_f32_16x16x32_bf16 v[84:87], v[148:151], v[164:167], v[96:99]
	v_mfma_f32_16x16x32_bf16 v[96:99], v[140:143], v[168:171], v[176:179]
	v_mfma_f32_16x16x32_bf16 v[100:103], v[148:151], v[168:171], v[180:183]
	v_mfma_f32_16x16x32_bf16 v[112:115], v[140:143], v[172:175], v[184:187]
	v_mfma_f32_16x16x32_bf16 v[116:119], v[148:151], v[172:175], v[188:191]
	s_barrier
	ds_read_b128 v[176:179], v225 offset:16384
	ds_read_b128 v[160:163], v225 offset:17408
	ds_read_b128 v[180:183], v225 offset:18432
	ds_read_b128 v[164:167], v225 offset:19456
	ds_read_b128 v[184:187], v225 offset:20480
	ds_read_b128 v[168:171], v225 offset:21504
	ds_read_b128 v[188:191], v225 offset:22528
	ds_read_b128 v[172:175], v225 offset:23552
	s_mov_b64 s[50:51], -1
	s_and_b64 vcc, exec, s[46:47]
	s_cbranch_vccz .LBB0_798
	s_lshl_b32 s2, s44, 7
	s_add_u32 s48, s95, s2
	s_addc_u32 s49, s94, 0
	s_mov_b64 s[50:51], 0

.LBB0_800:
	s_mov_b32 m0, s58
	v_lshl_add_u64 v[228:229], s[48:49], 0, v[218:219]
	global_load_lds_dwordx4 v[228:229], off
	s_mov_b32 m0, s61
	v_lshl_add_u64 v[228:229], s[48:49], 0, v[216:217]
	global_load_lds_dwordx4 v[228:229], off
	s_barrier
	s_waitcnt lgkmcnt(0)
	v_mfma_f32_16x16x32_bf16 v[60:63], v[136:139], v[176:179], v[60:63]
	v_mfma_f32_16x16x32_bf16 v[56:59], v[144:147], v[176:179], v[56:59]
	v_mfma_f32_16x16x32_bf16 v[44:47], v[136:139], v[180:183], v[44:47]
	v_mfma_f32_16x16x32_bf16 v[40:43], v[144:147], v[180:183], v[40:43]
	v_mfma_f32_16x16x32_bf16 v[228:231], v[136:139], v[184:187], v[28:31]
	v_mfma_f32_16x16x32_bf16 v[232:235], v[144:147], v[184:187], v[24:27]
	v_mfma_f32_16x16x32_bf16 v[136:139], v[136:139], v[188:191], v[12:15]
	v_mfma_f32_16x16x32_bf16 v[144:147], v[144:147], v[188:191], v[8:11]
	v_mfma_f32_16x16x32_bf16 v[8:11], v[128:131], v[160:163], v[60:63]
	v_mfma_f32_16x16x32_bf16 v[12:15], v[132:135], v[160:163], v[56:59]
	v_mfma_f32_16x16x32_bf16 v[24:27], v[128:131], v[164:167], v[44:47]
	v_mfma_f32_16x16x32_bf16 v[28:31], v[132:135], v[164:167], v[40:43]
	v_mfma_f32_16x16x32_bf16 v[40:43], v[128:131], v[168:171], v[228:231]
	v_mfma_f32_16x16x32_bf16 v[44:47], v[132:135], v[168:171], v[232:235]
	v_mfma_f32_16x16x32_bf16 v[56:59], v[128:131], v[172:175], v[136:139]
	v_mfma_f32_16x16x32_bf16 v[60:63], v[132:135], v[172:175], v[144:147]
	s_barrier
	s_mov_b64 s[50:51], -1
	s_and_b64 vcc, exec, s[46:47]
	s_cbranch_vccz .LBB0_802
	s_mov_b32 s45, s3
	s_lshl_b64 s[48:49], s[44:45], 11
	s_sub_u32 s2, 0, s48
	s_subb_u32 s45, 0, s49
	s_add_u32 s2, s91, s2
	s_addc_u32 s45, s90, s45
	s_add_u32 s48, s2, 0x1000
	s_addc_u32 s49, s45, 0
	s_mov_b64 s[50:51], 0

.LBB0_804:
	s_mov_b32 m0, s62
	v_lshl_add_u64 v[128:129], s[48:49], 0, v[214:215]
	global_load_lds_dwordx4 v[128:129], off
	s_mov_b32 m0, s63
	v_lshl_add_u64 v[128:129], s[48:49], 0, v[212:213]
	global_load_lds_dwordx4 v[128:129], off
	s_waitcnt vmcnt(6)
	s_barrier
	v_mfma_f32_16x16x32_bf16 v[52:55], v[152:155], v[176:179], v[52:55]
	v_mfma_f32_16x16x32_bf16 v[48:51], v[156:159], v[176:179], v[48:51]
	v_mfma_f32_16x16x32_bf16 v[36:39], v[152:155], v[180:183], v[36:39]
	v_mfma_f32_16x16x32_bf16 v[32:35], v[156:159], v[180:183], v[32:35]
	v_mfma_f32_16x16x32_bf16 v[128:131], v[152:155], v[184:187], v[20:23]
	v_mfma_f32_16x16x32_bf16 v[132:135], v[156:159], v[184:187], v[16:19]
	v_mfma_f32_16x16x32_bf16 v[136:139], v[152:155], v[188:191], v[4:7]
	v_mfma_f32_16x16x32_bf16 v[144:147], v[156:159], v[188:191], v[0:3]
	v_mfma_f32_16x16x32_bf16 v[0:3], v[140:143], v[160:163], v[52:55]
	v_mfma_f32_16x16x32_bf16 v[4:7], v[148:151], v[160:163], v[48:51]
	v_mfma_f32_16x16x32_bf16 v[16:19], v[140:143], v[164:167], v[36:39]
	v_mfma_f32_16x16x32_bf16 v[20:23], v[148:151], v[164:167], v[32:35]
	v_mfma_f32_16x16x32_bf16 v[32:35], v[140:143], v[168:171], v[128:131]
	v_mfma_f32_16x16x32_bf16 v[36:39], v[148:151], v[168:171], v[132:135]
	v_mfma_f32_16x16x32_bf16 v[48:51], v[140:143], v[172:175], v[136:139]
	v_mfma_f32_16x16x32_bf16 v[52:55], v[148:151], v[172:175], v[144:147]
	v_add_u32_e32 v132, 0x18000, v208
	s_barrier
	ds_read_b128 v[136:139], v132
	ds_read_b128 v[128:131], v132 offset:1024
	ds_read_b128 v[140:143], v132 offset:2048
	ds_read_b128 v[132:135], v132 offset:3072
	ds_read_b128 v[176:179], v225 offset:32768
	ds_read_b128 v[160:163], v225 offset:33792
	ds_read_b128 v[180:183], v225 offset:34816
	ds_read_b128 v[164:167], v225 offset:35840
	ds_read_b128 v[184:187], v225 offset:36864
	ds_read_b128 v[168:171], v225 offset:37888
	ds_read_b128 v[188:191], v225 offset:38912
	ds_read_b128 v[172:175], v225 offset:39936
	s_mov_b64 s[50:51], -1
	s_and_b64 vcc, exec, s[46:47]
	s_cbranch_vccz .LBB0_806
	s_lshl_b32 s2, s44, 7
	s_add_u32 s2, s95, s2
	s_addc_u32 s45, s94, 0
	s_add_u32 s48, s2, 0x40000
	s_addc_u32 s49, s45, 0
	s_mov_b64 s[50:51], 0

.LBB0_808:
	s_mov_b32 m0, s64
	v_lshl_add_u64 v[144:145], s[48:49], 0, v[218:219]
	global_load_lds_dwordx4 v[144:145], off
	v_lshl_add_u64 v[144:145], s[48:49], 0, v[216:217]
	s_mov_b32 m0, s65
	s_or_b32 s48, s44, 1
	global_load_lds_dwordx4 v[144:145], off
	s_waitcnt lgkmcnt(8)
	s_barrier
	s_waitcnt lgkmcnt(0)
	v_mfma_f32_16x16x32_bf16 v[72:75], v[136:139], v[176:179], v[72:75]
	v_mfma_f32_16x16x32_bf16 v[76:79], v[140:143], v[176:179], v[76:79]
	v_mfma_f32_16x16x32_bf16 v[88:91], v[136:139], v[180:183], v[88:91]
	v_mfma_f32_16x16x32_bf16 v[92:95], v[140:143], v[180:183], v[92:95]
	v_mfma_f32_16x16x32_bf16 v[144:147], v[136:139], v[184:187], v[104:107]
	v_mfma_f32_16x16x32_bf16 v[148:151], v[140:143], v[184:187], v[108:111]
	v_mfma_f32_16x16x32_bf16 v[152:155], v[136:139], v[188:191], v[120:123]
	v_mfma_f32_16x16x32_bf16 v[156:159], v[140:143], v[188:191], v[124:127]
	v_mfma_f32_16x16x32_bf16 v[124:127], v[128:131], v[160:163], v[72:75]
	v_mfma_f32_16x16x32_bf16 v[120:123], v[132:135], v[160:163], v[76:79]
	v_mfma_f32_16x16x32_bf16 v[108:111], v[128:131], v[164:167], v[88:91]
	v_mfma_f32_16x16x32_bf16 v[104:107], v[132:135], v[164:167], v[92:95]
	v_mfma_f32_16x16x32_bf16 v[92:95], v[128:131], v[168:171], v[144:147]
	v_mfma_f32_16x16x32_bf16 v[88:91], v[132:135], v[168:171], v[148:151]
	v_mfma_f32_16x16x32_bf16 v[76:79], v[128:131], v[172:175], v[152:155]
	v_mfma_f32_16x16x32_bf16 v[72:75], v[132:135], v[172:175], v[156:159]
	s_barrier
	v_add_u32_e32 v148, 0x1c000, v208
	ds_read_b128 v[152:155], v148
	ds_read_b128 v[144:147], v148 offset:1024
	ds_read_b128 v[156:159], v148 offset:2048
	ds_read_b128 v[148:151], v148 offset:3072
	s_mov_b64 s[52:53], -1
	s_and_b64 vcc, exec, s[46:47]
	s_cbranch_vccz .LBB0_810
	s_mov_b32 s49, s3
	s_lshl_b64 s[50:51], s[48:49], 11
	s_sub_u32 s2, 0, s50
	s_subb_u32 s45, 0, s51
	s_add_u32 s50, s91, s2
	s_addc_u32 s51, s90, s45
	s_mov_b64 s[52:53], 0

.LBB0_812:
	s_mov_b32 m0, s70
	v_lshl_add_u64 v[216:217], s[50:51], 0, v[214:215]
	global_load_lds_dwordx4 v[216:217], off
	s_mov_b32 m0, s71
	v_lshl_add_u64 v[216:217], s[50:51], 0, v[212:213]
	global_load_lds_dwordx4 v[216:217], off
	s_barrier
	s_waitcnt lgkmcnt(0)
	v_mfma_f32_16x16x32_bf16 v[64:67], v[152:155], v[176:179], v[64:67]
	v_mfma_f32_16x16x32_bf16 v[68:71], v[156:159], v[176:179], v[68:71]
	v_mfma_f32_16x16x32_bf16 v[80:83], v[152:155], v[180:183], v[80:83]
	v_mfma_f32_16x16x32_bf16 v[84:87], v[156:159], v[180:183], v[84:87]
	v_mfma_f32_16x16x32_bf16 v[176:179], v[152:155], v[184:187], v[96:99]
	v_mfma_f32_16x16x32_bf16 v[180:183], v[156:159], v[184:187], v[100:103]
	v_mfma_f32_16x16x32_bf16 v[184:187], v[152:155], v[188:191], v[112:115]
	v_mfma_f32_16x16x32_bf16 v[188:191], v[156:159], v[188:191], v[116:119]
	v_mfma_f32_16x16x32_bf16 v[116:119], v[144:147], v[160:163], v[64:67]
	v_mfma_f32_16x16x32_bf16 v[112:115], v[148:151], v[160:163], v[68:71]
	v_mfma_f32_16x16x32_bf16 v[100:103], v[144:147], v[164:167], v[80:83]
	v_mfma_f32_16x16x32_bf16 v[96:99], v[148:151], v[164:167], v[84:87]
	v_mfma_f32_16x16x32_bf16 v[84:87], v[144:147], v[168:171], v[176:179]
	v_mfma_f32_16x16x32_bf16 v[80:83], v[148:151], v[168:171], v[180:183]
	v_mfma_f32_16x16x32_bf16 v[68:71], v[144:147], v[172:175], v[184:187]
	v_mfma_f32_16x16x32_bf16 v[64:67], v[148:151], v[172:175], v[188:191]
	s_barrier
	ds_read_b128 v[176:179], v225 offset:49152
	ds_read_b128 v[160:163], v225 offset:50176
	ds_read_b128 v[180:183], v225 offset:51200
	ds_read_b128 v[164:167], v225 offset:52224
	ds_read_b128 v[184:187], v225 offset:53248
	ds_read_b128 v[168:171], v225 offset:54272
	ds_read_b128 v[188:191], v225 offset:55296
	ds_read_b128 v[172:175], v225 offset:56320
	s_mov_b64 s[52:53], -1
	s_and_b64 vcc, exec, s[46:47]
	s_cbranch_vccz .LBB0_814
	s_lshl_b32 s2, s48, 7
	s_add_u32 s50, s95, s2
	s_addc_u32 s51, s94, 0
	s_mov_b64 s[52:53], 0

.LBB0_816:
	s_mov_b32 m0, s72
	v_lshl_add_u64 v[218:219], s[50:51], 0, v[218:219]
	global_load_lds_dwordx4 v[218:219], off
	s_mov_b32 m0, s73
	v_lshl_add_u64 v[216:217], s[50:51], 0, v[216:217]
	global_load_lds_dwordx4 v[216:217], off
	s_barrier
	s_waitcnt lgkmcnt(0)
	v_mfma_f32_16x16x32_bf16 v[8:11], v[136:139], v[176:179], v[8:11]
	v_mfma_f32_16x16x32_bf16 v[12:15], v[140:143], v[176:179], v[12:15]
	v_mfma_f32_16x16x32_bf16 v[24:27], v[136:139], v[180:183], v[24:27]
	v_mfma_f32_16x16x32_bf16 v[28:31], v[140:143], v[180:183], v[28:31]
	v_mfma_f32_16x16x32_bf16 v[216:219], v[136:139], v[184:187], v[40:43]
	v_mfma_f32_16x16x32_bf16 v[228:231], v[140:143], v[184:187], v[44:47]
	v_mfma_f32_16x16x32_bf16 v[136:139], v[136:139], v[188:191], v[56:59]
	v_mfma_f32_16x16x32_bf16 v[140:143], v[140:143], v[188:191], v[60:63]
	v_mfma_f32_16x16x32_bf16 v[60:63], v[128:131], v[160:163], v[8:11]
	v_mfma_f32_16x16x32_bf16 v[56:59], v[132:135], v[160:163], v[12:15]
	v_mfma_f32_16x16x32_bf16 v[44:47], v[128:131], v[164:167], v[24:27]
	v_mfma_f32_16x16x32_bf16 v[40:43], v[132:135], v[164:167], v[28:31]
	v_mfma_f32_16x16x32_bf16 v[28:31], v[128:131], v[168:171], v[216:219]
	v_mfma_f32_16x16x32_bf16 v[24:27], v[132:135], v[168:171], v[228:231]
	v_mfma_f32_16x16x32_bf16 v[12:15], v[128:131], v[172:175], v[136:139]
	v_mfma_f32_16x16x32_bf16 v[8:11], v[132:135], v[172:175], v[140:143]
	s_barrier
	s_mov_b64 s[50:51], -1
	s_and_b64 vcc, exec, s[46:47]
	s_cbranch_vccz .LBB0_818
	s_mov_b32 s49, s3
	s_lshl_b64 s[46:47], s[48:49], 11
	s_sub_u32 s2, 0, s46
	s_subb_u32 s45, 0, s47
	s_add_u32 s2, s91, s2
	s_addc_u32 s45, s90, s45
	s_add_u32 s46, s2, 0x1000
	s_addc_u32 s47, s45, 0
	s_mov_b64 s[50:51], 0

;     ...
;         G_PAIR(0, 1);
; #pragma unroll 1
;         for (int t = 2; t < nt; t += 2) G_PAIR(t, 0);
.LBB0_820:
	s_mov_b32 m0, s74
	v_lshl_add_u64 v[128:129], s[46:47], 0, v[214:215]
	global_load_lds_dwordx4 v[128:129], off
	s_mov_b32 m0, s75
	v_lshl_add_u64 v[128:129], s[46:47], 0, v[212:213]
	global_load_lds_dwordx4 v[128:129], off
	s_waitcnt vmcnt(6)
	s_barrier
	v_mfma_f32_16x16x32_bf16 v[0:3], v[152:155], v[176:179], v[0:3]
	v_mfma_f32_16x16x32_bf16 v[4:7], v[156:159], v[176:179], v[4:7]
	v_mfma_f32_16x16x32_bf16 v[16:19], v[152:155], v[180:183], v[16:19]
	v_mfma_f32_16x16x32_bf16 v[20:23], v[156:159], v[180:183], v[20:23]
	v_mfma_f32_16x16x32_bf16 v[128:131], v[152:155], v[184:187], v[32:35]
	v_mfma_f32_16x16x32_bf16 v[132:135], v[156:159], v[184:187], v[36:39]
	v_mfma_f32_16x16x32_bf16 v[136:139], v[152:155], v[188:191], v[48:51]
	v_mfma_f32_16x16x32_bf16 v[140:143], v[156:159], v[188:191], v[52:55]
	v_mfma_f32_16x16x32_bf16 v[52:55], v[144:147], v[160:163], v[0:3]
	v_mfma_f32_16x16x32_bf16 v[48:51], v[148:151], v[160:163], v[4:7]
	v_mfma_f32_16x16x32_bf16 v[36:39], v[144:147], v[164:167], v[16:19]
	v_mfma_f32_16x16x32_bf16 v[32:35], v[148:151], v[164:167], v[20:23]
	v_mfma_f32_16x16x32_bf16 v[20:23], v[144:147], v[168:171], v[128:131]
	v_mfma_f32_16x16x32_bf16 v[16:19], v[148:151], v[168:171], v[132:135]
	v_mfma_f32_16x16x32_bf16 v[4:7], v[144:147], v[172:175], v[136:139]
	v_mfma_f32_16x16x32_bf16 v[0:3], v[148:151], v[172:175], v[140:143]
	s_add_u32 s42, s42, 0x100
	s_addc_u32 s43, s43, 0
	s_add_i32 s85, s85, 2
	s_cmp_gt_u32 s86, 17
	s_barrier
	s_cbranch_scc1 .LBB0_786
	s_mov_b32 s86, s87
	s_branch .LBB0_790

.LBB0_919:
	s_ashr_i32 s19, s18, 31
	s_waitcnt lgkmcnt(0)
	ds_read_b128 v[0:3], v172
	ds_read_b128 v[4:7], v172 offset:1024
	ds_read_b128 v[8:11], v172 offset:2048
	ds_read_b128 v[12:15], v172 offset:3072
	s_lshl_b64 s[20:21], s[18:19], 19
	s_add_u32 s20, s37, s20
	s_addc_u32 s21, s38, s21
	s_ashr_i32 s17, s16, 31
	s_lshl_b64 s[22:23], s[16:17], 19
	s_add_u32 s22, s39, s22
	s_addc_u32 s23, s40, s23
	s_add_u32 s30, s24, 0x40080
	s_addc_u32 s31, s25, 0
	s_mov_b32 m0, s48
	v_lshl_add_u64 v[48:49], s[30:31], 0, v[146:147]
	ds_read_b128 v[16:19], v173
	ds_read_b128 v[20:23], v173 offset:1024
	ds_read_b128 v[24:27], v173 offset:2048
	ds_read_b128 v[28:31], v173 offset:3072
	ds_read_b128 v[32:35], v173 offset:4096
	ds_read_b128 v[36:39], v173 offset:5120
	ds_read_b128 v[40:43], v173 offset:6144
	ds_read_b128 v[44:47], v173 offset:7168
	global_load_lds_dwordx4 v[48:49], off
	s_mov_b32 m0, s49
	v_lshl_add_u64 v[48:49], s[30:31], 0, v[142:143]
	global_load_lds_dwordx4 v[48:49], off
	s_waitcnt lgkmcnt(8)
	s_barrier
	s_waitcnt lgkmcnt(0)
	v_mfma_f32_16x16x32_bf16 v[48:51], v[0:3], v[16:19], 0
	v_mfma_f32_16x16x32_bf16 v[52:55], v[8:11], v[16:19], 0
	v_mfma_f32_16x16x32_bf16 v[56:59], v[0:3], v[24:27], 0
	v_mfma_f32_16x16x32_bf16 v[60:63], v[8:11], v[24:27], 0
	v_mfma_f32_16x16x32_bf16 v[64:67], v[0:3], v[32:35], 0
	v_mfma_f32_16x16x32_bf16 v[68:71], v[8:11], v[32:35], 0
	v_mfma_f32_16x16x32_bf16 v[72:75], v[0:3], v[40:43], 0
	v_mfma_f32_16x16x32_bf16 v[76:79], v[8:11], v[40:43], 0
	v_mfma_f32_16x16x32_bf16 v[48:51], v[4:7], v[20:23], v[48:51]
	v_mfma_f32_16x16x32_bf16 v[52:55], v[12:15], v[20:23], v[52:55]
	v_mfma_f32_16x16x32_bf16 v[56:59], v[4:7], v[28:31], v[56:59]
	v_mfma_f32_16x16x32_bf16 v[60:63], v[12:15], v[28:31], v[60:63]
	v_mfma_f32_16x16x32_bf16 v[64:67], v[4:7], v[36:39], v[64:67]
	v_mfma_f32_16x16x32_bf16 v[68:71], v[12:15], v[36:39], v[68:71]
	v_mfma_f32_16x16x32_bf16 v[72:75], v[4:7], v[44:47], v[72:75]
	v_mfma_f32_16x16x32_bf16 v[76:79], v[12:15], v[44:47], v[76:79]
	s_barrier
	v_lshl_add_u64 v[168:169], s[26:27], 0, v[144:145]
	s_mov_b32 m0, s50
	v_lshl_add_u64 v[96:97], v[168:169], 0, s[10:11]
	v_lshl_add_u64 v[218:219], s[26:27], 0, v[140:141]
	ds_read_b128 v[80:83], v174
	ds_read_b128 v[84:87], v174 offset:1024
	ds_read_b128 v[88:91], v174 offset:2048
	ds_read_b128 v[92:95], v174 offset:3072
	global_load_lds_dwordx4 v[96:97], off
	s_mov_b32 m0, s51
	v_lshl_add_u64 v[96:97], v[218:219], 0, s[10:11]
	global_load_lds_dwordx4 v[96:97], off
	s_barrier
	s_waitcnt lgkmcnt(0)
	v_mfma_f32_16x16x32_bf16 v[96:99], v[80:83], v[16:19], 0
	v_mfma_f32_16x16x32_bf16 v[16:19], v[88:91], v[16:19], 0
	v_mfma_f32_16x16x32_bf16 v[100:103], v[80:83], v[24:27], 0
	v_mfma_f32_16x16x32_bf16 v[24:27], v[88:91], v[24:27], 0
	v_mfma_f32_16x16x32_bf16 v[104:107], v[80:83], v[32:35], 0
	v_mfma_f32_16x16x32_bf16 v[32:35], v[88:91], v[32:35], 0
	v_mfma_f32_16x16x32_bf16 v[108:111], v[80:83], v[40:43], 0
	v_mfma_f32_16x16x32_bf16 v[40:43], v[88:91], v[40:43], 0
	v_mfma_f32_16x16x32_bf16 v[120:123], v[84:87], v[20:23], v[96:99]
	v_mfma_f32_16x16x32_bf16 v[16:19], v[92:95], v[20:23], v[16:19]
	v_mfma_f32_16x16x32_bf16 v[20:23], v[84:87], v[28:31], v[100:103]
	v_mfma_f32_16x16x32_bf16 v[24:27], v[92:95], v[28:31], v[24:27]
	v_mfma_f32_16x16x32_bf16 v[28:31], v[84:87], v[36:39], v[104:107]
	v_mfma_f32_16x16x32_bf16 v[32:35], v[92:95], v[36:39], v[32:35]
	v_mfma_f32_16x16x32_bf16 v[36:39], v[84:87], v[44:47], v[108:111]
	v_mfma_f32_16x16x32_bf16 v[40:43], v[92:95], v[44:47], v[40:43]
	v_lshl_add_u64 v[242:243], s[24:25], 0, v[146:147]
	s_mov_b32 m0, s41
	v_lshl_add_u64 v[128:129], v[242:243], 0, s[10:11]
	v_lshl_add_u64 v[244:245], s[24:25], 0, v[142:143]
	s_barrier
	ds_read_b128 v[44:47], v173 offset:16384
	ds_read_b128 v[96:99], v173 offset:17408
	ds_read_b128 v[100:103], v173 offset:18432
	ds_read_b128 v[104:107], v173 offset:19456
	ds_read_b128 v[108:111], v173 offset:20480
	ds_read_b128 v[112:115], v173 offset:21504
	ds_read_b128 v[116:119], v173 offset:22528
	ds_read_b128 v[124:127], v173 offset:23552
	global_load_lds_dwordx4 v[128:129], off
	s_mov_b32 m0, s42
	v_lshl_add_u64 v[128:129], v[244:245], 0, s[10:11]
	global_load_lds_dwordx4 v[128:129], off
	s_barrier
	s_waitcnt lgkmcnt(0)
	v_mfma_f32_16x16x32_bf16 v[128:131], v[0:3], v[44:47], 0
	v_mfma_f32_16x16x32_bf16 v[132:135], v[8:11], v[44:47], 0
	v_mfma_f32_16x16x32_bf16 v[136:139], v[0:3], v[100:103], 0
	v_mfma_f32_16x16x32_bf16 v[152:155], v[8:11], v[100:103], 0
	v_mfma_f32_16x16x32_bf16 v[156:159], v[0:3], v[108:111], 0
	v_mfma_f32_16x16x32_bf16 v[160:163], v[8:11], v[108:111], 0
	v_mfma_f32_16x16x32_bf16 v[0:3], v[0:3], v[116:119], 0
	v_mfma_f32_16x16x32_bf16 v[8:11], v[8:11], v[116:119], 0
	v_mfma_f32_16x16x32_bf16 v[164:167], v[4:7], v[96:99], v[128:131]
	v_mfma_f32_16x16x32_bf16 v[136:139], v[4:7], v[104:107], v[136:139]
	v_mfma_f32_16x16x32_bf16 v[156:159], v[4:7], v[112:115], v[156:159]
	v_mfma_f32_16x16x32_bf16 v[0:3], v[4:7], v[124:127], v[0:3]
	v_mfma_f32_16x16x32_bf16 v[4:7], v[12:15], v[124:127], v[8:11]
	v_mfma_f32_16x16x32_bf16 v[132:135], v[12:15], v[96:99], v[132:135]
	v_mfma_f32_16x16x32_bf16 v[152:155], v[12:15], v[104:107], v[152:155]
	v_mfma_f32_16x16x32_bf16 v[160:163], v[12:15], v[112:115], v[160:163]
	s_barrier
	s_add_u32 s30, s26, 0x40100
	s_addc_u32 s31, s27, 0
	s_mov_b32 m0, s52
	v_lshl_add_u64 v[8:9], s[30:31], 0, v[144:145]
	global_load_lds_dwordx4 v[8:9], off
	s_mov_b32 m0, s53
	v_lshl_add_u64 v[8:9], s[30:31], 0, v[140:141]
	global_load_lds_dwordx4 v[8:9], off
	s_waitcnt vmcnt(6)
	s_barrier
	v_mfma_f32_16x16x32_bf16 v[8:11], v[80:83], v[44:47], 0
	v_mfma_f32_16x16x32_bf16 v[12:15], v[88:91], v[44:47], 0
	v_mfma_f32_16x16x32_bf16 v[44:47], v[80:83], v[100:103], 0
	v_mfma_f32_16x16x32_bf16 v[100:103], v[88:91], v[100:103], 0
	v_mfma_f32_16x16x32_bf16 v[128:131], v[80:83], v[108:111], 0
	v_mfma_f32_16x16x32_bf16 v[108:111], v[88:91], v[108:111], 0
	v_mfma_f32_16x16x32_bf16 v[80:83], v[80:83], v[116:119], 0
	v_mfma_f32_16x16x32_bf16 v[88:91], v[88:91], v[116:119], 0
	v_mfma_f32_16x16x32_bf16 v[8:11], v[84:87], v[96:99], v[8:11]
	v_mfma_f32_16x16x32_bf16 v[12:15], v[92:95], v[96:99], v[12:15]
	v_mfma_f32_16x16x32_bf16 v[44:47], v[84:87], v[104:107], v[44:47]
	v_mfma_f32_16x16x32_bf16 v[178:181], v[92:95], v[104:107], v[100:103]
	v_mfma_f32_16x16x32_bf16 v[182:185], v[84:87], v[112:115], v[128:131]
	v_mfma_f32_16x16x32_bf16 v[186:189], v[92:95], v[112:115], v[108:111]
	v_mfma_f32_16x16x32_bf16 v[190:193], v[84:87], v[124:127], v[80:83]
	v_mfma_f32_16x16x32_bf16 v[194:197], v[92:95], v[124:127], v[88:91]
	s_barrier
	ds_read_b128 v[198:201], v176
	ds_read_b128 v[202:205], v176 offset:1024
	ds_read_b128 v[206:209], v176 offset:2048
	ds_read_b128 v[210:213], v176 offset:3072
	s_add_u32 s30, s24, 0x40100
	s_addc_u32 s31, s25, 0
	s_mov_b32 m0, s43
	v_lshl_add_u64 v[80:81], s[30:31], 0, v[146:147]
	ds_read_b128 v[88:91], v173 offset:32768
	ds_read_b128 v[92:95], v173 offset:33792
	ds_read_b128 v[104:107], v173 offset:34816
	ds_read_b128 v[214:217], v173 offset:35840
	ds_read_b128 v[108:111], v173 offset:36864
	ds_read_b128 v[222:225], v173 offset:37888
	ds_read_b128 v[124:127], v173 offset:38912
	ds_read_b128 v[226:229], v173 offset:39936
	global_load_lds_dwordx4 v[80:81], off
	s_mov_b32 m0, s44
	v_lshl_add_u64 v[80:81], s[30:31], 0, v[142:143]
	global_load_lds_dwordx4 v[80:81], off
	s_waitcnt lgkmcnt(8)
	s_barrier
	s_waitcnt lgkmcnt(0)
	v_mfma_f32_16x16x32_bf16 v[48:51], v[198:201], v[88:91], v[48:51]
	v_mfma_f32_16x16x32_bf16 v[52:55], v[206:209], v[88:91], v[52:55]
	v_mfma_f32_16x16x32_bf16 v[56:59], v[198:201], v[104:107], v[56:59]
	v_mfma_f32_16x16x32_bf16 v[60:63], v[206:209], v[104:107], v[60:63]
	v_mfma_f32_16x16x32_bf16 v[64:67], v[198:201], v[108:111], v[64:67]
	v_mfma_f32_16x16x32_bf16 v[68:71], v[206:209], v[108:111], v[68:71]
	v_mfma_f32_16x16x32_bf16 v[72:75], v[198:201], v[124:127], v[72:75]
	v_mfma_f32_16x16x32_bf16 v[76:79], v[206:209], v[124:127], v[76:79]
	v_mfma_f32_16x16x32_bf16 v[116:119], v[202:205], v[92:95], v[48:51]
	v_mfma_f32_16x16x32_bf16 v[112:115], v[210:213], v[92:95], v[52:55]
	v_mfma_f32_16x16x32_bf16 v[100:103], v[202:205], v[214:217], v[56:59]
	v_mfma_f32_16x16x32_bf16 v[96:99], v[210:213], v[214:217], v[60:63]
	v_mfma_f32_16x16x32_bf16 v[84:87], v[202:205], v[222:225], v[64:67]
	v_mfma_f32_16x16x32_bf16 v[80:83], v[210:213], v[222:225], v[68:71]
	v_mfma_f32_16x16x32_bf16 v[68:71], v[202:205], v[226:229], v[72:75]
	v_mfma_f32_16x16x32_bf16 v[64:67], v[210:213], v[226:229], v[76:79]
	s_barrier
	s_mov_b32 m0, s54
	v_lshl_add_u64 v[48:49], v[168:169], 0, s[12:13]
	ds_read_b128 v[56:59], v177
	ds_read_b128 v[230:233], v177 offset:1024
	ds_read_b128 v[60:63], v177 offset:2048
	ds_read_b128 v[234:237], v177 offset:3072
	global_load_lds_dwordx4 v[48:49], off
	s_mov_b32 m0, s55
	v_lshl_add_u64 v[48:49], v[218:219], 0, s[12:13]
	global_load_lds_dwordx4 v[48:49], off
	s_barrier
	s_waitcnt lgkmcnt(0)
	v_mfma_f32_16x16x32_bf16 v[48:51], v[56:59], v[88:91], v[120:123]
	v_mfma_f32_16x16x32_bf16 v[16:19], v[60:63], v[88:91], v[16:19]
	v_mfma_f32_16x16x32_bf16 v[20:23], v[56:59], v[104:107], v[20:23]
	v_mfma_f32_16x16x32_bf16 v[24:27], v[60:63], v[104:107], v[24:27]
	v_mfma_f32_16x16x32_bf16 v[28:31], v[56:59], v[108:111], v[28:31]
	v_mfma_f32_16x16x32_bf16 v[32:35], v[60:63], v[108:111], v[32:35]
	v_mfma_f32_16x16x32_bf16 v[36:39], v[56:59], v[124:127], v[36:39]
	v_mfma_f32_16x16x32_bf16 v[40:43], v[60:63], v[124:127], v[40:43]
	v_mfma_f32_16x16x32_bf16 v[128:131], v[230:233], v[92:95], v[48:51]
	v_mfma_f32_16x16x32_bf16 v[124:127], v[234:237], v[92:95], v[16:19]
	v_mfma_f32_16x16x32_bf16 v[108:111], v[230:233], v[214:217], v[20:23]
	v_mfma_f32_16x16x32_bf16 v[104:107], v[234:237], v[214:217], v[24:27]
	v_mfma_f32_16x16x32_bf16 v[92:95], v[230:233], v[222:225], v[28:31]
	v_mfma_f32_16x16x32_bf16 v[88:91], v[234:237], v[222:225], v[32:35]
	v_mfma_f32_16x16x32_bf16 v[76:79], v[230:233], v[226:229], v[36:39]
	v_mfma_f32_16x16x32_bf16 v[72:75], v[234:237], v[226:229], v[40:43]
	s_mov_b32 m0, s46
	v_lshl_add_u64 v[16:17], v[242:243], 0, s[12:13]
	s_barrier
	ds_read_b128 v[24:27], v173 offset:49152
	ds_read_b128 v[28:31], v173 offset:50176
	ds_read_b128 v[40:43], v173 offset:51200
	ds_read_b128 v[120:123], v173 offset:52224
	ds_read_b128 v[214:217], v173 offset:53248
	ds_read_b128 v[222:225], v173 offset:54272
	ds_read_b128 v[226:229], v173 offset:55296
	ds_read_b128 v[238:241], v173 offset:56320
	global_load_lds_dwordx4 v[16:17], off
	s_mov_b32 m0, s47
	v_lshl_add_u64 v[16:17], v[244:245], 0, s[12:13]
	global_load_lds_dwordx4 v[16:17], off
	s_barrier
	s_waitcnt lgkmcnt(0)
	v_mfma_f32_16x16x32_bf16 v[16:19], v[198:201], v[24:27], v[164:167]
	v_mfma_f32_16x16x32_bf16 v[20:23], v[206:209], v[24:27], v[132:135]
	v_mfma_f32_16x16x32_bf16 v[32:35], v[198:201], v[40:43], v[136:139]
	v_mfma_f32_16x16x32_bf16 v[132:135], v[206:209], v[40:43], v[152:155]
	v_mfma_f32_16x16x32_bf16 v[136:139], v[198:201], v[214:217], v[156:159]
	v_mfma_f32_16x16x32_bf16 v[152:155], v[206:209], v[214:217], v[160:163]
	v_mfma_f32_16x16x32_bf16 v[0:3], v[198:201], v[226:229], v[0:3]
	v_mfma_f32_16x16x32_bf16 v[156:159], v[206:209], v[226:229], v[4:7]
	v_mfma_f32_16x16x32_bf16 v[52:55], v[202:205], v[28:31], v[16:19]
	v_mfma_f32_16x16x32_bf16 v[48:51], v[210:213], v[28:31], v[20:23]
	v_mfma_f32_16x16x32_bf16 v[36:39], v[202:205], v[120:123], v[32:35]
	v_mfma_f32_16x16x32_bf16 v[32:35], v[210:213], v[120:123], v[132:135]
	v_mfma_f32_16x16x32_bf16 v[20:23], v[202:205], v[222:225], v[136:139]
	v_mfma_f32_16x16x32_bf16 v[16:19], v[210:213], v[222:225], v[152:155]
	v_mfma_f32_16x16x32_bf16 v[4:7], v[202:205], v[238:241], v[0:3]
	v_mfma_f32_16x16x32_bf16 v[0:3], v[210:213], v[238:241], v[156:159]
	s_barrier
;     ...
;         G_PAIR(0, 1);
; #pragma unroll 1
;         for (int t = 2; t < nt; t += 2) G_PAIR(t, 0);
	s_add_u32 s30, s26, 0x40180
	s_addc_u32 s31, s27, 0
	s_mov_b32 m0, s56
	v_lshl_add_u64 v[132:133], s[30:31], 0, v[144:145]
	global_load_lds_dwordx4 v[132:133], off
	v_lshl_add_u64 v[132:133], s[30:31], 0, v[140:141]
	s_mov_b32 m0, s57
	s_mov_b64 s[30:31], 0x40180
	global_load_lds_dwordx4 v[132:133], off
	s_waitcnt vmcnt(6)
	s_barrier
	v_mfma_f32_16x16x32_bf16 v[8:11], v[56:59], v[24:27], v[8:11]
	v_mfma_f32_16x16x32_bf16 v[12:15], v[60:63], v[24:27], v[12:15]
	v_mfma_f32_16x16x32_bf16 v[24:27], v[56:59], v[40:43], v[44:47]
	v_mfma_f32_16x16x32_bf16 v[40:43], v[60:63], v[40:43], v[178:181]
	v_mfma_f32_16x16x32_bf16 v[132:135], v[56:59], v[214:217], v[182:185]
	v_mfma_f32_16x16x32_bf16 v[136:139], v[60:63], v[214:217], v[186:189]
	v_mfma_f32_16x16x32_bf16 v[152:155], v[56:59], v[226:229], v[190:193]
	v_mfma_f32_16x16x32_bf16 v[156:159], v[60:63], v[226:229], v[194:197]
	v_mfma_f32_16x16x32_bf16 v[60:63], v[230:233], v[28:31], v[8:11]
	v_mfma_f32_16x16x32_bf16 v[56:59], v[234:237], v[28:31], v[12:15]
	v_mfma_f32_16x16x32_bf16 v[44:47], v[230:233], v[120:123], v[24:27]
	v_mfma_f32_16x16x32_bf16 v[40:43], v[234:237], v[120:123], v[40:43]
	v_mfma_f32_16x16x32_bf16 v[28:31], v[230:233], v[222:225], v[132:135]
	v_mfma_f32_16x16x32_bf16 v[24:27], v[234:237], v[222:225], v[136:139]
	v_mfma_f32_16x16x32_bf16 v[12:15], v[230:233], v[238:241], v[152:155]
	v_mfma_f32_16x16x32_bf16 v[8:11], v[234:237], v[238:241], v[156:159]
	v_lshl_add_u64 v[120:121], s[24:25], 0, v[148:149]
	v_lshl_add_u64 v[122:123], s[24:25], 0, v[150:151]
	s_mov_b32 s17, 0
	s_barrier
.LBB0_920:
	ds_read_b128 v[132:135], v172
	ds_read_b128 v[136:139], v172 offset:1024
	ds_read_b128 v[152:155], v172 offset:2048
	ds_read_b128 v[156:159], v172 offset:3072
	s_mov_b32 m0, s48
	v_lshl_add_u64 v[168:169], v[120:121], 0, s[30:31]
	ds_read_b128 v[160:163], v173
	ds_read_b128 v[164:167], v173 offset:1024
	ds_read_b128 v[178:181], v173 offset:2048
	ds_read_b128 v[182:185], v173 offset:3072
	ds_read_b128 v[186:189], v173 offset:4096
	ds_read_b128 v[190:193], v173 offset:5120
	ds_read_b128 v[194:197], v173 offset:6144
	ds_read_b128 v[198:201], v173 offset:7168
	global_load_lds_dwordx4 v[168:169], off
	s_mov_b32 m0, s49
	v_lshl_add_u64 v[168:169], v[122:123], 0, s[30:31]
	global_load_lds_dwordx4 v[168:169], off
	s_waitcnt lgkmcnt(8)
	s_barrier
	s_waitcnt lgkmcnt(0)
	v_mfma_f32_16x16x32_bf16 v[116:119], v[132:135], v[160:163], v[116:119]
	s_add_i32 s19, s30, 0xfffc0080
	v_mfma_f32_16x16x32_bf16 v[112:115], v[152:155], v[160:163], v[112:115]
	s_cmp_eq_u32 s17, 12
	v_mfma_f32_16x16x32_bf16 v[100:103], v[132:135], v[178:181], v[100:103]
	s_cselect_b64 s[34:35], -1, 0
	v_mfma_f32_16x16x32_bf16 v[96:99], v[152:155], v[178:181], v[96:99]
	s_and_b64 s[60:61], s[34:35], exec
	v_mfma_f32_16x16x32_bf16 v[84:87], v[132:135], v[186:189], v[84:87]
	s_cselect_b32 s19, 0, s19
	v_mfma_f32_16x16x32_bf16 v[80:83], v[152:155], v[186:189], v[80:83]
	s_and_b64 s[34:35], s[28:29], s[34:35]
	v_mfma_f32_16x16x32_bf16 v[68:71], v[132:135], v[194:197], v[68:71]
	s_and_b64 s[34:35], s[34:35], exec
	v_mfma_f32_16x16x32_bf16 v[64:67], v[152:155], v[194:197], v[64:67]
	s_cselect_b32 s61, s21, s25
	v_mfma_f32_16x16x32_bf16 v[116:119], v[136:139], v[164:167], v[116:119]
	s_cselect_b32 s60, s20, s24
	v_mfma_f32_16x16x32_bf16 v[112:115], v[156:159], v[164:167], v[112:115]
	s_cselect_b32 s35, s23, s27
	v_mfma_f32_16x16x32_bf16 v[100:103], v[136:139], v[182:185], v[100:103]
	s_cselect_b32 s34, s22, s26
	v_mfma_f32_16x16x32_bf16 v[96:99], v[156:159], v[182:185], v[96:99]
	v_mfma_f32_16x16x32_bf16 v[84:87], v[136:139], v[190:193], v[84:87]
	v_mfma_f32_16x16x32_bf16 v[80:83], v[156:159], v[190:193], v[80:83]
	v_mfma_f32_16x16x32_bf16 v[68:71], v[136:139], v[198:201], v[68:71]
	v_mfma_f32_16x16x32_bf16 v[64:67], v[156:159], v[198:201], v[64:67]
	s_barrier
	s_add_u32 s34, s34, s19
	s_addc_u32 s35, s35, 0
	s_mov_b32 m0, s50
	v_lshl_add_u64 v[168:169], s[34:35], 0, v[144:145]
	ds_read_b128 v[202:205], v174
	ds_read_b128 v[206:209], v174 offset:1024
	ds_read_b128 v[210:213], v174 offset:2048
	ds_read_b128 v[214:217], v174 offset:3072
	global_load_lds_dwordx4 v[168:169], off
	s_mov_b32 m0, s51
	v_lshl_add_u64 v[218:219], s[34:35], 0, v[140:141]
	global_load_lds_dwordx4 v[218:219], off
	s_barrier
	s_waitcnt lgkmcnt(0)
	v_mfma_f32_16x16x32_bf16 v[128:131], v[202:205], v[160:163], v[128:131]
	v_mfma_f32_16x16x32_bf16 v[124:127], v[210:213], v[160:163], v[124:127]
	v_mfma_f32_16x16x32_bf16 v[108:111], v[202:205], v[178:181], v[108:111]
	v_mfma_f32_16x16x32_bf16 v[104:107], v[210:213], v[178:181], v[104:107]
	v_mfma_f32_16x16x32_bf16 v[92:95], v[202:205], v[186:189], v[92:95]
	v_mfma_f32_16x16x32_bf16 v[88:91], v[210:213], v[186:189], v[88:91]
	v_mfma_f32_16x16x32_bf16 v[76:79], v[202:205], v[194:197], v[76:79]
	v_mfma_f32_16x16x32_bf16 v[72:75], v[210:213], v[194:197], v[72:75]
	v_mfma_f32_16x16x32_bf16 v[128:131], v[206:209], v[164:167], v[128:131]
	v_mfma_f32_16x16x32_bf16 v[124:127], v[214:217], v[164:167], v[124:127]
	v_mfma_f32_16x16x32_bf16 v[108:111], v[206:209], v[182:185], v[108:111]
	v_mfma_f32_16x16x32_bf16 v[104:107], v[214:217], v[182:185], v[104:107]
	v_mfma_f32_16x16x32_bf16 v[92:95], v[206:209], v[190:193], v[92:95]
	v_mfma_f32_16x16x32_bf16 v[88:91], v[214:217], v[190:193], v[88:91]
	v_mfma_f32_16x16x32_bf16 v[76:79], v[206:209], v[198:201], v[76:79]
	v_mfma_f32_16x16x32_bf16 v[72:75], v[214:217], v[198:201], v[72:75]
	s_add_u32 s60, s60, s19
	s_addc_u32 s61, s61, 0
	s_mov_b32 m0, s41
	v_lshl_add_u64 v[222:223], s[60:61], 0, v[146:147]
	s_barrier
	ds_read_b128 v[160:163], v173 offset:16384
	ds_read_b128 v[164:167], v173 offset:17408
	ds_read_b128 v[178:181], v173 offset:18432
	ds_read_b128 v[182:185], v173 offset:19456
	ds_read_b128 v[186:189], v173 offset:20480
	ds_read_b128 v[190:193], v173 offset:21504
	ds_read_b128 v[194:197], v173 offset:22528
	ds_read_b128 v[198:201], v173 offset:23552
	global_load_lds_dwordx4 v[222:223], off
	s_mov_b32 m0, s42
	v_lshl_add_u64 v[224:225], s[60:61], 0, v[142:143]
	global_load_lds_dwordx4 v[224:225], off
	s_barrier
	s_waitcnt lgkmcnt(0)
	v_mfma_f32_16x16x32_bf16 v[52:55], v[132:135], v[160:163], v[52:55]
	v_mfma_f32_16x16x32_bf16 v[48:51], v[152:155], v[160:163], v[48:51]
	v_mfma_f32_16x16x32_bf16 v[36:39], v[132:135], v[178:181], v[36:39]
	v_mfma_f32_16x16x32_bf16 v[32:35], v[152:155], v[178:181], v[32:35]
	v_mfma_f32_16x16x32_bf16 v[20:23], v[132:135], v[186:189], v[20:23]
	v_mfma_f32_16x16x32_bf16 v[16:19], v[152:155], v[186:189], v[16:19]
	v_mfma_f32_16x16x32_bf16 v[4:7], v[132:135], v[194:197], v[4:7]
	v_mfma_f32_16x16x32_bf16 v[0:3], v[152:155], v[194:197], v[0:3]
	v_mfma_f32_16x16x32_bf16 v[52:55], v[136:139], v[164:167], v[52:55]
	v_mfma_f32_16x16x32_bf16 v[48:51], v[156:159], v[164:167], v[48:51]
	v_mfma_f32_16x16x32_bf16 v[36:39], v[136:139], v[182:185], v[36:39]
	v_mfma_f32_16x16x32_bf16 v[32:35], v[156:159], v[182:185], v[32:35]
	v_mfma_f32_16x16x32_bf16 v[20:23], v[136:139], v[190:193], v[20:23]
	v_mfma_f32_16x16x32_bf16 v[16:19], v[156:159], v[190:193], v[16:19]
	v_mfma_f32_16x16x32_bf16 v[4:7], v[136:139], v[198:201], v[4:7]
	v_mfma_f32_16x16x32_bf16 v[0:3], v[156:159], v[198:201], v[0:3]
	s_barrier
	s_add_u32 s62, s34, 0x40000
	s_addc_u32 s63, s35, 0
	s_mov_b32 m0, s52
	v_lshl_add_u64 v[132:133], s[62:63], 0, v[144:145]
	global_load_lds_dwordx4 v[132:133], off
	s_mov_b32 m0, s53
	v_lshl_add_u64 v[132:133], s[62:63], 0, v[140:141]
	global_load_lds_dwordx4 v[132:133], off
	s_waitcnt vmcnt(6)
	s_barrier
	v_mfma_f32_16x16x32_bf16 v[60:63], v[202:205], v[160:163], v[60:63]
	v_mfma_f32_16x16x32_bf16 v[56:59], v[210:213], v[160:163], v[56:59]
	v_mfma_f32_16x16x32_bf16 v[44:47], v[202:205], v[178:181], v[44:47]
	v_mfma_f32_16x16x32_bf16 v[40:43], v[210:213], v[178:181], v[40:43]
	v_mfma_f32_16x16x32_bf16 v[28:31], v[202:205], v[186:189], v[28:31]
	v_mfma_f32_16x16x32_bf16 v[24:27], v[210:213], v[186:189], v[24:27]
	v_mfma_f32_16x16x32_bf16 v[12:15], v[202:205], v[194:197], v[12:15]
	v_mfma_f32_16x16x32_bf16 v[8:11], v[210:213], v[194:197], v[8:11]
	v_mfma_f32_16x16x32_bf16 v[60:63], v[206:209], v[164:167], v[60:63]
	v_mfma_f32_16x16x32_bf16 v[56:59], v[214:217], v[164:167], v[56:59]
	v_mfma_f32_16x16x32_bf16 v[44:47], v[206:209], v[182:185], v[44:47]
	v_mfma_f32_16x16x32_bf16 v[40:43], v[214:217], v[182:185], v[40:43]
	v_mfma_f32_16x16x32_bf16 v[28:31], v[206:209], v[190:193], v[28:31]
	v_mfma_f32_16x16x32_bf16 v[24:27], v[214:217], v[190:193], v[24:27]
	v_mfma_f32_16x16x32_bf16 v[12:15], v[206:209], v[198:201], v[12:15]
	v_mfma_f32_16x16x32_bf16 v[8:11], v[214:217], v[198:201], v[8:11]
	s_barrier
	ds_read_b128 v[132:135], v176
	ds_read_b128 v[136:139], v176 offset:1024
	ds_read_b128 v[152:155], v176 offset:2048
	ds_read_b128 v[156:159], v176 offset:3072
	s_add_u32 s60, s60, 0x40000
	s_addc_u32 s61, s61, 0
	s_mov_b32 m0, s43
	v_lshl_add_u64 v[202:203], s[60:61], 0, v[146:147]
	ds_read_b128 v[160:163], v173 offset:32768
	ds_read_b128 v[164:167], v173 offset:33792
	ds_read_b128 v[178:181], v173 offset:34816
	ds_read_b128 v[182:185], v173 offset:35840
	ds_read_b128 v[186:189], v173 offset:36864
	ds_read_b128 v[190:193], v173 offset:37888
	ds_read_b128 v[194:197], v173 offset:38912
	ds_read_b128 v[198:201], v173 offset:39936
	global_load_lds_dwordx4 v[202:203], off
	s_mov_b32 m0, s44
	v_lshl_add_u64 v[202:203], s[60:61], 0, v[142:143]
	global_load_lds_dwordx4 v[202:203], off
	s_waitcnt lgkmcnt(8)
	s_barrier
	s_waitcnt lgkmcnt(0)
	v_mfma_f32_16x16x32_bf16 v[116:119], v[132:135], v[160:163], v[116:119]
	v_mfma_f32_16x16x32_bf16 v[112:115], v[152:155], v[160:163], v[112:115]
	v_mfma_f32_16x16x32_bf16 v[100:103], v[132:135], v[178:181], v[100:103]
	v_mfma_f32_16x16x32_bf16 v[96:99], v[152:155], v[178:181], v[96:99]
	v_mfma_f32_16x16x32_bf16 v[84:87], v[132:135], v[186:189], v[84:87]
	v_mfma_f32_16x16x32_bf16 v[80:83], v[152:155], v[186:189], v[80:83]
	v_mfma_f32_16x16x32_bf16 v[68:71], v[132:135], v[194:197], v[68:71]
	v_mfma_f32_16x16x32_bf16 v[64:67], v[152:155], v[194:197], v[64:67]
	v_mfma_f32_16x16x32_bf16 v[116:119], v[136:139], v[164:167], v[116:119]
	v_mfma_f32_16x16x32_bf16 v[112:115], v[156:159], v[164:167], v[112:115]
	v_mfma_f32_16x16x32_bf16 v[100:103], v[136:139], v[182:185], v[100:103]
	v_mfma_f32_16x16x32_bf16 v[96:99], v[156:159], v[182:185], v[96:99]
	v_mfma_f32_16x16x32_bf16 v[84:87], v[136:139], v[190:193], v[84:87]
	v_mfma_f32_16x16x32_bf16 v[80:83], v[156:159], v[190:193], v[80:83]
	v_mfma_f32_16x16x32_bf16 v[68:71], v[136:139], v[198:201], v[68:71]
	v_mfma_f32_16x16x32_bf16 v[64:67], v[156:159], v[198:201], v[64:67]
	s_barrier
	s_mov_b32 m0, s54
	v_lshl_add_u64 v[168:169], v[168:169], 0, s[6:7]
	ds_read_b128 v[202:205], v177
	ds_read_b128 v[206:209], v177 offset:1024
	ds_read_b128 v[210:213], v177 offset:2048
	ds_read_b128 v[214:217], v177 offset:3072
	global_load_lds_dwordx4 v[168:169], off
	s_mov_b32 m0, s55
	v_lshl_add_u64 v[168:169], v[218:219], 0, s[6:7]
	global_load_lds_dwordx4 v[168:169], off
	s_barrier
;     ...
;         G_PAIR(0, 1);
; #pragma unroll 1
;         for (int t = 2; t < nt; t += 2) G_PAIR(t, 0);
	s_waitcnt lgkmcnt(0)
	v_mfma_f32_16x16x32_bf16 v[128:131], v[202:205], v[160:163], v[128:131]
	v_mfma_f32_16x16x32_bf16 v[124:127], v[210:213], v[160:163], v[124:127]
	v_mfma_f32_16x16x32_bf16 v[108:111], v[202:205], v[178:181], v[108:111]
	v_mfma_f32_16x16x32_bf16 v[104:107], v[210:213], v[178:181], v[104:107]
	v_mfma_f32_16x16x32_bf16 v[92:95], v[202:205], v[186:189], v[92:95]
	v_mfma_f32_16x16x32_bf16 v[88:91], v[210:213], v[186:189], v[88:91]
	v_mfma_f32_16x16x32_bf16 v[76:79], v[202:205], v[194:197], v[76:79]
	v_mfma_f32_16x16x32_bf16 v[72:75], v[210:213], v[194:197], v[72:75]
	v_mfma_f32_16x16x32_bf16 v[128:131], v[206:209], v[164:167], v[128:131]
	v_mfma_f32_16x16x32_bf16 v[124:127], v[214:217], v[164:167], v[124:127]
	v_mfma_f32_16x16x32_bf16 v[108:111], v[206:209], v[182:185], v[108:111]
	v_mfma_f32_16x16x32_bf16 v[104:107], v[214:217], v[182:185], v[104:107]
	v_mfma_f32_16x16x32_bf16 v[92:95], v[206:209], v[190:193], v[92:95]
	v_mfma_f32_16x16x32_bf16 v[88:91], v[214:217], v[190:193], v[88:91]
	v_mfma_f32_16x16x32_bf16 v[76:79], v[206:209], v[198:201], v[76:79]
	v_mfma_f32_16x16x32_bf16 v[72:75], v[214:217], v[198:201], v[72:75]
	s_mov_b32 m0, s46
	v_lshl_add_u64 v[168:169], v[222:223], 0, s[6:7]
	s_barrier
	ds_read_b128 v[160:163], v173 offset:49152
	ds_read_b128 v[164:167], v173 offset:50176
	ds_read_b128 v[178:181], v173 offset:51200
	ds_read_b128 v[182:185], v173 offset:52224
	ds_read_b128 v[186:189], v173 offset:53248
	ds_read_b128 v[190:193], v173 offset:54272
	ds_read_b128 v[194:197], v173 offset:55296
	ds_read_b128 v[198:201], v173 offset:56320
	global_load_lds_dwordx4 v[168:169], off
	s_mov_b32 m0, s47
	v_lshl_add_u64 v[168:169], v[224:225], 0, s[6:7]
	global_load_lds_dwordx4 v[168:169], off
	s_barrier
	s_waitcnt lgkmcnt(0)
	v_mfma_f32_16x16x32_bf16 v[52:55], v[132:135], v[160:163], v[52:55]
	v_mfma_f32_16x16x32_bf16 v[48:51], v[152:155], v[160:163], v[48:51]
	v_mfma_f32_16x16x32_bf16 v[36:39], v[132:135], v[178:181], v[36:39]
	v_mfma_f32_16x16x32_bf16 v[32:35], v[152:155], v[178:181], v[32:35]
	v_mfma_f32_16x16x32_bf16 v[20:23], v[132:135], v[186:189], v[20:23]
	v_mfma_f32_16x16x32_bf16 v[16:19], v[152:155], v[186:189], v[16:19]
	v_mfma_f32_16x16x32_bf16 v[4:7], v[132:135], v[194:197], v[4:7]
	v_mfma_f32_16x16x32_bf16 v[0:3], v[152:155], v[194:197], v[0:3]
	v_mfma_f32_16x16x32_bf16 v[52:55], v[136:139], v[164:167], v[52:55]
	v_mfma_f32_16x16x32_bf16 v[48:51], v[156:159], v[164:167], v[48:51]
	v_mfma_f32_16x16x32_bf16 v[36:39], v[136:139], v[182:185], v[36:39]
	v_mfma_f32_16x16x32_bf16 v[32:35], v[156:159], v[182:185], v[32:35]
	v_mfma_f32_16x16x32_bf16 v[20:23], v[136:139], v[190:193], v[20:23]
	v_mfma_f32_16x16x32_bf16 v[16:19], v[156:159], v[190:193], v[16:19]
	v_mfma_f32_16x16x32_bf16 v[4:7], v[136:139], v[198:201], v[4:7]
	v_mfma_f32_16x16x32_bf16 v[0:3], v[156:159], v[198:201], v[0:3]
	s_barrier
	s_add_u32 s34, s34, 0x40080
	s_addc_u32 s35, s35, 0
	s_mov_b32 m0, s56
	v_lshl_add_u64 v[132:133], s[34:35], 0, v[144:145]
	global_load_lds_dwordx4 v[132:133], off
	s_mov_b32 m0, s57
	v_lshl_add_u64 v[132:133], s[34:35], 0, v[140:141]
	global_load_lds_dwordx4 v[132:133], off
	s_waitcnt vmcnt(6)
	s_barrier
	v_mfma_f32_16x16x32_bf16 v[60:63], v[202:205], v[160:163], v[60:63]
	v_mfma_f32_16x16x32_bf16 v[56:59], v[210:213], v[160:163], v[56:59]
	v_mfma_f32_16x16x32_bf16 v[44:47], v[202:205], v[178:181], v[44:47]
	v_mfma_f32_16x16x32_bf16 v[40:43], v[210:213], v[178:181], v[40:43]
	v_mfma_f32_16x16x32_bf16 v[28:31], v[202:205], v[186:189], v[28:31]
	v_mfma_f32_16x16x32_bf16 v[24:27], v[210:213], v[186:189], v[24:27]
	v_mfma_f32_16x16x32_bf16 v[12:15], v[202:205], v[194:197], v[12:15]
	v_mfma_f32_16x16x32_bf16 v[8:11], v[210:213], v[194:197], v[8:11]
	v_mfma_f32_16x16x32_bf16 v[60:63], v[206:209], v[164:167], v[60:63]
	v_mfma_f32_16x16x32_bf16 v[56:59], v[214:217], v[164:167], v[56:59]
	v_mfma_f32_16x16x32_bf16 v[44:47], v[206:209], v[182:185], v[44:47]
	v_mfma_f32_16x16x32_bf16 v[40:43], v[214:217], v[182:185], v[40:43]
	v_mfma_f32_16x16x32_bf16 v[28:31], v[206:209], v[190:193], v[28:31]
	v_mfma_f32_16x16x32_bf16 v[24:27], v[214:217], v[190:193], v[24:27]
	v_mfma_f32_16x16x32_bf16 v[12:15], v[206:209], v[198:201], v[12:15]
	v_mfma_f32_16x16x32_bf16 v[8:11], v[214:217], v[198:201], v[8:11]
	s_add_i32 s17, s17, 2
	s_add_u32 s30, s30, 0x100
	s_addc_u32 s31, s31, 0
	s_cmp_gt_u32 s17, 13
	s_barrier
	s_cbranch_scc0 .LBB0_920
; __device__ __forceinline__ unsigned pk2(float lo, float hi) { unsigned r; asm volatile("v_cvt_pk_bf16_f32 %0, %1, %2" : "=v"(r) : "v"(lo), "v"(hi)); return r; }
; __device__ __forceinline__ unsigned pk2(float lo, float hi) { return f2bf(lo) | (f2bf(hi) << 16); }
; __device__ __forceinline__ float fast_sigmoid(float z) { return __builtin_amdgcn_rcpf(1.0f + __expf(-z)); }
;     __device__ __forceinline__ void epi(const f32x4 (&acc)[2][2][4][2], const Unit& u, int wr, int wc, int fr, int fq) const {
;         const int row0 = u.pm * 256 + wr * 64 + fr, col0 = u.pn * 128 + wc * 32 + 8 * fq;
; #pragma unroll
;         for (int ai = 0; ai < 2; ++ai) {
;             u32x4 xo[4];
; #pragma unroll
;             for (int m = 0; m < 4; ++m) xo[m] = *(const u32x4*)(xb + (size_t)(row0 + ai * 128 + m * 16) * D + col0);
; #pragma unroll
;             for (int m = 0; m < 4; ++m) {
;                 const int row = row0 + ai * 128 + m * 16; const size_t off = (size_t)row * D + col0;
;                 const u32x4 o = xo[m]; const f32x4 a0v = acc[ai][0][m][0], a1v = acc[ai][0][m][1], b0v = acc[ai][1][m][0], b1v = acc[ai][1][m][1];
;                 const float v0 = bf_lo(o.x) + coef * a0v[0] * fast_sigmoid(b0v[0]), v1 = bf_hi(o.x) + coef * a0v[1] * fast_sigmoid(b0v[1]);
;                 const float v2 = bf_lo(o.y) + coef * a0v[2] * fast_sigmoid(b0v[2]), v3 = bf_hi(o.y) + coef * a0v[3] * fast_sigmoid(b0v[3]);
;                 const float v4 = bf_lo(o.z) + coef * a1v[0] * fast_sigmoid(b1v[0]), v5 = bf_hi(o.z) + coef * a1v[1] * fast_sigmoid(b1v[1]);
;                 const float v6 = bf_lo(o.w) + coef * a1v[2] * fast_sigmoid(b1v[2]), v7 = bf_hi(o.w) + coef * a1v[3] * fast_sigmoid(b1v[3]);
;                 u32x4 w; w.x = pk2(v0, v1); w.y = pk2(v2, v3); w.z = pk2(v4, v5); w.w = pk2(v6, v7);
;                 *(u32x4*)(xb + off) = w;
;                 float ss = ((v0 * v0 + v1 * v1) + (v2 * v2 + v3 * v3)) + ((v4 * v4 + v5 * v5) + (v6 * v6 + v7 * v7));
;                 ss += __shfl_xor(ss, 16); ss += __shfl_xor(ss, 32);
;                 if (fq == 0) rowss[(size_t)row * 32 + u.pn * 4 + wc] = ss;
	v_lshl_or_b32 v152, s59, 7, v171
	v_lshl_add_u32 v156, s8, 8, v170
	v_ashrrev_i32_e32 v153, 31, v152
	v_lshlrev_b64 v[182:183], 1, v[152:153]
	v_ashrrev_i32_e32 v157, 31, v156
	v_lshl_add_u64 v[154:155], s[0:1], 0, v[182:183]
	v_lshlrev_b64 v[184:185], 11, v[156:157]
	v_lshl_add_u64 v[120:121], v[154:155], 0, v[184:185]
	v_mov_b32_e32 v236, 0x40000
	v_mov_b32_e32 v237, 0
	v_lshl_add_u64 v[234:235], v[120:121], 0, v[236:237]
	v_mov_b32_e32 v236, 0x8000
	global_load_dwordx4 v[178:181], v[120:121], off
	v_or_b32_e32 v166, 16, v156
	v_or_b32_e32 v162, 32, v156
	v_or_b32_e32 v158, 48, v156
	v_ashrrev_i32_e32 v167, 31, v166
	v_ashrrev_i32_e32 v163, 31, v162
	v_ashrrev_i32_e32 v159, 31, v158
	v_lshlrev_b64 v[168:169], 11, v[166:167]
	v_lshlrev_b64 v[164:165], 11, v[162:163]
	v_lshlrev_b64 v[160:161], 11, v[158:159]
	v_lshl_add_u64 v[120:121], v[154:155], 0, v[168:169]
	v_lshl_add_u64 v[122:123], v[154:155], 0, v[164:165]
	v_lshl_add_u64 v[186:187], v[154:155], 0, v[160:161]
	global_load_dwordx4 v[136:139], v[120:121], off
	global_load_dwordx4 v[132:135], v[122:123], off
	s_nop 0
	global_load_dwordx4 v[120:123], v[186:187], off
	global_load_dwordx4 v[238:241], v[234:235], off
	v_lshl_add_u64 v[234:235], v[234:235], 0, v[236:237]
	global_load_dwordx4 v[242:245], v[234:235], off
	v_lshl_add_u64 v[234:235], v[234:235], 0, v[236:237]
	global_load_dwordx4 v[246:249], v[234:235], off
	v_lshl_add_u64 v[234:235], v[234:235], 0, v[236:237]
	global_load_dwordx4 v[250:253], v[234:235], off
	v_mul_f32_e32 v129, 0xbfb8aa3b, v129
	v_mul_f32_e32 v131, 0xbfb8aa3b, v131
	v_mul_f32_e32 v125, 0xbfb8aa3b, v125
	v_mul_f32_e32 v127, 0xbfb8aa3b, v127
	v_mul_f32_e32 v128, 0xbfb8aa3b, v128
	v_mul_f32_e32 v130, 0xbfb8aa3b, v130
	v_mul_f32_e32 v124, 0xbfb8aa3b, v124
	v_mul_f32_e32 v126, 0xbfb8aa3b, v126
	v_exp_f32_e32 v129, v129
	v_exp_f32_e32 v131, v131
	v_exp_f32_e32 v125, v125
	v_exp_f32_e32 v127, v127
	v_exp_f32_e32 v128, v128
	v_exp_f32_e32 v130, v130
	v_exp_f32_e32 v189, v124
	v_exp_f32_e32 v126, v126
	v_and_b32_e32 v187, 64, v175
	v_xor_b32_e32 v186, 16, v175
	v_add_u32_e32 v187, 64, v187
	v_cmp_lt_i32_e32 vcc, v186, v187
	v_add_f32_e32 v129, 1.0, v129
	v_add_f32_e32 v131, 1.0, v131
	v_add_f32_e32 v125, 1.0, v125
	v_add_f32_e32 v127, 1.0, v127
	v_cndmask_b32_e32 v124, v175, v186, vcc
	v_add_f32_e32 v128, 1.0, v128
	v_add_f32_e32 v130, 1.0, v130
	v_add_f32_e32 v186, 1.0, v189
	v_add_f32_e32 v126, 1.0, v126
	v_rcp_f32_e32 v129, v129
	v_rcp_f32_e32 v131, v131
	v_rcp_f32_e32 v125, v125
	v_rcp_f32_e32 v127, v127
	v_rcp_f32_e32 v128, v128
	v_rcp_f32_e32 v130, v130
	v_rcp_f32_e32 v186, v186
	v_rcp_f32_e32 v126, v126
	v_lshlrev_b32_e32 v124, 2, v124
	v_xor_b32_e32 v188, 32, v175
	v_cmp_lt_i32_e32 vcc, v188, v187
	s_lshl_b32 s24, s59, 2
	s_ashr_i32 s25, s24, 31
	s_waitcnt vmcnt(4)
	v_lshlrev_b32_e32 v189, 16, v178
	v_and_b32_e32 v178, 0xffff0000, v178
	v_lshlrev_b32_e32 v190, 16, v179
	v_and_b32_e32 v179, 0xffff0000, v179
	v_lshlrev_b32_e32 v191, 16, v180
	v_and_b32_e32 v180, 0xffff0000, v180
	v_lshlrev_b32_e32 v192, 16, v181
	v_and_b32_e32 v181, 0xffff0000, v181
	v_fmac_f32_e32 v178, v117, v129
	v_fmac_f32_e32 v179, v119, v131
	v_fmac_f32_e32 v180, v113, v125
	v_fmac_f32_e32 v181, v115, v127
	v_fmac_f32_e32 v189, v116, v128
	v_fmac_f32_e32 v190, v118, v130
	v_fmac_f32_e32 v191, v112, v186
	v_fmac_f32_e32 v192, v114, v126
	v_mul_f32_e32 v112, v178, v178
	v_mul_f32_e32 v113, v179, v179
	v_mul_f32_e32 v114, v180, v180
	v_mul_f32_e32 v115, v181, v181
	v_fmac_f32_e32 v112, v189, v189
	v_fmac_f32_e32 v113, v190, v190
	v_fmac_f32_e32 v114, v191, v191
	v_fmac_f32_e32 v115, v192, v192
	v_add_f32_e32 v112, v112, v113
	v_add_f32_e32 v113, v114, v115
	v_add_f32_e32 v112, v112, v113
	ds_bpermute_b32 v113, v124, v112
	v_lshl_add_u64 v[126:127], s[0:1], 0, v[184:185]
	v_lshl_add_u64 v[126:127], v[126:127], 0, v[182:183]
	v_cvt_pk_bf16_f32 v116, v189, v178
	v_cvt_pk_bf16_f32 v117, v190, v179
	s_waitcnt lgkmcnt(0)
	v_add_f32_e32 v113, v112, v113
	v_cndmask_b32_e32 v112, v175, v188, vcc
	v_lshlrev_b32_e32 v112, 2, v112
	ds_bpermute_b32 v114, v112, v113
	v_cvt_pk_bf16_f32 v118, v191, v180
	v_cvt_pk_bf16_f32 v119, v192, v181
	global_store_dwordx4 v[126:127], v[116:119], off
	s_and_saveexec_b64 s[26:27], s[4:5]
	s_cbranch_execz .LBB0_923
	v_lshlrev_b64 v[116:117], 7, v[156:157]
	v_lshl_add_u64 v[116:117], s[2:3], 0, v[116:117]
	v_lshl_add_u64 v[116:117], s[24:25], 2, v[116:117]
	s_lshl_b32 s8, s45, 2
	v_lshl_add_u64 v[116:117], v[116:117], 0, s[8:9]
	s_waitcnt lgkmcnt(0)
	v_add_f32_e32 v113, v113, v114
	global_store_dword v[116:117], v113, off

.LBB0_1670:
	s_waitcnt lgkmcnt(0)
	ds_read_b128 v[0:3], v173
	ds_read_b128 v[4:7], v173 offset:1024
	ds_read_b128 v[8:11], v173 offset:2048
	ds_read_b128 v[12:15], v173 offset:3072
	s_lshl_b64 s[22:23], s[16:17], 17
	s_add_u32 s22, s35, s22
	s_addc_u32 s23, s36, s23
	s_add_u32 s52, s24, 0x40080
	s_addc_u32 s53, s25, 0
	s_mov_b32 m0, s47
	v_lshl_add_u64 v[48:49], s[52:53], 0, v[150:151]
	ds_read_b128 v[16:19], v174
	ds_read_b128 v[20:23], v174 offset:1024
	ds_read_b128 v[24:27], v174 offset:2048
	ds_read_b128 v[28:31], v174 offset:3072
	ds_read_b128 v[32:35], v174 offset:4096
	ds_read_b128 v[36:39], v174 offset:5120
	ds_read_b128 v[40:43], v174 offset:6144
	ds_read_b128 v[44:47], v174 offset:7168
	global_load_lds_dwordx4 v[48:49], off
	s_mov_b32 m0, s48
	v_lshl_add_u64 v[48:49], s[52:53], 0, v[146:147]
	global_load_lds_dwordx4 v[48:49], off
	s_waitcnt lgkmcnt(8)
	s_barrier
	s_waitcnt lgkmcnt(0)
	v_mfma_f32_16x16x32_bf16 v[48:51], v[0:3], v[16:19], 0
	v_mfma_f32_16x16x32_bf16 v[52:55], v[8:11], v[16:19], 0
	v_mfma_f32_16x16x32_bf16 v[56:59], v[0:3], v[24:27], 0
	v_mfma_f32_16x16x32_bf16 v[60:63], v[8:11], v[24:27], 0
	v_mfma_f32_16x16x32_bf16 v[64:67], v[0:3], v[32:35], 0
	v_mfma_f32_16x16x32_bf16 v[68:71], v[8:11], v[32:35], 0
	v_mfma_f32_16x16x32_bf16 v[72:75], v[0:3], v[40:43], 0
	v_mfma_f32_16x16x32_bf16 v[76:79], v[8:11], v[40:43], 0
	v_mfma_f32_16x16x32_bf16 v[48:51], v[4:7], v[20:23], v[48:51]
	v_mfma_f32_16x16x32_bf16 v[52:55], v[12:15], v[20:23], v[52:55]
	v_mfma_f32_16x16x32_bf16 v[56:59], v[4:7], v[28:31], v[56:59]
	v_mfma_f32_16x16x32_bf16 v[60:63], v[12:15], v[28:31], v[60:63]
	v_mfma_f32_16x16x32_bf16 v[64:67], v[4:7], v[36:39], v[64:67]
	v_mfma_f32_16x16x32_bf16 v[68:71], v[12:15], v[36:39], v[68:71]
	v_mfma_f32_16x16x32_bf16 v[72:75], v[4:7], v[44:47], v[72:75]
	v_mfma_f32_16x16x32_bf16 v[76:79], v[12:15], v[44:47], v[76:79]
	s_barrier
	v_lshl_add_u64 v[168:169], s[26:27], 0, v[148:149]
	s_mov_b32 m0, s49
	v_lshl_add_u64 v[96:97], v[168:169], 0, s[10:11]
	v_lshl_add_u64 v[212:213], s[26:27], 0, v[144:145]
	ds_read_b128 v[80:83], v175
	ds_read_b128 v[84:87], v175 offset:1024
	ds_read_b128 v[88:91], v175 offset:2048
	ds_read_b128 v[92:95], v175 offset:3072
	global_load_lds_dwordx4 v[96:97], off
	s_mov_b32 m0, s50
	v_lshl_add_u64 v[96:97], v[212:213], 0, s[10:11]
	global_load_lds_dwordx4 v[96:97], off
	s_barrier
	s_waitcnt lgkmcnt(0)
	v_mfma_f32_16x16x32_bf16 v[96:99], v[80:83], v[16:19], 0
	v_mfma_f32_16x16x32_bf16 v[16:19], v[88:91], v[16:19], 0
	v_mfma_f32_16x16x32_bf16 v[100:103], v[80:83], v[24:27], 0
	v_mfma_f32_16x16x32_bf16 v[24:27], v[88:91], v[24:27], 0
	v_mfma_f32_16x16x32_bf16 v[104:107], v[80:83], v[32:35], 0
	v_mfma_f32_16x16x32_bf16 v[32:35], v[88:91], v[32:35], 0
	v_mfma_f32_16x16x32_bf16 v[108:111], v[80:83], v[40:43], 0
	v_mfma_f32_16x16x32_bf16 v[40:43], v[88:91], v[40:43], 0
	v_mfma_f32_16x16x32_bf16 v[96:99], v[84:87], v[20:23], v[96:99]
	v_mfma_f32_16x16x32_bf16 v[16:19], v[92:95], v[20:23], v[16:19]
	v_mfma_f32_16x16x32_bf16 v[20:23], v[84:87], v[28:31], v[100:103]
	v_mfma_f32_16x16x32_bf16 v[24:27], v[92:95], v[28:31], v[24:27]
	v_mfma_f32_16x16x32_bf16 v[28:31], v[84:87], v[36:39], v[104:107]
	v_mfma_f32_16x16x32_bf16 v[32:35], v[92:95], v[36:39], v[32:35]
	v_mfma_f32_16x16x32_bf16 v[36:39], v[84:87], v[44:47], v[108:111]
	v_mfma_f32_16x16x32_bf16 v[40:43], v[92:95], v[44:47], v[40:43]
	v_lshl_add_u64 v[214:215], s[24:25], 0, v[150:151]
	s_mov_b32 m0, s38
	v_lshl_add_u64 v[128:129], v[214:215], 0, s[10:11]
	v_lshl_add_u64 v[216:217], s[24:25], 0, v[146:147]
	s_barrier
	ds_read_b128 v[44:47], v174 offset:16384
	ds_read_b128 v[100:103], v174 offset:17408
	ds_read_b128 v[104:107], v174 offset:18432
	ds_read_b128 v[108:111], v174 offset:19456
	ds_read_b128 v[112:115], v174 offset:20480
	ds_read_b128 v[116:119], v174 offset:21504
	ds_read_b128 v[120:123], v174 offset:22528
	ds_read_b128 v[124:127], v174 offset:23552
	global_load_lds_dwordx4 v[128:129], off
	s_mov_b32 m0, s39
	v_lshl_add_u64 v[128:129], v[216:217], 0, s[10:11]
	global_load_lds_dwordx4 v[128:129], off
	s_barrier
	s_waitcnt lgkmcnt(0)
	v_mfma_f32_16x16x32_bf16 v[128:131], v[0:3], v[44:47], 0
	v_mfma_f32_16x16x32_bf16 v[132:135], v[8:11], v[44:47], 0
	v_mfma_f32_16x16x32_bf16 v[136:139], v[0:3], v[104:107], 0
	v_mfma_f32_16x16x32_bf16 v[140:143], v[8:11], v[104:107], 0
	v_mfma_f32_16x16x32_bf16 v[152:155], v[0:3], v[112:115], 0
	v_mfma_f32_16x16x32_bf16 v[156:159], v[8:11], v[112:115], 0
	v_mfma_f32_16x16x32_bf16 v[0:3], v[0:3], v[120:123], 0
	v_mfma_f32_16x16x32_bf16 v[8:11], v[8:11], v[120:123], 0
	v_mfma_f32_16x16x32_bf16 v[128:131], v[4:7], v[100:103], v[128:131]
	v_mfma_f32_16x16x32_bf16 v[136:139], v[4:7], v[108:111], v[136:139]
	v_mfma_f32_16x16x32_bf16 v[140:143], v[12:15], v[108:111], v[140:143]
	v_mfma_f32_16x16x32_bf16 v[152:155], v[4:7], v[116:119], v[152:155]
	v_mfma_f32_16x16x32_bf16 v[156:159], v[12:15], v[116:119], v[156:159]
	v_mfma_f32_16x16x32_bf16 v[0:3], v[4:7], v[124:127], v[0:3]
	v_mfma_f32_16x16x32_bf16 v[4:7], v[12:15], v[124:127], v[8:11]
	v_mfma_f32_16x16x32_bf16 v[132:135], v[12:15], v[100:103], v[132:135]
	s_barrier
	s_add_u32 s52, s26, 0x10100
	s_addc_u32 s53, s27, 0
	s_add_i32 s19, s46, s37
	v_lshl_add_u64 v[8:9], s[52:53], 0, v[148:149]
	s_mov_b32 m0, s19
	s_add_i32 s17, s19, 0x2000
	global_load_lds_dwordx4 v[8:9], off
	s_mov_b32 m0, s17
	v_lshl_add_u64 v[8:9], s[52:53], 0, v[144:145]
	global_load_lds_dwordx4 v[8:9], off
	s_waitcnt vmcnt(6)
	s_barrier
	v_mfma_f32_16x16x32_bf16 v[8:11], v[80:83], v[44:47], 0
	v_mfma_f32_16x16x32_bf16 v[12:15], v[88:91], v[44:47], 0
	v_mfma_f32_16x16x32_bf16 v[44:47], v[80:83], v[104:107], 0
	v_mfma_f32_16x16x32_bf16 v[104:107], v[88:91], v[104:107], 0
	v_mfma_f32_16x16x32_bf16 v[160:163], v[80:83], v[112:115], 0
	v_mfma_f32_16x16x32_bf16 v[112:115], v[88:91], v[112:115], 0
	v_mfma_f32_16x16x32_bf16 v[80:83], v[80:83], v[120:123], 0
	v_mfma_f32_16x16x32_bf16 v[88:91], v[88:91], v[120:123], 0
	v_mfma_f32_16x16x32_bf16 v[8:11], v[84:87], v[100:103], v[8:11]
	v_mfma_f32_16x16x32_bf16 v[12:15], v[92:95], v[100:103], v[12:15]
	v_mfma_f32_16x16x32_bf16 v[44:47], v[84:87], v[108:111], v[44:47]
	v_mfma_f32_16x16x32_bf16 v[100:103], v[92:95], v[108:111], v[104:107]
	v_mfma_f32_16x16x32_bf16 v[104:107], v[84:87], v[116:119], v[160:163]
	v_mfma_f32_16x16x32_bf16 v[108:111], v[92:95], v[116:119], v[112:115]
	v_mfma_f32_16x16x32_bf16 v[80:83], v[84:87], v[124:127], v[80:83]
	v_mfma_f32_16x16x32_bf16 v[84:87], v[92:95], v[124:127], v[88:91]
	s_add_i32 s51, 0, 0x18000
	v_add_u32_e32 v221, s51, v171
	s_barrier
	ds_read_b128 v[88:91], v221
	ds_read_b128 v[92:95], v221 offset:1024
	ds_read_b128 v[112:115], v221 offset:2048
	ds_read_b128 v[116:119], v221 offset:3072
	s_add_u32 s52, s24, 0x40100
	s_addc_u32 s53, s25, 0
	s_mov_b32 m0, s40
	v_lshl_add_u64 v[196:197], s[52:53], 0, v[150:151]
	ds_read_b128 v[120:123], v174 offset:32768
	ds_read_b128 v[124:127], v174 offset:33792
	ds_read_b128 v[160:163], v174 offset:34816
	ds_read_b128 v[164:167], v174 offset:35840
	ds_read_b128 v[180:183], v174 offset:36864
	ds_read_b128 v[184:187], v174 offset:37888
	ds_read_b128 v[188:191], v174 offset:38912
	ds_read_b128 v[192:195], v174 offset:39936
	global_load_lds_dwordx4 v[196:197], off
	s_mov_b32 m0, s41
	v_lshl_add_u64 v[196:197], s[52:53], 0, v[146:147]
	global_load_lds_dwordx4 v[196:197], off
	s_waitcnt lgkmcnt(8)
	s_barrier
	s_waitcnt lgkmcnt(0)
	v_mfma_f32_16x16x32_bf16 v[48:51], v[88:91], v[120:123], v[48:51]
	v_mfma_f32_16x16x32_bf16 v[52:55], v[112:115], v[120:123], v[52:55]
	v_mfma_f32_16x16x32_bf16 v[56:59], v[88:91], v[160:163], v[56:59]
	v_mfma_f32_16x16x32_bf16 v[60:63], v[112:115], v[160:163], v[60:63]
	v_mfma_f32_16x16x32_bf16 v[64:67], v[88:91], v[180:183], v[64:67]
	v_mfma_f32_16x16x32_bf16 v[68:71], v[112:115], v[180:183], v[68:71]
	v_mfma_f32_16x16x32_bf16 v[72:75], v[88:91], v[188:191], v[72:75]
	v_mfma_f32_16x16x32_bf16 v[76:79], v[112:115], v[188:191], v[76:79]
	v_mfma_f32_16x16x32_bf16 v[48:51], v[92:95], v[124:127], v[48:51]
	v_mfma_f32_16x16x32_bf16 v[52:55], v[116:119], v[124:127], v[52:55]
	v_mfma_f32_16x16x32_bf16 v[56:59], v[92:95], v[164:167], v[56:59]
	v_mfma_f32_16x16x32_bf16 v[60:63], v[116:119], v[164:167], v[60:63]
	v_mfma_f32_16x16x32_bf16 v[64:67], v[92:95], v[184:187], v[64:67]
	v_mfma_f32_16x16x32_bf16 v[68:71], v[116:119], v[184:187], v[68:71]
	v_mfma_f32_16x16x32_bf16 v[72:75], v[92:95], v[192:195], v[72:75]
	v_mfma_f32_16x16x32_bf16 v[76:79], v[116:119], v[192:195], v[76:79]
	s_barrier
	s_add_i32 s54, 0, 0x1c000
	s_add_i32 s53, s51, s37
	v_add_u32_e32 v226, s54, v171
	v_lshl_add_u64 v[168:169], v[168:169], 0, s[12:13]
	s_mov_b32 m0, s53
	s_add_i32 s51, s53, 0x2000
	ds_read_b128 v[196:199], v226
	ds_read_b128 v[200:203], v226 offset:1024
	ds_read_b128 v[204:207], v226 offset:2048
	ds_read_b128 v[208:211], v226 offset:3072
	global_load_lds_dwordx4 v[168:169], off
	s_mov_b32 m0, s51
	v_lshl_add_u64 v[168:169], v[212:213], 0, s[12:13]
	global_load_lds_dwordx4 v[168:169], off
	s_barrier
	s_waitcnt lgkmcnt(0)
	v_mfma_f32_16x16x32_bf16 v[96:99], v[196:199], v[120:123], v[96:99]
	v_mfma_f32_16x16x32_bf16 v[16:19], v[204:207], v[120:123], v[16:19]
	v_mfma_f32_16x16x32_bf16 v[20:23], v[196:199], v[160:163], v[20:23]
	v_mfma_f32_16x16x32_bf16 v[24:27], v[204:207], v[160:163], v[24:27]
	v_mfma_f32_16x16x32_bf16 v[28:31], v[196:199], v[180:183], v[28:31]
	v_mfma_f32_16x16x32_bf16 v[32:35], v[204:207], v[180:183], v[32:35]
	v_mfma_f32_16x16x32_bf16 v[36:39], v[196:199], v[188:191], v[36:39]
	v_mfma_f32_16x16x32_bf16 v[40:43], v[204:207], v[188:191], v[40:43]
	v_mfma_f32_16x16x32_bf16 v[96:99], v[200:203], v[124:127], v[96:99]
	v_mfma_f32_16x16x32_bf16 v[16:19], v[208:211], v[124:127], v[16:19]
	v_mfma_f32_16x16x32_bf16 v[20:23], v[200:203], v[164:167], v[20:23]
	v_mfma_f32_16x16x32_bf16 v[24:27], v[208:211], v[164:167], v[24:27]
	v_mfma_f32_16x16x32_bf16 v[28:31], v[200:203], v[184:187], v[28:31]
	v_mfma_f32_16x16x32_bf16 v[32:35], v[208:211], v[184:187], v[32:35]
	v_mfma_f32_16x16x32_bf16 v[36:39], v[200:203], v[192:195], v[36:39]
	v_mfma_f32_16x16x32_bf16 v[40:43], v[208:211], v[192:195], v[40:43]
	s_mov_b32 m0, s43
	v_lshl_add_u64 v[168:169], v[214:215], 0, s[12:13]
	s_barrier
	ds_read_b128 v[120:123], v174 offset:49152
	ds_read_b128 v[124:127], v174 offset:50176
	ds_read_b128 v[160:163], v174 offset:51200
	ds_read_b128 v[164:167], v174 offset:52224
	ds_read_b128 v[180:183], v174 offset:53248
	ds_read_b128 v[184:187], v174 offset:54272
	ds_read_b128 v[188:191], v174 offset:55296
	ds_read_b128 v[192:195], v174 offset:56320
	global_load_lds_dwordx4 v[168:169], off
	s_mov_b32 m0, s44
	v_lshl_add_u64 v[168:169], v[216:217], 0, s[12:13]
	global_load_lds_dwordx4 v[168:169], off
	s_barrier
	s_waitcnt lgkmcnt(0)
	v_mfma_f32_16x16x32_bf16 v[128:131], v[88:91], v[120:123], v[128:131]
	v_mfma_f32_16x16x32_bf16 v[132:135], v[112:115], v[120:123], v[132:135]
	v_mfma_f32_16x16x32_bf16 v[136:139], v[88:91], v[160:163], v[136:139]
	v_mfma_f32_16x16x32_bf16 v[140:143], v[112:115], v[160:163], v[140:143]
	v_mfma_f32_16x16x32_bf16 v[152:155], v[88:91], v[180:183], v[152:155]
	v_mfma_f32_16x16x32_bf16 v[156:159], v[112:115], v[180:183], v[156:159]
	v_mfma_f32_16x16x32_bf16 v[0:3], v[88:91], v[188:191], v[0:3]
	v_mfma_f32_16x16x32_bf16 v[4:7], v[112:115], v[188:191], v[4:7]
	v_mfma_f32_16x16x32_bf16 v[88:91], v[92:95], v[124:127], v[128:131]
	v_mfma_f32_16x16x32_bf16 v[112:115], v[116:119], v[124:127], v[132:135]
	v_mfma_f32_16x16x32_bf16 v[128:131], v[92:95], v[164:167], v[136:139]
	v_mfma_f32_16x16x32_bf16 v[132:135], v[116:119], v[164:167], v[140:143]
	v_mfma_f32_16x16x32_bf16 v[136:139], v[92:95], v[184:187], v[152:155]
	v_mfma_f32_16x16x32_bf16 v[140:143], v[116:119], v[184:187], v[156:159]
	v_mfma_f32_16x16x32_bf16 v[0:3], v[92:95], v[192:195], v[0:3]
	v_mfma_f32_16x16x32_bf16 v[4:7], v[116:119], v[192:195], v[4:7]
	s_barrier
	s_add_u32 s56, s26, 0x10180
	s_addc_u32 s57, s27, 0
	s_add_i32 s54, s54, s37
	v_lshl_add_u64 v[92:93], s[56:57], 0, v[148:149]
	s_mov_b32 m0, s54
	s_add_i32 s52, s54, 0x2000
	global_load_lds_dwordx4 v[92:93], off
	s_mov_b32 m0, s52
	v_lshl_add_u64 v[92:93], s[56:57], 0, v[144:145]
	global_load_lds_dwordx4 v[92:93], off
	s_waitcnt vmcnt(6)
	s_barrier
	v_mfma_f32_16x16x32_bf16 v[8:11], v[196:199], v[120:123], v[8:11]
	s_and_b64 s[28:29], s[28:29], exec
	s_cselect_b32 s27, s23, s27
	s_cselect_b32 s26, s22, s26
	v_mfma_f32_16x16x32_bf16 v[12:15], v[204:207], v[120:123], v[12:15]
	v_mfma_f32_16x16x32_bf16 v[44:47], v[196:199], v[160:163], v[44:47]
	v_mfma_f32_16x16x32_bf16 v[92:95], v[204:207], v[160:163], v[100:103]
	v_mfma_f32_16x16x32_bf16 v[100:103], v[196:199], v[180:183], v[104:107]
	v_mfma_f32_16x16x32_bf16 v[104:107], v[204:207], v[180:183], v[108:111]
	v_mfma_f32_16x16x32_bf16 v[80:83], v[196:199], v[188:191], v[80:83]
	v_mfma_f32_16x16x32_bf16 v[84:87], v[204:207], v[188:191], v[84:87]
	v_mfma_f32_16x16x32_bf16 v[8:11], v[200:203], v[124:127], v[8:11]
	v_mfma_f32_16x16x32_bf16 v[12:15], v[208:211], v[124:127], v[12:15]
	v_mfma_f32_16x16x32_bf16 v[44:47], v[200:203], v[164:167], v[44:47]
	v_mfma_f32_16x16x32_bf16 v[92:95], v[208:211], v[164:167], v[92:95]
	v_mfma_f32_16x16x32_bf16 v[100:103], v[200:203], v[184:187], v[100:103]
	v_mfma_f32_16x16x32_bf16 v[104:107], v[208:211], v[184:187], v[104:107]
	v_mfma_f32_16x16x32_bf16 v[80:83], v[200:203], v[192:195], v[80:83]
	v_mfma_f32_16x16x32_bf16 v[84:87], v[208:211], v[192:195], v[84:87]
	s_barrier
	ds_read_b128 v[108:111], v173
	ds_read_b128 v[116:119], v173 offset:1024
	ds_read_b128 v[120:123], v173 offset:2048
	ds_read_b128 v[124:127], v173 offset:3072
	s_add_u32 s24, s24, 0x40180
	s_addc_u32 s25, s25, 0
	s_mov_b32 m0, s47
	v_lshl_add_u64 v[168:169], s[24:25], 0, v[150:151]
	ds_read_b128 v[152:155], v174
	ds_read_b128 v[156:159], v174 offset:1024
	ds_read_b128 v[160:163], v174 offset:2048
	ds_read_b128 v[164:167], v174 offset:3072
	ds_read_b128 v[180:183], v174 offset:4096
	ds_read_b128 v[184:187], v174 offset:5120
	ds_read_b128 v[188:191], v174 offset:6144
	ds_read_b128 v[192:195], v174 offset:7168
	global_load_lds_dwordx4 v[168:169], off
	s_mov_b32 m0, s48
	v_lshl_add_u64 v[168:169], s[24:25], 0, v[146:147]
	global_load_lds_dwordx4 v[168:169], off
	s_waitcnt lgkmcnt(8)
	s_barrier
	s_waitcnt lgkmcnt(0)
	v_mfma_f32_16x16x32_bf16 v[48:51], v[108:111], v[152:155], v[48:51]
	v_mfma_f32_16x16x32_bf16 v[52:55], v[120:123], v[152:155], v[52:55]
	v_mfma_f32_16x16x32_bf16 v[56:59], v[108:111], v[160:163], v[56:59]
	v_mfma_f32_16x16x32_bf16 v[60:63], v[120:123], v[160:163], v[60:63]
	v_mfma_f32_16x16x32_bf16 v[64:67], v[108:111], v[180:183], v[64:67]
	v_mfma_f32_16x16x32_bf16 v[68:71], v[120:123], v[180:183], v[68:71]
	v_mfma_f32_16x16x32_bf16 v[72:75], v[108:111], v[188:191], v[72:75]
	v_mfma_f32_16x16x32_bf16 v[76:79], v[120:123], v[188:191], v[76:79]
	v_mfma_f32_16x16x32_bf16 v[48:51], v[116:119], v[156:159], v[48:51]
	v_mfma_f32_16x16x32_bf16 v[52:55], v[124:127], v[156:159], v[52:55]
	v_mfma_f32_16x16x32_bf16 v[56:59], v[116:119], v[164:167], v[56:59]
	v_mfma_f32_16x16x32_bf16 v[60:63], v[124:127], v[164:167], v[60:63]
	v_mfma_f32_16x16x32_bf16 v[64:67], v[116:119], v[184:187], v[64:67]
	v_mfma_f32_16x16x32_bf16 v[68:71], v[124:127], v[184:187], v[68:71]
	v_mfma_f32_16x16x32_bf16 v[72:75], v[116:119], v[192:195], v[72:75]
	v_mfma_f32_16x16x32_bf16 v[76:79], v[124:127], v[192:195], v[76:79]
	s_barrier
	s_mov_b32 m0, s49
	v_lshl_add_u64 v[168:169], s[26:27], 0, v[148:149]
	ds_read_b128 v[196:199], v175
	ds_read_b128 v[200:203], v175 offset:1024
	ds_read_b128 v[204:207], v175 offset:2048
	ds_read_b128 v[208:211], v175 offset:3072
	global_load_lds_dwordx4 v[168:169], off
	s_mov_b32 m0, s50
	v_lshl_add_u64 v[230:231], s[26:27], 0, v[144:145]
	global_load_lds_dwordx4 v[230:231], off
	s_barrier
	s_waitcnt lgkmcnt(0)
	v_mfma_f32_16x16x32_bf16 v[96:99], v[196:199], v[152:155], v[96:99]
	v_mfma_f32_16x16x32_bf16 v[16:19], v[204:207], v[152:155], v[16:19]
	v_mfma_f32_16x16x32_bf16 v[20:23], v[196:199], v[160:163], v[20:23]
	v_mfma_f32_16x16x32_bf16 v[24:27], v[204:207], v[160:163], v[24:27]
	v_mfma_f32_16x16x32_bf16 v[28:31], v[196:199], v[180:183], v[28:31]
	v_mfma_f32_16x16x32_bf16 v[32:35], v[204:207], v[180:183], v[32:35]
	v_mfma_f32_16x16x32_bf16 v[36:39], v[196:199], v[188:191], v[36:39]
	v_mfma_f32_16x16x32_bf16 v[40:43], v[204:207], v[188:191], v[40:43]
	v_mfma_f32_16x16x32_bf16 v[152:155], v[200:203], v[156:159], v[96:99]
	v_mfma_f32_16x16x32_bf16 v[16:19], v[208:211], v[156:159], v[16:19]
	v_mfma_f32_16x16x32_bf16 v[20:23], v[200:203], v[164:167], v[20:23]
	v_mfma_f32_16x16x32_bf16 v[24:27], v[208:211], v[164:167], v[24:27]
	v_mfma_f32_16x16x32_bf16 v[28:31], v[200:203], v[184:187], v[28:31]
	v_mfma_f32_16x16x32_bf16 v[32:35], v[208:211], v[184:187], v[32:35]
	v_mfma_f32_16x16x32_bf16 v[36:39], v[200:203], v[192:195], v[36:39]
	v_mfma_f32_16x16x32_bf16 v[40:43], v[208:211], v[192:195], v[40:43]
	s_mov_b32 m0, s38
	v_lshl_add_u64 v[234:235], s[20:21], 0, v[150:151]
	s_barrier
	ds_read_b128 v[96:99], v174 offset:16384
	ds_read_b128 v[156:159], v174 offset:17408
	ds_read_b128 v[160:163], v174 offset:18432
	ds_read_b128 v[164:167], v174 offset:19456
	ds_read_b128 v[180:183], v174 offset:20480
	ds_read_b128 v[184:187], v174 offset:21504
	ds_read_b128 v[188:191], v174 offset:22528
	ds_read_b128 v[192:195], v174 offset:23552
	global_load_lds_dwordx4 v[234:235], off
	s_mov_b32 m0, s39
	v_lshl_add_u64 v[236:237], s[20:21], 0, v[146:147]
	global_load_lds_dwordx4 v[236:237], off
	s_barrier
	s_waitcnt lgkmcnt(0)
	v_mfma_f32_16x16x32_bf16 v[88:91], v[108:111], v[96:99], v[88:91]
	v_mfma_f32_16x16x32_bf16 v[112:115], v[120:123], v[96:99], v[112:115]
	v_mfma_f32_16x16x32_bf16 v[136:139], v[108:111], v[180:183], v[136:139]
	v_mfma_f32_16x16x32_bf16 v[140:143], v[120:123], v[180:183], v[140:143]
	v_mfma_f32_16x16x32_bf16 v[0:3], v[108:111], v[188:191], v[0:3]
	v_mfma_f32_16x16x32_bf16 v[4:7], v[120:123], v[188:191], v[4:7]
	v_mfma_f32_16x16x32_bf16 v[128:131], v[108:111], v[160:163], v[128:131]
	v_mfma_f32_16x16x32_bf16 v[132:135], v[120:123], v[160:163], v[132:135]
	v_mfma_f32_16x16x32_bf16 v[88:91], v[116:119], v[156:159], v[88:91]
	v_mfma_f32_16x16x32_bf16 v[112:115], v[124:127], v[156:159], v[112:115]
	v_mfma_f32_16x16x32_bf16 v[136:139], v[116:119], v[184:187], v[136:139]
	v_mfma_f32_16x16x32_bf16 v[140:143], v[124:127], v[184:187], v[140:143]
	v_mfma_f32_16x16x32_bf16 v[0:3], v[116:119], v[192:195], v[0:3]
	v_mfma_f32_16x16x32_bf16 v[4:7], v[124:127], v[192:195], v[4:7]
	v_mfma_f32_16x16x32_bf16 v[212:215], v[116:119], v[164:167], v[128:131]
	v_mfma_f32_16x16x32_bf16 v[216:219], v[124:127], v[164:167], v[132:135]
	s_barrier
	s_add_u32 s24, s26, 0x10000
	s_addc_u32 s25, s27, 0
	s_mov_b32 m0, s19
	v_lshl_add_u64 v[108:109], s[24:25], 0, v[148:149]
	global_load_lds_dwordx4 v[108:109], off
	s_mov_b32 m0, s17
	v_lshl_add_u64 v[108:109], s[24:25], 0, v[144:145]
	global_load_lds_dwordx4 v[108:109], off
	s_waitcnt vmcnt(6)
	s_barrier
	v_mfma_f32_16x16x32_bf16 v[8:11], v[196:199], v[96:99], v[8:11]
	v_mfma_f32_16x16x32_bf16 v[12:15], v[204:207], v[96:99], v[12:15]
	v_mfma_f32_16x16x32_bf16 v[44:47], v[196:199], v[160:163], v[44:47]
	v_mfma_f32_16x16x32_bf16 v[92:95], v[204:207], v[160:163], v[92:95]
	v_mfma_f32_16x16x32_bf16 v[96:99], v[196:199], v[180:183], v[100:103]
	v_mfma_f32_16x16x32_bf16 v[100:103], v[204:207], v[180:183], v[104:107]
	v_mfma_f32_16x16x32_bf16 v[80:83], v[196:199], v[188:191], v[80:83]
	v_mfma_f32_16x16x32_bf16 v[84:87], v[204:207], v[188:191], v[84:87]
	v_mfma_f32_16x16x32_bf16 v[124:127], v[200:203], v[156:159], v[8:11]
	v_mfma_f32_16x16x32_bf16 v[156:159], v[208:211], v[156:159], v[12:15]
	v_mfma_f32_16x16x32_bf16 v[160:163], v[200:203], v[164:167], v[44:47]
	v_mfma_f32_16x16x32_bf16 v[164:167], v[208:211], v[164:167], v[92:95]
	v_mfma_f32_16x16x32_bf16 v[180:183], v[200:203], v[184:187], v[96:99]
	v_mfma_f32_16x16x32_bf16 v[100:103], v[208:211], v[184:187], v[100:103]
	v_mfma_f32_16x16x32_bf16 v[184:187], v[200:203], v[192:195], v[80:83]
	v_mfma_f32_16x16x32_bf16 v[188:191], v[208:211], v[192:195], v[84:87]
	s_barrier
	ds_read_b128 v[8:11], v221
	ds_read_b128 v[12:15], v221 offset:1024
	ds_read_b128 v[44:47], v221 offset:2048
	ds_read_b128 v[192:195], v221 offset:3072
	s_add_u32 s24, s20, 0x40000
	s_addc_u32 s25, s21, 0
	s_mov_b32 m0, s40
	v_lshl_add_u64 v[92:93], s[24:25], 0, v[150:151]
	ds_read_b128 v[80:83], v174 offset:32768
	ds_read_b128 v[84:87], v174 offset:33792
	ds_read_b128 v[104:107], v174 offset:34816
	ds_read_b128 v[196:199], v174 offset:35840
	ds_read_b128 v[108:111], v174 offset:36864
	ds_read_b128 v[200:203], v174 offset:37888
	ds_read_b128 v[204:207], v174 offset:38912
	ds_read_b128 v[208:211], v174 offset:39936
	global_load_lds_dwordx4 v[92:93], off
	s_mov_b32 m0, s41
	v_lshl_add_u64 v[92:93], s[24:25], 0, v[146:147]
	global_load_lds_dwordx4 v[92:93], off
	s_waitcnt lgkmcnt(8)
	s_barrier
;     ...
;         G_PAIR(0, 1);
; #pragma unroll 1
;         for (int t = 2; t < nt; t += 2) G_PAIR(t, 0);
;         p.epi(acc, cur, wr, wc, fr, fq);
;     __device__ __forceinline__ void epi(const f32x4 (&acc)[2][2][4][2], const Unit& u, int wr, int wc, int fr, int fq) const {
;     ...
;         const int row0 = u.pm * 256 + wr * 64 + fr, col0 = u.pn * 256 + wc * 32 + 8 * fq;
; #pragma unroll
;         for (int ai = 0; ai < 2; ++ai) {
;             u32x4 xo[4][2];
; #pragma unroll
;             for (int m = 0; m < 4; ++m)
; #pragma unroll
;                 for (int bj = 0; bj < 2; ++bj) xo[m][bj] = *(const u32x4*)(xb + (size_t)(row0 + ai * 128 + m * 16) * D + col0 + bj * 128);
	s_waitcnt lgkmcnt(0)
	v_mfma_f32_16x16x32_bf16 v[52:55], v[44:47], v[80:83], v[52:55]
	v_mfma_f32_16x16x32_bf16 v[56:59], v[8:11], v[104:107], v[56:59]
	v_mfma_f32_16x16x32_bf16 v[60:63], v[44:47], v[104:107], v[60:63]
	v_mfma_f32_16x16x32_bf16 v[64:67], v[8:11], v[108:111], v[64:67]
	v_mfma_f32_16x16x32_bf16 v[68:71], v[44:47], v[108:111], v[68:71]
	v_mfma_f32_16x16x32_bf16 v[72:75], v[8:11], v[204:207], v[72:75]
	v_mfma_f32_16x16x32_bf16 v[222:225], v[44:47], v[204:207], v[76:79]
	v_mfma_f32_16x16x32_bf16 v[48:51], v[8:11], v[80:83], v[48:51]
	v_mfma_f32_16x16x32_bf16 v[128:131], v[192:195], v[84:87], v[52:55]
	v_mfma_f32_16x16x32_bf16 v[120:123], v[12:15], v[196:199], v[56:59]
	v_mfma_f32_16x16x32_bf16 v[116:119], v[192:195], v[196:199], v[60:63]
	v_mfma_f32_16x16x32_bf16 v[96:99], v[12:15], v[200:203], v[64:67]
	v_mfma_f32_16x16x32_bf16 v[92:95], v[192:195], v[200:203], v[68:71]
	v_mfma_f32_16x16x32_bf16 v[76:79], v[12:15], v[208:211], v[72:75]
	v_mfma_f32_16x16x32_bf16 v[72:75], v[192:195], v[208:211], v[222:225]
	v_mfma_f32_16x16x32_bf16 v[132:135], v[12:15], v[84:87], v[48:51]
	s_barrier
	s_mov_b32 m0, s53
	v_lshl_add_u64 v[48:49], v[168:169], 0, s[6:7]
	ds_read_b128 v[56:59], v226
	ds_read_b128 v[222:225], v226 offset:1024
	ds_read_b128 v[60:63], v226 offset:2048
	ds_read_b128 v[226:229], v226 offset:3072
	global_load_lds_dwordx4 v[48:49], off
	s_mov_b32 m0, s51
	v_lshl_add_u64 v[48:49], v[230:231], 0, s[6:7]
	global_load_lds_dwordx4 v[48:49], off
	s_barrier
	s_waitcnt lgkmcnt(0)
	v_mfma_f32_16x16x32_bf16 v[48:51], v[56:59], v[80:83], v[152:155]
	v_mfma_f32_16x16x32_bf16 v[16:19], v[60:63], v[80:83], v[16:19]
	v_mfma_f32_16x16x32_bf16 v[20:23], v[56:59], v[104:107], v[20:23]
	v_mfma_f32_16x16x32_bf16 v[24:27], v[60:63], v[104:107], v[24:27]
	v_mfma_f32_16x16x32_bf16 v[28:31], v[56:59], v[108:111], v[28:31]
	v_mfma_f32_16x16x32_bf16 v[32:35], v[60:63], v[108:111], v[32:35]
	v_mfma_f32_16x16x32_bf16 v[36:39], v[56:59], v[204:207], v[36:39]
	v_mfma_f32_16x16x32_bf16 v[40:43], v[60:63], v[204:207], v[40:43]
	v_mfma_f32_16x16x32_bf16 v[204:207], v[222:225], v[84:87], v[48:51]
	v_mfma_f32_16x16x32_bf16 v[230:233], v[226:229], v[84:87], v[16:19]
	v_mfma_f32_16x16x32_bf16 v[108:111], v[222:225], v[196:199], v[20:23]
	v_mfma_f32_16x16x32_bf16 v[104:107], v[226:229], v[196:199], v[24:27]
	v_mfma_f32_16x16x32_bf16 v[84:87], v[222:225], v[200:203], v[28:31]
	v_mfma_f32_16x16x32_bf16 v[80:83], v[226:229], v[200:203], v[32:35]
	v_mfma_f32_16x16x32_bf16 v[68:71], v[222:225], v[208:211], v[36:39]
	v_mfma_f32_16x16x32_bf16 v[64:67], v[226:229], v[208:211], v[40:43]
	s_mov_b32 m0, s43
	v_lshl_add_u64 v[24:25], v[234:235], 0, s[6:7]
	s_barrier
	ds_read_b128 v[16:19], v174 offset:49152
	ds_read_b128 v[20:23], v174 offset:50176
	ds_read_b128 v[32:35], v174 offset:51200
	ds_read_b128 v[152:155], v174 offset:52224
	ds_read_b128 v[36:39], v174 offset:53248
	ds_read_b128 v[196:199], v174 offset:54272
	ds_read_b128 v[200:203], v174 offset:55296
	ds_read_b128 v[208:211], v174 offset:56320
	global_load_lds_dwordx4 v[24:25], off
	s_mov_b32 m0, s44
	v_lshl_add_u64 v[24:25], v[236:237], 0, s[6:7]
	global_load_lds_dwordx4 v[24:25], off
	s_barrier
	s_waitcnt lgkmcnt(0)
	v_mfma_f32_16x16x32_bf16 v[24:27], v[8:11], v[16:19], v[88:91]
	v_mfma_f32_16x16x32_bf16 v[28:31], v[44:47], v[16:19], v[112:115]
	v_mfma_f32_16x16x32_bf16 v[40:43], v[8:11], v[32:35], v[212:215]
	v_mfma_f32_16x16x32_bf16 v[88:91], v[44:47], v[32:35], v[216:219]
	v_mfma_f32_16x16x32_bf16 v[112:115], v[8:11], v[36:39], v[136:139]
	v_mfma_f32_16x16x32_bf16 v[136:139], v[44:47], v[36:39], v[140:143]
	v_mfma_f32_16x16x32_bf16 v[0:3], v[8:11], v[200:203], v[0:3]
	v_mfma_f32_16x16x32_bf16 v[4:7], v[44:47], v[200:203], v[4:7]
	v_mfma_f32_16x16x32_bf16 v[52:55], v[12:15], v[20:23], v[24:27]
	v_mfma_f32_16x16x32_bf16 v[48:51], v[192:195], v[20:23], v[28:31]
	v_mfma_f32_16x16x32_bf16 v[44:47], v[12:15], v[152:155], v[40:43]
	v_mfma_f32_16x16x32_bf16 v[40:43], v[192:195], v[152:155], v[88:91]
	v_mfma_f32_16x16x32_bf16 v[28:31], v[12:15], v[196:199], v[112:115]
	v_mfma_f32_16x16x32_bf16 v[24:27], v[192:195], v[196:199], v[136:139]
	v_mfma_f32_16x16x32_bf16 v[12:15], v[12:15], v[208:211], v[0:3]
	v_mfma_f32_16x16x32_bf16 v[8:11], v[192:195], v[208:211], v[4:7]
	s_barrier
	s_add_u32 s24, s26, 0x10080
	s_addc_u32 s25, s27, 0
	s_mov_b32 m0, s54
	v_lshl_add_u64 v[0:1], s[24:25], 0, v[148:149]
	global_load_lds_dwordx4 v[0:1], off
	s_mov_b32 m0, s52
	v_lshl_add_u64 v[0:1], s[24:25], 0, v[144:145]
	global_load_lds_dwordx4 v[0:1], off
	s_waitcnt vmcnt(6)
	s_barrier
	v_mfma_f32_16x16x32_bf16 v[0:3], v[56:59], v[16:19], v[124:127]
	v_mfma_f32_16x16x32_bf16 v[4:7], v[60:63], v[16:19], v[156:159]
	v_mfma_f32_16x16x32_bf16 v[16:19], v[56:59], v[32:35], v[160:163]
	v_mfma_f32_16x16x32_bf16 v[32:35], v[60:63], v[32:35], v[164:167]
	v_mfma_f32_16x16x32_bf16 v[88:91], v[56:59], v[36:39], v[180:183]
	v_mfma_f32_16x16x32_bf16 v[100:103], v[60:63], v[36:39], v[100:103]
	v_mfma_f32_16x16x32_bf16 v[112:115], v[56:59], v[200:203], v[184:187]
	v_mfma_f32_16x16x32_bf16 v[124:127], v[60:63], v[200:203], v[188:191]
	v_mfma_f32_16x16x32_bf16 v[60:63], v[222:225], v[20:23], v[0:3]
	v_mfma_f32_16x16x32_bf16 v[56:59], v[226:229], v[20:23], v[4:7]
	v_mfma_f32_16x16x32_bf16 v[36:39], v[222:225], v[152:155], v[16:19]
	v_mfma_f32_16x16x32_bf16 v[32:35], v[226:229], v[152:155], v[32:35]
	v_mfma_f32_16x16x32_bf16 v[20:23], v[222:225], v[196:199], v[88:91]
	v_mfma_f32_16x16x32_bf16 v[16:19], v[226:229], v[196:199], v[100:103]
	v_mfma_f32_16x16x32_bf16 v[4:7], v[222:225], v[208:211], v[112:115]
	v_mfma_f32_16x16x32_bf16 v[0:3], v[226:229], v[208:211], v[124:127]
	v_lshl_or_b32 v152, s45, 8, v172
	v_lshl_add_u32 v156, s8, 8, v170
	v_ashrrev_i32_e32 v153, 31, v152
	v_lshlrev_b64 v[190:191], 1, v[152:153]
	v_ashrrev_i32_e32 v157, 31, v156
	v_lshl_add_u64 v[154:155], s[0:1], 0, v[190:191]
	v_lshlrev_b64 v[192:193], 11, v[156:157]
	v_lshl_add_u64 v[88:89], v[154:155], 0, v[192:193]
	s_barrier
; __device__ __forceinline__ unsigned pk2(float lo, float hi) { unsigned r; asm volatile("v_cvt_pk_bf16_f32 %0, %1, %2" : "=v"(r) : "v"(lo), "v"(hi)); return r; }
; __device__ __forceinline__ unsigned pk2(float lo, float hi) { return f2bf(lo) | (f2bf(hi) << 16); }
;     __device__ __forceinline__ void epi(const f32x4 (&acc)[2][2][4][2], const Unit& u, int wr, int wc, int fr, int fq) const {
;     ...
;             for (int m = 0; m < 4; ++m)
; #pragma unroll
;                 for (int bj = 0; bj < 2; ++bj) xo[m][bj] = *(const u32x4*)(xb + (size_t)(row0 + ai * 128 + m * 16) * D + col0 + bj * 128);
; #pragma unroll
;             for (int m = 0; m < 4; ++m) {
;                 const int row = row0 + ai * 128 + m * 16; const size_t off = (size_t)row * D + col0; float ss = 0.f;
; #pragma unroll
;                 for (int bj = 0; bj < 2; ++bj) {
;                     const u32x4 o = xo[m][bj]; const f32x4 a0v = acc[ai][bj][m][0], a1v = acc[ai][bj][m][1];
;                     const float v0 = bf_lo(o.x) + coef * a0v[0], v1 = bf_hi(o.x) + coef * a0v[1], v2 = bf_lo(o.y) + coef * a0v[2], v3 = bf_hi(o.y) + coef * a0v[3];
;                     const float v4 = bf_lo(o.z) + coef * a1v[0], v5 = bf_hi(o.z) + coef * a1v[1], v6 = bf_lo(o.w) + coef * a1v[2], v7 = bf_hi(o.w) + coef * a1v[3];
;                     u32x4 w; w.x = pk2(v0, v1); w.y = pk2(v2, v3); w.z = pk2(v4, v5); w.w = pk2(v6, v7);
;                     *(u32x4*)(xb + off + bj * 128) = w;
;                     ss += ((v0 * v0 + v1 * v1) + (v2 * v2 + v3 * v3)) + ((v4 * v4 + v5 * v5) + (v6 * v6 + v7 * v7));
;                 }
;                 ss += __shfl_xor(ss, 16); ss += __shfl_xor(ss, 32);
;                 if (fq == 0) rowss[(size_t)row * 32 + u.pn * 4 + wc] = ss;
;             }
;             asm volatile("" ::: "memory");
;         }
;         ch.finish();
	v_mov_b32_e32 v214, 0x40000
	v_mov_b32_e32 v215, 0
	v_lshl_add_u64 v[212:213], v[88:89], 0, v[214:215]
	v_mov_b32_e32 v214, 0x8000
	global_load_dwordx4 v[182:185], v[88:89], off
	global_load_dwordx4 v[186:189], v[88:89], off offset:256
	v_or_b32_e32 v166, 16, v156
	v_or_b32_e32 v162, 32, v156
	v_or_b32_e32 v158, 48, v156
	v_ashrrev_i32_e32 v167, 31, v166
	v_ashrrev_i32_e32 v163, 31, v162
	v_ashrrev_i32_e32 v159, 31, v158
	v_lshlrev_b64 v[168:169], 11, v[166:167]
	v_lshlrev_b64 v[164:165], 11, v[162:163]
	v_lshlrev_b64 v[160:161], 11, v[158:159]
	v_lshl_add_u64 v[88:89], v[154:155], 0, v[168:169]
	v_lshl_add_u64 v[90:91], v[154:155], 0, v[164:165]
	v_lshl_add_u64 v[180:181], v[154:155], 0, v[160:161]
	global_load_dwordx4 v[140:143], v[88:89], off
	global_load_dwordx4 v[136:139], v[88:89], off offset:256
	global_load_dwordx4 v[124:127], v[90:91], off
	global_load_dwordx4 v[112:115], v[90:91], off offset:256
	global_load_dwordx4 v[100:103], v[180:181], off
	s_nop 0
	global_load_dwordx4 v[88:91], v[180:181], off offset:256
	global_load_dwordx4 v[216:219], v[212:213], off
	global_load_dwordx4 v[222:225], v[212:213], off offset:256
	v_lshl_add_u64 v[212:213], v[212:213], 0, v[214:215]
	global_load_dwordx4 v[226:229], v[212:213], off
	global_load_dwordx4 v[234:237], v[212:213], off offset:256
	v_lshl_add_u64 v[212:213], v[212:213], 0, v[214:215]
	global_load_dwordx4 v[238:241], v[212:213], off
	global_load_dwordx4 v[242:245], v[212:213], off offset:256
	v_lshl_add_u64 v[212:213], v[212:213], 0, v[214:215]
	global_load_dwordx4 v[246:249], v[212:213], off
	global_load_dwordx4 v[250:253], v[212:213], off offset:256
	v_lshl_add_u64 v[192:193], s[0:1], 0, v[192:193]
	v_lshl_add_u64 v[190:191], v[192:193], 0, v[190:191]
	v_cmp_lt_i32_e32 vcc, v177, v178
	s_waitcnt vmcnt(8)
	v_lshlrev_b32_e32 v181, 16, v182
	v_and_b32_e32 v182, 0xffff0000, v182
	v_lshlrev_b32_e32 v192, 16, v183
	v_and_b32_e32 v183, 0xffff0000, v183
	v_lshlrev_b32_e32 v193, 16, v184
	v_and_b32_e32 v184, 0xffff0000, v184
	v_lshlrev_b32_e32 v194, 16, v185
	v_and_b32_e32 v185, 0xffff0000, v185
	v_lshlrev_b32_e32 v195, 16, v186
	v_and_b32_e32 v186, 0xffff0000, v186
	v_lshlrev_b32_e32 v196, 16, v187
	v_and_b32_e32 v187, 0xffff0000, v187
	v_lshlrev_b32_e32 v197, 16, v188
	v_and_b32_e32 v188, 0xffff0000, v188
	v_lshlrev_b32_e32 v198, 16, v189
	v_and_b32_e32 v189, 0xffff0000, v189
	v_add_f32_e32 v133, v133, v182
	v_add_f32_e32 v135, v135, v183
	v_add_f32_e32 v182, v129, v184
	v_add_f32_e32 v131, v131, v185
	v_add_f32_e32 v185, v205, v186
	v_add_f32_e32 v187, v207, v187
	v_add_f32_e32 v188, v231, v188
	v_add_f32_e32 v189, v233, v189
	v_add_f32_e32 v132, v132, v181
	v_add_f32_e32 v134, v134, v192
	v_add_f32_e32 v181, v128, v193
	v_add_f32_e32 v183, v130, v194
	v_add_f32_e32 v184, v204, v195
	v_add_f32_e32 v186, v206, v196
	v_add_f32_e32 v192, v230, v197
	v_add_f32_e32 v193, v232, v198
	v_cvt_pk_bf16_f32 v128, v132, v133
	v_cvt_pk_bf16_f32 v129, v134, v135
	v_mul_f32_e32 v130, v133, v133
	v_mul_f32_e32 v133, v135, v135
	v_mul_f32_e32 v135, v182, v182
	v_mul_f32_e32 v194, v131, v131
	v_mul_f32_e32 v195, v185, v185
	v_mul_f32_e32 v196, v187, v187
	v_mul_f32_e32 v197, v188, v188
	v_mul_f32_e32 v198, v189, v189
	v_fmac_f32_e32 v130, v132, v132
	v_fmac_f32_e32 v133, v134, v134
	v_fmac_f32_e32 v135, v181, v181
	v_fmac_f32_e32 v194, v183, v183
	v_fmac_f32_e32 v195, v184, v184
	v_fmac_f32_e32 v196, v186, v186
	v_fmac_f32_e32 v197, v192, v192
	v_fmac_f32_e32 v198, v193, v193
	v_add_f32_e32 v130, v130, v133
	v_add_f32_e32 v132, v135, v194
	v_add_f32_e32 v133, v195, v196
	v_add_f32_e32 v134, v197, v198
	v_cndmask_b32_e32 v180, v176, v177, vcc
	v_add_f32_e32 v130, v130, v132
	v_add_f32_e32 v132, v133, v134
	v_lshlrev_b32_e32 v180, 2, v180
	v_add_f32_e32 v133, v130, v132
	ds_bpermute_b32 v134, v180, v133
	v_cmp_lt_i32_e32 vcc, v179, v178
	v_cvt_pk_bf16_f32 v130, v181, v182
	v_cvt_pk_bf16_f32 v131, v183, v131
	global_store_dwordx4 v[190:191], v[128:131], off
	v_cvt_pk_bf16_f32 v132, v184, v185
	s_nop 1
	v_cndmask_b32_e32 v128, v176, v179, vcc
	s_waitcnt lgkmcnt(0)
	v_add_f32_e32 v129, v133, v134
	v_lshlrev_b32_e32 v128, 2, v128
	ds_bpermute_b32 v130, v128, v129
	v_cvt_pk_bf16_f32 v133, v186, v187
	v_cvt_pk_bf16_f32 v134, v192, v188
	v_cvt_pk_bf16_f32 v135, v193, v189
	global_store_dwordx4 v[190:191], v[132:135], off offset:256
	s_and_saveexec_b64 s[24:25], s[4:5]
	s_cbranch_execz .LBB0_1672
	s_waitcnt lgkmcnt(0)
	v_add_f32_e32 v129, v129, v130
	s_lshl_b32 s26, s45, 2
	v_lshlrev_b64 v[130:131], 7, v[156:157]
	s_ashr_i32 s27, s26, 31
	v_lshl_add_u64 v[130:131], s[2:3], 0, v[130:131]
	v_lshl_add_u64 v[130:131], s[26:27], 2, v[130:131]
	s_lshl_b32 s8, s42, 2
	v_lshl_add_u64 v[130:131], v[130:131], 0, s[8:9]
	global_store_dword v[130:131], v129, off

.LBB0_1905:
	s_waitcnt lgkmcnt(0)
	ds_read_b128 v[0:3], v185
	ds_read_b128 v[4:7], v185 offset:1024
	ds_read_b128 v[8:11], v185 offset:2048
	ds_read_b128 v[12:15], v185 offset:3072
	s_add_u32 s24, s20, 0xb0080
	s_addc_u32 s25, s21, 0
	s_mov_b32 m0, s45
	v_lshl_add_u64 v[48:49], s[24:25], 0, v[152:153]
	ds_read_b128 v[16:19], v186
	ds_read_b128 v[20:23], v186 offset:1024
	ds_read_b128 v[24:27], v186 offset:2048
	ds_read_b128 v[28:31], v186 offset:3072
	ds_read_b128 v[32:35], v186 offset:4096
	ds_read_b128 v[36:39], v186 offset:5120
	ds_read_b128 v[40:43], v186 offset:6144
	ds_read_b128 v[44:47], v186 offset:7168
	global_load_lds_dwordx4 v[48:49], off
	s_mov_b32 m0, s46
	v_lshl_add_u64 v[48:49], s[24:25], 0, v[156:157]
	global_load_lds_dwordx4 v[48:49], off
	s_waitcnt lgkmcnt(8)
	s_barrier
	s_waitcnt lgkmcnt(0)
	v_mfma_f32_16x16x32_bf16 v[48:51], v[0:3], v[16:19], 0
	v_mfma_f32_16x16x32_bf16 v[52:55], v[8:11], v[16:19], 0
	v_mfma_f32_16x16x32_bf16 v[56:59], v[0:3], v[24:27], 0
	v_mfma_f32_16x16x32_bf16 v[60:63], v[8:11], v[24:27], 0
	v_mfma_f32_16x16x32_bf16 v[64:67], v[0:3], v[32:35], 0
	v_mfma_f32_16x16x32_bf16 v[68:71], v[8:11], v[32:35], 0
	v_mfma_f32_16x16x32_bf16 v[72:75], v[0:3], v[40:43], 0
	v_mfma_f32_16x16x32_bf16 v[76:79], v[8:11], v[40:43], 0
	v_mfma_f32_16x16x32_bf16 v[48:51], v[4:7], v[20:23], v[48:51]
	v_mfma_f32_16x16x32_bf16 v[52:55], v[12:15], v[20:23], v[52:55]
	v_mfma_f32_16x16x32_bf16 v[56:59], v[4:7], v[28:31], v[56:59]
	v_mfma_f32_16x16x32_bf16 v[60:63], v[12:15], v[28:31], v[60:63]
	v_mfma_f32_16x16x32_bf16 v[64:67], v[4:7], v[36:39], v[64:67]
	v_mfma_f32_16x16x32_bf16 v[68:71], v[12:15], v[36:39], v[68:71]
	v_mfma_f32_16x16x32_bf16 v[72:75], v[4:7], v[44:47], v[72:75]
	v_mfma_f32_16x16x32_bf16 v[76:79], v[12:15], v[44:47], v[76:79]
	s_barrier
	v_lshl_add_u64 v[180:181], s[22:23], 0, v[154:155]
	s_mov_b32 m0, s47
	v_lshl_add_u64 v[96:97], v[180:181], 0, s[12:13]
	v_lshl_add_u64 v[218:219], s[22:23], 0, v[158:159]
	ds_read_b128 v[80:83], v187
	ds_read_b128 v[84:87], v187 offset:1024
	ds_read_b128 v[88:91], v187 offset:2048
	ds_read_b128 v[92:95], v187 offset:3072
	global_load_lds_dwordx4 v[96:97], off
	s_mov_b32 m0, s48
	v_lshl_add_u64 v[96:97], v[218:219], 0, s[12:13]
	global_load_lds_dwordx4 v[96:97], off
	s_barrier
	s_waitcnt lgkmcnt(0)
	v_mfma_f32_16x16x32_bf16 v[96:99], v[80:83], v[16:19], 0
	v_mfma_f32_16x16x32_bf16 v[16:19], v[88:91], v[16:19], 0
	v_mfma_f32_16x16x32_bf16 v[100:103], v[80:83], v[24:27], 0
	v_mfma_f32_16x16x32_bf16 v[24:27], v[88:91], v[24:27], 0
	v_mfma_f32_16x16x32_bf16 v[104:107], v[80:83], v[32:35], 0
	v_mfma_f32_16x16x32_bf16 v[32:35], v[88:91], v[32:35], 0
	v_mfma_f32_16x16x32_bf16 v[108:111], v[80:83], v[40:43], 0
	v_mfma_f32_16x16x32_bf16 v[40:43], v[88:91], v[40:43], 0
	v_mfma_f32_16x16x32_bf16 v[96:99], v[84:87], v[20:23], v[96:99]
	v_mfma_f32_16x16x32_bf16 v[16:19], v[92:95], v[20:23], v[16:19]
	v_mfma_f32_16x16x32_bf16 v[20:23], v[84:87], v[28:31], v[100:103]
	v_mfma_f32_16x16x32_bf16 v[24:27], v[92:95], v[28:31], v[24:27]
	v_mfma_f32_16x16x32_bf16 v[28:31], v[84:87], v[36:39], v[104:107]
	v_mfma_f32_16x16x32_bf16 v[32:35], v[92:95], v[36:39], v[32:35]
	v_mfma_f32_16x16x32_bf16 v[36:39], v[84:87], v[44:47], v[108:111]
	v_mfma_f32_16x16x32_bf16 v[40:43], v[92:95], v[44:47], v[40:43]
	v_lshl_add_u64 v[242:243], s[20:21], 0, v[152:153]
	s_mov_b32 m0, s37
	v_lshl_add_u64 v[128:129], v[242:243], 0, s[12:13]
	v_lshl_add_u64 v[244:245], s[20:21], 0, v[156:157]
	s_barrier
	ds_read_b128 v[44:47], v186 offset:16384
	ds_read_b128 v[100:103], v186 offset:17408
	ds_read_b128 v[104:107], v186 offset:18432
	ds_read_b128 v[108:111], v186 offset:19456
	ds_read_b128 v[112:115], v186 offset:20480
	ds_read_b128 v[116:119], v186 offset:21504
	ds_read_b128 v[120:123], v186 offset:22528
	ds_read_b128 v[124:127], v186 offset:23552
	global_load_lds_dwordx4 v[128:129], off
	s_mov_b32 m0, s38
	v_lshl_add_u64 v[128:129], v[244:245], 0, s[12:13]
	global_load_lds_dwordx4 v[128:129], off
	s_barrier
	s_waitcnt lgkmcnt(0)
	v_mfma_f32_16x16x32_bf16 v[128:131], v[0:3], v[44:47], 0
	v_mfma_f32_16x16x32_bf16 v[132:135], v[8:11], v[44:47], 0
	v_mfma_f32_16x16x32_bf16 v[136:139], v[0:3], v[104:107], 0
	v_mfma_f32_16x16x32_bf16 v[140:143], v[8:11], v[104:107], 0
	v_mfma_f32_16x16x32_bf16 v[144:147], v[0:3], v[112:115], 0
	v_mfma_f32_16x16x32_bf16 v[148:151], v[8:11], v[112:115], 0
	v_mfma_f32_16x16x32_bf16 v[0:3], v[0:3], v[120:123], 0
	v_mfma_f32_16x16x32_bf16 v[8:11], v[8:11], v[120:123], 0
	v_mfma_f32_16x16x32_bf16 v[128:131], v[4:7], v[100:103], v[128:131]
	v_mfma_f32_16x16x32_bf16 v[164:167], v[12:15], v[100:103], v[132:135]
	v_mfma_f32_16x16x32_bf16 v[134:137], v[4:7], v[108:111], v[136:139]
	v_mfma_f32_16x16x32_bf16 v[138:141], v[12:15], v[108:111], v[140:143]
	v_mfma_f32_16x16x32_bf16 v[142:145], v[4:7], v[116:119], v[144:147]
	v_mfma_f32_16x16x32_bf16 v[0:3], v[4:7], v[124:127], v[0:3]
	v_mfma_f32_16x16x32_bf16 v[4:7], v[12:15], v[124:127], v[8:11]
	v_mfma_f32_16x16x32_bf16 v[146:149], v[12:15], v[116:119], v[148:151]
	s_barrier
	s_add_u32 s24, s22, 0xb0100
	s_addc_u32 s25, s23, 0
	s_add_i32 s52, s44, s36
	v_lshl_add_u64 v[8:9], s[24:25], 0, v[154:155]
	s_mov_b32 m0, s52
	s_add_i32 s53, s52, 0x2000
	global_load_lds_dwordx4 v[8:9], off
	s_mov_b32 m0, s53
	v_lshl_add_u64 v[8:9], s[24:25], 0, v[158:159]
	global_load_lds_dwordx4 v[8:9], off
	s_waitcnt vmcnt(6)
	s_barrier
	v_mfma_f32_16x16x32_bf16 v[8:11], v[80:83], v[44:47], 0
	v_mfma_f32_16x16x32_bf16 v[12:15], v[88:91], v[44:47], 0
	v_mfma_f32_16x16x32_bf16 v[44:47], v[80:83], v[104:107], 0
	v_mfma_f32_16x16x32_bf16 v[104:107], v[88:91], v[104:107], 0
	v_mfma_f32_16x16x32_bf16 v[168:171], v[80:83], v[112:115], 0
	v_mfma_f32_16x16x32_bf16 v[112:115], v[88:91], v[112:115], 0
	v_mfma_f32_16x16x32_bf16 v[80:83], v[80:83], v[120:123], 0
	v_mfma_f32_16x16x32_bf16 v[88:91], v[88:91], v[120:123], 0
	v_mfma_f32_16x16x32_bf16 v[8:11], v[84:87], v[100:103], v[8:11]
	v_mfma_f32_16x16x32_bf16 v[172:175], v[92:95], v[100:103], v[12:15]
	v_mfma_f32_16x16x32_bf16 v[176:179], v[84:87], v[108:111], v[44:47]
	v_mfma_f32_16x16x32_bf16 v[190:193], v[92:95], v[108:111], v[104:107]
	v_mfma_f32_16x16x32_bf16 v[168:171], v[84:87], v[116:119], v[168:171]
	v_mfma_f32_16x16x32_bf16 v[194:197], v[92:95], v[116:119], v[112:115]
	v_mfma_f32_16x16x32_bf16 v[198:201], v[84:87], v[124:127], v[80:83]
	v_mfma_f32_16x16x32_bf16 v[202:205], v[92:95], v[124:127], v[88:91]
	s_add_i32 s54, 0, 0x18000
	v_add_u32_e32 v132, s54, v183
	s_barrier
	ds_read_b128 v[12:15], v132
	ds_read_b128 v[206:209], v132 offset:1024
	ds_read_b128 v[44:47], v132 offset:2048
	ds_read_b128 v[210:213], v132 offset:3072
	s_add_u32 s24, s20, 0xb0100
	s_addc_u32 s25, s21, 0
	s_mov_b32 m0, s39
	v_lshl_add_u64 v[88:89], s[24:25], 0, v[152:153]
	ds_read_b128 v[80:83], v186 offset:32768
	ds_read_b128 v[84:87], v186 offset:33792
	ds_read_b128 v[100:103], v186 offset:34816
	ds_read_b128 v[214:217], v186 offset:35840
	ds_read_b128 v[120:123], v186 offset:36864
	ds_read_b128 v[222:225], v186 offset:37888
	ds_read_b128 v[124:127], v186 offset:38912
	ds_read_b128 v[226:229], v186 offset:39936
	global_load_lds_dwordx4 v[88:89], off
	s_mov_b32 m0, s40
	v_lshl_add_u64 v[88:89], s[24:25], 0, v[156:157]
	global_load_lds_dwordx4 v[88:89], off
	s_waitcnt lgkmcnt(8)
	s_barrier
	s_waitcnt lgkmcnt(0)
	v_mfma_f32_16x16x32_bf16 v[48:51], v[12:15], v[80:83], v[48:51]
	v_mfma_f32_16x16x32_bf16 v[52:55], v[44:47], v[80:83], v[52:55]
	v_mfma_f32_16x16x32_bf16 v[56:59], v[12:15], v[100:103], v[56:59]
	v_mfma_f32_16x16x32_bf16 v[60:63], v[44:47], v[100:103], v[60:63]
	v_mfma_f32_16x16x32_bf16 v[64:67], v[12:15], v[120:123], v[64:67]
	v_mfma_f32_16x16x32_bf16 v[68:71], v[44:47], v[120:123], v[68:71]
	v_mfma_f32_16x16x32_bf16 v[72:75], v[12:15], v[124:127], v[72:75]
	v_mfma_f32_16x16x32_bf16 v[230:233], v[44:47], v[124:127], v[76:79]
	v_mfma_f32_16x16x32_bf16 v[116:119], v[206:209], v[84:87], v[48:51]
	v_mfma_f32_16x16x32_bf16 v[112:115], v[210:213], v[84:87], v[52:55]
	v_mfma_f32_16x16x32_bf16 v[108:111], v[206:209], v[214:217], v[56:59]
	v_mfma_f32_16x16x32_bf16 v[104:107], v[210:213], v[214:217], v[60:63]
	v_mfma_f32_16x16x32_bf16 v[92:95], v[206:209], v[222:225], v[64:67]
	v_mfma_f32_16x16x32_bf16 v[88:91], v[210:213], v[222:225], v[68:71]
	v_mfma_f32_16x16x32_bf16 v[76:79], v[206:209], v[226:229], v[72:75]
	v_mfma_f32_16x16x32_bf16 v[72:75], v[210:213], v[226:229], v[230:233]
	s_barrier
	s_add_i32 s56, 0, 0x1c000
	s_add_i32 s54, s54, s36
	v_add_u32_e32 v133, s56, v183
	v_lshl_add_u64 v[48:49], v[180:181], 0, s[14:15]
	s_mov_b32 m0, s54
	s_add_i32 s55, s54, 0x2000
	ds_read_b128 v[56:59], v133
	ds_read_b128 v[230:233], v133 offset:1024
	ds_read_b128 v[60:63], v133 offset:2048
	ds_read_b128 v[234:237], v133 offset:3072
	global_load_lds_dwordx4 v[48:49], off
	s_mov_b32 m0, s55
	v_lshl_add_u64 v[48:49], v[218:219], 0, s[14:15]
	global_load_lds_dwordx4 v[48:49], off
	s_barrier
	s_waitcnt lgkmcnt(0)
	v_mfma_f32_16x16x32_bf16 v[48:51], v[56:59], v[80:83], v[96:99]
	v_mfma_f32_16x16x32_bf16 v[16:19], v[60:63], v[80:83], v[16:19]
	v_mfma_f32_16x16x32_bf16 v[20:23], v[56:59], v[100:103], v[20:23]
	v_mfma_f32_16x16x32_bf16 v[24:27], v[60:63], v[100:103], v[24:27]
	v_mfma_f32_16x16x32_bf16 v[28:31], v[56:59], v[120:123], v[28:31]
	v_mfma_f32_16x16x32_bf16 v[32:35], v[60:63], v[120:123], v[32:35]
	v_mfma_f32_16x16x32_bf16 v[36:39], v[56:59], v[124:127], v[36:39]
	v_mfma_f32_16x16x32_bf16 v[40:43], v[60:63], v[124:127], v[40:43]
	v_mfma_f32_16x16x32_bf16 v[124:127], v[230:233], v[84:87], v[48:51]
	v_mfma_f32_16x16x32_bf16 v[120:123], v[234:237], v[84:87], v[16:19]
	v_mfma_f32_16x16x32_bf16 v[100:103], v[230:233], v[214:217], v[20:23]
	v_mfma_f32_16x16x32_bf16 v[96:99], v[234:237], v[214:217], v[24:27]
	v_mfma_f32_16x16x32_bf16 v[84:87], v[230:233], v[222:225], v[28:31]
	v_mfma_f32_16x16x32_bf16 v[80:83], v[234:237], v[222:225], v[32:35]
	v_mfma_f32_16x16x32_bf16 v[68:71], v[230:233], v[226:229], v[36:39]
	v_mfma_f32_16x16x32_bf16 v[64:67], v[234:237], v[226:229], v[40:43]
	s_mov_b32 m0, s42
	v_lshl_add_u64 v[20:21], v[242:243], 0, s[14:15]
	s_barrier
	ds_read_b128 v[16:19], v186 offset:49152
	ds_read_b128 v[24:27], v186 offset:50176
	ds_read_b128 v[32:35], v186 offset:51200
	ds_read_b128 v[214:217], v186 offset:52224
	ds_read_b128 v[40:43], v186 offset:53248
	ds_read_b128 v[222:225], v186 offset:54272
	ds_read_b128 v[226:229], v186 offset:55296
	ds_read_b128 v[238:241], v186 offset:56320
	global_load_lds_dwordx4 v[20:21], off
	s_mov_b32 m0, s43
	v_lshl_add_u64 v[20:21], v[244:245], 0, s[14:15]
	global_load_lds_dwordx4 v[20:21], off
	s_barrier
	s_waitcnt lgkmcnt(0)
	v_mfma_f32_16x16x32_bf16 v[20:23], v[12:15], v[16:19], v[128:131]
	v_mfma_f32_16x16x32_bf16 v[28:31], v[44:47], v[16:19], v[164:167]
	v_mfma_f32_16x16x32_bf16 v[36:39], v[12:15], v[32:35], v[134:137]
	v_mfma_f32_16x16x32_bf16 v[128:131], v[44:47], v[32:35], v[138:141]
	v_mfma_f32_16x16x32_bf16 v[134:137], v[12:15], v[40:43], v[142:145]
	v_mfma_f32_16x16x32_bf16 v[138:141], v[44:47], v[40:43], v[146:149]
	v_mfma_f32_16x16x32_bf16 v[0:3], v[12:15], v[226:229], v[0:3]
	v_mfma_f32_16x16x32_bf16 v[4:7], v[44:47], v[226:229], v[4:7]
	v_mfma_f32_16x16x32_bf16 v[52:55], v[206:209], v[24:27], v[20:23]
	v_mfma_f32_16x16x32_bf16 v[48:51], v[210:213], v[24:27], v[28:31]
	v_mfma_f32_16x16x32_bf16 v[44:47], v[206:209], v[214:217], v[36:39]
	v_mfma_f32_16x16x32_bf16 v[36:39], v[210:213], v[214:217], v[128:131]
	v_mfma_f32_16x16x32_bf16 v[28:31], v[206:209], v[222:225], v[134:137]
	v_mfma_f32_16x16x32_bf16 v[20:23], v[210:213], v[222:225], v[138:141]
	v_mfma_f32_16x16x32_bf16 v[12:15], v[206:209], v[238:241], v[0:3]
	v_mfma_f32_16x16x32_bf16 v[4:7], v[210:213], v[238:241], v[4:7]
	s_barrier
	s_add_u32 s24, s22, 0xb0180
	s_addc_u32 s25, s23, 0
	s_add_i32 s56, s56, s36
	v_lshl_add_u64 v[0:1], s[24:25], 0, v[154:155]
	s_mov_b32 m0, s56
	s_add_i32 s57, s56, 0x2000
	global_load_lds_dwordx4 v[0:1], off
	v_lshl_add_u64 v[0:1], s[24:25], 0, v[158:159]
	s_mov_b32 m0, s57
	s_mov_b64 s[24:25], 0xb0180
	global_load_lds_dwordx4 v[0:1], off
	s_waitcnt vmcnt(6)
	s_barrier
	v_mfma_f32_16x16x32_bf16 v[0:3], v[56:59], v[16:19], v[8:11]
	v_mfma_f32_16x16x32_bf16 v[8:11], v[60:63], v[16:19], v[172:175]
	v_mfma_f32_16x16x32_bf16 v[16:19], v[56:59], v[32:35], v[176:179]
	v_mfma_f32_16x16x32_bf16 v[32:35], v[60:63], v[32:35], v[190:193]
	v_mfma_f32_16x16x32_bf16 v[128:131], v[56:59], v[40:43], v[168:171]
	v_mfma_f32_16x16x32_bf16 v[134:137], v[60:63], v[40:43], v[194:197]
	v_mfma_f32_16x16x32_bf16 v[138:141], v[56:59], v[226:229], v[198:201]
	v_mfma_f32_16x16x32_bf16 v[142:145], v[60:63], v[226:229], v[202:205]
	v_mfma_f32_16x16x32_bf16 v[60:63], v[230:233], v[24:27], v[0:3]
	v_mfma_f32_16x16x32_bf16 v[56:59], v[234:237], v[24:27], v[8:11]
	v_mfma_f32_16x16x32_bf16 v[40:43], v[230:233], v[214:217], v[16:19]
	v_mfma_f32_16x16x32_bf16 v[32:35], v[234:237], v[214:217], v[32:35]
	v_mfma_f32_16x16x32_bf16 v[24:27], v[230:233], v[222:225], v[128:131]
	v_mfma_f32_16x16x32_bf16 v[16:19], v[234:237], v[222:225], v[134:137]
	v_mfma_f32_16x16x32_bf16 v[8:11], v[230:233], v[238:241], v[138:141]
	v_mfma_f32_16x16x32_bf16 v[0:3], v[234:237], v[238:241], v[142:145]
	v_lshl_add_u64 v[128:129], s[20:21], 0, v[160:161]
	v_lshl_add_u64 v[130:131], s[20:21], 0, v[162:163]
	s_mov_b32 s58, 0
	s_barrier
.LBB0_1906:
	ds_read_b128 v[134:137], v185
	ds_read_b128 v[138:141], v185 offset:1024
	ds_read_b128 v[142:145], v185 offset:2048
	ds_read_b128 v[146:149], v185 offset:3072
	s_mov_b32 m0, s45
	v_lshl_add_u64 v[150:151], v[128:129], 0, s[24:25]
	ds_read_b128 v[164:167], v186
	ds_read_b128 v[168:171], v186 offset:1024
	ds_read_b128 v[172:175], v186 offset:2048
	ds_read_b128 v[176:179], v186 offset:3072
	ds_read_b128 v[190:193], v186 offset:4096
	ds_read_b128 v[194:197], v186 offset:5120
	ds_read_b128 v[198:201], v186 offset:6144
	ds_read_b128 v[202:205], v186 offset:7168
	global_load_lds_dwordx4 v[150:151], off
	s_mov_b32 m0, s46
	v_lshl_add_u64 v[150:151], v[130:131], 0, s[24:25]
	global_load_lds_dwordx4 v[150:151], off
	s_waitcnt lgkmcnt(8)
	s_barrier
	s_waitcnt lgkmcnt(0)
	v_mfma_f32_16x16x32_bf16 v[116:119], v[134:137], v[164:167], v[116:119]
	s_add_i32 s26, s24, 0xfff50080
	v_mfma_f32_16x16x32_bf16 v[112:115], v[142:145], v[164:167], v[112:115]
	s_cmp_eq_u32 s58, 40
	v_mfma_f32_16x16x32_bf16 v[108:111], v[134:137], v[172:175], v[108:111]
	s_cselect_b32 s59, s19, s21
	v_mfma_f32_16x16x32_bf16 v[104:107], v[142:145], v[172:175], v[104:107]
	s_cselect_b32 s60, s18, s20
	v_mfma_f32_16x16x32_bf16 v[92:95], v[134:137], v[190:193], v[92:95]
	s_cselect_b32 s27, s7, s23
	v_mfma_f32_16x16x32_bf16 v[88:91], v[142:145], v[190:193], v[88:91]
	s_cselect_b32 s61, s6, s22
	v_mfma_f32_16x16x32_bf16 v[76:79], v[134:137], v[198:201], v[76:79]
	v_mfma_f32_16x16x32_bf16 v[72:75], v[142:145], v[198:201], v[72:75]
	v_mfma_f32_16x16x32_bf16 v[116:119], v[138:141], v[168:171], v[116:119]
	v_mfma_f32_16x16x32_bf16 v[112:115], v[146:149], v[168:171], v[112:115]
	v_mfma_f32_16x16x32_bf16 v[108:111], v[138:141], v[176:179], v[108:111]
	v_mfma_f32_16x16x32_bf16 v[104:107], v[146:149], v[176:179], v[104:107]
	v_mfma_f32_16x16x32_bf16 v[92:95], v[138:141], v[194:197], v[92:95]
	v_mfma_f32_16x16x32_bf16 v[88:91], v[146:149], v[194:197], v[88:91]
	v_mfma_f32_16x16x32_bf16 v[76:79], v[138:141], v[202:205], v[76:79]
	v_mfma_f32_16x16x32_bf16 v[72:75], v[146:149], v[202:205], v[72:75]
	s_barrier
	s_cselect_b32 s62, 0, s26
	s_add_u32 s26, s61, s62
	s_addc_u32 s27, s27, 0
	s_mov_b32 m0, s47
	v_lshl_add_u64 v[150:151], s[26:27], 0, v[154:155]
	ds_read_b128 v[206:209], v187
	ds_read_b128 v[210:213], v187 offset:1024
	ds_read_b128 v[214:217], v187 offset:2048
	ds_read_b128 v[222:225], v187 offset:3072
	global_load_lds_dwordx4 v[150:151], off
	s_mov_b32 m0, s48
	v_lshl_add_u64 v[180:181], s[26:27], 0, v[158:159]
	global_load_lds_dwordx4 v[180:181], off
	s_barrier
	s_waitcnt lgkmcnt(0)
	v_mfma_f32_16x16x32_bf16 v[124:127], v[206:209], v[164:167], v[124:127]
	v_mfma_f32_16x16x32_bf16 v[120:123], v[214:217], v[164:167], v[120:123]
	v_mfma_f32_16x16x32_bf16 v[100:103], v[206:209], v[172:175], v[100:103]
	v_mfma_f32_16x16x32_bf16 v[96:99], v[214:217], v[172:175], v[96:99]
	v_mfma_f32_16x16x32_bf16 v[84:87], v[206:209], v[190:193], v[84:87]
	v_mfma_f32_16x16x32_bf16 v[80:83], v[214:217], v[190:193], v[80:83]
	v_mfma_f32_16x16x32_bf16 v[68:71], v[206:209], v[198:201], v[68:71]
	v_mfma_f32_16x16x32_bf16 v[64:67], v[214:217], v[198:201], v[64:67]
	v_mfma_f32_16x16x32_bf16 v[124:127], v[210:213], v[168:171], v[124:127]
	v_mfma_f32_16x16x32_bf16 v[120:123], v[222:225], v[168:171], v[120:123]
	v_mfma_f32_16x16x32_bf16 v[100:103], v[210:213], v[176:179], v[100:103]
	v_mfma_f32_16x16x32_bf16 v[96:99], v[222:225], v[176:179], v[96:99]
	v_mfma_f32_16x16x32_bf16 v[84:87], v[210:213], v[194:197], v[84:87]
	v_mfma_f32_16x16x32_bf16 v[80:83], v[222:225], v[194:197], v[80:83]
	v_mfma_f32_16x16x32_bf16 v[68:71], v[210:213], v[202:205], v[68:71]
	v_mfma_f32_16x16x32_bf16 v[64:67], v[222:225], v[202:205], v[64:67]
	s_add_u32 s60, s60, s62
	s_addc_u32 s61, s59, 0
	s_mov_b32 m0, s37
	v_lshl_add_u64 v[218:219], s[60:61], 0, v[152:153]
	s_barrier
	ds_read_b128 v[164:167], v186 offset:16384
	ds_read_b128 v[168:171], v186 offset:17408
	ds_read_b128 v[172:175], v186 offset:18432
	ds_read_b128 v[176:179], v186 offset:19456
	ds_read_b128 v[190:193], v186 offset:20480
	ds_read_b128 v[194:197], v186 offset:21504
	ds_read_b128 v[198:201], v186 offset:22528
	ds_read_b128 v[202:205], v186 offset:23552
	global_load_lds_dwordx4 v[218:219], off
	s_mov_b32 m0, s38
	v_lshl_add_u64 v[226:227], s[60:61], 0, v[156:157]
	global_load_lds_dwordx4 v[226:227], off
	s_barrier
	s_waitcnt lgkmcnt(0)
	v_mfma_f32_16x16x32_bf16 v[52:55], v[134:137], v[164:167], v[52:55]
	v_mfma_f32_16x16x32_bf16 v[48:51], v[142:145], v[164:167], v[48:51]
	v_mfma_f32_16x16x32_bf16 v[44:47], v[134:137], v[172:175], v[44:47]
	v_mfma_f32_16x16x32_bf16 v[36:39], v[142:145], v[172:175], v[36:39]
	v_mfma_f32_16x16x32_bf16 v[28:31], v[134:137], v[190:193], v[28:31]
	v_mfma_f32_16x16x32_bf16 v[20:23], v[142:145], v[190:193], v[20:23]
	v_mfma_f32_16x16x32_bf16 v[12:15], v[134:137], v[198:201], v[12:15]
	v_mfma_f32_16x16x32_bf16 v[4:7], v[142:145], v[198:201], v[4:7]
	v_mfma_f32_16x16x32_bf16 v[52:55], v[138:141], v[168:171], v[52:55]
	v_mfma_f32_16x16x32_bf16 v[48:51], v[146:149], v[168:171], v[48:51]
	v_mfma_f32_16x16x32_bf16 v[44:47], v[138:141], v[176:179], v[44:47]
	v_mfma_f32_16x16x32_bf16 v[36:39], v[146:149], v[176:179], v[36:39]
	v_mfma_f32_16x16x32_bf16 v[28:31], v[138:141], v[194:197], v[28:31]
	v_mfma_f32_16x16x32_bf16 v[20:23], v[146:149], v[194:197], v[20:23]
	v_mfma_f32_16x16x32_bf16 v[12:15], v[138:141], v[202:205], v[12:15]
	v_mfma_f32_16x16x32_bf16 v[4:7], v[146:149], v[202:205], v[4:7]
	s_barrier
	s_add_u32 s62, s26, 0xb0000
	s_addc_u32 s63, s27, 0
	s_mov_b32 m0, s52
	v_lshl_add_u64 v[134:135], s[62:63], 0, v[154:155]
	global_load_lds_dwordx4 v[134:135], off
	s_mov_b32 m0, s53
	v_lshl_add_u64 v[134:135], s[62:63], 0, v[158:159]
	global_load_lds_dwordx4 v[134:135], off
	s_waitcnt vmcnt(6)
	s_barrier
	v_mfma_f32_16x16x32_bf16 v[60:63], v[206:209], v[164:167], v[60:63]
	v_mfma_f32_16x16x32_bf16 v[56:59], v[214:217], v[164:167], v[56:59]
	v_mfma_f32_16x16x32_bf16 v[40:43], v[206:209], v[172:175], v[40:43]
	v_mfma_f32_16x16x32_bf16 v[32:35], v[214:217], v[172:175], v[32:35]
	v_mfma_f32_16x16x32_bf16 v[24:27], v[206:209], v[190:193], v[24:27]
	v_mfma_f32_16x16x32_bf16 v[16:19], v[214:217], v[190:193], v[16:19]
	v_mfma_f32_16x16x32_bf16 v[8:11], v[206:209], v[198:201], v[8:11]
	v_mfma_f32_16x16x32_bf16 v[0:3], v[214:217], v[198:201], v[0:3]
	v_mfma_f32_16x16x32_bf16 v[60:63], v[210:213], v[168:171], v[60:63]
	v_mfma_f32_16x16x32_bf16 v[56:59], v[222:225], v[168:171], v[56:59]
	v_mfma_f32_16x16x32_bf16 v[40:43], v[210:213], v[176:179], v[40:43]
	v_mfma_f32_16x16x32_bf16 v[32:35], v[222:225], v[176:179], v[32:35]
	v_mfma_f32_16x16x32_bf16 v[24:27], v[210:213], v[194:197], v[24:27]
	v_mfma_f32_16x16x32_bf16 v[16:19], v[222:225], v[194:197], v[16:19]
	v_mfma_f32_16x16x32_bf16 v[8:11], v[210:213], v[202:205], v[8:11]
	v_mfma_f32_16x16x32_bf16 v[0:3], v[222:225], v[202:205], v[0:3]
	s_barrier
	ds_read_b128 v[134:137], v132
	ds_read_b128 v[138:141], v132 offset:1024
	ds_read_b128 v[142:145], v132 offset:2048
	ds_read_b128 v[146:149], v132 offset:3072
	s_add_u32 s60, s60, 0xb0000
	s_addc_u32 s61, s61, 0
	s_mov_b32 m0, s39
	v_lshl_add_u64 v[206:207], s[60:61], 0, v[152:153]
	ds_read_b128 v[164:167], v186 offset:32768
	ds_read_b128 v[168:171], v186 offset:33792
	ds_read_b128 v[172:175], v186 offset:34816
	ds_read_b128 v[176:179], v186 offset:35840
	ds_read_b128 v[190:193], v186 offset:36864
	ds_read_b128 v[194:197], v186 offset:37888
	ds_read_b128 v[198:201], v186 offset:38912
	ds_read_b128 v[202:205], v186 offset:39936
	global_load_lds_dwordx4 v[206:207], off
	s_mov_b32 m0, s40
	v_lshl_add_u64 v[206:207], s[60:61], 0, v[156:157]
	global_load_lds_dwordx4 v[206:207], off
	s_waitcnt lgkmcnt(8)
	s_barrier
	s_waitcnt lgkmcnt(0)
	v_mfma_f32_16x16x32_bf16 v[116:119], v[134:137], v[164:167], v[116:119]
	v_mfma_f32_16x16x32_bf16 v[112:115], v[142:145], v[164:167], v[112:115]
	v_mfma_f32_16x16x32_bf16 v[108:111], v[134:137], v[172:175], v[108:111]
	v_mfma_f32_16x16x32_bf16 v[104:107], v[142:145], v[172:175], v[104:107]
	v_mfma_f32_16x16x32_bf16 v[92:95], v[134:137], v[190:193], v[92:95]
	v_mfma_f32_16x16x32_bf16 v[88:91], v[142:145], v[190:193], v[88:91]
	v_mfma_f32_16x16x32_bf16 v[76:79], v[134:137], v[198:201], v[76:79]
	v_mfma_f32_16x16x32_bf16 v[72:75], v[142:145], v[198:201], v[72:75]
	v_mfma_f32_16x16x32_bf16 v[116:119], v[138:141], v[168:171], v[116:119]
	v_mfma_f32_16x16x32_bf16 v[112:115], v[146:149], v[168:171], v[112:115]
	v_mfma_f32_16x16x32_bf16 v[108:111], v[138:141], v[176:179], v[108:111]
	v_mfma_f32_16x16x32_bf16 v[104:107], v[146:149], v[176:179], v[104:107]
	v_mfma_f32_16x16x32_bf16 v[92:95], v[138:141], v[194:197], v[92:95]
	v_mfma_f32_16x16x32_bf16 v[88:91], v[146:149], v[194:197], v[88:91]
	v_mfma_f32_16x16x32_bf16 v[76:79], v[138:141], v[202:205], v[76:79]
	v_mfma_f32_16x16x32_bf16 v[72:75], v[146:149], v[202:205], v[72:75]
	s_barrier
	s_mov_b32 m0, s54
	v_lshl_add_u64 v[150:151], v[150:151], 0, s[10:11]
	ds_read_b128 v[206:209], v133
	ds_read_b128 v[210:213], v133 offset:1024
	ds_read_b128 v[214:217], v133 offset:2048
	ds_read_b128 v[222:225], v133 offset:3072
	global_load_lds_dwordx4 v[150:151], off
	s_mov_b32 m0, s55
	v_lshl_add_u64 v[150:151], v[180:181], 0, s[10:11]
	global_load_lds_dwordx4 v[150:151], off
	s_barrier
	s_waitcnt lgkmcnt(0)
	v_mfma_f32_16x16x32_bf16 v[124:127], v[206:209], v[164:167], v[124:127]
	v_mfma_f32_16x16x32_bf16 v[120:123], v[214:217], v[164:167], v[120:123]
	v_mfma_f32_16x16x32_bf16 v[100:103], v[206:209], v[172:175], v[100:103]
	v_mfma_f32_16x16x32_bf16 v[96:99], v[214:217], v[172:175], v[96:99]
	v_mfma_f32_16x16x32_bf16 v[84:87], v[206:209], v[190:193], v[84:87]
	v_mfma_f32_16x16x32_bf16 v[80:83], v[214:217], v[190:193], v[80:83]
	v_mfma_f32_16x16x32_bf16 v[68:71], v[206:209], v[198:201], v[68:71]
	v_mfma_f32_16x16x32_bf16 v[64:67], v[214:217], v[198:201], v[64:67]
	v_mfma_f32_16x16x32_bf16 v[124:127], v[210:213], v[168:171], v[124:127]
	v_mfma_f32_16x16x32_bf16 v[120:123], v[222:225], v[168:171], v[120:123]
	v_mfma_f32_16x16x32_bf16 v[100:103], v[210:213], v[176:179], v[100:103]
	v_mfma_f32_16x16x32_bf16 v[96:99], v[222:225], v[176:179], v[96:99]
	v_mfma_f32_16x16x32_bf16 v[84:87], v[210:213], v[194:197], v[84:87]
	v_mfma_f32_16x16x32_bf16 v[80:83], v[222:225], v[194:197], v[80:83]
	v_mfma_f32_16x16x32_bf16 v[68:71], v[210:213], v[202:205], v[68:71]
	v_mfma_f32_16x16x32_bf16 v[64:67], v[222:225], v[202:205], v[64:67]
	s_mov_b32 m0, s42
	v_lshl_add_u64 v[150:151], v[218:219], 0, s[10:11]
	s_barrier
	ds_read_b128 v[164:167], v186 offset:49152
	ds_read_b128 v[168:171], v186 offset:50176
	ds_read_b128 v[172:175], v186 offset:51200
	ds_read_b128 v[176:179], v186 offset:52224
	ds_read_b128 v[190:193], v186 offset:53248
	ds_read_b128 v[194:197], v186 offset:54272
	ds_read_b128 v[198:201], v186 offset:55296
	ds_read_b128 v[202:205], v186 offset:56320
	global_load_lds_dwordx4 v[150:151], off
	s_mov_b32 m0, s43
	v_lshl_add_u64 v[150:151], v[226:227], 0, s[10:11]
	global_load_lds_dwordx4 v[150:151], off
	s_barrier
	s_waitcnt lgkmcnt(0)
	v_mfma_f32_16x16x32_bf16 v[52:55], v[134:137], v[164:167], v[52:55]
	v_mfma_f32_16x16x32_bf16 v[48:51], v[142:145], v[164:167], v[48:51]
	v_mfma_f32_16x16x32_bf16 v[44:47], v[134:137], v[172:175], v[44:47]
	v_mfma_f32_16x16x32_bf16 v[36:39], v[142:145], v[172:175], v[36:39]
	v_mfma_f32_16x16x32_bf16 v[28:31], v[134:137], v[190:193], v[28:31]
	v_mfma_f32_16x16x32_bf16 v[20:23], v[142:145], v[190:193], v[20:23]
	v_mfma_f32_16x16x32_bf16 v[12:15], v[134:137], v[198:201], v[12:15]
	v_mfma_f32_16x16x32_bf16 v[4:7], v[142:145], v[198:201], v[4:7]
	v_mfma_f32_16x16x32_bf16 v[52:55], v[138:141], v[168:171], v[52:55]
	v_mfma_f32_16x16x32_bf16 v[48:51], v[146:149], v[168:171], v[48:51]
	v_mfma_f32_16x16x32_bf16 v[44:47], v[138:141], v[176:179], v[44:47]
	v_mfma_f32_16x16x32_bf16 v[36:39], v[146:149], v[176:179], v[36:39]
	v_mfma_f32_16x16x32_bf16 v[28:31], v[138:141], v[194:197], v[28:31]
	v_mfma_f32_16x16x32_bf16 v[20:23], v[146:149], v[194:197], v[20:23]
	v_mfma_f32_16x16x32_bf16 v[12:15], v[138:141], v[202:205], v[12:15]
	v_mfma_f32_16x16x32_bf16 v[4:7], v[146:149], v[202:205], v[4:7]
	s_barrier
	s_add_u32 s26, s26, 0xb0080
	s_addc_u32 s27, s27, 0
	s_mov_b32 m0, s56
	v_lshl_add_u64 v[134:135], s[26:27], 0, v[154:155]
	global_load_lds_dwordx4 v[134:135], off
	s_mov_b32 m0, s57
	v_lshl_add_u64 v[134:135], s[26:27], 0, v[158:159]
	global_load_lds_dwordx4 v[134:135], off
	s_waitcnt vmcnt(6)
	s_barrier
	v_mfma_f32_16x16x32_bf16 v[60:63], v[206:209], v[164:167], v[60:63]
	v_mfma_f32_16x16x32_bf16 v[56:59], v[214:217], v[164:167], v[56:59]
	v_mfma_f32_16x16x32_bf16 v[40:43], v[206:209], v[172:175], v[40:43]
	v_mfma_f32_16x16x32_bf16 v[32:35], v[214:217], v[172:175], v[32:35]
	v_mfma_f32_16x16x32_bf16 v[24:27], v[206:209], v[190:193], v[24:27]
	v_mfma_f32_16x16x32_bf16 v[16:19], v[214:217], v[190:193], v[16:19]
	v_mfma_f32_16x16x32_bf16 v[8:11], v[206:209], v[198:201], v[8:11]
	v_mfma_f32_16x16x32_bf16 v[0:3], v[214:217], v[198:201], v[0:3]
	v_mfma_f32_16x16x32_bf16 v[60:63], v[210:213], v[168:171], v[60:63]
	v_mfma_f32_16x16x32_bf16 v[56:59], v[222:225], v[168:171], v[56:59]
	v_mfma_f32_16x16x32_bf16 v[40:43], v[210:213], v[176:179], v[40:43]
	v_mfma_f32_16x16x32_bf16 v[32:35], v[222:225], v[176:179], v[32:35]
	v_mfma_f32_16x16x32_bf16 v[24:27], v[210:213], v[194:197], v[24:27]
	v_mfma_f32_16x16x32_bf16 v[16:19], v[222:225], v[194:197], v[16:19]
	v_mfma_f32_16x16x32_bf16 v[8:11], v[210:213], v[202:205], v[8:11]
	v_mfma_f32_16x16x32_bf16 v[0:3], v[222:225], v[202:205], v[0:3]
	s_add_i32 s58, s58, 2
	s_add_u32 s24, s24, 0x100
	s_addc_u32 s25, s25, 0
	s_cmp_gt_u32 s58, 39
	s_barrier
	s_cbranch_scc0 .LBB0_1906
	ds_read_b128 v[134:137], v185
	ds_read_b128 v[138:141], v185 offset:1024
	ds_read_b128 v[142:145], v185 offset:2048
	ds_read_b128 v[146:149], v185 offset:3072
	s_mov_b32 m0, s45
	v_lshl_add_u64 v[150:151], v[128:129], 0, s[24:25]
	ds_read_b128 v[164:167], v186
	ds_read_b128 v[168:171], v186 offset:1024
	ds_read_b128 v[172:175], v186 offset:2048
	ds_read_b128 v[176:179], v186 offset:3072
	ds_read_b128 v[190:193], v186 offset:4096
	ds_read_b128 v[194:197], v186 offset:5120
	ds_read_b128 v[198:201], v186 offset:6144
	ds_read_b128 v[202:205], v186 offset:7168
	global_load_lds_dwordx4 v[150:151], off
	s_mov_b32 m0, s46
	v_lshl_add_u64 v[150:151], v[130:131], 0, s[24:25]
	global_load_lds_dwordx4 v[150:151], off
	s_waitcnt lgkmcnt(8)
	s_barrier
	s_waitcnt lgkmcnt(0)
	v_mfma_f32_16x16x32_bf16 v[116:119], v[134:137], v[164:167], v[116:119]
	s_add_i32 s26, s24, 0xfff50080
	v_mfma_f32_16x16x32_bf16 v[112:115], v[142:145], v[164:167], v[112:115]
	s_cmp_eq_u32 s58, 40
	v_mfma_f32_16x16x32_bf16 v[108:111], v[134:137], v[172:175], v[108:111]
	s_cselect_b32 s59, s19, s21
	v_mfma_f32_16x16x32_bf16 v[104:107], v[142:145], v[172:175], v[104:107]
	s_cselect_b32 s60, s18, s20
	v_mfma_f32_16x16x32_bf16 v[92:95], v[134:137], v[190:193], v[92:95]
	s_cselect_b32 s27, s7, s23
	v_mfma_f32_16x16x32_bf16 v[88:91], v[142:145], v[190:193], v[88:91]
	s_cselect_b32 s61, s6, s22
	v_mfma_f32_16x16x32_bf16 v[76:79], v[134:137], v[198:201], v[76:79]
	v_mfma_f32_16x16x32_bf16 v[72:75], v[142:145], v[198:201], v[72:75]
	v_mfma_f32_16x16x32_bf16 v[116:119], v[138:141], v[168:171], v[116:119]
	v_mfma_f32_16x16x32_bf16 v[112:115], v[146:149], v[168:171], v[112:115]
	v_mfma_f32_16x16x32_bf16 v[108:111], v[138:141], v[176:179], v[108:111]
	v_mfma_f32_16x16x32_bf16 v[104:107], v[146:149], v[176:179], v[104:107]
	v_mfma_f32_16x16x32_bf16 v[92:95], v[138:141], v[194:197], v[92:95]
	v_mfma_f32_16x16x32_bf16 v[88:91], v[146:149], v[194:197], v[88:91]
	v_mfma_f32_16x16x32_bf16 v[76:79], v[138:141], v[202:205], v[76:79]
	v_mfma_f32_16x16x32_bf16 v[72:75], v[146:149], v[202:205], v[72:75]
	s_barrier
	s_cselect_b32 s62, 0, s26
	s_add_u32 s26, s61, s62
	s_addc_u32 s27, s27, 0
	s_mov_b32 m0, s47
	v_lshl_add_u64 v[150:151], s[26:27], 0, v[154:155]
	ds_read_b128 v[206:209], v187
	ds_read_b128 v[210:213], v187 offset:1024
	ds_read_b128 v[214:217], v187 offset:2048
	ds_read_b128 v[222:225], v187 offset:3072
	global_load_lds_dwordx4 v[150:151], off
	s_mov_b32 m0, s48
	v_lshl_add_u64 v[180:181], s[26:27], 0, v[158:159]
	global_load_lds_dwordx4 v[180:181], off
	s_barrier
	s_waitcnt lgkmcnt(0)
	v_mfma_f32_16x16x32_bf16 v[124:127], v[206:209], v[164:167], v[124:127]
	v_mfma_f32_16x16x32_bf16 v[120:123], v[214:217], v[164:167], v[120:123]
	v_mfma_f32_16x16x32_bf16 v[100:103], v[206:209], v[172:175], v[100:103]
	v_mfma_f32_16x16x32_bf16 v[96:99], v[214:217], v[172:175], v[96:99]
	v_mfma_f32_16x16x32_bf16 v[84:87], v[206:209], v[190:193], v[84:87]
	v_mfma_f32_16x16x32_bf16 v[80:83], v[214:217], v[190:193], v[80:83]
	v_mfma_f32_16x16x32_bf16 v[68:71], v[206:209], v[198:201], v[68:71]
	v_mfma_f32_16x16x32_bf16 v[64:67], v[214:217], v[198:201], v[64:67]
	v_mfma_f32_16x16x32_bf16 v[124:127], v[210:213], v[168:171], v[124:127]
	v_mfma_f32_16x16x32_bf16 v[120:123], v[222:225], v[168:171], v[120:123]
	v_mfma_f32_16x16x32_bf16 v[100:103], v[210:213], v[176:179], v[100:103]
	v_mfma_f32_16x16x32_bf16 v[96:99], v[222:225], v[176:179], v[96:99]
	v_mfma_f32_16x16x32_bf16 v[84:87], v[210:213], v[194:197], v[84:87]
	v_mfma_f32_16x16x32_bf16 v[80:83], v[222:225], v[194:197], v[80:83]
	v_mfma_f32_16x16x32_bf16 v[68:71], v[210:213], v[202:205], v[68:71]
	v_mfma_f32_16x16x32_bf16 v[64:67], v[222:225], v[202:205], v[64:67]
	s_add_u32 s60, s60, s62
	s_addc_u32 s61, s59, 0
	s_mov_b32 m0, s37
	v_lshl_add_u64 v[218:219], s[60:61], 0, v[152:153]
	s_barrier
	ds_read_b128 v[164:167], v186 offset:16384
	ds_read_b128 v[168:171], v186 offset:17408
	ds_read_b128 v[172:175], v186 offset:18432
	ds_read_b128 v[176:179], v186 offset:19456
	ds_read_b128 v[190:193], v186 offset:20480
	ds_read_b128 v[194:197], v186 offset:21504
	ds_read_b128 v[198:201], v186 offset:22528
	ds_read_b128 v[202:205], v186 offset:23552
	global_load_lds_dwordx4 v[218:219], off
	s_mov_b32 m0, s38
	v_lshl_add_u64 v[226:227], s[60:61], 0, v[156:157]
	global_load_lds_dwordx4 v[226:227], off
	s_barrier
	s_waitcnt lgkmcnt(0)
	v_mfma_f32_16x16x32_bf16 v[52:55], v[134:137], v[164:167], v[52:55]
	v_mfma_f32_16x16x32_bf16 v[48:51], v[142:145], v[164:167], v[48:51]
	v_mfma_f32_16x16x32_bf16 v[44:47], v[134:137], v[172:175], v[44:47]
	v_mfma_f32_16x16x32_bf16 v[36:39], v[142:145], v[172:175], v[36:39]
	v_mfma_f32_16x16x32_bf16 v[28:31], v[134:137], v[190:193], v[28:31]
	v_mfma_f32_16x16x32_bf16 v[20:23], v[142:145], v[190:193], v[20:23]
	v_mfma_f32_16x16x32_bf16 v[12:15], v[134:137], v[198:201], v[12:15]
	v_mfma_f32_16x16x32_bf16 v[4:7], v[142:145], v[198:201], v[4:7]
	v_mfma_f32_16x16x32_bf16 v[52:55], v[138:141], v[168:171], v[52:55]
	v_mfma_f32_16x16x32_bf16 v[48:51], v[146:149], v[168:171], v[48:51]
	v_mfma_f32_16x16x32_bf16 v[44:47], v[138:141], v[176:179], v[44:47]
	v_mfma_f32_16x16x32_bf16 v[36:39], v[146:149], v[176:179], v[36:39]
	v_mfma_f32_16x16x32_bf16 v[28:31], v[138:141], v[194:197], v[28:31]
	v_mfma_f32_16x16x32_bf16 v[20:23], v[146:149], v[194:197], v[20:23]
	v_mfma_f32_16x16x32_bf16 v[12:15], v[138:141], v[202:205], v[12:15]
	v_mfma_f32_16x16x32_bf16 v[4:7], v[146:149], v[202:205], v[4:7]
	s_barrier
;     __device__ __forceinline__ void epi(const f32x4 (&acc)[2][2][4][2], const Unit& u, int wr, int wc, int fr, int fq) const {
;     ...
;             u32x4 xo[4][2];
; #pragma unroll
;             for (int m = 0; m < 4; ++m)
; #pragma unroll
;                 for (int bj = 0; bj < 2; ++bj) xo[m][bj] = *(const u32x4*)(xb + (size_t)(row0 + ai * 128 + m * 16) * D + col0 + bj * 128);
	s_add_u32 s62, s26, 0xb0000
	s_addc_u32 s63, s27, 0
	s_mov_b32 m0, s52
	v_lshl_add_u64 v[134:135], s[62:63], 0, v[154:155]
	global_load_lds_dwordx4 v[134:135], off
	s_mov_b32 m0, s53
	v_lshl_add_u64 v[134:135], s[62:63], 0, v[158:159]
	global_load_lds_dwordx4 v[134:135], off
	s_waitcnt vmcnt(6)
	s_barrier
	v_mfma_f32_16x16x32_bf16 v[60:63], v[206:209], v[164:167], v[60:63]
	v_lshl_or_b32 v248, s30, 8, v184
	v_mfma_f32_16x16x32_bf16 v[56:59], v[214:217], v[164:167], v[56:59]
	v_lshl_add_u32 v250, s2, 8, v182
	v_mfma_f32_16x16x32_bf16 v[40:43], v[206:209], v[172:175], v[40:43]
	v_ashrrev_i32_e32 v249, 31, v248
	v_mfma_f32_16x16x32_bf16 v[32:35], v[214:217], v[172:175], v[32:35]
	v_lshlrev_b64 v[248:249], 1, v[248:249]
	v_mfma_f32_16x16x32_bf16 v[24:27], v[206:209], v[190:193], v[24:27]
	v_ashrrev_i32_e32 v251, 31, v250
	v_mfma_f32_16x16x32_bf16 v[16:19], v[214:217], v[190:193], v[16:19]
	v_lshl_add_u64 v[248:249], s[0:1], 0, v[248:249]
	v_mfma_f32_16x16x32_bf16 v[8:11], v[206:209], v[198:201], v[8:11]
	v_lshlrev_b64 v[250:251], 11, v[250:251]
	v_mfma_f32_16x16x32_bf16 v[0:3], v[214:217], v[198:201], v[0:3]
	v_lshl_add_u64 v[252:253], v[248:249], 0, v[250:251]
	v_mfma_f32_16x16x32_bf16 v[60:63], v[210:213], v[168:171], v[60:63]
	global_load_dwordx4 v[232:235], v[252:253], off
	v_mfma_f32_16x16x32_bf16 v[56:59], v[222:225], v[168:171], v[56:59]
	global_load_dwordx4 v[236:239], v[252:253], off offset:256
	v_mfma_f32_16x16x32_bf16 v[40:43], v[210:213], v[176:179], v[40:43]
	v_mov_b32_e32 v250, 0x8000
	v_mfma_f32_16x16x32_bf16 v[32:35], v[222:225], v[176:179], v[32:35]
	v_mov_b32_e32 v251, 0
	v_mfma_f32_16x16x32_bf16 v[24:27], v[210:213], v[194:197], v[24:27]
	v_lshl_add_u64 v[250:251], v[252:253], 0, v[250:251]
	v_mfma_f32_16x16x32_bf16 v[16:19], v[222:225], v[194:197], v[16:19]
	global_load_dwordx4 v[240:243], v[250:251], off
	v_mfma_f32_16x16x32_bf16 v[8:11], v[210:213], v[202:205], v[8:11]
	global_load_dwordx4 v[244:247], v[250:251], off offset:256
	v_mfma_f32_16x16x32_bf16 v[0:3], v[222:225], v[202:205], v[0:3]
	s_barrier
	ds_read_b128 v[134:137], v132
	ds_read_b128 v[138:141], v132 offset:1024
	ds_read_b128 v[142:145], v132 offset:2048
	ds_read_b128 v[146:149], v132 offset:3072
	s_add_u32 s60, s60, 0xb0000
	s_addc_u32 s61, s61, 0
	s_mov_b32 m0, s39
	v_lshl_add_u64 v[206:207], s[60:61], 0, v[152:153]
	ds_read_b128 v[164:167], v186 offset:32768
	ds_read_b128 v[168:171], v186 offset:33792
	ds_read_b128 v[172:175], v186 offset:34816
	ds_read_b128 v[176:179], v186 offset:35840
	ds_read_b128 v[190:193], v186 offset:36864
	ds_read_b128 v[194:197], v186 offset:37888
	ds_read_b128 v[198:201], v186 offset:38912
	ds_read_b128 v[202:205], v186 offset:39936
	global_load_lds_dwordx4 v[206:207], off
	s_mov_b32 m0, s40
	v_lshl_add_u64 v[206:207], s[60:61], 0, v[156:157]
	global_load_lds_dwordx4 v[206:207], off
	s_waitcnt lgkmcnt(8)
	s_barrier
	s_waitcnt lgkmcnt(0)
	v_mfma_f32_16x16x32_bf16 v[116:119], v[134:137], v[164:167], v[116:119]
	v_mfma_f32_16x16x32_bf16 v[112:115], v[142:145], v[164:167], v[112:115]
	v_mfma_f32_16x16x32_bf16 v[108:111], v[134:137], v[172:175], v[108:111]
	v_mfma_f32_16x16x32_bf16 v[104:107], v[142:145], v[172:175], v[104:107]
	v_mfma_f32_16x16x32_bf16 v[92:95], v[134:137], v[190:193], v[92:95]
	v_mfma_f32_16x16x32_bf16 v[88:91], v[142:145], v[190:193], v[88:91]
	v_mfma_f32_16x16x32_bf16 v[76:79], v[134:137], v[198:201], v[76:79]
	v_mfma_f32_16x16x32_bf16 v[72:75], v[142:145], v[198:201], v[72:75]
	v_mfma_f32_16x16x32_bf16 v[116:119], v[138:141], v[168:171], v[116:119]
	v_mfma_f32_16x16x32_bf16 v[112:115], v[146:149], v[168:171], v[112:115]
	v_mfma_f32_16x16x32_bf16 v[108:111], v[138:141], v[176:179], v[108:111]
	v_mfma_f32_16x16x32_bf16 v[104:107], v[146:149], v[176:179], v[104:107]
	v_mfma_f32_16x16x32_bf16 v[92:95], v[138:141], v[194:197], v[92:95]
	v_mfma_f32_16x16x32_bf16 v[88:91], v[146:149], v[194:197], v[88:91]
	v_mfma_f32_16x16x32_bf16 v[76:79], v[138:141], v[202:205], v[76:79]
	v_mfma_f32_16x16x32_bf16 v[72:75], v[146:149], v[202:205], v[72:75]
	s_barrier
	s_mov_b32 m0, s54
	v_lshl_add_u64 v[150:151], v[150:151], 0, s[10:11]
	ds_read_b128 v[206:209], v133
	ds_read_b128 v[210:213], v133 offset:1024
	ds_read_b128 v[214:217], v133 offset:2048
	ds_read_b128 v[222:225], v133 offset:3072
	global_load_lds_dwordx4 v[150:151], off
	s_mov_b32 m0, s55
	v_lshl_add_u64 v[150:151], v[180:181], 0, s[10:11]
	global_load_lds_dwordx4 v[150:151], off
	s_barrier
	s_waitcnt lgkmcnt(0)
	v_mfma_f32_16x16x32_bf16 v[124:127], v[206:209], v[164:167], v[124:127]
	v_mfma_f32_16x16x32_bf16 v[120:123], v[214:217], v[164:167], v[120:123]
	v_mfma_f32_16x16x32_bf16 v[100:103], v[206:209], v[172:175], v[100:103]
	v_mfma_f32_16x16x32_bf16 v[96:99], v[214:217], v[172:175], v[96:99]
	v_mfma_f32_16x16x32_bf16 v[84:87], v[206:209], v[190:193], v[84:87]
	v_mfma_f32_16x16x32_bf16 v[80:83], v[214:217], v[190:193], v[80:83]
	v_mfma_f32_16x16x32_bf16 v[68:71], v[206:209], v[198:201], v[68:71]
	v_mfma_f32_16x16x32_bf16 v[64:67], v[214:217], v[198:201], v[64:67]
	v_mfma_f32_16x16x32_bf16 v[124:127], v[210:213], v[168:171], v[124:127]
	v_mfma_f32_16x16x32_bf16 v[120:123], v[222:225], v[168:171], v[120:123]
	v_mfma_f32_16x16x32_bf16 v[100:103], v[210:213], v[176:179], v[100:103]
	v_mfma_f32_16x16x32_bf16 v[96:99], v[222:225], v[176:179], v[96:99]
	v_mfma_f32_16x16x32_bf16 v[84:87], v[210:213], v[194:197], v[84:87]
	v_mfma_f32_16x16x32_bf16 v[80:83], v[222:225], v[194:197], v[80:83]
	v_mfma_f32_16x16x32_bf16 v[68:71], v[210:213], v[202:205], v[68:71]
	v_mfma_f32_16x16x32_bf16 v[64:67], v[222:225], v[202:205], v[64:67]
	s_mov_b32 m0, s42
	v_lshl_add_u64 v[150:151], v[218:219], 0, s[10:11]
	s_barrier
	ds_read_b128 v[164:167], v186 offset:49152
	ds_read_b128 v[168:171], v186 offset:50176
	ds_read_b128 v[172:175], v186 offset:51200
	ds_read_b128 v[176:179], v186 offset:52224
	ds_read_b128 v[190:193], v186 offset:53248
	ds_read_b128 v[194:197], v186 offset:54272
	ds_read_b128 v[198:201], v186 offset:55296
	ds_read_b128 v[202:205], v186 offset:56320
	global_load_lds_dwordx4 v[150:151], off
	s_mov_b32 m0, s43
	v_lshl_add_u64 v[150:151], v[226:227], 0, s[10:11]
	global_load_lds_dwordx4 v[150:151], off
	s_barrier
	s_waitcnt lgkmcnt(0)
	v_mfma_f32_16x16x32_bf16 v[52:55], v[134:137], v[164:167], v[52:55]
	v_mfma_f32_16x16x32_bf16 v[48:51], v[142:145], v[164:167], v[48:51]
	v_mfma_f32_16x16x32_bf16 v[44:47], v[134:137], v[172:175], v[44:47]
	v_mfma_f32_16x16x32_bf16 v[36:39], v[142:145], v[172:175], v[36:39]
	v_mfma_f32_16x16x32_bf16 v[28:31], v[134:137], v[190:193], v[28:31]
	v_mfma_f32_16x16x32_bf16 v[20:23], v[142:145], v[190:193], v[20:23]
	v_mfma_f32_16x16x32_bf16 v[12:15], v[134:137], v[198:201], v[12:15]
	v_mfma_f32_16x16x32_bf16 v[4:7], v[142:145], v[198:201], v[4:7]
	v_mfma_f32_16x16x32_bf16 v[52:55], v[138:141], v[168:171], v[52:55]
	v_mfma_f32_16x16x32_bf16 v[48:51], v[146:149], v[168:171], v[48:51]
	v_mfma_f32_16x16x32_bf16 v[44:47], v[138:141], v[176:179], v[44:47]
	v_mfma_f32_16x16x32_bf16 v[36:39], v[146:149], v[176:179], v[36:39]
	v_mfma_f32_16x16x32_bf16 v[28:31], v[138:141], v[194:197], v[28:31]
	v_mfma_f32_16x16x32_bf16 v[20:23], v[146:149], v[194:197], v[20:23]
	v_mfma_f32_16x16x32_bf16 v[12:15], v[138:141], v[202:205], v[12:15]
	v_mfma_f32_16x16x32_bf16 v[4:7], v[146:149], v[202:205], v[4:7]
	s_barrier
	s_add_u32 s26, s26, 0xb0080
	s_addc_u32 s27, s27, 0
	s_mov_b32 m0, s56
	v_lshl_add_u64 v[134:135], s[26:27], 0, v[154:155]
	global_load_lds_dwordx4 v[134:135], off
	s_mov_b32 m0, s57
	v_lshl_add_u64 v[134:135], s[26:27], 0, v[158:159]
	global_load_lds_dwordx4 v[134:135], off
	s_waitcnt vmcnt(6)
	s_barrier
	v_mfma_f32_16x16x32_bf16 v[60:63], v[206:209], v[164:167], v[60:63]
	v_mfma_f32_16x16x32_bf16 v[56:59], v[214:217], v[164:167], v[56:59]
	v_mfma_f32_16x16x32_bf16 v[40:43], v[206:209], v[172:175], v[40:43]
	v_mfma_f32_16x16x32_bf16 v[32:35], v[214:217], v[172:175], v[32:35]
	v_mfma_f32_16x16x32_bf16 v[24:27], v[206:209], v[190:193], v[24:27]
	v_mfma_f32_16x16x32_bf16 v[16:19], v[214:217], v[190:193], v[16:19]
	v_mfma_f32_16x16x32_bf16 v[8:11], v[206:209], v[198:201], v[8:11]
	v_mfma_f32_16x16x32_bf16 v[0:3], v[214:217], v[198:201], v[0:3]
	v_mfma_f32_16x16x32_bf16 v[60:63], v[210:213], v[168:171], v[60:63]
	v_mfma_f32_16x16x32_bf16 v[56:59], v[222:225], v[168:171], v[56:59]
	v_mfma_f32_16x16x32_bf16 v[40:43], v[210:213], v[176:179], v[40:43]
	v_mfma_f32_16x16x32_bf16 v[32:35], v[222:225], v[176:179], v[32:35]
	v_mfma_f32_16x16x32_bf16 v[24:27], v[210:213], v[194:197], v[24:27]
	v_mfma_f32_16x16x32_bf16 v[16:19], v[222:225], v[194:197], v[16:19]
	v_mfma_f32_16x16x32_bf16 v[8:11], v[210:213], v[202:205], v[8:11]
	v_mfma_f32_16x16x32_bf16 v[0:3], v[222:225], v[202:205], v[0:3]
	s_add_i32 s58, s58, 2
	s_add_u32 s24, s24, 0x100
	s_addc_u32 s25, s25, 0
	s_cmp_gt_u32 s58, 41
	s_barrier
; __device__ __forceinline__ unsigned pk2(float lo, float hi) { unsigned r; asm volatile("v_cvt_pk_bf16_f32 %0, %1, %2" : "=v"(r) : "v"(lo), "v"(hi)); return r; }
; __device__ __forceinline__ unsigned pk2(float lo, float hi) { return f2bf(lo) | (f2bf(hi) << 16); }
;     __device__ __forceinline__ void epi(const f32x4 (&acc)[2][2][4][2], const Unit& u, int wr, int wc, int fr, int fq) const {
;     ...
;         const int row0 = u.pm * 256 + wr * 64 + fr, col0 = u.pn * 256 + wc * 32 + 8 * fq;
; #pragma unroll
;         for (int ai = 0; ai < 2; ++ai) {
;             u32x4 xo[4][2];
; #pragma unroll
;             for (int m = 0; m < 4; ++m)
; #pragma unroll
;                 for (int bj = 0; bj < 2; ++bj) xo[m][bj] = *(const u32x4*)(xb + (size_t)(row0 + ai * 128 + m * 16) * D + col0 + bj * 128);
; #pragma unroll
;             for (int m = 0; m < 4; ++m) {
;                 const int row = row0 + ai * 128 + m * 16; const size_t off = (size_t)row * D + col0; float ss = 0.f;
; #pragma unroll
;                 for (int bj = 0; bj < 2; ++bj) {
;                     const u32x4 o = xo[m][bj]; const f32x4 a0v = acc[ai][bj][m][0], a1v = acc[ai][bj][m][1];
;                     const float v0 = bf_lo(o.x) + coef * a0v[0], v1 = bf_hi(o.x) + coef * a0v[1], v2 = bf_lo(o.y) + coef * a0v[2], v3 = bf_hi(o.y) + coef * a0v[3];
;                     const float v4 = bf_lo(o.z) + coef * a1v[0], v5 = bf_hi(o.z) + coef * a1v[1], v6 = bf_lo(o.w) + coef * a1v[2], v7 = bf_hi(o.w) + coef * a1v[3];
;                     u32x4 w; w.x = pk2(v0, v1); w.y = pk2(v2, v3); w.z = pk2(v4, v5); w.w = pk2(v6, v7);
;                     *(u32x4*)(xb + off + bj * 128) = w;
;                     ss += ((v0 * v0 + v1 * v1) + (v2 * v2 + v3 * v3)) + ((v4 * v4 + v5 * v5) + (v6 * v6 + v7 * v7));
;                 }
;                 ss += __shfl_xor(ss, 16); ss += __shfl_xor(ss, 32);
;                 if (fq == 0) rowss[(size_t)row * 32 + u.pn * 4 + wc] = ss;
;             }
	v_lshl_or_b32 v164, s30, 8, v184
	v_lshl_add_u32 v168, s2, 8, v182
	v_ashrrev_i32_e32 v165, 31, v164
	v_lshlrev_b64 v[198:199], 1, v[164:165]
	v_ashrrev_i32_e32 v169, 31, v168
	v_lshl_add_u64 v[166:167], s[0:1], 0, v[198:199]
	v_lshlrev_b64 v[200:201], 11, v[168:169]
	v_lshl_add_u64 v[128:129], v[166:167], 0, v[200:201]
	v_mov_b32_e32 v218, 0x40000
	v_mov_b32_e32 v219, 0
	v_lshl_add_u64 v[216:217], v[128:129], 0, v[218:219]
	v_mov_b32_e32 v218, 0x8000
	s_waitcnt vmcnt(8)
	v_mov_b64_e32 v[190:191], v[232:233]
	v_mov_b64_e32 v[192:193], v[234:235]
	v_mov_b64_e32 v[194:195], v[236:237]
	v_mov_b64_e32 v[196:197], v[238:239]
	v_or_b32_e32 v178, 16, v168
	v_or_b32_e32 v174, 32, v168
	v_or_b32_e32 v170, 48, v168
	v_ashrrev_i32_e32 v179, 31, v178
	v_ashrrev_i32_e32 v175, 31, v174
	v_ashrrev_i32_e32 v171, 31, v170
	v_lshlrev_b64 v[180:181], 11, v[178:179]
	v_lshlrev_b64 v[176:177], 11, v[174:175]
	v_lshlrev_b64 v[172:173], 11, v[170:171]
	v_lshl_add_u64 v[128:129], v[166:167], 0, v[180:181]
	v_lshl_add_u64 v[130:131], v[166:167], 0, v[176:177]
	v_lshl_add_u64 v[202:203], v[166:167], 0, v[172:173]
	v_mov_b64_e32 v[148:149], v[240:241]
	v_mov_b64_e32 v[150:151], v[242:243]
	v_mov_b64_e32 v[144:145], v[244:245]
	v_mov_b64_e32 v[146:147], v[246:247]
	global_load_dwordx4 v[140:143], v[130:131], off
	global_load_dwordx4 v[136:139], v[130:131], off offset:256
	global_load_dwordx4 v[132:135], v[202:203], off
	s_nop 0
	global_load_dwordx4 v[128:131], v[202:203], off offset:256
	global_load_dwordx4 v[222:225], v[216:217], off
	global_load_dwordx4 v[226:229], v[216:217], off offset:256
	v_lshl_add_u64 v[216:217], v[216:217], 0, v[218:219]
	global_load_dwordx4 v[230:233], v[216:217], off
	global_load_dwordx4 v[234:237], v[216:217], off offset:256
	v_lshl_add_u64 v[216:217], v[216:217], 0, v[218:219]
	global_load_dwordx4 v[238:241], v[216:217], off
	global_load_dwordx4 v[242:245], v[216:217], off offset:256
	v_lshl_add_u64 v[216:217], v[216:217], 0, v[218:219]
	global_load_dwordx4 v[246:249], v[216:217], off
	global_load_dwordx4 v[250:253], v[216:217], off offset:256
	v_and_b32_e32 v202, 64, v188
	v_xor_b32_e32 v189, 16, v188
	v_add_u32_e32 v202, 64, v202
	v_cmp_lt_i32_e32 vcc, v189, v202
	v_lshlrev_b32_e32 v203, 16, v190
	v_and_b32_e32 v190, 0xffff0000, v190
	v_lshlrev_b32_e32 v204, 16, v191
	v_and_b32_e32 v191, 0xffff0000, v191
	v_lshlrev_b32_e32 v205, 16, v192
	v_and_b32_e32 v192, 0xffff0000, v192
	v_lshlrev_b32_e32 v206, 16, v193
	v_and_b32_e32 v193, 0xffff0000, v193
	v_lshlrev_b32_e32 v207, 16, v194
	v_and_b32_e32 v194, 0xffff0000, v194
	v_lshlrev_b32_e32 v208, 16, v195
	v_and_b32_e32 v195, 0xffff0000, v195
	v_lshlrev_b32_e32 v209, 16, v196
	v_and_b32_e32 v196, 0xffff0000, v196
	v_lshlrev_b32_e32 v210, 16, v197
	v_and_b32_e32 v197, 0xffff0000, v197
	v_fmac_f32_e32 v190, 0.5, v117
	v_fmac_f32_e32 v191, 0.5, v119
	v_fmac_f32_e32 v192, 0.5, v113
	v_fmac_f32_e32 v193, 0.5, v115
	v_fmac_f32_e32 v194, 0.5, v125
	v_fmac_f32_e32 v195, 0.5, v127
	v_fmac_f32_e32 v196, 0.5, v121
	v_fmac_f32_e32 v197, 0.5, v123
	v_fmac_f32_e32 v203, 0.5, v116
	v_fmac_f32_e32 v204, 0.5, v118
	v_fmac_f32_e32 v205, 0.5, v112
	v_fmac_f32_e32 v206, 0.5, v114
	v_fmac_f32_e32 v207, 0.5, v124
	v_fmac_f32_e32 v208, 0.5, v126
	v_fmac_f32_e32 v209, 0.5, v120
	v_fmac_f32_e32 v210, 0.5, v122
	v_mul_f32_e32 v112, v190, v190
	v_mul_f32_e32 v113, v191, v191
	v_mul_f32_e32 v118, v192, v192
	v_mul_f32_e32 v119, v193, v193
	v_mul_f32_e32 v120, v194, v194
	v_mul_f32_e32 v121, v195, v195
	v_mul_f32_e32 v122, v196, v196
	v_mul_f32_e32 v123, v197, v197
	v_fmac_f32_e32 v112, v203, v203
	v_fmac_f32_e32 v113, v204, v204
	v_fmac_f32_e32 v118, v205, v205
	v_fmac_f32_e32 v119, v206, v206
	v_fmac_f32_e32 v120, v207, v207
	v_fmac_f32_e32 v121, v208, v208
	v_fmac_f32_e32 v122, v209, v209
	v_fmac_f32_e32 v123, v210, v210
	v_add_f32_e32 v112, v112, v113
	v_add_f32_e32 v113, v118, v119
	v_add_f32_e32 v118, v120, v121
	v_add_f32_e32 v119, v122, v123
	v_cndmask_b32_e32 v189, v188, v189, vcc
	v_add_f32_e32 v112, v112, v113
	v_add_f32_e32 v113, v118, v119
	v_add_f32_e32 v113, v112, v113
	v_lshlrev_b32_e32 v112, 2, v189
	ds_bpermute_b32 v122, v112, v113
	v_lshl_add_u64 v[118:119], s[0:1], 0, v[200:201]
	v_cvt_pk_bf16_f32 v114, v203, v190
	v_lshl_add_u64 v[120:121], v[118:119], 0, v[198:199]
	v_cvt_pk_bf16_f32 v115, v204, v191
	v_cvt_pk_bf16_f32 v116, v205, v192
	v_cvt_pk_bf16_f32 v117, v206, v193
	global_store_dwordx4 v[120:121], v[114:117], off
	s_waitcnt lgkmcnt(0)
	s_nop 0
	v_add_f32_e32 v114, v113, v122
	v_xor_b32_e32 v113, 32, v188
	v_cmp_lt_i32_e32 vcc, v113, v202
	v_cvt_pk_bf16_f32 v116, v207, v194
	v_cvt_pk_bf16_f32 v117, v208, v195
	v_cvt_pk_bf16_f32 v118, v209, v196
	v_cvt_pk_bf16_f32 v119, v210, v197
	global_store_dwordx4 v[120:121], v[116:119], off offset:256
	s_nop 0
	v_cndmask_b32_e32 v113, v188, v113, vcc
	v_lshlrev_b32_e32 v113, 2, v113
	ds_bpermute_b32 v115, v113, v114
	s_and_saveexec_b64 s[20:21], s[4:5]
	s_cbranch_execz .LBB0_1909
	s_waitcnt lgkmcnt(0)
	v_add_f32_e32 v116, v114, v115
	s_lshl_b32 s22, s30, 2
	v_lshlrev_b64 v[114:115], 7, v[168:169]
	s_ashr_i32 s23, s22, 31
	v_lshl_add_u64 v[114:115], s[8:9], 0, v[114:115]
	v_lshl_add_u64 v[114:115], s[22:23], 2, v[114:115]
	s_lshl_b32 s2, s41, 2
	v_lshl_add_u64 v[114:115], v[114:115], 0, s[2:3]
	global_store_dword v[114:115], v116, off
